# removed initial cooperative grid.sync; 4x-unrolled f32->bf16 conversion loops for p/x (8 loads in flight per lane)
# speedup vs baseline: 1.0045x; 1.0045x over previous
; #define LAS __attribute__((address_space(3)))
; __device__ __forceinline__ void wconv_phase(KP Pk, int L, unsigned char* lds, int G, int blk) {
;     ...
;     int tid_l = threadIdx.x; asm volatile("" : "+v"(tid_l)); const int tid = tid_l, lane = tid & 63, wid = __builtin_amdgcn_readfirstlane(tid >> 6), j = L >> 1; const bool att = (L & 1) == 0;
;     float* scr = (float*)(lds + wid * 16384);
;     unsigned char* ws = P.ws;
;     bf16_t *WIN = (bf16_t*)(ws + WS_WIN), *WOUT = (bf16_t*)(ws + WS_WOUT), *W1 = (bf16_t*)(ws + WS_W1), *W2 = (bf16_t*)(ws + WS_W2), *WG = (bf16_t*)(ws + WS_WG), *WP = (bf16_t*)(ws + WS_WP);
;     float* vecp = (float*)(ws + WS_VECP);
;     const int nin = att ? NQKV / 32 : HIN / 32;
;     const int I0 = nin * 16, I1 = I0 + 32 * 16, I2 = I1 + 176 * 16, I3 = I2 + 32 * 44, I4 = I3 + 32 * 16, I5 = I4 + 32 * 4;
;     for (int it = wid * G + blk; it < I5; it += 8 * G) {
; __global__ void __launch_bounds__(512, 2) mk_fwd(Ptrs Parg) {
;     extern __shared__ __attribute__((aligned(16))) unsigned char lds[];
;     cg::grid_group grid = cg::this_grid();
;     volatile LAS unsigned* bst = (volatile LAS unsigned*)((LAS unsigned char*)lds + (LDS_BYTES - 16));
;     if (threadIdx.x < 4) bst[threadIdx.x] = 0u;
;     __syncthreads();
;     XcdBarrier bar = xcd_barrier_post((unsigned*)(Parg.ws + WS_CTL), bst);
;     grid.sync();
;     layer_fwd<0>(lds, bar); layer_fwd<1>(lds, bar); layer_fwd<2>(lds, bar); layer_fwd<3>(lds, bar);
.LBB0_5:
	s_or_b64 exec, exec, s[4:5]
	s_or_b64 exec, exec, s[4:5]
	s_mov_b64 s[14:15], s[0:1]
	s_mov_b32 s10, s2
	s_mov_b32 s8, s74
	v_mov_b32_e32 v0, v254
	s_barrier
	s_load_dwordx2 s[12:13], s[14:15], 0x90
	v_readfirstlane_b32 s3, v0
	s_ashr_i32 s3, s3, 6
	s_mul_i32 s4, s3, s8
	s_add_i32 s9, s4, s10
	s_cmpk_gt_i32 s9, 0x17ff
	s_cbranch_scc1 .LBB0_54
	s_waitcnt lgkmcnt(0)
	s_add_u32 s11, s12, 0x1fd00000
	v_lshlrev_b32_e32 v18, 3, v0
	s_addc_u32 s22, s13, 0
	s_lshl_b32 s3, s3, 14
	v_and_b32_e32 v4, 56, v18
	v_bfe_u32 v3, v0, 3, 3
	s_add_i32 s4, s3, 0
	v_mul_u32_u24_e32 v5, 0x84, v4
	v_lshlrev_b32_e32 v6, 2, v3
	v_add3_u32 v48, s4, v5, v6
	v_lshlrev_b32_e32 v4, 1, v4
	v_mov_b32_e32 v5, 0
	v_bfe_u32 v2, v0, 5, 1
	v_lshl_add_u64 v[6:7], s[12:13], 0, v[4:5]
	s_mov_b64 s[4:5], 0x1f00000
	v_and_b32_e32 v4, 1, v0
	v_and_b32_e32 v12, 63, v0
	v_and_b32_e32 v1, 31, v0
	v_lshl_add_u64 v[8:9], v[6:7], 0, s[4:5]
	s_mov_b64 s[4:5], 0x1d00000
	s_mov_b64 s[6:7], 0x1700000
	v_cmp_eq_u32_e32 vcc, 1, v4
	v_mul_u32_u24_e32 v4, 0x84, v2
	v_lshl_add_u64 v[10:11], v[6:7], 0, s[4:5]
	v_cmp_gt_u32_e64 s[4:5], 32, v12
	v_lshl_add_u64 v[12:13], v[6:7], 0, s[6:7]
	v_mov_b32_e32 v14, 0xb00
	s_mov_b64 s[6:7], 0xc00000
	v_and_b32_e32 v53, 8, v18
	v_or_b32_e32 v4, s3, v4
	v_lshlrev_b32_e32 v18, 2, v1
	v_cndmask_b32_e32 v52, 0, v14, vcc
	v_lshl_add_u64 v[14:15], v[6:7], 0, s[6:7]
	s_mov_b64 s[6:7], 0xa00000
	v_add3_u32 v54, v4, v18, 0
	s_lshl_b32 s3, s9, 3
	s_add_i32 s30, s9, 0xfffffb00
	v_mbcnt_lo_u32_b32 v4, -1, 0
	s_mov_b32 s17, 0
	v_or_b32_e32 v49, 8, v3
	v_or_b32_e32 v50, 16, v3
	v_or_b32_e32 v51, 24, v3
	v_lshl_add_u64 v[16:17], v[6:7], 0, s[6:7]
	s_lshl_b32 s23, s8, 3
	s_add_i32 s24, s3, 0xffff4400
	s_lshl_b32 s25, s8, 6
	v_or_b32_e32 v55, 14, v2
	s_lshl_b32 s26, s9, 6
	s_lshl_b32 s27, s8, 9
	v_or_b32_e32 v56, 12, v2
	v_or_b32_e32 v57, 10, v2
	v_or_b32_e32 v58, 8, v2
	v_or_b32_e32 v59, 6, v2
	v_or_b32_e32 v60, 4, v2
	v_or_b32_e32 v61, 2, v2
	v_or_b32_e32 v62, 0xffffd500, v1
	s_lshl_b32 s28, s9, 1
	s_lshl_b32 s29, s8, 4
	v_lshlrev_b32_e32 v18, 2, v2
	v_mov_b32_e32 v19, v5
	s_lshl_b32 s31, s30, 1
	v_or_b32_e32 v63, 0xfffffa00, v1
	s_mov_b64 s[18:19], 0x10000
	s_mov_b64 s[20:21], 0x58000
	s_movk_i32 s34, 0x1800
	s_movk_i32 s35, 0x500
	v_mbcnt_hi_u32_b32 v64, -1, v4
	s_mov_b32 s36, s9
	s_branch .LBB0_18

; __device__ __forceinline__ u32x4 pack8(const f32x4 a, const f32x4 b) { u32x4 w; w.x = cvt_pk_bf16(a[0], a[1]); w.y = cvt_pk_bf16(a[2], a[3]); w.z = cvt_pk_bf16(b[0], b[1]); w.w = cvt_pk_bf16(b[2], b[3]); return w; }
; __device__ __forceinline__ void cvt_f32_bf16(const float* src, bf16_t* dst, size_t n, size_t gt, size_t GT) {
;     for (size_t i = gt * 8; i < n; i += GT * 8) { const f32x4 a = *(const f32x4*)(src + i), b = *(const f32x4*)(src + i + 4); *(u32x4*)(dst + i) = pack8(a, b); }
; }
; __device__ __forceinline__ void wconv_phase(KP Pk, int L, unsigned char* lds, int G, int blk) {
;     ...
;     cvt_f32_bf16(P.p + (size_t)L * M * PLE, (bf16_t*)(ws + WS_PB), (size_t)M * PLE, gt, GT);
.LBB0_54:
	s_ashr_i32 s11, s10, 31
	s_lshl_b64 s[4:5], s[10:11], 9
	v_ashrrev_i32_e32 v1, 31, v0
	v_lshl_add_u64 v[2:3], s[4:5], 0, v[0:1]
	v_lshlrev_b64 v[4:5], 3, v[2:3]
	s_mov_b64 s[4:5], 0x800000
	s_ashr_i32 s9, s8, 31
	v_cmp_gt_u64_e32 vcc, s[4:5], v[4:5]
	v_lshlrev_b64 v[6:7], 5, v[0:1]
	s_and_saveexec_b64 s[4:5], vcc
	s_cbranch_execz .LBB0_57
	s_load_dwordx2 s[18:19], s[14:15], 0x8
	s_lshl_b64 s[6:7], s[8:9], 12
	s_lshl_b64 s[16:17], s[10:11], 13
	s_waitcnt lgkmcnt(0)
	s_add_u32 s16, s12, s16
	s_addc_u32 s17, s13, s17
	v_lshl_add_u64 v[8:9], v[0:1], 4, s[16:17]
	s_mov_b64 s[16:17], 0x1e800000
	v_lshl_add_u64 v[8:9], v[8:9], 0, s[16:17]
	s_lshl_b64 s[16:17], s[8:9], 13
	s_lshl_b64 s[20:21], s[10:11], 14
	s_add_u32 s18, s18, s20
	s_addc_u32 s19, s19, s21
	v_lshl_add_u64 v[10:11], s[18:19], 0, v[6:7]
	v_lshl_add_u64 v[10:11], v[10:11], 0, 16
	s_lshl_b64 s[18:19], s[8:9], 14
	s_mov_b64 s[20:21], 0
	s_mov_b64 s[22:23], 0x7fffff
	v_mov_b64_e32 v[12:13], v[4:5]
	s_lshl_b64 s[50:51], s[18:19], 1
	s_add_u32 s52, s50, s18
	s_addc_u32 s53, s51, s19
	s_lshl_b64 s[54:55], s[16:17], 1
	s_add_u32 s56, s54, s16
	s_addc_u32 s57, s55, s17
	s_lshl_b64 s[58:59], s[6:7], 1
	s_add_u32 s60, s58, s6
	s_addc_u32 s61, s59, s7
	s_lshl_b64 s[62:63], s[6:7], 2
	s_lshl_b64 s[64:65], s[18:19], 2
	s_lshl_b64 s[66:67], s[16:17], 2
.Lcvt4_top_p0:
	v_lshl_add_u64 v[200:201], v[12:13], 0, s[60:61]
	v_cmp_ge_u64_e32 vcc, s[22:23], v[200:201]
	s_cmp_eq_u64 vcc, exec
	s_cbranch_scc0 .Lcvt4_rem_p0
	v_lshl_add_u64 v[202:203], v[10:11], 0, s[18:19]
	v_lshl_add_u64 v[204:205], v[10:11], 0, s[50:51]
	v_lshl_add_u64 v[206:207], v[10:11], 0, s[52:53]
	global_load_dwordx4 v[208:211], v[10:11], off offset:-16
	global_load_dwordx4 v[212:215], v[10:11], off
	global_load_dwordx4 v[216:219], v[202:203], off offset:-16
	global_load_dwordx4 v[220:223], v[202:203], off
	global_load_dwordx4 v[224:227], v[204:205], off offset:-16
	global_load_dwordx4 v[228:231], v[204:205], off
	global_load_dwordx4 v[232:235], v[206:207], off offset:-16
	global_load_dwordx4 v[236:239], v[206:207], off
	v_lshl_add_u64 v[240:241], v[8:9], 0, s[16:17]
	v_lshl_add_u64 v[242:243], v[8:9], 0, s[54:55]
	v_lshl_add_u64 v[244:245], v[8:9], 0, s[56:57]
	s_waitcnt vmcnt(6)
	v_cvt_pk_bf16_f32 v208, v208, v209
	v_cvt_pk_bf16_f32 v209, v210, v211
	v_cvt_pk_bf16_f32 v210, v212, v213
	v_cvt_pk_bf16_f32 v211, v214, v215
	global_store_dwordx4 v[8:9], v[208:211], off
	s_waitcnt vmcnt(5)
	v_cvt_pk_bf16_f32 v216, v216, v217
	v_cvt_pk_bf16_f32 v217, v218, v219
	v_cvt_pk_bf16_f32 v218, v220, v221
	v_cvt_pk_bf16_f32 v219, v222, v223
	global_store_dwordx4 v[240:241], v[216:219], off
	s_waitcnt vmcnt(4)
	v_cvt_pk_bf16_f32 v224, v224, v225
	v_cvt_pk_bf16_f32 v225, v226, v227
	v_cvt_pk_bf16_f32 v226, v228, v229
	v_cvt_pk_bf16_f32 v227, v230, v231
	global_store_dwordx4 v[242:243], v[224:227], off
	s_waitcnt vmcnt(3)
	v_cvt_pk_bf16_f32 v232, v232, v233
	v_cvt_pk_bf16_f32 v233, v234, v235
	v_cvt_pk_bf16_f32 v234, v236, v237
	v_cvt_pk_bf16_f32 v235, v238, v239
	global_store_dwordx4 v[244:245], v[232:235], off
	v_lshl_add_u64 v[10:11], v[10:11], 0, s[64:65]
	v_lshl_add_u64 v[8:9], v[8:9], 0, s[66:67]
	v_lshl_add_u64 v[12:13], v[12:13], 0, s[62:63]
	v_cmp_ge_u64_e32 vcc, s[22:23], v[12:13]
	s_cbranch_vccnz .Lcvt4_top_p0
	s_branch .LBB0_57
.Lcvt4_rem_p0:
	v_cmp_ge_u64_e32 vcc, s[22:23], v[12:13]
	s_and_b64 exec, exec, vcc
	s_cbranch_execz .LBB0_57

; __device__ __forceinline__ u32x4 pack8(const f32x4 a, const f32x4 b) { u32x4 w; w.x = cvt_pk_bf16(a[0], a[1]); w.y = cvt_pk_bf16(a[2], a[3]); w.z = cvt_pk_bf16(b[0], b[1]); w.w = cvt_pk_bf16(b[2], b[3]); return w; }
; __device__ __forceinline__ void cvt_f32_bf16(const float* src, bf16_t* dst, size_t n, size_t gt, size_t GT) {
;     for (size_t i = gt * 8; i < n; i += GT * 8) { const f32x4 a = *(const f32x4*)(src + i), b = *(const f32x4*)(src + i + 4); *(u32x4*)(dst + i) = pack8(a, b); }
; }
; __device__ __forceinline__ void wconv_phase(KP Pk, int L, unsigned char* lds, int G, int blk) {
;     ...
;         cvt_f32_bf16(P.x, (bf16_t*)(ws + WS_XBX), (size_t)M * D, gt, GT);
.LBB0_57:
	s_or_b64 exec, exec, s[4:5]
	s_mov_b64 s[4:5], 0x2000000
	v_cmp_gt_u64_e32 vcc, s[4:5], v[4:5]
	s_and_saveexec_b64 s[4:5], vcc
	s_cbranch_execz .LBB0_60
	s_load_dwordx2 s[16:17], s[14:15], 0x0
	s_lshl_b64 s[6:7], s[8:9], 12
	s_lshl_b64 s[14:15], s[10:11], 13
	s_waitcnt lgkmcnt(0)
	s_add_u32 s14, s12, s14
	s_addc_u32 s15, s13, s15
	v_lshl_add_u64 v[8:9], v[0:1], 4, s[14:15]
	s_mov_b64 s[14:15], 0x2800000
	v_lshl_add_u64 v[8:9], v[8:9], 0, s[14:15]
	s_lshl_b64 s[14:15], s[8:9], 13
	s_lshl_b64 s[18:19], s[10:11], 14
	s_add_u32 s16, s16, s18
	s_addc_u32 s17, s17, s19
	v_lshl_add_u64 v[6:7], s[16:17], 0, v[6:7]
	v_lshl_add_u64 v[6:7], v[6:7], 0, 16
	s_lshl_b64 s[16:17], s[8:9], 14
	s_mov_b64 s[18:19], 0
	s_mov_b64 s[20:21], 0x1ffffff
	s_lshl_b64 s[50:51], s[16:17], 1
	s_add_u32 s52, s50, s16
	s_addc_u32 s53, s51, s17
	s_lshl_b64 s[54:55], s[14:15], 1
	s_add_u32 s56, s54, s14
	s_addc_u32 s57, s55, s15
	s_lshl_b64 s[58:59], s[6:7], 1
	s_add_u32 s60, s58, s6
	s_addc_u32 s61, s59, s7
	s_lshl_b64 s[62:63], s[6:7], 2
	s_lshl_b64 s[64:65], s[16:17], 2
	s_lshl_b64 s[66:67], s[14:15], 2
.Lcvt4_top_x0:
	v_lshl_add_u64 v[200:201], v[4:5], 0, s[60:61]
	v_cmp_ge_u64_e32 vcc, s[20:21], v[200:201]
	s_cmp_eq_u64 vcc, exec
	s_cbranch_scc0 .Lcvt4_rem_x0
	v_lshl_add_u64 v[202:203], v[6:7], 0, s[16:17]
	v_lshl_add_u64 v[204:205], v[6:7], 0, s[50:51]
	v_lshl_add_u64 v[206:207], v[6:7], 0, s[52:53]
	global_load_dwordx4 v[208:211], v[6:7], off offset:-16
	global_load_dwordx4 v[212:215], v[6:7], off
	global_load_dwordx4 v[216:219], v[202:203], off offset:-16
	global_load_dwordx4 v[220:223], v[202:203], off
	global_load_dwordx4 v[224:227], v[204:205], off offset:-16
	global_load_dwordx4 v[228:231], v[204:205], off
	global_load_dwordx4 v[232:235], v[206:207], off offset:-16
	global_load_dwordx4 v[236:239], v[206:207], off
	v_lshl_add_u64 v[240:241], v[8:9], 0, s[14:15]
	v_lshl_add_u64 v[242:243], v[8:9], 0, s[54:55]
	v_lshl_add_u64 v[244:245], v[8:9], 0, s[56:57]
	s_waitcnt vmcnt(6)
	v_cvt_pk_bf16_f32 v208, v208, v209
	v_cvt_pk_bf16_f32 v209, v210, v211
	v_cvt_pk_bf16_f32 v210, v212, v213
	v_cvt_pk_bf16_f32 v211, v214, v215
	global_store_dwordx4 v[8:9], v[208:211], off
	s_waitcnt vmcnt(5)
	v_cvt_pk_bf16_f32 v216, v216, v217
	v_cvt_pk_bf16_f32 v217, v218, v219
	v_cvt_pk_bf16_f32 v218, v220, v221
	v_cvt_pk_bf16_f32 v219, v222, v223
	global_store_dwordx4 v[240:241], v[216:219], off
	s_waitcnt vmcnt(4)
	v_cvt_pk_bf16_f32 v224, v224, v225
	v_cvt_pk_bf16_f32 v225, v226, v227
	v_cvt_pk_bf16_f32 v226, v228, v229
	v_cvt_pk_bf16_f32 v227, v230, v231
	global_store_dwordx4 v[242:243], v[224:227], off
	s_waitcnt vmcnt(3)
	v_cvt_pk_bf16_f32 v232, v232, v233
	v_cvt_pk_bf16_f32 v233, v234, v235
	v_cvt_pk_bf16_f32 v234, v236, v237
	v_cvt_pk_bf16_f32 v235, v238, v239
	global_store_dwordx4 v[244:245], v[232:235], off
	v_lshl_add_u64 v[6:7], v[6:7], 0, s[64:65]
	v_lshl_add_u64 v[8:9], v[8:9], 0, s[66:67]
	v_lshl_add_u64 v[4:5], v[4:5], 0, s[62:63]
	v_cmp_ge_u64_e32 vcc, s[20:21], v[4:5]
	s_cbranch_vccnz .Lcvt4_top_x0
	s_branch .LBB0_60
.Lcvt4_rem_x0:
	v_cmp_ge_u64_e32 vcc, s[20:21], v[4:5]
	s_and_b64 exec, exec, vcc
	s_cbranch_execz .LBB0_60

; __device__ __forceinline__ u32x4 pack8(const f32x4 a, const f32x4 b) { u32x4 w; w.x = cvt_pk_bf16(a[0], a[1]); w.y = cvt_pk_bf16(a[2], a[3]); w.z = cvt_pk_bf16(b[0], b[1]); w.w = cvt_pk_bf16(b[2], b[3]); return w; }
; __device__ __forceinline__ void cvt_f32_bf16(const float* src, bf16_t* dst, size_t n, size_t gt, size_t GT) {
;     for (size_t i = gt * 8; i < n; i += GT * 8) { const f32x4 a = *(const f32x4*)(src + i), b = *(const f32x4*)(src + i + 4); *(u32x4*)(dst + i) = pack8(a, b); }
; }
; __device__ __forceinline__ void wconv_phase(KP Pk, int L, unsigned char* lds, int G, int blk) {
;     ...
;     cvt_f32_bf16(P.p + (size_t)L * M * PLE, (bf16_t*)(ws + WS_PB), (size_t)M * PLE, gt, GT);
.LBB0_710:
	s_ashr_i32 s9, s8, 31
	s_lshl_b64 s[4:5], s[8:9], 9
	v_ashrrev_i32_e32 v1, 31, v0
	v_lshl_add_u64 v[2:3], s[4:5], 0, v[0:1]
	v_lshlrev_b64 v[4:5], 3, v[2:3]
	s_mov_b64 s[4:5], 0x800000
	s_ashr_i32 s7, s6, 31
	v_cmp_gt_u64_e32 vcc, s[4:5], v[4:5]
	s_and_saveexec_b64 s[4:5], vcc
	s_cbranch_execz .LBB0_713
	s_load_dwordx2 s[18:19], s[10:11], 0x8
	s_lshl_b64 s[14:15], s[6:7], 12
	s_lshl_b64 s[16:17], s[8:9], 13
	s_waitcnt lgkmcnt(0)
	s_add_u32 s16, s12, s16
	s_addc_u32 s17, s13, s17
	v_lshl_add_u64 v[6:7], v[0:1], 4, s[16:17]
	s_mov_b64 s[16:17], 0x1e800000
	v_lshl_add_u64 v[6:7], v[6:7], 0, s[16:17]
	s_lshl_b64 s[16:17], s[6:7], 13
	s_lshl_b64 s[20:21], s[8:9], 14
	s_add_u32 s18, s18, s20
	v_lshlrev_b64 v[8:9], 5, v[0:1]
	s_addc_u32 s19, s19, s21
	v_lshl_add_u64 v[8:9], s[18:19], 0, v[8:9]
	s_mov_b64 s[18:19], 0x2000010
	v_lshl_add_u64 v[8:9], v[8:9], 0, s[18:19]
	s_lshl_b64 s[18:19], s[6:7], 14
	s_mov_b64 s[20:21], 0
	s_mov_b64 s[22:23], 0x7fffff
	s_lshl_b64 s[50:51], s[18:19], 1
	s_add_u32 s52, s50, s18
	s_addc_u32 s53, s51, s19
	s_lshl_b64 s[54:55], s[16:17], 1
	s_add_u32 s56, s54, s16
	s_addc_u32 s57, s55, s17
	s_lshl_b64 s[58:59], s[14:15], 1
	s_add_u32 s60, s58, s14
	s_addc_u32 s61, s59, s15
	s_lshl_b64 s[62:63], s[14:15], 2
	s_lshl_b64 s[64:65], s[18:19], 2
	s_lshl_b64 s[66:67], s[16:17], 2
.Lcvt4_top_p1:
	v_lshl_add_u64 v[200:201], v[4:5], 0, s[60:61]
	v_cmp_ge_u64_e32 vcc, s[22:23], v[200:201]
	s_cmp_eq_u64 vcc, exec
	s_cbranch_scc0 .Lcvt4_rem_p1
	v_lshl_add_u64 v[202:203], v[8:9], 0, s[18:19]
	v_lshl_add_u64 v[204:205], v[8:9], 0, s[50:51]
	v_lshl_add_u64 v[206:207], v[8:9], 0, s[52:53]
	global_load_dwordx4 v[208:211], v[8:9], off offset:-16
	global_load_dwordx4 v[212:215], v[8:9], off
	global_load_dwordx4 v[216:219], v[202:203], off offset:-16
	global_load_dwordx4 v[220:223], v[202:203], off
	global_load_dwordx4 v[224:227], v[204:205], off offset:-16
	global_load_dwordx4 v[228:231], v[204:205], off
	global_load_dwordx4 v[232:235], v[206:207], off offset:-16
	global_load_dwordx4 v[236:239], v[206:207], off
	v_lshl_add_u64 v[240:241], v[6:7], 0, s[16:17]
	v_lshl_add_u64 v[242:243], v[6:7], 0, s[54:55]
	v_lshl_add_u64 v[244:245], v[6:7], 0, s[56:57]
	s_waitcnt vmcnt(6)
	v_cvt_pk_bf16_f32 v208, v208, v209
	v_cvt_pk_bf16_f32 v209, v210, v211
	v_cvt_pk_bf16_f32 v210, v212, v213
	v_cvt_pk_bf16_f32 v211, v214, v215
	global_store_dwordx4 v[6:7], v[208:211], off
	s_waitcnt vmcnt(5)
	v_cvt_pk_bf16_f32 v216, v216, v217
	v_cvt_pk_bf16_f32 v217, v218, v219
	v_cvt_pk_bf16_f32 v218, v220, v221
	v_cvt_pk_bf16_f32 v219, v222, v223
	global_store_dwordx4 v[240:241], v[216:219], off
	s_waitcnt vmcnt(4)
	v_cvt_pk_bf16_f32 v224, v224, v225
	v_cvt_pk_bf16_f32 v225, v226, v227
	v_cvt_pk_bf16_f32 v226, v228, v229
	v_cvt_pk_bf16_f32 v227, v230, v231
	global_store_dwordx4 v[242:243], v[224:227], off
	s_waitcnt vmcnt(3)
	v_cvt_pk_bf16_f32 v232, v232, v233
	v_cvt_pk_bf16_f32 v233, v234, v235
	v_cvt_pk_bf16_f32 v234, v236, v237
	v_cvt_pk_bf16_f32 v235, v238, v239
	global_store_dwordx4 v[244:245], v[232:235], off
	v_lshl_add_u64 v[8:9], v[8:9], 0, s[64:65]
	v_lshl_add_u64 v[6:7], v[6:7], 0, s[66:67]
	v_lshl_add_u64 v[4:5], v[4:5], 0, s[62:63]
	v_cmp_ge_u64_e32 vcc, s[22:23], v[4:5]
	s_cbranch_vccnz .Lcvt4_top_p1
	s_branch .LBB0_713
.Lcvt4_rem_p1:
	v_cmp_ge_u64_e32 vcc, s[22:23], v[4:5]
	s_and_b64 exec, exec, vcc
	s_cbranch_execz .LBB0_713

; __device__ __forceinline__ bf16x8 pk8(const float* v) { u32x4 w; w.x = cvt_pk_bf16(v[0], v[1]); w.y = cvt_pk_bf16(v[2], v[3]); w.z = cvt_pk_bf16(v[4], v[5]); w.w = cvt_pk_bf16(v[6], v[7]); return __builtin_bit_cast(bf16x8, w); }
; #define WAVE_LDS_FENCE() do { asm volatile("s_waitcnt lgkmcnt(0)" ::: "memory"); __builtin_amdgcn_wave_barrier(); } while (0)
; template <int DIR> __device__ __forceinline__ void h3_dir(unsigned char* lds, const bf16_t* zrow, int h, const bf16_t* slot, f32x4 (&o)[8]) {
;     ...
; #pragma unroll
;     for (int i = 0; i < 32; ++i) qin[i] *= run[i];
;     WAVE_LDS_FENCE();
; #pragma unroll
;     for (int ks = 0; ks < 4; ++ks) {
;         const bf16x8 aq = pk8(qin + 8 * ks), ap = *(const bf16x8*)(Pw + r * HP + 32 * ks + 8 * kq);
; #pragma unroll
;         for (int nt = 0; nt < 8; ++nt) {
;             o[nt] = __builtin_amdgcn_mfma_f32_16x16x32_bf16(aq, *(const bf16x8*)(ST + (16 * nt + r) * HP + 32 * ks + 8 * kq), o[nt], 0, 0, 0);
;             o[nt] = __builtin_amdgcn_mfma_f32_16x16x32_bf16(ap, *(const bf16x8*)(VT + (16 * nt + r) * HP + 32 * ks + 8 * kq), o[nt], 0, 0, 0);
;         }
;     }
.LBB0_1099:
	v_mul_u32_u24_e32 v77, 0x88, v149
	v_lshlrev_b32_e32 v77, 1, v77
	v_mul_f32_e32 v56, v92, v56
	v_mul_f32_e32 v57, v93, v57
	v_mul_f32_e32 v58, v94, v58
	v_mul_f32_e32 v59, v95, v59
	v_mul_f32_e32 v60, v96, v60
	v_mul_f32_e32 v61, v97, v61
	v_mul_f32_e32 v62, v98, v62
	v_mul_f32_e32 v63, v91, v63
	v_lshlrev_b32_e32 v76, 1, v148
	v_add_u32_e32 v72, v72, v77
	v_mul_u32_u24_e32 v91, 0x110, v149
	s_waitcnt lgkmcnt(0)
	v_cvt_pk_bf16_f32 v56, v56, v57
	v_cvt_pk_bf16_f32 v57, v58, v59
	v_cvt_pk_bf16_f32 v58, v60, v61
	v_cvt_pk_bf16_f32 v59, v62, v63
	ds_read_b128 v[60:63], v72 offset:43008
	v_add3_u32 v108, s4, v91, v76
	ds_read_b128 v[92:95], v108
	v_add3_u32 v76, s35, v76, v77
	v_add_u32_e32 v77, 0xa800, v72
	ds_read_b128 v[96:99], v77 offset:30464
	s_waitcnt lgkmcnt(2)
	v_mfma_f32_16x16x32_bf16 v[24:27], v[56:59], v[60:63], v[24:27]
	ds_read_b128 v[60:63], v76
	v_mul_f32_e32 v52, v89, v52
	v_mul_f32_e32 v53, v90, v53
	s_waitcnt lgkmcnt(0)
	v_mfma_f32_16x16x32_bf16 v[24:27], v[92:95], v[60:63], v[24:27]
	ds_read_b128 v[60:63], v72 offset:47360
	ds_read_b128 v[100:103], v72 offset:51712
	v_mul_f32_e32 v54, v86, v54
	v_mul_f32_e32 v55, v87, v55
	s_waitcnt lgkmcnt(1)
	v_mfma_f32_16x16x32_bf16 v[0:3], v[56:59], v[60:63], v[0:3]
	ds_read_b128 v[60:63], v76 offset:4352
	ds_read_b128 v[104:107], v76 offset:8704
	v_mul_f32_e32 v78, v78, v47
	v_mul_f32_e32 v43, v66, v43
	s_waitcnt lgkmcnt(1)
	v_mfma_f32_16x16x32_bf16 v[0:3], v[92:95], v[60:63], v[0:3]
	v_mul_f32_e32 v79, v79, v40
	v_mul_f32_e32 v65, v65, v36
	v_add_u32_e32 v36, 0xa880, v72
	v_mfma_f32_16x16x32_bf16 v[4:7], v[56:59], v[100:103], v[4:7]
	ds_read_b128 v[60:63], v72 offset:56064
	ds_read_b128 v[100:103], v72 offset:60416
	v_mul_f32_e32 v64, v64, v37
	v_mul_f32_e32 v66, v69, v38
	s_waitcnt lgkmcnt(2)
	v_mfma_f32_16x16x32_bf16 v[4:7], v[92:95], v[104:107], v[4:7]
	v_mul_f32_e32 v67, v67, v39
	v_mul_f32_e32 v68, v68, v32
	s_add_i32 s16, s16, s17
	s_waitcnt lgkmcnt(1)
	v_mfma_f32_16x16x32_bf16 v[8:11], v[56:59], v[60:63], v[8:11]
	ds_read_b128 v[60:63], v76 offset:13056
	ds_read_b128 v[104:107], v76 offset:17408
	s_cmpk_lt_i32 s16, 0x800
	s_waitcnt lgkmcnt(1)
	v_mfma_f32_16x16x32_bf16 v[8:11], v[92:95], v[60:63], v[8:11]
	v_mfma_f32_16x16x32_bf16 v[12:15], v[56:59], v[100:103], v[12:15]
	ds_read_b128 v[60:63], v72 offset:64768
	ds_read_b128 v[100:103], v77 offset:26112
	v_mul_f32_e32 v77, v82, v44
	s_waitcnt lgkmcnt(2)
	v_mfma_f32_16x16x32_bf16 v[12:15], v[92:95], v[104:107], v[12:15]
	s_waitcnt lgkmcnt(1)
	v_mfma_f32_16x16x32_bf16 v[16:19], v[56:59], v[60:63], v[16:19]
	ds_read_b128 v[60:63], v76 offset:21760
	ds_read_b128 v[104:107], v76 offset:26112
	s_waitcnt lgkmcnt(1)
	v_mfma_f32_16x16x32_bf16 v[16:19], v[92:95], v[60:63], v[16:19]
	v_mul_f32_e32 v60, v88, v48
	v_mul_f32_e32 v61, v84, v49
	v_mul_f32_e32 v62, v85, v50
	v_mul_f32_e32 v63, v83, v51
	ds_read_b128 v[48:51], v76 offset:30464
	v_mfma_f32_16x16x32_bf16 v[28:31], v[56:59], v[96:99], v[28:31]
	v_cvt_pk_bf16_f32 v52, v52, v53
	v_cvt_pk_bf16_f32 v53, v54, v55
	v_cvt_pk_bf16_f32 v54, v60, v61
	v_mfma_f32_16x16x32_bf16 v[20:23], v[56:59], v[100:103], v[20:23]
	v_cvt_pk_bf16_f32 v55, v62, v63
	ds_read_b128 v[56:59], v72 offset:43072
	s_waitcnt lgkmcnt(1)
	v_mfma_f32_16x16x32_bf16 v[28:31], v[92:95], v[48:51], v[28:31]
	ds_read_b128 v[48:51], v108 offset:64
	s_waitcnt lgkmcnt(1)
	v_mfma_f32_16x16x32_bf16 v[24:27], v[52:55], v[56:59], v[24:27]
	ds_read_b128 v[56:59], v76 offset:64
	ds_read_b128 v[60:63], v72 offset:64832
	s_waitcnt lgkmcnt(1)
	v_mfma_f32_16x16x32_bf16 v[24:27], v[48:51], v[56:59], v[24:27]
	ds_read_b128 v[56:59], v72 offset:47424
	ds_read_b128 v[84:87], v72 offset:51776
	s_waitcnt lgkmcnt(1)
	v_mfma_f32_16x16x32_bf16 v[0:3], v[52:55], v[56:59], v[0:3]
	ds_read_b128 v[56:59], v76 offset:4416
	ds_read_b128 v[88:91], v76 offset:8768
	s_waitcnt lgkmcnt(1)
	v_mfma_f32_16x16x32_bf16 v[0:3], v[48:51], v[56:59], v[0:3]
	v_mfma_f32_16x16x32_bf16 v[4:7], v[52:55], v[84:87], v[4:7]
	ds_read_b128 v[56:59], v72 offset:56128
	ds_read_b128 v[84:87], v72 offset:60480
	s_waitcnt lgkmcnt(2)
	v_mfma_f32_16x16x32_bf16 v[4:7], v[48:51], v[88:91], v[4:7]
	s_waitcnt lgkmcnt(1)
	v_mfma_f32_16x16x32_bf16 v[8:11], v[52:55], v[56:59], v[8:11]
	ds_read_b128 v[56:59], v76 offset:13120
	ds_read_b128 v[88:91], v76 offset:17472
	s_waitcnt lgkmcnt(1)
	v_mfma_f32_16x16x32_bf16 v[8:11], v[48:51], v[56:59], v[8:11]
	ds_read_b128 v[56:59], v76 offset:21824
	v_mfma_f32_16x16x32_bf16 v[16:19], v[52:55], v[60:63], v[16:19]
	v_mfma_f32_16x16x32_bf16 v[12:15], v[52:55], v[84:87], v[12:15]
	v_add_u32_e32 v86, 0xa840, v72
	v_mul_f32_e32 v84, v80, v45
	v_mul_f32_e32 v85, v81, v46
	ds_read_b128 v[60:63], v86 offset:26112
	ds_read_b128 v[80:83], v76 offset:26176
	s_waitcnt lgkmcnt(2)
	v_mfma_f32_16x16x32_bf16 v[16:19], v[48:51], v[56:59], v[16:19]
	ds_read_b128 v[44:47], v76 offset:30528
	ds_read_b128 v[56:59], v86 offset:30464
	v_cvt_pk_bf16_f32 v40, v77, v84
	v_mfma_f32_16x16x32_bf16 v[20:23], v[92:95], v[104:107], v[20:23]
	s_waitcnt lgkmcnt(0)
	v_mfma_f32_16x16x32_bf16 v[28:31], v[52:55], v[56:59], v[28:31]
	v_mfma_f32_16x16x32_bf16 v[20:23], v[52:55], v[60:63], v[20:23]
	v_mul_f32_e32 v60, v73, v41
	v_mul_f32_e32 v61, v74, v42
	v_cvt_pk_bf16_f32 v41, v85, v78
	v_cvt_pk_bf16_f32 v42, v79, v60
	v_cvt_pk_bf16_f32 v43, v61, v43
	ds_read_b128 v[52:55], v72 offset:43136
	v_mfma_f32_16x16x32_bf16 v[28:31], v[48:51], v[44:47], v[28:31]
	ds_read_b128 v[44:47], v108 offset:128
	v_mfma_f32_16x16x32_bf16 v[12:15], v[48:51], v[88:91], v[12:15]
	v_mfma_f32_16x16x32_bf16 v[20:23], v[48:51], v[80:83], v[20:23]
	s_waitcnt lgkmcnt(1)
; __device__ __forceinline__ bf16x8 pk8(const float* v) { u32x4 w; w.x = cvt_pk_bf16(v[0], v[1]); w.y = cvt_pk_bf16(v[2], v[3]); w.z = cvt_pk_bf16(v[4], v[5]); w.w = cvt_pk_bf16(v[6], v[7]); return __builtin_bit_cast(bf16x8, w); }
; template <int DIR> __device__ __forceinline__ void h3_dir(unsigned char* lds, const bf16_t* zrow, int h, const bf16_t* slot, f32x4 (&o)[8]) {
;     ...
;     for (int ks = 0; ks < 4; ++ks) {
;         const bf16x8 aq = pk8(qin + 8 * ks), ap = *(const bf16x8*)(Pw + r * HP + 32 * ks + 8 * kq);
; #pragma unroll
;         for (int nt = 0; nt < 8; ++nt) {
;             o[nt] = __builtin_amdgcn_mfma_f32_16x16x32_bf16(aq, *(const bf16x8*)(ST + (16 * nt + r) * HP + 32 * ks + 8 * kq), o[nt], 0, 0, 0);
;             o[nt] = __builtin_amdgcn_mfma_f32_16x16x32_bf16(ap, *(const bf16x8*)(VT + (16 * nt + r) * HP + 32 * ks + 8 * kq), o[nt], 0, 0, 0);
;         }
;     }
;     __syncthreads();
; template <bool STORE> __device__ __forceinline__ void h3_phase(unsigned char* lds, unsigned char* ws, const bf16_t* SF, const float* norm_g, int G, int blk) {
;     ...
;         float ssq[4];
; #pragma unroll
;         for (int i = 0; i < 4; ++i) { float s = 0.f;
; #pragma unroll
;             for (int nt = 0; nt < 8; ++nt) s += o[nt][i] * o[nt][i];
;             s += __shfl_xor(s, 1); s += __shfl_xor(s, 2); s += __shfl_xor(s, 4); s += __shfl_xor(s, 8);
;             ssq[i] = 1.0f / sqrtf(s * (1.0f / 128.0f) + LN_EPS); }
	v_mfma_f32_16x16x32_bf16 v[24:27], v[40:43], v[52:55], v[24:27]
	ds_read_b128 v[48:51], v76 offset:128
	ds_read_b128 v[52:55], v72 offset:64896
	s_waitcnt lgkmcnt(1)
	v_mfma_f32_16x16x32_bf16 v[24:27], v[44:47], v[48:51], v[24:27]
	ds_read_b128 v[48:51], v72 offset:47488
	ds_read_b128 v[56:59], v72 offset:51840
	s_waitcnt lgkmcnt(1)
	v_mfma_f32_16x16x32_bf16 v[0:3], v[40:43], v[48:51], v[0:3]
	ds_read_b128 v[48:51], v76 offset:4480
	ds_read_b128 v[60:63], v76 offset:8832
	s_waitcnt lgkmcnt(1)
	v_mfma_f32_16x16x32_bf16 v[0:3], v[44:47], v[48:51], v[0:3]
	v_mfma_f32_16x16x32_bf16 v[4:7], v[40:43], v[56:59], v[4:7]
	ds_read_b128 v[48:51], v72 offset:56192
	ds_read_b128 v[56:59], v72 offset:60544
	s_waitcnt lgkmcnt(2)
	v_mfma_f32_16x16x32_bf16 v[4:7], v[44:47], v[60:63], v[4:7]
	s_waitcnt lgkmcnt(1)
	v_mfma_f32_16x16x32_bf16 v[8:11], v[40:43], v[48:51], v[8:11]
	ds_read_b128 v[48:51], v76 offset:13184
	ds_read_b128 v[60:63], v76 offset:17536
	s_waitcnt lgkmcnt(1)
	v_mfma_f32_16x16x32_bf16 v[48:51], v[44:47], v[48:51], v[8:11]
	v_mfma_f32_16x16x32_bf16 v[8:11], v[40:43], v[56:59], v[12:15]
	s_waitcnt lgkmcnt(0)
	v_mfma_f32_16x16x32_bf16 v[56:59], v[44:47], v[60:63], v[8:11]
	v_mfma_f32_16x16x32_bf16 v[12:15], v[40:43], v[52:55], v[16:19]
	s_nop 4
	ds_read_b128 v[8:11], v76 offset:21888
	ds_read_b128 v[16:19], v36 offset:26112
	ds_read_b128 v[52:55], v76 offset:26240
	s_waitcnt lgkmcnt(2)
	v_mfma_f32_16x16x32_bf16 v[60:63], v[44:47], v[8:11], v[12:15]
	ds_read_b128 v[8:11], v76 offset:30592
	s_waitcnt lgkmcnt(2)
	v_mfma_f32_16x16x32_bf16 v[12:15], v[40:43], v[16:19], v[20:23]
	ds_read_b128 v[16:19], v36 offset:30464
	v_cvt_pk_bf16_f32 v32, v65, v64
	s_waitcnt lgkmcnt(2)
	v_mfma_f32_16x16x32_bf16 v[36:39], v[44:47], v[52:55], v[12:15]
	v_mul_f32_e32 v20, v71, v33
	v_mul_f32_e32 v21, v75, v34
	v_mul_f32_e32 v22, v70, v35
	v_cvt_pk_bf16_f32 v33, v66, v67
	s_waitcnt lgkmcnt(0)
	v_mfma_f32_16x16x32_bf16 v[12:15], v[40:43], v[16:19], v[28:31]
	v_cvt_pk_bf16_f32 v34, v68, v20
	v_cvt_pk_bf16_f32 v35, v21, v22
	ds_read_b128 v[16:19], v72 offset:43200
	ds_read_b128 v[40:43], v108 offset:192
	v_mfma_f32_16x16x32_bf16 v[28:31], v[44:47], v[8:11], v[12:15]
	v_add_u32_e32 v52, 0xa8c0, v72
	s_waitcnt lgkmcnt(1)
	v_mfma_f32_16x16x32_bf16 v[8:11], v[32:35], v[16:19], v[24:27]
	s_nop 1
	ds_read_b128 v[12:15], v76 offset:192
	ds_read_b128 v[16:19], v72 offset:64960
	s_waitcnt lgkmcnt(1)
	v_mfma_f32_16x16x32_bf16 v[20:23], v[40:43], v[12:15], v[8:11]
	s_nop 2
	ds_read_b128 v[8:11], v72 offset:47552
	ds_read_b128 v[24:27], v72 offset:51904
	s_waitcnt lgkmcnt(1)
	v_mfma_f32_16x16x32_bf16 v[0:3], v[32:35], v[8:11], v[0:3]
	ds_read_b128 v[8:11], v76 offset:4544
	ds_read_b128 v[44:47], v76 offset:8896
	s_waitcnt lgkmcnt(1)
	v_mfma_f32_16x16x32_bf16 v[12:15], v[40:43], v[8:11], v[0:3]
	v_mfma_f32_16x16x32_bf16 v[0:3], v[32:35], v[24:27], v[4:7]
	s_waitcnt lgkmcnt(0)
	v_mfma_f32_16x16x32_bf16 v[8:11], v[40:43], v[44:47], v[0:3]
	s_nop 5
	ds_read_b128 v[0:3], v72 offset:56256
	ds_read_b128 v[24:27], v72 offset:60608
	ds_read_b128 v[4:7], v76 offset:13248
	ds_read_b128 v[44:47], v76 offset:17600
	s_waitcnt lgkmcnt(3)
	v_mfma_f32_16x16x32_bf16 v[0:3], v[32:35], v[0:3], v[48:51]
	s_waitcnt lgkmcnt(1)
	v_mfma_f32_16x16x32_bf16 v[4:7], v[40:43], v[4:7], v[0:3]
	v_mfma_f32_16x16x32_bf16 v[0:3], v[32:35], v[24:27], v[56:59]
	s_waitcnt lgkmcnt(0)
	v_mfma_f32_16x16x32_bf16 v[0:3], v[40:43], v[44:47], v[0:3]
	ds_read_b128 v[24:27], v76 offset:21952
	ds_read_b128 v[44:47], v76 offset:26304
	ds_read_b128 v[48:51], v52 offset:30464
	ds_read_b128 v[52:55], v52 offset:26112
	ds_read_b128 v[56:59], v76 offset:30656
	s_waitcnt lgkmcnt(0)
	v_mfma_f32_16x16x32_bf16 v[16:19], v[32:35], v[16:19], v[60:63]
	s_barrier
	v_mfma_f32_16x16x32_bf16 v[16:19], v[40:43], v[24:27], v[16:19]
	v_and_b32_e32 v24, 64, v147
	v_add_u32_e32 v61, 64, v24
	v_xor_b32_e32 v60, 1, v147
	v_mfma_f32_16x16x32_bf16 v[24:27], v[32:35], v[52:55], v[36:39]
	v_cmp_lt_i32_e32 vcc, v60, v61
	v_mfma_f32_16x16x32_bf16 v[28:31], v[32:35], v[48:51], v[28:31]
	s_nop 0
	v_mul_f32_e32 v37, v12, v12
	v_fmac_f32_e32 v37, v20, v20
	v_fmac_f32_e32 v37, v8, v8
	v_mfma_f32_16x16x32_bf16 v[24:27], v[40:43], v[44:47], v[24:27]
	v_fmac_f32_e32 v37, v4, v4
	v_fmac_f32_e32 v37, v0, v0
	v_fmac_f32_e32 v37, v16, v16
	v_mfma_f32_16x16x32_bf16 v[28:31], v[40:43], v[56:59], v[28:31]
	v_cndmask_b32_e32 v36, v147, v60, vcc
	s_nop 2
	v_fmac_f32_e32 v37, v24, v24
	v_lshlrev_b32_e32 v36, 2, v36
	v_xor_b32_e32 v33, 2, v147
	v_cmp_lt_i32_e32 vcc, v33, v61
	v_fmac_f32_e32 v37, v28, v28
	ds_bpermute_b32 v32, v36, v37
	v_cndmask_b32_e32 v33, v147, v33, vcc
	v_lshlrev_b32_e32 v33, 2, v33
	v_xor_b32_e32 v35, 4, v147
	v_cmp_lt_i32_e32 vcc, v35, v61
	s_waitcnt lgkmcnt(0)
	v_add_f32_e32 v32, v37, v32
	ds_bpermute_b32 v34, v33, v32
	v_cndmask_b32_e32 v35, v147, v35, vcc
	v_lshlrev_b32_e32 v35, 2, v35
	v_xor_b32_e32 v37, 8, v147
	v_cmp_lt_i32_e32 vcc, v37, v61
	s_waitcnt lgkmcnt(0)
	v_add_f32_e32 v32, v32, v34
	ds_bpermute_b32 v34, v35, v32
	v_cndmask_b32_e32 v37, v147, v37, vcc
	v_lshlrev_b32_e32 v37, 2, v37
	v_mul_f32_e32 v40, v13, v13
	v_fmac_f32_e32 v40, v21, v21
	s_waitcnt lgkmcnt(0)
	v_add_f32_e32 v32, v32, v34
	ds_bpermute_b32 v34, v37, v32
	v_fmac_f32_e32 v40, v9, v9
	v_fmac_f32_e32 v40, v5, v5
	v_fmac_f32_e32 v40, v1, v1
	v_fmac_f32_e32 v40, v17, v17
	s_waitcnt lgkmcnt(0)
; template <bool STORE> __device__ __forceinline__ void h3_phase(unsigned char* lds, unsigned char* ws, const bf16_t* SF, const float* norm_g, int G, int blk) {
;     ...
;         for (int i = 0; i < 4; ++i) { float s = 0.f;
; #pragma unroll
;             for (int nt = 0; nt < 8; ++nt) s += o[nt][i] * o[nt][i];
;             s += __shfl_xor(s, 1); s += __shfl_xor(s, 2); s += __shfl_xor(s, 4); s += __shfl_xor(s, 8);
;             ssq[i] = 1.0f / sqrtf(s * (1.0f / 128.0f) + LN_EPS); }
; #pragma unroll
;         for (int nt = 0; nt < 8; ++nt)
; #pragma unroll
;             for (int i = 0; i < 4; ++i) STGF[(4 * kq + i) * 132 + 16 * nt + r] = o[nt][i] * ssq[i];
	v_add_f32_e32 v32, v32, v34
	v_fmamk_f32 v32, v32, 0x3c000000, v142
	v_mul_f32_e32 v34, 0x4f800000, v32
	v_cmp_gt_f32_e32 vcc, s29, v32
	v_fmac_f32_e32 v40, v25, v25
	v_fmac_f32_e32 v40, v29, v29
	v_cndmask_b32_e32 v32, v32, v34, vcc
	v_sqrt_f32_e32 v34, v32
	ds_bpermute_b32 v41, v36, v40
	v_mul_f32_e32 v44, v14, v14
	v_fmac_f32_e32 v44, v22, v22
	v_add_u32_e32 v38, -1, v34
	v_fma_f32 v39, -v38, v34, v32
	v_cmp_ge_f32_e64 s[4:5], 0, v39
	v_add_u32_e32 v39, 1, v34
	v_fmac_f32_e32 v44, v10, v10
	v_cndmask_b32_e64 v38, v34, v38, s[4:5]
	v_fma_f32 v34, -v39, v34, v32
	v_cmp_lt_f32_e64 s[4:5], 0, v34
	v_fmac_f32_e32 v44, v6, v6
	v_fmac_f32_e32 v44, v2, v2
	v_cndmask_b32_e64 v34, v38, v39, s[4:5]
	v_mul_f32_e32 v38, 0x37800000, v34
	v_cndmask_b32_e32 v34, v34, v38, vcc
	s_waitcnt lgkmcnt(0)
	v_add_f32_e32 v38, v40, v41
	ds_bpermute_b32 v39, v33, v38
	v_cmp_class_f32_e32 vcc, v32, v143
	v_fmac_f32_e32 v44, v18, v18
	v_fmac_f32_e32 v44, v26, v26
	v_cndmask_b32_e32 v32, v34, v32, vcc
	s_waitcnt lgkmcnt(0)
	v_add_f32_e32 v38, v38, v39
	ds_bpermute_b32 v39, v35, v38
	v_div_scale_f32 v34, s[4:5], v32, v32, 1.0
	v_rcp_f32_e32 v40, v34
	v_fmac_f32_e32 v44, v30, v30
	s_waitcnt lgkmcnt(0)
	v_add_f32_e32 v38, v38, v39
	ds_bpermute_b32 v39, v37, v38
	v_fma_f32 v41, -v34, v40, 1.0
	v_fmac_f32_e32 v40, v41, v40
	v_div_scale_f32 v41, vcc, 1.0, v32, 1.0
	s_waitcnt lgkmcnt(0)
	v_add_f32_e32 v38, v38, v39
	v_fmamk_f32 v38, v38, 0x3c000000, v142
	v_mul_f32_e32 v39, 0x4f800000, v38
	v_cmp_gt_f32_e64 s[4:5], s29, v38
	v_mul_f32_e32 v42, v41, v40
	v_fma_f32 v43, -v34, v42, v41
	v_cndmask_b32_e64 v38, v38, v39, s[4:5]
	v_sqrt_f32_e32 v39, v38
	v_fmac_f32_e32 v42, v43, v40
	v_fma_f32 v34, -v34, v42, v41
	ds_bpermute_b32 v45, v36, v44
	v_add_u32_e32 v41, -1, v39
	v_fma_f32 v43, -v41, v39, v38
	v_cmp_ge_f32_e64 s[6:7], 0, v43
	v_add_u32_e32 v43, 1, v39
	v_div_fmas_f32 v34, v34, v40, v42
	v_cndmask_b32_e64 v41, v39, v41, s[6:7]
	v_fma_f32 v39, -v43, v39, v38
	v_cmp_lt_f32_e64 s[6:7], 0, v39
	v_div_fixup_f32 v32, v34, v32, 1.0
	v_mul_f32_e32 v8, v8, v32
	v_cndmask_b32_e64 v39, v41, v43, s[6:7]
	v_mul_f32_e32 v41, 0x37800000, v39
	v_cndmask_b32_e64 v39, v39, v41, s[4:5]
	s_waitcnt lgkmcnt(0)
	v_add_f32_e32 v41, v44, v45
	ds_bpermute_b32 v43, v33, v41
	v_mul_f32_e32 v45, v15, v15
	v_fmac_f32_e32 v45, v23, v23
	v_fmac_f32_e32 v45, v11, v11
	v_fmac_f32_e32 v45, v7, v7
	s_waitcnt lgkmcnt(0)
	v_add_f32_e32 v41, v41, v43
	ds_bpermute_b32 v43, v35, v41
	v_fmac_f32_e32 v45, v3, v3
	v_fmac_f32_e32 v45, v19, v19
	v_fmac_f32_e32 v45, v27, v27
	v_fmac_f32_e32 v45, v31, v31
	s_waitcnt lgkmcnt(0)
	v_add_f32_e32 v40, v41, v43
	ds_bpermute_b32 v41, v37, v40
	ds_bpermute_b32 v36, v36, v45
	v_cmp_class_f32_e64 s[4:5], v38, v143
	v_mul_f32_e32 v4, v4, v32
	v_mul_f32_e32 v20, v20, v32
	v_cndmask_b32_e64 v38, v39, v38, s[4:5]
	v_div_scale_f32 v39, s[4:5], v38, v38, 1.0
	v_rcp_f32_e32 v44, v39
	s_waitcnt lgkmcnt(1)
	v_add_f32_e32 v40, v40, v41
	s_waitcnt lgkmcnt(0)
	v_add_f32_e32 v36, v45, v36
	v_fmamk_f32 v40, v40, 0x3c000000, v142
	ds_bpermute_b32 v33, v33, v36
	v_mul_f32_e32 v41, 0x4f800000, v40
	v_cmp_gt_f32_e64 s[4:5], s29, v40
	v_fma_f32 v34, -v39, v44, 1.0
	v_fmac_f32_e32 v44, v34, v44
	v_cndmask_b32_e64 v40, v40, v41, s[4:5]
	v_div_scale_f32 v34, vcc, 1.0, v38, 1.0
	v_sqrt_f32_e32 v41, v40
	v_mul_f32_e32 v42, v34, v44
	v_fma_f32 v43, -v39, v42, v34
	s_waitcnt lgkmcnt(0)
	v_add_f32_e32 v33, v36, v33
	v_fmac_f32_e32 v42, v43, v44
	ds_bpermute_b32 v35, v35, v33
	v_fma_f32 v34, -v39, v42, v34
	v_add_u32_e32 v39, -1, v41
	v_fma_f32 v43, -v39, v41, v40
	v_cmp_ge_f32_e64 s[6:7], 0, v43
	v_add_u32_e32 v43, 1, v41
	s_waitcnt lgkmcnt(0)
	v_add_f32_e32 v33, v33, v35
	v_cndmask_b32_e64 v39, v41, v39, s[6:7]
	v_fma_f32 v41, -v43, v41, v40
	v_cmp_lt_f32_e64 s[6:7], 0, v41
	ds_bpermute_b32 v35, v37, v33
	v_div_fmas_f32 v34, v34, v44, v42
	v_cndmask_b32_e64 v39, v39, v43, s[6:7]
	v_mul_f32_e32 v41, 0x37800000, v39
	v_cndmask_b32_e64 v39, v39, v41, s[4:5]
	v_cmp_class_f32_e64 s[4:5], v40, v143
	s_waitcnt lgkmcnt(0)
	v_add_f32_e32 v33, v33, v35
	v_fmamk_f32 v33, v33, 0x3c000000, v142
	v_cndmask_b32_e64 v39, v39, v40, s[4:5]
	v_div_scale_f32 v40, s[4:5], v39, v39, 1.0
	v_rcp_f32_e32 v41, v40
	v_mul_f32_e32 v35, 0x4f800000, v33
	v_cmp_gt_f32_e64 s[4:5], s29, v33
	v_div_fixup_f32 v34, v34, v38, 1.0
	v_fma_f32 v36, -v40, v41, 1.0
	v_cndmask_b32_e64 v33, v33, v35, s[4:5]
	v_sqrt_f32_e32 v35, v33
	v_fmac_f32_e32 v41, v36, v41
	v_div_scale_f32 v36, vcc, 1.0, v39, 1.0
	v_mul_f32_e32 v37, v36, v41
	v_fma_f32 v38, -v40, v37, v36
	v_fmac_f32_e32 v37, v38, v41
	v_add_u32_e32 v38, -1, v35
	v_fma_f32 v36, -v40, v37, v36
	v_fma_f32 v40, -v38, v35, v33
	v_cmp_ge_f32_e64 s[6:7], 0, v40
	v_add_u32_e32 v40, 1, v35
	v_div_fmas_f32 v36, v36, v41, v37
	v_cndmask_b32_e64 v38, v35, v38, s[6:7]
	v_fma_f32 v35, -v40, v35, v33
	v_cmp_lt_f32_e64 s[6:7], 0, v35
	v_div_fixup_f32 v36, v36, v39, 1.0
	v_mul_f32_e32 v12, v12, v32
	v_cndmask_b32_e64 v35, v38, v40, s[6:7]
	v_mul_f32_e32 v38, 0x37800000, v35
	v_cndmask_b32_e64 v35, v35, v38, s[4:5]
	v_cmp_class_f32_e64 s[4:5], v33, v143
	v_mul_f32_e32 v9, v9, v34
	v_mul_f32_e32 v10, v10, v36
	v_cndmask_b32_e64 v33, v35, v33, s[4:5]
	v_div_scale_f32 v35, s[4:5], v33, v33, 1.0
	v_rcp_f32_e32 v38, v35
	v_mul_f32_e32 v0, v0, v32
	v_mul_f32_e32 v1, v1, v34
	v_mul_f32_e32 v2, v2, v36
	v_fma_f32 v37, -v35, v38, 1.0
	v_fmac_f32_e32 v38, v37, v38
	v_div_scale_f32 v37, vcc, 1.0, v33, 1.0
	v_mul_f32_e32 v39, v37, v38
	v_fma_f32 v40, -v35, v39, v37
	v_fmac_f32_e32 v39, v40, v38
	v_fma_f32 v35, -v35, v39, v37
	v_div_fmas_f32 v35, v35, v38, v39
	v_div_fixup_f32 v33, v35, v33, 1.0
	v_add_u32_e32 v35, 0x2000, v144
; __device__ __forceinline__ float bf_lo(unsigned w) { return __uint_as_float(w << 16); }
; __device__ __forceinline__ float bf_hi(unsigned w) { return __uint_as_float(w & 0xffff0000u); }
; __device__ __forceinline__ u32x4 pack8(const f32x4 a, const f32x4 b) { u32x4 w; w.x = cvt_pk_bf16(a[0], a[1]); w.y = cvt_pk_bf16(a[2], a[3]); w.z = cvt_pk_bf16(b[0], b[1]); w.w = cvt_pk_bf16(b[2], b[3]); return w; }
; #define WAVE_LDS_FENCE() do { asm volatile("s_waitcnt lgkmcnt(0)" ::: "memory"); __builtin_amdgcn_wave_barrier(); } while (0)
; template <bool STORE> __device__ __forceinline__ void h3_phase(unsigned char* lds, unsigned char* ws, const bf16_t* SF, const float* norm_g, int G, int blk) {
;     ...
; #pragma unroll
;         for (int nt = 0; nt < 8; ++nt)
; #pragma unroll
;             for (int i = 0; i < 4; ++i) STGF[(4 * kq + i) * 132 + 16 * nt + r] = o[nt][i] * ssq[i];
;         WAVE_LDS_FENCE();
; #pragma unroll
;         for (int it = 0; it < 4; ++it) {
;             const int p = lane + 64 * it, row = p >> 4, c8 = p & 15;
;             const f32x4 a = *(const f32x4*)(STGF + row * 132 + c8 * 8), bq = *(const f32x4*)(STGF + row * 132 + c8 * 8 + 4);
;             const f32x4 g0 = *(const f32x4*)(norm_g + c8 * 8), g1 = *(const f32x4*)(norm_g + c8 * 8 + 4);
;             bf16_t* zr = Z + ((size_t)h * M + tok0 + row) * 128 + c8 * 8;
;             const u32x4 gw = *(const u32x4*)(zr + 4 * ZSEG);
;             const f32x4 t0 = {bf_lo(gw.x), bf_hi(gw.x), bf_lo(gw.y), bf_hi(gw.y)}, t1 = {bf_lo(gw.z), bf_hi(gw.z), bf_lo(gw.w), bf_hi(gw.w)};
;             if (STORE || a[0] == 123.456f) *(u32x4*)zr = pack8(a * g0 * t0, bq * g1 * t1);
;         }
;         asm volatile("s_waitcnt lgkmcnt(0)\n\ts_barrier" ::: "memory");
	ds_write2_b32 v35, v8, v4 offset0:32 offset1:48
	v_mul_f32_e32 v4, v5, v34
	ds_write2_b32 v35, v20, v12 offset1:16
	v_mul_f32_e32 v12, v13, v34
	v_add_u32_e32 v13, 0x2400, v144
	ds_write2_b32 v35, v9, v4 offset0:164 offset1:180
	v_mul_f32_e32 v4, v6, v36
	v_mul_f32_e32 v11, v11, v33
	ds_write2_b32 v13, v10, v4 offset0:40 offset1:56
	v_mul_f32_e32 v4, v7, v33
	ds_write2_b32 v13, v11, v4 offset0:172 offset1:188
	v_mul_f32_e32 v4, v16, v32
	ds_write2_b32 v35, v0, v4 offset0:64 offset1:80
	v_mul_f32_e32 v0, v17, v34
	ds_write2_b32 v35, v1, v0 offset0:196 offset1:212
	v_mul_f32_e32 v0, v18, v36
	v_mul_f32_e32 v3, v3, v33
	ds_write2_b32 v13, v2, v0 offset0:72 offset1:88
	v_mul_f32_e32 v0, v19, v33
	ds_write2_b32 v13, v3, v0 offset0:204 offset1:220
	v_mul_f32_e32 v0, v24, v32
	v_mul_f32_e32 v4, v28, v32
	v_mul_f32_e32 v1, v25, v34
	ds_write2_b32 v35, v0, v4 offset0:96 offset1:112
	v_mul_f32_e32 v0, v29, v34
	v_mul_f32_e32 v2, v26, v36
	ds_write2_b32 v35, v1, v0 offset0:228 offset1:244
	v_mul_f32_e32 v0, v30, v36
	v_mul_f32_e32 v3, v27, v33
	ds_write2_b32 v13, v2, v0 offset0:104 offset1:120
	v_mul_f32_e32 v0, v31, v33
	v_mul_f32_e32 v21, v21, v34
	ds_write2_b32 v13, v3, v0 offset0:236 offset1:252
	v_mov_b32_e32 v1, s34
	v_or_b32_e32 v0, s31, v114
	v_mul_f32_e32 v22, v22, v36
	ds_write2_b32 v35, v21, v12 offset0:132 offset1:148
	v_mul_f32_e32 v12, v14, v36
	v_lshlrev_b64 v[0:1], 8, v[0:1]
	v_mul_f32_e32 v23, v23, v33
	ds_write2_b32 v13, v22, v12 offset0:8 offset1:24
	v_mul_f32_e32 v12, v15, v33
	v_lshl_add_u64 v[20:21], v[120:121], 0, v[0:1]
	ds_write2_b32 v13, v23, v12 offset0:140 offset1:156
	v_add_co_u32_e32 v12, vcc, s30, v20
	s_waitcnt lgkmcnt(0)
	s_nop 1
	v_addc_co_u32_e32 v13, vcc, 0, v21, vcc
	global_load_dwordx4 v[0:3], v[12:13], off
	global_load_dwordx4 v[4:7], v[118:119], off
	global_load_dwordx4 v[8:11], v[118:119], off offset:16
	ds_read_b128 v[12:15], v145 offset:8192
	ds_read_b128 v[16:19], v145 offset:8208
	s_waitcnt vmcnt(2)
	v_lshlrev_b32_e32 v22, 16, v0
	v_and_b32_e32 v23, 0xffff0000, v0
	v_lshlrev_b32_e32 v0, 16, v1
	v_and_b32_e32 v1, 0xffff0000, v1
	s_waitcnt vmcnt(1) lgkmcnt(1)
	v_pk_mul_f32 v[6:7], v[14:15], v[6:7]
	v_pk_mul_f32 v[4:5], v[12:13], v[4:5]
	v_lshlrev_b32_e32 v24, 16, v2
	v_and_b32_e32 v25, 0xffff0000, v2
	v_lshlrev_b32_e32 v2, 16, v3
	v_and_b32_e32 v3, 0xffff0000, v3
	v_pk_mul_f32 v[6:7], v[6:7], v[0:1]
	v_pk_mul_f32 v[0:1], v[4:5], v[22:23]
	s_waitcnt vmcnt(0) lgkmcnt(0)
	v_pk_mul_f32 v[4:5], v[18:19], v[10:11]
	v_pk_mul_f32 v[8:9], v[16:17], v[8:9]
	v_pk_mul_f32 v[4:5], v[4:5], v[2:3]
	v_pk_mul_f32 v[2:3], v[8:9], v[24:25]
	v_cvt_pk_bf16_f32 v0, v0, v1
	v_cvt_pk_bf16_f32 v1, v6, v7
	s_nop 0
	v_cvt_pk_bf16_f32 v2, v2, v3
	v_cvt_pk_bf16_f32 v3, v4, v5
	global_store_dwordx4 v[20:21], v[0:3], off
	s_nop 1
	v_mov_b32_e32 v1, s34
	v_or_b32_e32 v0, s31, v122
	v_lshlrev_b64 v[0:1], 8, v[0:1]
	v_lshl_add_u64 v[20:21], v[120:121], 0, v[0:1]
	v_add_co_u32_e32 v12, vcc, s30, v20
	s_nop 1
	v_addc_co_u32_e32 v13, vcc, 0, v21, vcc
	global_load_dwordx4 v[0:3], v[12:13], off
	global_load_dwordx4 v[4:7], v[118:119], off
	global_load_dwordx4 v[8:11], v[118:119], off offset:16
	ds_read_b128 v[12:15], v146 offset:8192
	ds_read_b128 v[16:19], v146 offset:8208
	s_waitcnt vmcnt(2)
	v_lshlrev_b32_e32 v22, 16, v0
	v_and_b32_e32 v23, 0xffff0000, v0
	v_lshlrev_b32_e32 v0, 16, v1
	v_and_b32_e32 v1, 0xffff0000, v1
	s_waitcnt vmcnt(1) lgkmcnt(1)
	v_pk_mul_f32 v[6:7], v[14:15], v[6:7]
	v_pk_mul_f32 v[4:5], v[12:13], v[4:5]
	v_lshlrev_b32_e32 v24, 16, v2
	v_and_b32_e32 v25, 0xffff0000, v2
	v_lshlrev_b32_e32 v2, 16, v3
	v_and_b32_e32 v3, 0xffff0000, v3
	v_pk_mul_f32 v[6:7], v[6:7], v[0:1]
	v_pk_mul_f32 v[0:1], v[4:5], v[22:23]
	s_waitcnt vmcnt(0) lgkmcnt(0)
	v_pk_mul_f32 v[4:5], v[18:19], v[10:11]
	v_pk_mul_f32 v[8:9], v[16:17], v[8:9]
	v_pk_mul_f32 v[4:5], v[4:5], v[2:3]
	v_pk_mul_f32 v[2:3], v[8:9], v[24:25]
	v_cvt_pk_bf16_f32 v0, v0, v1
	v_cvt_pk_bf16_f32 v1, v6, v7
	s_nop 0
	v_cvt_pk_bf16_f32 v2, v2, v3
	v_cvt_pk_bf16_f32 v3, v4, v5
	global_store_dwordx4 v[20:21], v[0:3], off
	s_nop 1
	v_mov_b32_e32 v1, s34
	v_or_b32_e32 v0, s31, v124
	v_lshlrev_b64 v[0:1], 8, v[0:1]
	v_lshl_add_u64 v[20:21], v[120:121], 0, v[0:1]
	v_add_co_u32_e32 v12, vcc, s30, v20
	s_nop 1
	v_addc_co_u32_e32 v13, vcc, 0, v21, vcc
	global_load_dwordx4 v[0:3], v[12:13], off
	global_load_dwordx4 v[4:7], v[118:119], off
	global_load_dwordx4 v[8:11], v[118:119], off offset:16
	ds_read_b128 v[12:15], v146 offset:10304
	ds_read_b128 v[16:19], v146 offset:10320
	s_waitcnt vmcnt(2)
	v_lshlrev_b32_e32 v22, 16, v0
	v_and_b32_e32 v23, 0xffff0000, v0
	v_lshlrev_b32_e32 v0, 16, v1
	v_and_b32_e32 v1, 0xffff0000, v1
	s_waitcnt vmcnt(1) lgkmcnt(1)
	v_pk_mul_f32 v[6:7], v[14:15], v[6:7]
	v_pk_mul_f32 v[4:5], v[12:13], v[4:5]
	v_lshlrev_b32_e32 v24, 16, v2
	v_and_b32_e32 v25, 0xffff0000, v2
	v_lshlrev_b32_e32 v2, 16, v3
	v_and_b32_e32 v3, 0xffff0000, v3
	v_pk_mul_f32 v[6:7], v[6:7], v[0:1]
	v_pk_mul_f32 v[0:1], v[4:5], v[22:23]
	s_waitcnt vmcnt(0) lgkmcnt(0)
	v_pk_mul_f32 v[4:5], v[18:19], v[10:11]
	v_pk_mul_f32 v[8:9], v[16:17], v[8:9]
	v_pk_mul_f32 v[4:5], v[4:5], v[2:3]
	v_pk_mul_f32 v[2:3], v[8:9], v[24:25]
	v_cvt_pk_bf16_f32 v0, v0, v1
	v_cvt_pk_bf16_f32 v1, v6, v7
	s_nop 0
	v_cvt_pk_bf16_f32 v2, v2, v3
	v_cvt_pk_bf16_f32 v3, v4, v5
	global_store_dwordx4 v[20:21], v[0:3], off
	s_nop 1
	v_mov_b32_e32 v1, s34
	v_or_b32_e32 v0, s31, v126
	v_lshlrev_b64 v[0:1], 8, v[0:1]
	v_lshl_add_u64 v[20:21], v[120:121], 0, v[0:1]
	v_add_co_u32_e32 v12, vcc, s30, v20
	s_nop 1
	v_addc_co_u32_e32 v13, vcc, 0, v21, vcc
	global_load_dwordx4 v[0:3], v[12:13], off
	global_load_dwordx4 v[4:7], v[118:119], off
	global_load_dwordx4 v[8:11], v[118:119], off offset:16
	ds_read_b128 v[12:15], v146 offset:12416
	ds_read_b128 v[16:19], v146 offset:12432
	s_waitcnt vmcnt(2)
	v_lshlrev_b32_e32 v22, 16, v0
	v_and_b32_e32 v23, 0xffff0000, v0
	v_lshlrev_b32_e32 v0, 16, v1
	v_and_b32_e32 v1, 0xffff0000, v1
	s_waitcnt vmcnt(1) lgkmcnt(1)
	v_pk_mul_f32 v[6:7], v[14:15], v[6:7]
	v_pk_mul_f32 v[4:5], v[12:13], v[4:5]
	v_lshlrev_b32_e32 v24, 16, v2
	v_and_b32_e32 v25, 0xffff0000, v2
	v_lshlrev_b32_e32 v2, 16, v3
	v_and_b32_e32 v3, 0xffff0000, v3
	v_pk_mul_f32 v[6:7], v[6:7], v[0:1]
	v_pk_mul_f32 v[0:1], v[4:5], v[22:23]
	s_waitcnt vmcnt(0) lgkmcnt(0)
	v_pk_mul_f32 v[4:5], v[18:19], v[10:11]
	v_pk_mul_f32 v[8:9], v[16:17], v[8:9]
	v_pk_mul_f32 v[4:5], v[4:5], v[2:3]
	v_pk_mul_f32 v[2:3], v[8:9], v[24:25]
	v_cvt_pk_bf16_f32 v0, v0, v1
	v_cvt_pk_bf16_f32 v1, v6, v7
	s_nop 0
	v_cvt_pk_bf16_f32 v2, v2, v3
	v_cvt_pk_bf16_f32 v3, v4, v5
	global_store_dwordx4 v[20:21], v[0:3], off
	s_waitcnt lgkmcnt(0)
	s_barrier
	s_cbranch_scc0 .LBB0_1120
; template <int DIR> __device__ __forceinline__ void h3_dir(unsigned char* lds, const bf16_t* zrow, int h, const bf16_t* slot, f32x4 (&o)[8]) {
;     ...
;     float bl[32], qin[32]; bf16x8 kin[4];
;     load32(zrow + (size_t)(1 + DIR) * ZSEG + 8 * kq, bl);
;     load32(zrow + 8 * kq, qin);
;     {
;         float kk[32];
; #pragma unroll
;         for (int i = 0; i < 32; ++i) kk[i] = 1.0f - __builtin_amdgcn_exp2f(bl[i]);
;         scan16x8<DIR>(bl); scan16x8<DIR>(bl + 8); scan16x8<DIR>(bl + 16); scan16x8<DIR>(bl + 24);
; template <bool STORE> __device__ __forceinline__ void h3_phase(unsigned char* lds, unsigned char* ws, const bf16_t* SF, const float* norm_g, int G, int blk) {
;     ...
;         {
; #pragma unroll
;           for (int ks = 0; ks < 4; ++ks) { const u32x4 w = *(const u32x4*)(zrow + 3 * ZSEG + 8 * kq + 32 * ks);
; #pragma unroll
;               for (int e = 0; e < 4; ++e) { VT[(32 * ks + 8 * kq + 2 * e) * HP + 16 * wid + r] = (bf16_t)(w[e] & 0xffffu); VT[(32 * ks + 8 * kq + 2 * e + 1) * HP + 16 * wid + r] = (bf16_t)(w[e] >> 16); } } }
.LBB0_1100:
	s_ashr_i32 s4, s16, 10
	s_bfe_u32 s3, s16, 0x70003
	s_and_b32 s36, s16, 7
	s_ashr_i32 s5, s4, 31
	s_lshl_b64 s[6:7], s[4:5], 14
	s_lshl_b32 s5, s3, 7
	s_lshl_b32 s31, s36, 15
	s_add_u32 s6, s6, s20
	s_addc_u32 s7, s7, s21
	s_add_u32 s6, s6, s31
	s_addc_u32 s7, s7, 0
	s_add_u32 s31, s6, s5
	s_addc_u32 s34, s7, 0
	v_mov_b32_e32 v1, s34
	v_or_b32_e32 v0, s31, v112
	v_lshlrev_b64 v[0:1], 8, v[0:1]
	v_lshl_add_u64 v[80:81], s[10:11], 0, v[0:1]
	v_lshl_add_u64 v[4:5], v[80:81], 0, v[128:129]
	v_add_co_u32_e32 v0, vcc, s25, v4
	v_lshl_add_u64 v[16:17], v[4:5], 0, s[12:13]
	s_nop 0
	v_addc_co_u32_e32 v1, vcc, 0, v5, vcc
	global_load_dwordx4 v[0:3], v[0:1], off
	s_nop 0
	global_load_dwordx4 v[4:7], v[16:17], off offset:64
	global_load_dwordx4 v[8:11], v[16:17], off offset:128
	global_load_dwordx4 v[12:15], v[16:17], off offset:192
	v_mov_b32_e32 v85, v254
	s_waitcnt vmcnt(3)
	ds_write_b16 v113, v0
	ds_write_b16_d16_hi v115, v0 offset:272
	ds_write_b16 v113, v1 offset:544
	ds_write_b16_d16_hi v123, v1 offset:272
	ds_write_b16 v113, v2 offset:1088
	ds_write_b16_d16_hi v125, v2 offset:272
	ds_write_b16 v113, v3 offset:1632
	ds_write_b16_d16_hi v127, v3 offset:272
	s_waitcnt vmcnt(2)
	ds_write_b16 v113, v4 offset:8704
	ds_write_b16_d16_hi v130, v4 offset:272
	ds_write_b16 v113, v5 offset:9248
	ds_write_b16_d16_hi v131, v5 offset:272
	ds_write_b16 v113, v6 offset:9792
	ds_write_b16_d16_hi v132, v6 offset:272
	ds_write_b16 v113, v7 offset:10336
	ds_write_b16_d16_hi v133, v7 offset:272
	s_waitcnt vmcnt(1)
	ds_write_b16 v113, v8 offset:17408
	ds_write_b16_d16_hi v134, v8 offset:272
	ds_write_b16 v113, v9 offset:17952
	ds_write_b16_d16_hi v135, v9 offset:272
	ds_write_b16 v113, v10 offset:18496
	ds_write_b16_d16_hi v136, v10 offset:272
	ds_write_b16 v113, v11 offset:19040
	ds_write_b16_d16_hi v137, v11 offset:272
	s_waitcnt vmcnt(0)
	ds_write_b16 v113, v12 offset:26112
	ds_write_b16_d16_hi v138, v12 offset:272
	ds_write_b16 v113, v13 offset:26656
	ds_write_b16_d16_hi v139, v13 offset:272
	ds_write_b16 v113, v14 offset:27200
	ds_write_b16_d16_hi v140, v14 offset:272
	ds_write_b16 v113, v15 offset:27744
	ds_write_b16_d16_hi v141, v15 offset:272
	s_nop 0
	v_bfe_u32 v84, v85, 4, 2
	v_lshlrev_b32_e32 v116, 4, v84
	v_lshl_add_u64 v[16:17], v[80:81], 0, v[116:117]
	v_add_co_u32_e32 v0, vcc, s26, v16
	v_lshl_add_u64 v[18:19], v[16:17], 0, s[8:9]
	s_nop 0
	v_addc_co_u32_e32 v1, vcc, 0, v17, vcc
	global_load_dwordx4 v[0:3], v[0:1], off
	s_nop 0
	global_load_dwordx4 v[4:7], v[18:19], off offset:64
	global_load_dwordx4 v[8:11], v[18:19], off offset:128
	global_load_dwordx4 v[12:15], v[18:19], off offset:192
	global_load_dwordx4 v[64:67], v[16:17], off
	global_load_dwordx4 v[52:55], v[16:17], off offset:64
	global_load_dwordx4 v[48:51], v[16:17], off offset:128
	global_load_dwordx4 v[44:47], v[16:17], off offset:192
	v_readfirstlane_b32 s5, v85
	s_ashr_i32 s35, s5, 6
	v_and_b32_e32 v83, 15, v85
	v_lshlrev_b32_e32 v82, 3, v84
	v_cmp_eq_u32_e32 vcc, 15, v83
	s_lshl_b32 s37, s35, 9
	s_waitcnt vmcnt(6)
	v_lshlrev_b32_e32 v111, 16, v4
	v_lshlrev_b32_e32 v107, 16, v0
	v_and_b32_e32 v106, 0xffff0000, v0
	v_lshlrev_b32_e32 v152, 16, v1
	v_and_b32_e32 v151, 0xffff0000, v1
	v_lshlrev_b32_e32 v150, 16, v2
	v_and_b32_e32 v149, 0xffff0000, v2
	v_lshlrev_b32_e32 v148, 16, v3
	v_and_b32_e32 v116, 0xffff0000, v3
	v_mov_b32_e32 v26, v148
	v_mov_b32_e32 v33, v106
	v_mov_b32_e32 v35, v151
	v_mov_b32_e32 v25, v149
	v_mov_b32_e32 v32, v107
	v_mov_b32_e32 v27, v116
	v_mov_b32_e32 v34, v152
	v_mov_b32_e32 v24, v150
	s_nop 1
	v_add_f32_dpp v32, v32, v32 row_shr:1 row_mask:0xf bank_mask:0xf bound_ctrl:1
	v_add_f32_dpp v33, v33, v33 row_shr:1 row_mask:0xf bank_mask:0xf bound_ctrl:1
	v_add_f32_dpp v34, v34, v34 row_shr:1 row_mask:0xf bank_mask:0xf bound_ctrl:1
	v_add_f32_dpp v35, v35, v35 row_shr:1 row_mask:0xf bank_mask:0xf bound_ctrl:1
	v_add_f32_dpp v24, v24, v24 row_shr:1 row_mask:0xf bank_mask:0xf bound_ctrl:1
	v_add_f32_dpp v25, v25, v25 row_shr:1 row_mask:0xf bank_mask:0xf bound_ctrl:1
	v_add_f32_dpp v26, v26, v26 row_shr:1 row_mask:0xf bank_mask:0xf bound_ctrl:1
	v_add_f32_dpp v27, v27, v27 row_shr:1 row_mask:0xf bank_mask:0xf bound_ctrl:1
	v_and_b32_e32 v110, 0xffff0000, v4
	v_lshlrev_b32_e32 v109, 16, v5
	v_and_b32_e32 v108, 0xffff0000, v5
	v_lshlrev_b32_e32 v102, 16, v6
	v_and_b32_e32 v103, 0xffff0000, v6
	v_lshlrev_b32_e32 v104, 16, v7
	v_and_b32_e32 v105, 0xffff0000, v7
	s_nop 1
	v_add_f32_dpp v32, v32, v32 row_shr:2 row_mask:0xf bank_mask:0xf bound_ctrl:1
	v_add_f32_dpp v33, v33, v33 row_shr:2 row_mask:0xf bank_mask:0xf bound_ctrl:1
	v_add_f32_dpp v34, v34, v34 row_shr:2 row_mask:0xf bank_mask:0xf bound_ctrl:1
	v_add_f32_dpp v35, v35, v35 row_shr:2 row_mask:0xf bank_mask:0xf bound_ctrl:1
	v_add_f32_dpp v24, v24, v24 row_shr:2 row_mask:0xf bank_mask:0xf bound_ctrl:1
	v_add_f32_dpp v25, v25, v25 row_shr:2 row_mask:0xf bank_mask:0xf bound_ctrl:1
	v_add_f32_dpp v26, v26, v26 row_shr:2 row_mask:0xf bank_mask:0xf bound_ctrl:1
	v_add_f32_dpp v27, v27, v27 row_shr:2 row_mask:0xf bank_mask:0xf bound_ctrl:1
	v_mov_b32_e32 v18, v104
	v_mov_b32_e32 v21, v110
	v_mov_b32_e32 v23, v108
	v_mov_b32_e32 v17, v103
	v_mov_b32_e32 v20, v111
	v_mov_b32_e32 v19, v105
	v_mov_b32_e32 v22, v109
	v_mov_b32_e32 v16, v102
	s_nop 1
	v_add_f32_dpp v32, v32, v32 row_shr:4 row_mask:0xf bank_mask:0xf bound_ctrl:1
	v_add_f32_dpp v33, v33, v33 row_shr:4 row_mask:0xf bank_mask:0xf bound_ctrl:1
	v_add_f32_dpp v34, v34, v34 row_shr:4 row_mask:0xf bank_mask:0xf bound_ctrl:1
	v_add_f32_dpp v35, v35, v35 row_shr:4 row_mask:0xf bank_mask:0xf bound_ctrl:1
	v_add_f32_dpp v24, v24, v24 row_shr:4 row_mask:0xf bank_mask:0xf bound_ctrl:1
	v_add_f32_dpp v25, v25, v25 row_shr:4 row_mask:0xf bank_mask:0xf bound_ctrl:1
	v_add_f32_dpp v26, v26, v26 row_shr:4 row_mask:0xf bank_mask:0xf bound_ctrl:1
	v_add_f32_dpp v27, v27, v27 row_shr:4 row_mask:0xf bank_mask:0xf bound_ctrl:1
	s_waitcnt vmcnt(5)
; __device__ __forceinline__ float bf_lo(unsigned w) { return __uint_as_float(w << 16); }
; __device__ __forceinline__ float bf_hi(unsigned w) { return __uint_as_float(w & 0xffff0000u); }
; template <int DIR> __device__ __forceinline__ void scan16x8(float* v) {
;     if (DIR == 0) { SCAN_STEP("row_shr:", 1); SCAN_STEP("row_shr:", 2); SCAN_STEP("row_shr:", 4); SCAN_STEP("row_shr:", 8); }
;     else          { SCAN_STEP("row_shl:", 1); SCAN_STEP("row_shl:", 2); SCAN_STEP("row_shl:", 4); SCAN_STEP("row_shl:", 8); }
; }
; __device__ __forceinline__ void load32(const bf16_t* p, float (&v)[32]) {
; #pragma unroll
;     for (int ks = 0; ks < 4; ++ks) { const u32x4 w = *(const u32x4*)(p + 32 * ks);
;         v[8 * ks + 0] = bf_lo(w.x); v[8 * ks + 1] = bf_hi(w.x); v[8 * ks + 2] = bf_lo(w.y); v[8 * ks + 3] = bf_hi(w.y); v[8 * ks + 4] = bf_lo(w.z); v[8 * ks + 5] = bf_hi(w.z); v[8 * ks + 6] = bf_lo(w.w); v[8 * ks + 7] = bf_hi(w.w); }
; template <int DIR> __device__ __forceinline__ void h3_dir(unsigned char* lds, const bf16_t* zrow, int h, const bf16_t* slot, f32x4 (&o)[8]) {
;     ...
;         scan16x8<DIR>(bl); scan16x8<DIR>(bl + 8); scan16x8<DIR>(bl + 16); scan16x8<DIR>(bl + 24);
	v_lshlrev_b32_e32 v98, 16, v8
	s_nop 1
	v_add_f32_dpp v32, v32, v32 row_shr:8 row_mask:0xf bank_mask:0xf bound_ctrl:1
	v_add_f32_dpp v33, v33, v33 row_shr:8 row_mask:0xf bank_mask:0xf bound_ctrl:1
	v_add_f32_dpp v34, v34, v34 row_shr:8 row_mask:0xf bank_mask:0xf bound_ctrl:1
	v_add_f32_dpp v35, v35, v35 row_shr:8 row_mask:0xf bank_mask:0xf bound_ctrl:1
	v_add_f32_dpp v24, v24, v24 row_shr:8 row_mask:0xf bank_mask:0xf bound_ctrl:1
	v_add_f32_dpp v25, v25, v25 row_shr:8 row_mask:0xf bank_mask:0xf bound_ctrl:1
	v_add_f32_dpp v26, v26, v26 row_shr:8 row_mask:0xf bank_mask:0xf bound_ctrl:1
	v_add_f32_dpp v27, v27, v27 row_shr:8 row_mask:0xf bank_mask:0xf bound_ctrl:1
	s_nop 1
	v_add_f32_dpp v20, v20, v20 row_shr:1 row_mask:0xf bank_mask:0xf bound_ctrl:1
	v_add_f32_dpp v21, v21, v21 row_shr:1 row_mask:0xf bank_mask:0xf bound_ctrl:1
	v_add_f32_dpp v22, v22, v22 row_shr:1 row_mask:0xf bank_mask:0xf bound_ctrl:1
	v_add_f32_dpp v23, v23, v23 row_shr:1 row_mask:0xf bank_mask:0xf bound_ctrl:1
	v_add_f32_dpp v16, v16, v16 row_shr:1 row_mask:0xf bank_mask:0xf bound_ctrl:1
	v_add_f32_dpp v17, v17, v17 row_shr:1 row_mask:0xf bank_mask:0xf bound_ctrl:1
	v_add_f32_dpp v18, v18, v18 row_shr:1 row_mask:0xf bank_mask:0xf bound_ctrl:1
	v_add_f32_dpp v19, v19, v19 row_shr:1 row_mask:0xf bank_mask:0xf bound_ctrl:1
	v_and_b32_e32 v99, 0xffff0000, v8
	v_lshlrev_b32_e32 v100, 16, v9
	v_and_b32_e32 v101, 0xffff0000, v9
	v_lshlrev_b32_e32 v94, 16, v10
	v_and_b32_e32 v95, 0xffff0000, v10
	v_lshlrev_b32_e32 v96, 16, v11
	v_and_b32_e32 v97, 0xffff0000, v11
	s_nop 1
	v_add_f32_dpp v20, v20, v20 row_shr:2 row_mask:0xf bank_mask:0xf bound_ctrl:1
	v_add_f32_dpp v21, v21, v21 row_shr:2 row_mask:0xf bank_mask:0xf bound_ctrl:1
	v_add_f32_dpp v22, v22, v22 row_shr:2 row_mask:0xf bank_mask:0xf bound_ctrl:1
	v_add_f32_dpp v23, v23, v23 row_shr:2 row_mask:0xf bank_mask:0xf bound_ctrl:1
	v_add_f32_dpp v16, v16, v16 row_shr:2 row_mask:0xf bank_mask:0xf bound_ctrl:1
	v_add_f32_dpp v17, v17, v17 row_shr:2 row_mask:0xf bank_mask:0xf bound_ctrl:1
	v_add_f32_dpp v18, v18, v18 row_shr:2 row_mask:0xf bank_mask:0xf bound_ctrl:1
	v_add_f32_dpp v19, v19, v19 row_shr:2 row_mask:0xf bank_mask:0xf bound_ctrl:1
	s_waitcnt vmcnt(4)
	v_lshlrev_b32_e32 v90, 16, v12
	v_and_b32_e32 v91, 0xffff0000, v12
	v_lshlrev_b32_e32 v92, 16, v13
	v_and_b32_e32 v93, 0xffff0000, v13
	v_lshlrev_b32_e32 v86, 16, v14
	v_and_b32_e32 v87, 0xffff0000, v14
	v_lshlrev_b32_e32 v88, 16, v15
	v_and_b32_e32 v89, 0xffff0000, v15
	v_mov_b32_e32 v10, v96
	v_mov_b32_e32 v13, v99
	v_mov_b32_e32 v15, v101
	v_mov_b32_e32 v9, v95
	v_mov_b32_e32 v12, v98
	v_mov_b32_e32 v11, v97
	v_mov_b32_e32 v14, v100
	v_mov_b32_e32 v8, v94
	s_nop 1
	v_add_f32_dpp v20, v20, v20 row_shr:4 row_mask:0xf bank_mask:0xf bound_ctrl:1
	v_add_f32_dpp v21, v21, v21 row_shr:4 row_mask:0xf bank_mask:0xf bound_ctrl:1
	v_add_f32_dpp v22, v22, v22 row_shr:4 row_mask:0xf bank_mask:0xf bound_ctrl:1
	v_add_f32_dpp v23, v23, v23 row_shr:4 row_mask:0xf bank_mask:0xf bound_ctrl:1
	v_add_f32_dpp v16, v16, v16 row_shr:4 row_mask:0xf bank_mask:0xf bound_ctrl:1
	v_add_f32_dpp v17, v17, v17 row_shr:4 row_mask:0xf bank_mask:0xf bound_ctrl:1
	v_add_f32_dpp v18, v18, v18 row_shr:4 row_mask:0xf bank_mask:0xf bound_ctrl:1
	v_add_f32_dpp v19, v19, v19 row_shr:4 row_mask:0xf bank_mask:0xf bound_ctrl:1
	v_mov_b32_e32 v2, v88
	s_nop 1
	v_add_f32_dpp v20, v20, v20 row_shr:8 row_mask:0xf bank_mask:0xf bound_ctrl:1
	v_add_f32_dpp v21, v21, v21 row_shr:8 row_mask:0xf bank_mask:0xf bound_ctrl:1
	v_add_f32_dpp v22, v22, v22 row_shr:8 row_mask:0xf bank_mask:0xf bound_ctrl:1
	v_add_f32_dpp v23, v23, v23 row_shr:8 row_mask:0xf bank_mask:0xf bound_ctrl:1
	v_add_f32_dpp v16, v16, v16 row_shr:8 row_mask:0xf bank_mask:0xf bound_ctrl:1
	v_add_f32_dpp v17, v17, v17 row_shr:8 row_mask:0xf bank_mask:0xf bound_ctrl:1
	v_add_f32_dpp v18, v18, v18 row_shr:8 row_mask:0xf bank_mask:0xf bound_ctrl:1
	v_add_f32_dpp v19, v19, v19 row_shr:8 row_mask:0xf bank_mask:0xf bound_ctrl:1
	s_nop 1
	v_add_f32_dpp v12, v12, v12 row_shr:1 row_mask:0xf bank_mask:0xf bound_ctrl:1
	v_add_f32_dpp v13, v13, v13 row_shr:1 row_mask:0xf bank_mask:0xf bound_ctrl:1
	v_add_f32_dpp v14, v14, v14 row_shr:1 row_mask:0xf bank_mask:0xf bound_ctrl:1
	v_add_f32_dpp v15, v15, v15 row_shr:1 row_mask:0xf bank_mask:0xf bound_ctrl:1
	v_add_f32_dpp v8, v8, v8 row_shr:1 row_mask:0xf bank_mask:0xf bound_ctrl:1
	v_add_f32_dpp v9, v9, v9 row_shr:1 row_mask:0xf bank_mask:0xf bound_ctrl:1
	v_add_f32_dpp v10, v10, v10 row_shr:1 row_mask:0xf bank_mask:0xf bound_ctrl:1
	v_add_f32_dpp v11, v11, v11 row_shr:1 row_mask:0xf bank_mask:0xf bound_ctrl:1
	v_mov_b32_e32 v5, v91
	s_nop 1
	v_add_f32_dpp v12, v12, v12 row_shr:2 row_mask:0xf bank_mask:0xf bound_ctrl:1
	v_add_f32_dpp v13, v13, v13 row_shr:2 row_mask:0xf bank_mask:0xf bound_ctrl:1
	v_add_f32_dpp v14, v14, v14 row_shr:2 row_mask:0xf bank_mask:0xf bound_ctrl:1
	v_add_f32_dpp v15, v15, v15 row_shr:2 row_mask:0xf bank_mask:0xf bound_ctrl:1
	v_add_f32_dpp v8, v8, v8 row_shr:2 row_mask:0xf bank_mask:0xf bound_ctrl:1
	v_add_f32_dpp v9, v9, v9 row_shr:2 row_mask:0xf bank_mask:0xf bound_ctrl:1
	v_add_f32_dpp v10, v10, v10 row_shr:2 row_mask:0xf bank_mask:0xf bound_ctrl:1
	v_add_f32_dpp v11, v11, v11 row_shr:2 row_mask:0xf bank_mask:0xf bound_ctrl:1
	v_mov_b32_e32 v7, v93
	v_mov_b32_e32 v1, v87
	v_mov_b32_e32 v4, v90
	v_mov_b32_e32 v3, v89
	v_mov_b32_e32 v6, v92
	v_mov_b32_e32 v0, v86
	s_nop 1
	v_add_f32_dpp v12, v12, v12 row_shr:4 row_mask:0xf bank_mask:0xf bound_ctrl:1
	v_add_f32_dpp v13, v13, v13 row_shr:4 row_mask:0xf bank_mask:0xf bound_ctrl:1
	v_add_f32_dpp v14, v14, v14 row_shr:4 row_mask:0xf bank_mask:0xf bound_ctrl:1
; template <int DIR> __device__ __forceinline__ void h3_dir(unsigned char* lds, const bf16_t* zrow, int h, const bf16_t* slot, f32x4 (&o)[8]) {
;     ...
;         scan16x8<DIR>(bl); scan16x8<DIR>(bl + 8); scan16x8<DIR>(bl + 16); scan16x8<DIR>(bl + 24);
;         float eb[32];
; #pragma unroll
;         for (int i = 0; i < 32; ++i) { eb[i] = __builtin_amdgcn_exp2f(bl[i]); qin[i] *= eb[i]; }
;         if (r == (DIR ? 0 : 15)) {
; #pragma unroll
;             for (int ks = 0; ks < 4; ++ks) { *(f32x4*)(TOT + wid * 128 + 32 * ks + 8 * kq) = (f32x4){bl[8 * ks], bl[8 * ks + 1], bl[8 * ks + 2], bl[8 * ks + 3]}; *(f32x4*)(TOT + wid * 128 + 32 * ks + 8 * kq + 4) = (f32x4){bl[8 * ks + 4], bl[8 * ks + 5], bl[8 * ks + 6], bl[8 * ks + 7]}; }
; #pragma unroll
;             for (int ks = 0; ks < 4; ++ks) { *(f32x4*)(TOTE + wid * 128 + 32 * ks + 8 * kq) = (f32x4){eb[8 * ks], eb[8 * ks + 1], eb[8 * ks + 2], eb[8 * ks + 3]}; *(f32x4*)(TOTE + wid * 128 + 32 * ks + 8 * kq + 4) = (f32x4){eb[8 * ks + 4], eb[8 * ks + 5], eb[8 * ks + 6], eb[8 * ks + 7]}; }
;         }
	v_add_f32_dpp v15, v15, v15 row_shr:4 row_mask:0xf bank_mask:0xf bound_ctrl:1
	v_add_f32_dpp v8, v8, v8 row_shr:4 row_mask:0xf bank_mask:0xf bound_ctrl:1
	v_add_f32_dpp v9, v9, v9 row_shr:4 row_mask:0xf bank_mask:0xf bound_ctrl:1
	v_add_f32_dpp v10, v10, v10 row_shr:4 row_mask:0xf bank_mask:0xf bound_ctrl:1
	v_add_f32_dpp v11, v11, v11 row_shr:4 row_mask:0xf bank_mask:0xf bound_ctrl:1
	v_exp_f32_e32 v60, v32
	s_nop 1
	v_add_f32_dpp v12, v12, v12 row_shr:8 row_mask:0xf bank_mask:0xf bound_ctrl:1
	v_add_f32_dpp v13, v13, v13 row_shr:8 row_mask:0xf bank_mask:0xf bound_ctrl:1
	v_add_f32_dpp v14, v14, v14 row_shr:8 row_mask:0xf bank_mask:0xf bound_ctrl:1
	v_add_f32_dpp v15, v15, v15 row_shr:8 row_mask:0xf bank_mask:0xf bound_ctrl:1
	v_add_f32_dpp v8, v8, v8 row_shr:8 row_mask:0xf bank_mask:0xf bound_ctrl:1
	v_add_f32_dpp v9, v9, v9 row_shr:8 row_mask:0xf bank_mask:0xf bound_ctrl:1
	v_add_f32_dpp v10, v10, v10 row_shr:8 row_mask:0xf bank_mask:0xf bound_ctrl:1
	v_add_f32_dpp v11, v11, v11 row_shr:8 row_mask:0xf bank_mask:0xf bound_ctrl:1
	s_nop 1
	v_add_f32_dpp v4, v4, v4 row_shr:1 row_mask:0xf bank_mask:0xf bound_ctrl:1
	v_add_f32_dpp v5, v5, v5 row_shr:1 row_mask:0xf bank_mask:0xf bound_ctrl:1
	v_add_f32_dpp v6, v6, v6 row_shr:1 row_mask:0xf bank_mask:0xf bound_ctrl:1
	v_add_f32_dpp v7, v7, v7 row_shr:1 row_mask:0xf bank_mask:0xf bound_ctrl:1
	v_add_f32_dpp v0, v0, v0 row_shr:1 row_mask:0xf bank_mask:0xf bound_ctrl:1
	v_add_f32_dpp v1, v1, v1 row_shr:1 row_mask:0xf bank_mask:0xf bound_ctrl:1
	v_add_f32_dpp v2, v2, v2 row_shr:1 row_mask:0xf bank_mask:0xf bound_ctrl:1
	v_add_f32_dpp v3, v3, v3 row_shr:1 row_mask:0xf bank_mask:0xf bound_ctrl:1
	v_exp_f32_e32 v61, v33
	s_nop 1
	v_add_f32_dpp v4, v4, v4 row_shr:2 row_mask:0xf bank_mask:0xf bound_ctrl:1
	v_add_f32_dpp v5, v5, v5 row_shr:2 row_mask:0xf bank_mask:0xf bound_ctrl:1
	v_add_f32_dpp v6, v6, v6 row_shr:2 row_mask:0xf bank_mask:0xf bound_ctrl:1
	v_add_f32_dpp v7, v7, v7 row_shr:2 row_mask:0xf bank_mask:0xf bound_ctrl:1
	v_add_f32_dpp v0, v0, v0 row_shr:2 row_mask:0xf bank_mask:0xf bound_ctrl:1
	v_add_f32_dpp v1, v1, v1 row_shr:2 row_mask:0xf bank_mask:0xf bound_ctrl:1
	v_add_f32_dpp v2, v2, v2 row_shr:2 row_mask:0xf bank_mask:0xf bound_ctrl:1
	v_add_f32_dpp v3, v3, v3 row_shr:2 row_mask:0xf bank_mask:0xf bound_ctrl:1
	v_exp_f32_e32 v62, v34
	s_nop 1
	v_add_f32_dpp v4, v4, v4 row_shr:4 row_mask:0xf bank_mask:0xf bound_ctrl:1
	v_add_f32_dpp v5, v5, v5 row_shr:4 row_mask:0xf bank_mask:0xf bound_ctrl:1
	v_add_f32_dpp v6, v6, v6 row_shr:4 row_mask:0xf bank_mask:0xf bound_ctrl:1
	v_add_f32_dpp v7, v7, v7 row_shr:4 row_mask:0xf bank_mask:0xf bound_ctrl:1
	v_add_f32_dpp v0, v0, v0 row_shr:4 row_mask:0xf bank_mask:0xf bound_ctrl:1
	v_add_f32_dpp v1, v1, v1 row_shr:4 row_mask:0xf bank_mask:0xf bound_ctrl:1
	v_add_f32_dpp v2, v2, v2 row_shr:4 row_mask:0xf bank_mask:0xf bound_ctrl:1
	v_add_f32_dpp v3, v3, v3 row_shr:4 row_mask:0xf bank_mask:0xf bound_ctrl:1
	v_exp_f32_e32 v63, v35
	v_exp_f32_e32 v56, v24
	v_exp_f32_e32 v57, v25
	v_exp_f32_e32 v58, v26
	v_exp_f32_e32 v59, v27
	v_exp_f32_e32 v72, v20
	v_exp_f32_e32 v73, v21
	v_exp_f32_e32 v74, v22
	v_exp_f32_e32 v75, v23
	v_exp_f32_e32 v68, v16
	v_exp_f32_e32 v69, v17
	v_exp_f32_e32 v70, v18
	v_exp_f32_e32 v71, v19
	v_exp_f32_e32 v76, v12
	v_exp_f32_e32 v77, v13
	v_exp_f32_e32 v78, v14
	v_exp_f32_e32 v79, v15
	v_exp_f32_e32 v40, v8
	v_exp_f32_e32 v41, v9
	v_exp_f32_e32 v42, v10
	v_exp_f32_e32 v43, v11
	s_nop 1
	v_add_f32_dpp v4, v4, v4 row_shr:8 row_mask:0xf bank_mask:0xf bound_ctrl:1
	v_add_f32_dpp v5, v5, v5 row_shr:8 row_mask:0xf bank_mask:0xf bound_ctrl:1
	v_add_f32_dpp v6, v6, v6 row_shr:8 row_mask:0xf bank_mask:0xf bound_ctrl:1
	v_add_f32_dpp v7, v7, v7 row_shr:8 row_mask:0xf bank_mask:0xf bound_ctrl:1
	v_add_f32_dpp v0, v0, v0 row_shr:8 row_mask:0xf bank_mask:0xf bound_ctrl:1
	v_add_f32_dpp v1, v1, v1 row_shr:8 row_mask:0xf bank_mask:0xf bound_ctrl:1
	v_add_f32_dpp v2, v2, v2 row_shr:8 row_mask:0xf bank_mask:0xf bound_ctrl:1
	v_add_f32_dpp v3, v3, v3 row_shr:8 row_mask:0xf bank_mask:0xf bound_ctrl:1
	s_nop 0
	v_exp_f32_e32 v36, v4
	v_exp_f32_e32 v37, v5
	v_exp_f32_e32 v38, v6
	v_exp_f32_e32 v39, v7
	v_exp_f32_e32 v28, v0
	v_exp_f32_e32 v29, v1
	v_exp_f32_e32 v30, v2
	v_exp_f32_e32 v31, v3
	s_and_saveexec_b64 s[6:7], vcc
	s_cbranch_execz .LBB0_1102
	s_add_i32 s5, s37, 0
	v_lshl_add_u32 v153, v82, 2, s5
	ds_write_b128 v153, v[32:35]
	ds_write_b128 v153, v[24:27] offset:16
	ds_write_b128 v153, v[20:23] offset:128
	ds_write_b128 v153, v[16:19] offset:144
	ds_write_b128 v153, v[12:15] offset:256
	ds_write_b128 v153, v[8:11] offset:272
	ds_write_b128 v153, v[4:7] offset:384
	ds_write_b128 v153, v[0:3] offset:400
	ds_write_b128 v153, v[60:63] offset:4096
	ds_write_b128 v153, v[56:59] offset:4112
	ds_write_b128 v153, v[72:75] offset:4224
	ds_write_b128 v153, v[68:71] offset:4240
	ds_write_b128 v153, v[76:79] offset:4352
	ds_write_b128 v153, v[40:43] offset:4368
	ds_write_b128 v153, v[36:39] offset:4480
	ds_write_b128 v153, v[28:31] offset:4496
; template <int DIR> __device__ __forceinline__ void h3_dir(unsigned char* lds, const bf16_t* zrow, int h, const bf16_t* slot, f32x4 (&o)[8]) {
;     ...
;         float kk[32];
; #pragma unroll
;         for (int i = 0; i < 32; ++i) kk[i] = 1.0f - __builtin_amdgcn_exp2f(bl[i]);
;         scan16x8<DIR>(bl); scan16x8<DIR>(bl + 8); scan16x8<DIR>(bl + 16); scan16x8<DIR>(bl + 24);
;         float eb[32];
; #pragma unroll
;         for (int i = 0; i < 32; ++i) { eb[i] = __builtin_amdgcn_exp2f(bl[i]); qin[i] *= eb[i]; }
;         if (r == (DIR ? 0 : 15)) {
; #pragma unroll
;             for (int ks = 0; ks < 4; ++ks) { *(f32x4*)(TOT + wid * 128 + 32 * ks + 8 * kq) = (f32x4){bl[8 * ks], bl[8 * ks + 1], bl[8 * ks + 2], bl[8 * ks + 3]}; *(f32x4*)(TOT + wid * 128 + 32 * ks + 8 * kq + 4) = (f32x4){bl[8 * ks + 4], bl[8 * ks + 5], bl[8 * ks + 6], bl[8 * ks + 7]}; }
; #pragma unroll
;             for (int ks = 0; ks < 4; ++ks) { *(f32x4*)(TOTE + wid * 128 + 32 * ks + 8 * kq) = (f32x4){eb[8 * ks], eb[8 * ks + 1], eb[8 * ks + 2], eb[8 * ks + 3]}; *(f32x4*)(TOTE + wid * 128 + 32 * ks + 8 * kq + 4) = (f32x4){eb[8 * ks + 4], eb[8 * ks + 5], eb[8 * ks + 6], eb[8 * ks + 7]}; }
;         }
; #pragma unroll
;         for (int it = 0; it < 4; ++it) { const int p = tid + 512 * it, v = p >> 4, c16 = p & 15; *(u32x4*)(ST + v * HP + c16 * 8) = *(const u32x4*)(slot + (size_t)v * 128 + c16 * 8); }
; #pragma unroll
;         for (int it = 0; it < 4; ++it) { const int p = lane + 64 * it; *(u32x4*)(Pw + (p >> 4) * HP + (p & 15) * 8) = (u32x4){0u, 0u, 0u, 0u}; }
;         __syncthreads();
.LBB0_1102:
	s_or_b64 exec, exec, s[6:7]
	s_waitcnt vmcnt(0)
	v_lshlrev_b32_e32 v191, 16, v44
	v_and_b32_e32 v192, 0xffff0000, v44
	v_exp_f32_e32 v44, v107
	v_lshlrev_b32_e32 v193, 16, v45
	v_and_b32_e32 v194, 0xffff0000, v45
	v_exp_f32_e32 v45, v106
	v_sub_f32_e32 v196, 1.0, v44
	v_exp_f32_e32 v44, v152
	s_lshl_b32 s4, s4, 3
	v_lshlrev_b32_e32 v171, 16, v67
	v_and_b32_e32 v172, 0xffff0000, v67
	v_lshlrev_b32_e32 v195, 16, v46
	v_and_b32_e32 v67, 0xffff0000, v46
	v_lshlrev_b32_e32 v106, 16, v47
	v_and_b32_e32 v107, 0xffff0000, v47
	v_sub_f32_e32 v197, 1.0, v45
	v_exp_f32_e32 v45, v151
	v_exp_f32_e32 v46, v150
	v_exp_f32_e32 v47, v149
	s_or_b32 s4, s4, s36
	s_ashr_i32 s5, s4, 31
	v_sub_f32_e32 v198, 1.0, v44
	v_exp_f32_e32 v44, v148
	s_lshl_b64 s[4:5], s[4:5], 21
	s_lshl_b32 s3, s3, 14
	s_or_b32 s4, s4, s3
	v_sub_f32_e32 v199, 1.0, v45
	v_sub_f32_e32 v200, 1.0, v46
	v_sub_f32_e32 v201, 1.0, v47
	v_exp_f32_e32 v45, v116
	v_exp_f32_e32 v46, v111
	v_exp_f32_e32 v47, v110
	s_lshl_b64 s[4:5], s[4:5], 1
	s_add_u32 s6, s18, s4
	v_lshlrev_b32_e32 v179, 16, v48
	v_and_b32_e32 v180, 0xffff0000, v48
	v_sub_f32_e32 v202, 1.0, v44
	v_lshlrev_b32_e32 v44, 4, v85
	v_ashrrev_i32_e32 v160, 4, v85
	v_add_u32_e32 v48, 0x200, v85
	s_addc_u32 s7, s19, s5
	v_and_b32_e32 v116, 0xf0, v44
	v_ashrrev_i32_e32 v161, 31, v160
	v_ashrrev_i32_e32 v162, 4, v48
	v_sub_f32_e32 v203, 1.0, v45
	v_sub_f32_e32 v204, 1.0, v46
	v_sub_f32_e32 v205, 1.0, v47
	v_lshl_add_u64 v[44:45], s[6:7], 0, v[116:117]
	v_lshlrev_b64 v[46:47], 8, v[160:161]
	v_ashrrev_i32_e32 v163, 31, v162
	v_lshlrev_b32_e32 v181, 16, v49
	v_and_b32_e32 v182, 0xffff0000, v49
	v_lshl_add_u64 v[46:47], v[44:45], 0, v[46:47]
	v_lshlrev_b64 v[48:49], 8, v[162:163]
	v_lshlrev_b32_e32 v183, 16, v50
	v_and_b32_e32 v188, 0xffff0000, v50
	v_lshlrev_b32_e32 v189, 16, v51
	v_and_b32_e32 v190, 0xffff0000, v51
	v_exp_f32_e32 v50, v109
	v_exp_f32_e32 v51, v108
	v_lshl_add_u64 v[48:49], v[44:45], 0, v[48:49]
	global_load_dwordx4 v[108:111], v[46:47], off
	global_load_dwordx4 v[148:151], v[48:49], off
	v_add_u32_e32 v46, 0x400, v85
	v_ashrrev_i32_e32 v164, 4, v46
	v_ashrrev_i32_e32 v165, 31, v164
	v_lshlrev_b64 v[46:47], 8, v[164:165]
	v_lshl_add_u64 v[46:47], v[44:45], 0, v[46:47]
	global_load_dwordx4 v[152:155], v[46:47], off
	v_add_u32_e32 v46, 0x600, v85
	v_ashrrev_i32_e32 v166, 4, v46
	v_ashrrev_i32_e32 v167, 31, v166
	v_lshlrev_b64 v[46:47], 8, v[166:167]
	v_lshl_add_u64 v[44:45], v[44:45], 0, v[46:47]
	global_load_dwordx4 v[156:159], v[44:45], off
	v_exp_f32_e32 v44, v102
	v_exp_f32_e32 v45, v103
	v_mul_f32_e32 v48, v40, v183
	v_mul_f32_e32 v41, v41, v188
	v_sub_f32_e32 v102, 1.0, v44
	v_sub_f32_e32 v103, 1.0, v45
	v_exp_f32_e32 v44, v98
	v_exp_f32_e32 v45, v99
	v_add_u32_e32 v40, 0, v116
	s_mul_i32 s3, s35, 0x1100
	v_sub_f32_e32 v98, 1.0, v44
	v_sub_f32_e32 v99, 1.0, v45
	v_exp_f32_e32 v44, v94
	v_exp_f32_e32 v45, v95
	s_add_i32 s6, s3, 0
	s_add_i32 s6, s6, 0x1b800
	v_sub_f32_e32 v94, 1.0, v44
	v_sub_f32_e32 v95, 1.0, v45
	v_exp_f32_e32 v44, v90
	v_exp_f32_e32 v45, v91
	s_add_i32 s3, s37, 0
	v_lshlrev_b32_e32 v168, 16, v64
	v_sub_f32_e32 v90, 1.0, v44
	v_sub_f32_e32 v91, 1.0, v45
	v_exp_f32_e32 v44, v86
	v_exp_f32_e32 v45, v87
	v_and_b32_e32 v64, 0xffff0000, v64
	v_lshlrev_b32_e32 v169, 16, v65
	v_sub_f32_e32 v86, 1.0, v44
	v_sub_f32_e32 v87, 1.0, v45
	v_mad_u64_u32 v[44:45], s[38:39], v160, s27, v[40:41]
	v_and_b32_e32 v65, 0xffff0000, v65
	v_lshlrev_b32_e32 v170, 16, v66
	v_and_b32_e32 v66, 0xffff0000, v66
	v_lshlrev_b32_e32 v173, 16, v52
	v_and_b32_e32 v52, 0xffff0000, v52
	v_lshlrev_b32_e32 v174, 16, v53
	v_and_b32_e32 v53, 0xffff0000, v53
	v_lshlrev_b32_e32 v175, 16, v54
	v_and_b32_e32 v176, 0xffff0000, v54
	v_lshlrev_b32_e32 v177, 16, v55
	v_and_b32_e32 v178, 0xffff0000, v55
	v_mul_f32_e32 v49, v76, v179
	v_lshl_add_u32 v76, v82, 2, s3
	v_sub_f32_e32 v161, 1.0, v51
	v_mul_f32_e32 v61, v61, v64
	v_mul_f32_e32 v63, v63, v65
	v_mul_f32_e32 v64, v56, v170
	v_mul_f32_e32 v65, v57, v66
	v_mul_f32_e32 v66, v58, v171
	v_mul_f32_e32 v58, v73, v52
	v_mul_f32_e32 v55, v75, v53
	v_mul_f32_e32 v56, v68, v175
	v_mul_f32_e32 v51, v69, v176
	v_mul_f32_e32 v52, v70, v177
	v_mul_f32_e32 v53, v71, v178
	v_mul_f32_e32 v57, v72, v173
	v_mul_f32_e32 v54, v74, v174
	v_exp_f32_e32 v47, v105
	v_exp_f32_e32 v46, v104
	v_sub_f32_e32 v85, 1.0, v50
	v_mul_f32_e32 v60, v60, v168
	v_sub_f32_e32 v105, 1.0, v47
	v_sub_f32_e32 v104, 1.0, v46
	v_exp_f32_e32 v46, v100
	s_waitcnt vmcnt(3)
	ds_write_b128 v44, v[108:111] offset:43008
	v_mad_u64_u32 v[44:45], s[38:39], v162, s27, v[40:41]
	s_waitcnt vmcnt(2)
	ds_write_b128 v44, v[148:151] offset:43008
	v_mad_u64_u32 v[44:45], s[38:39], v164, s27, v[40:41]
	v_exp_f32_e32 v47, v101
	s_waitcnt vmcnt(1)
	ds_write_b128 v44, v[152:155] offset:43008
	v_mad_u64_u32 v[44:45], s[38:39], v166, s27, v[40:41]
	v_mul_u32_u24_e32 v40, 0x110, v84
	v_add3_u32 v40, s6, v116, v40
	v_sub_f32_e32 v100, 1.0, v46
	s_waitcnt vmcnt(0)
	ds_write_b128 v44, v[156:159] offset:43008
	ds_write_b128 v40, v[184:187]
	ds_write_b128 v40, v[184:187] offset:1088
	ds_write_b128 v40, v[184:187] offset:2176
	ds_write_b128 v40, v[184:187] offset:3264
	s_waitcnt lgkmcnt(0)
	s_barrier
; __device__ __forceinline__ bf16x8 pk8(const float* v) { u32x4 w; w.x = cvt_pk_bf16(v[0], v[1]); w.y = cvt_pk_bf16(v[2], v[3]); w.z = cvt_pk_bf16(v[4], v[5]); w.w = cvt_pk_bf16(v[6], v[7]); return __builtin_bit_cast(bf16x8, w); }
; template <int DIR> __device__ __forceinline__ void h3_dir(unsigned char* lds, const bf16_t* zrow, int h, const bf16_t* slot, f32x4 (&o)[8]) {
;     ...
;         float tmp[8];
; #pragma unroll
;         for (int ks = 0; ks < 4; ++ks) {
;             const f32x4 a = *(const f32x4*)(TOT + wid * 128 + 32 * ks + 8 * kq), b = *(const f32x4*)(TOT + wid * 128 + 32 * ks + 8 * kq + 4);
;             const float tw[8] = {a[0], a[1], a[2], a[3], b[0], b[1], b[2], b[3]};
; #pragma unroll
;             for (int e = 0; e < 8; ++e) tmp[e] = kk[8 * ks + e] * __builtin_amdgcn_exp2f(tw[e] - bl[8 * ks + e]);
;             *(bf16x8*)(KO + (16 * wid + r) * HP + 32 * ks + 8 * kq) = pk8(tmp);
; #pragma unroll
;             for (int e = 0; e < 8; ++e) tmp[e] = kk[8 * ks + e] * __builtin_amdgcn_exp2f(fminf(-bl[8 * ks + e], 115.f));
;             kin[ks] = pk8(tmp);
;         }
	ds_read_b128 v[68:71], v76
	ds_read_b128 v[72:75], v76 offset:16
	v_lshl_or_b32 v44, s35, 4, v83
	v_lshl_add_u32 v40, v82, 1, 0
	v_mad_u64_u32 v[44:45], s[36:37], v44, s27, v[40:41]
	s_waitcnt lgkmcnt(1)
	v_sub_f32_e32 v45, v68, v32
	v_sub_f32_e32 v68, v69, v33
	v_sub_f32_e32 v69, v70, v34
	v_exp_f32_e32 v68, v68
	v_exp_f32_e32 v69, v69
	v_sub_f32_e32 v70, v71, v35
	s_waitcnt lgkmcnt(0)
	v_sub_f32_e32 v71, v72, v24
	v_sub_f32_e32 v72, v73, v25
	v_sub_f32_e32 v73, v74, v26
	v_sub_f32_e32 v74, v75, v27
	v_max_f32_e64 v25, -v25, -v25
	v_max_f32_e64 v26, -v26, -v26
	v_max_f32_e64 v27, -v27, -v27
	v_exp_f32_e32 v45, v45
	v_exp_f32_e32 v70, v70
	v_exp_f32_e32 v71, v71
	v_max_f32_e64 v32, -v32, -v32
	v_max_f32_e64 v33, -v33, -v33
	v_max_f32_e64 v34, -v34, -v34
	v_max_f32_e64 v35, -v35, -v35
	v_max_f32_e64 v24, -v24, -v24
	v_min_f32_e32 v25, 0x42e60000, v25
	v_min_f32_e32 v26, 0x42e60000, v26
	v_min_f32_e32 v27, 0x42e60000, v27
	v_exp_f32_e32 v72, v72
	v_exp_f32_e32 v73, v73
	v_exp_f32_e32 v74, v74
	v_min_f32_e32 v32, 0x42e60000, v32
	v_min_f32_e32 v33, 0x42e60000, v33
	v_min_f32_e32 v34, 0x42e60000, v34
	v_min_f32_e32 v35, 0x42e60000, v35
	v_min_f32_e32 v24, 0x42e60000, v24
	v_exp_f32_e32 v25, v25
	v_exp_f32_e32 v26, v26
	v_exp_f32_e32 v27, v27
	v_exp_f32_e32 v32, v32
	v_exp_f32_e32 v33, v33
	v_exp_f32_e32 v34, v34
	v_exp_f32_e32 v35, v35
	v_exp_f32_e32 v24, v24
	v_mul_f32_e32 v68, v197, v68
	v_mul_f32_e32 v69, v198, v69
	v_mul_f32_e32 v45, v196, v45
	v_mul_f32_e32 v70, v199, v70
	v_mul_f32_e32 v71, v200, v71
	v_cvt_pk_bf16_f32 v68, v45, v68
	v_cvt_pk_bf16_f32 v69, v69, v70
	v_mul_f32_e32 v72, v201, v72
	v_mul_f32_e32 v73, v202, v73
	v_mul_f32_e32 v74, v203, v74
	v_cvt_pk_bf16_f32 v70, v71, v72
	v_cvt_pk_bf16_f32 v71, v73, v74
	ds_write_b128 v44, v[68:71] offset:8192
	v_mul_f32_e32 v68, v201, v25
	v_mul_f32_e32 v69, v202, v26
	v_mul_f32_e32 v27, v203, v27
	v_mul_f32_e32 v32, v196, v32
	v_mul_f32_e32 v33, v197, v33
	v_mul_f32_e32 v34, v198, v34
	v_mul_f32_e32 v35, v199, v35
	v_mul_f32_e32 v45, v200, v24
	v_cvt_pk_bf16_f32 v24, v32, v33
	v_cvt_pk_bf16_f32 v25, v34, v35
	v_cvt_pk_bf16_f32 v26, v45, v68
	v_cvt_pk_bf16_f32 v27, v69, v27
	ds_read_b128 v[68:71], v76 offset:128
	ds_read_b128 v[72:75], v76 offset:144
	v_mul_f32_e32 v34, v43, v190
	v_mul_f32_e32 v32, v36, v191
	v_mul_f32_e32 v33, v37, v192
	s_waitcnt lgkmcnt(1)
	v_sub_f32_e32 v35, v68, v20
	v_sub_f32_e32 v36, v69, v21
	v_sub_f32_e32 v37, v70, v22
	v_sub_f32_e32 v43, v71, v23
	s_waitcnt lgkmcnt(0)
	v_sub_f32_e32 v70, v75, v19
	v_max_f32_e64 v20, -v20, -v20
	v_max_f32_e64 v21, -v21, -v21
	v_max_f32_e64 v22, -v22, -v22
	v_max_f32_e64 v23, -v23, -v23
	v_max_f32_e64 v19, -v19, -v19
	v_sub_f32_e32 v45, v72, v16
	v_sub_f32_e32 v68, v73, v17
	v_sub_f32_e32 v69, v74, v18
	v_min_f32_e32 v20, 0x42e60000, v20
	v_min_f32_e32 v21, 0x42e60000, v21
	v_min_f32_e32 v22, 0x42e60000, v22
	v_min_f32_e32 v23, 0x42e60000, v23
	v_max_f32_e64 v16, -v16, -v16
	v_max_f32_e64 v17, -v17, -v17
	v_max_f32_e64 v18, -v18, -v18
	v_min_f32_e32 v19, 0x42e60000, v19
	v_exp_f32_e32 v35, v35
	v_exp_f32_e32 v36, v36
	v_exp_f32_e32 v37, v37
	v_exp_f32_e32 v68, v68
	v_exp_f32_e32 v20, v20
	v_exp_f32_e32 v21, v21
	v_exp_f32_e32 v22, v22
	v_exp_f32_e32 v23, v23
	v_min_f32_e32 v16, 0x42e60000, v16
	v_min_f32_e32 v17, 0x42e60000, v17
	v_min_f32_e32 v18, 0x42e60000, v18
	v_exp_f32_e32 v19, v19
	v_exp_f32_e32 v43, v43
	v_exp_f32_e32 v45, v45
	v_exp_f32_e32 v69, v69
	v_exp_f32_e32 v70, v70
	v_exp_f32_e32 v16, v16
	v_exp_f32_e32 v17, v17
	v_exp_f32_e32 v18, v18
	v_mul_f32_e32 v35, v204, v35
	v_mul_f32_e32 v36, v205, v36
	v_mul_f32_e32 v37, v85, v37
	v_mul_f32_e32 v71, v103, v68
	v_mul_f32_e32 v20, v204, v20
	v_mul_f32_e32 v21, v205, v21
	v_mul_f32_e32 v22, v85, v22
	v_mul_f32_e32 v23, v161, v23
	v_mul_f32_e32 v19, v105, v19
	v_mul_f32_e32 v43, v161, v43
	v_mul_f32_e32 v45, v102, v45
	v_mul_f32_e32 v72, v104, v69
	v_mul_f32_e32 v73, v105, v70
	v_cvt_pk_bf16_f32 v68, v35, v36
	v_cvt_pk_bf16_f32 v69, v37, v43
	v_cvt_pk_bf16_f32 v70, v45, v71
	v_cvt_pk_bf16_f32 v71, v72, v73
	ds_write_b128 v44, v[68:71] offset:8256
	v_mul_f32_e32 v35, v102, v16
	v_mul_f32_e32 v36, v103, v17
	v_mul_f32_e32 v37, v104, v18
	v_cvt_pk_bf16_f32 v16, v20, v21
	v_cvt_pk_bf16_f32 v17, v22, v23
	v_cvt_pk_bf16_f32 v18, v35, v36
	v_cvt_pk_bf16_f32 v19, v37, v19
	ds_read_b128 v[20:23], v76 offset:256
	ds_read_b128 v[68:71], v76 offset:272
	v_mul_f32_e32 v36, v38, v193
	v_mul_f32_e32 v37, v39, v194
	v_mul_f32_e32 v35, v28, v195
	s_waitcnt lgkmcnt(1)
	v_sub_f32_e32 v20, v20, v12
	v_sub_f32_e32 v21, v21, v13
	v_sub_f32_e32 v22, v22, v14
	v_exp_f32_e32 v20, v20
	v_exp_f32_e32 v21, v21
	v_exp_f32_e32 v22, v22
	v_sub_f32_e32 v23, v23, v15
	s_waitcnt lgkmcnt(0)
; __device__ __forceinline__ unsigned cvt_pk_c(float lo, float hi) { const f32x2_cv v = {lo, hi}; const bf16x2_cv b = __builtin_convertvector(v, bf16x2_cv); return __builtin_bit_cast(unsigned, b); }
; __device__ __forceinline__ bf16x8 pk8(const float* v) { u32x4 w; w.x = cvt_pk_bf16(v[0], v[1]); w.y = cvt_pk_bf16(v[2], v[3]); w.z = cvt_pk_bf16(v[4], v[5]); w.w = cvt_pk_bf16(v[6], v[7]); return __builtin_bit_cast(bf16x8, w); }
; template <int DIR> __device__ __forceinline__ void h3_dir(unsigned char* lds, const bf16_t* zrow, int h, const bf16_t* slot, f32x4 (&o)[8]) {
;     ...
; #pragma unroll
;         for (int ks = 0; ks < 4; ++ks) {
;             const f32x4 a = *(const f32x4*)(TOT + wid * 128 + 32 * ks + 8 * kq), b = *(const f32x4*)(TOT + wid * 128 + 32 * ks + 8 * kq + 4);
;             const float tw[8] = {a[0], a[1], a[2], a[3], b[0], b[1], b[2], b[3]};
; #pragma unroll
;             for (int e = 0; e < 8; ++e) tmp[e] = kk[8 * ks + e] * __builtin_amdgcn_exp2f(tw[e] - bl[8 * ks + e]);
;             *(bf16x8*)(KO + (16 * wid + r) * HP + 32 * ks + 8 * kq) = pk8(tmp);
; #pragma unroll
;             for (int e = 0; e < 8; ++e) tmp[e] = kk[8 * ks + e] * __builtin_amdgcn_exp2f(fminf(-bl[8 * ks + e], 115.f));
;             kin[ks] = pk8(tmp);
;         }
;     }
;     __syncthreads();
;     {
;         f32x4 sc = {0.f, 0.f, 0.f, 0.f};
; #pragma unroll
;         for (int ks = 0; ks < 4; ++ks) sc = __builtin_amdgcn_mfma_f32_16x16x32_bf16(pk8(qin + 8 * ks), kin[ks], sc, 0, 0, 0);
; #pragma unroll
;         for (int i = 0; i < 4; i += 2) { const int t = 4 * kq + i; const bool k0 = DIR ? (r >= t) : (r <= t), k1 = DIR ? (r >= t + 1) : (r <= t + 1); const unsigned w = cvt_pk_c(k0 ? sc[i] : 0.f, k1 ? sc[i + 1] : 0.f);
;             Pw[t * HP + 16 * wid + r] = (bf16_t)(w & 0xffffu); Pw[(t + 1) * HP + 16 * wid + r] = (bf16_t)(w >> 16); }
;     }
;     float run[32];
; #pragma unroll
;     for (int i = 0; i < 32; ++i) run[i] = 1.f;
;     for (int d = 1; d < 8; ++d) {
;         const int m = DIR ? wid + d : wid - d;
;         if (m < 0 || m > 7) break;
	v_sub_f32_e32 v28, v68, v8
	v_sub_f32_e32 v38, v69, v9
	v_sub_f32_e32 v39, v70, v10
	v_sub_f32_e32 v43, v71, v11
	v_max_f32_e64 v12, -v12, -v12
	v_max_f32_e64 v13, -v13, -v13
	v_max_f32_e64 v14, -v14, -v14
	v_max_f32_e64 v15, -v15, -v15
	v_max_f32_e64 v8, -v8, -v8
	v_max_f32_e64 v9, -v9, -v9
	v_max_f32_e64 v10, -v10, -v10
	v_max_f32_e64 v11, -v11, -v11
	v_sub_f32_e32 v101, 1.0, v47
	v_exp_f32_e32 v46, v96
	v_exp_f32_e32 v47, v97
	v_exp_f32_e32 v23, v23
	v_exp_f32_e32 v28, v28
	v_exp_f32_e32 v38, v38
	v_min_f32_e32 v12, 0x42e60000, v12
	v_min_f32_e32 v13, 0x42e60000, v13
	v_min_f32_e32 v14, 0x42e60000, v14
	v_min_f32_e32 v15, 0x42e60000, v15
	v_min_f32_e32 v8, 0x42e60000, v8
	v_min_f32_e32 v9, 0x42e60000, v9
	v_min_f32_e32 v10, 0x42e60000, v10
	v_min_f32_e32 v11, 0x42e60000, v11
	v_exp_f32_e32 v39, v39
	v_exp_f32_e32 v43, v43
	v_exp_f32_e32 v12, v12
	v_exp_f32_e32 v13, v13
	v_exp_f32_e32 v14, v14
	v_exp_f32_e32 v15, v15
	v_exp_f32_e32 v8, v8
	v_exp_f32_e32 v9, v9
	v_exp_f32_e32 v10, v10
	v_exp_f32_e32 v11, v11
	v_mul_f32_e32 v20, v98, v20
	v_mul_f32_e32 v21, v99, v21
	v_mul_f32_e32 v22, v100, v22
	v_sub_f32_e32 v96, 1.0, v46
	v_sub_f32_e32 v97, 1.0, v47
	v_mul_f32_e32 v23, v101, v23
	v_mul_f32_e32 v28, v94, v28
	v_mul_f32_e32 v38, v95, v38
	v_cvt_pk_bf16_f32 v20, v20, v21
	v_cvt_pk_bf16_f32 v21, v22, v23
	v_cvt_pk_bf16_f32 v22, v28, v38
	v_mul_f32_e32 v39, v96, v39
	v_mul_f32_e32 v43, v97, v43
	v_cvt_pk_bf16_f32 v23, v39, v43
	ds_write_b128 v44, v[20:23] offset:8320
	v_mul_f32_e32 v12, v98, v12
	v_mul_f32_e32 v13, v99, v13
	v_mul_f32_e32 v14, v100, v14
	v_mul_f32_e32 v15, v101, v15
	v_mul_f32_e32 v20, v94, v8
	v_mul_f32_e32 v21, v95, v9
	v_mul_f32_e32 v22, v96, v10
	v_mul_f32_e32 v11, v97, v11
	v_cvt_pk_bf16_f32 v8, v12, v13
	v_cvt_pk_bf16_f32 v9, v14, v15
	v_cvt_pk_bf16_f32 v10, v20, v21
	v_cvt_pk_bf16_f32 v11, v22, v11
	ds_read_b128 v[12:15], v76 offset:384
	ds_read_b128 v[20:23], v76 offset:400
	v_exp_f32_e32 v47, v93
	v_exp_f32_e32 v46, v92
	v_mul_f32_e32 v62, v62, v169
	s_waitcnt lgkmcnt(1)
	v_sub_f32_e32 v12, v12, v4
	v_sub_f32_e32 v13, v13, v5
	v_sub_f32_e32 v14, v14, v6
	v_sub_f32_e32 v15, v15, v7
	s_waitcnt lgkmcnt(0)
	v_sub_f32_e32 v23, v23, v3
	v_max_f32_e64 v4, -v4, -v4
	v_max_f32_e64 v5, -v5, -v5
	v_max_f32_e64 v6, -v6, -v6
	v_max_f32_e64 v7, -v7, -v7
	v_max_f32_e64 v3, -v3, -v3
	v_sub_f32_e32 v93, 1.0, v47
	v_exp_f32_e32 v47, v89
	v_exp_f32_e32 v12, v12
	v_exp_f32_e32 v13, v13
	v_exp_f32_e32 v14, v14
	v_sub_f32_e32 v20, v20, v0
	v_sub_f32_e32 v21, v21, v1
	v_sub_f32_e32 v22, v22, v2
	v_min_f32_e32 v4, 0x42e60000, v4
	v_min_f32_e32 v5, 0x42e60000, v5
	v_min_f32_e32 v6, 0x42e60000, v6
	v_min_f32_e32 v7, 0x42e60000, v7
	v_max_f32_e64 v0, -v0, -v0
	v_max_f32_e64 v1, -v1, -v1
	v_max_f32_e64 v2, -v2, -v2
	v_min_f32_e32 v3, 0x42e60000, v3
	v_sub_f32_e32 v92, 1.0, v46
	v_exp_f32_e32 v46, v88
	v_exp_f32_e32 v15, v15
	v_exp_f32_e32 v20, v20
	v_exp_f32_e32 v21, v21
	v_exp_f32_e32 v4, v4
	v_exp_f32_e32 v5, v5
	v_exp_f32_e32 v6, v6
	v_exp_f32_e32 v7, v7
	v_min_f32_e32 v0, 0x42e60000, v0
	v_min_f32_e32 v1, 0x42e60000, v1
	v_min_f32_e32 v2, 0x42e60000, v2
	v_exp_f32_e32 v3, v3
	v_exp_f32_e32 v22, v22
	v_exp_f32_e32 v23, v23
	v_exp_f32_e32 v0, v0
	v_exp_f32_e32 v1, v1
	v_exp_f32_e32 v2, v2
	v_sub_f32_e32 v89, 1.0, v47
	v_mul_f32_e32 v12, v90, v12
	v_mul_f32_e32 v13, v91, v13
	v_mul_f32_e32 v14, v92, v14
	v_sub_f32_e32 v88, 1.0, v46
	v_mul_f32_e32 v15, v93, v15
	v_mul_f32_e32 v20, v86, v20
	v_mul_f32_e32 v21, v87, v21
	v_cvt_pk_bf16_f32 v12, v12, v13
	v_cvt_pk_bf16_f32 v13, v14, v15
	v_cvt_pk_bf16_f32 v14, v20, v21
	v_mul_f32_e32 v4, v90, v4
	v_mul_f32_e32 v5, v91, v5
	v_mul_f32_e32 v6, v92, v6
	v_mul_f32_e32 v7, v93, v7
	v_mul_f32_e32 v3, v89, v3
	v_mul_f32_e32 v59, v59, v172
	v_mul_f32_e32 v22, v88, v22
	v_mul_f32_e32 v23, v89, v23
	v_cvt_pk_bf16_f32 v15, v22, v23
	ds_write_b128 v44, v[12:15] offset:8384
	v_mul_f32_e32 v12, v86, v0
	v_mul_f32_e32 v13, v87, v1
	v_mul_f32_e32 v14, v88, v2
	v_cvt_pk_bf16_f32 v0, v4, v5
	v_cvt_pk_bf16_f32 v1, v6, v7
	v_cvt_pk_bf16_f32 v2, v12, v13
	v_cvt_pk_bf16_f32 v3, v14, v3
	s_waitcnt lgkmcnt(0)
	s_barrier
	v_cvt_pk_bf16_f32 v4, v60, v61
	v_cvt_pk_bf16_f32 v5, v62, v63
	v_cvt_pk_bf16_f32 v6, v64, v65
	v_cvt_pk_bf16_f32 v7, v66, v59
	v_cvt_pk_bf16_f32 v12, v57, v58
	v_cvt_pk_bf16_f32 v13, v54, v55
	v_cvt_pk_bf16_f32 v14, v56, v51
	v_cvt_pk_bf16_f32 v15, v52, v53
	v_mul_f32_e32 v50, v77, v180
	v_mfma_f32_16x16x32_bf16 v[4:7], v[4:7], v[24:27], 0
	v_mul_f32_e32 v46, v78, v181
	v_mul_f32_e32 v47, v79, v182
	v_mul_f32_e32 v42, v42, v189
	v_mfma_f32_16x16x32_bf16 v[4:7], v[12:15], v[16:19], v[4:7]
	v_cvt_pk_bf16_f32 v12, v49, v50
	v_cvt_pk_bf16_f32 v13, v46, v47
	v_cvt_pk_bf16_f32 v14, v48, v41
	v_cvt_pk_bf16_f32 v15, v42, v34
	v_mul_f32_e32 v43, v29, v67
	v_mfma_f32_16x16x32_bf16 v[4:7], v[12:15], v[8:11], v[4:7]
	v_mul_f32_e32 v38, v30, v106
	v_mul_f32_e32 v39, v31, v107
	v_cvt_pk_bf16_f32 v8, v32, v33
	v_cvt_pk_bf16_f32 v9, v36, v37
	v_cvt_pk_bf16_f32 v10, v35, v43
	v_cvt_pk_bf16_f32 v11, v38, v39
	s_lshl_b32 s3, s35, 5
	v_mfma_f32_16x16x32_bf16 v[0:3], v[8:11], v[0:3], v[4:7]
	s_add_i32 s3, s6, s3
	v_mov_b32_e32 v24, 1.0
	v_mov_b32_e32 v25, 1.0
	s_nop 0
	v_lshlrev_b32_e32 v4, 2, v84
	v_or_b32_e32 v6, 1, v4
	v_cmp_le_u32_e32 vcc, v83, v4
	v_lshl_add_u32 v5, v83, 1, s3
	v_or_b32_e32 v69, 2, v4
	v_cndmask_b32_e32 v0, 0, v0, vcc
	v_cmp_le_u32_e32 vcc, v83, v6
	s_add_i32 s3, s35, -1
	s_cmp_gt_u32 s3, 7
	v_cndmask_b32_e32 v1, 0, v1, vcc
	v_cvt_pk_bf16_f32 v0, v0, v1
	v_mad_u32_u24 v1, v84, s24, v5
	ds_write_b16 v1, v0
	v_mad_u32_u24 v1, v6, s27, v5
	ds_write_b16_d16_hi v1, v0
	v_or_b32_e32 v0, 3, v4
	v_cmp_le_u32_e32 vcc, v83, v69
	v_mov_b32_e32 v26, 1.0
	v_mov_b32_e32 v27, 1.0
	v_cndmask_b32_e32 v2, 0, v2, vcc
	v_cmp_le_u32_e32 vcc, v83, v0
	v_mov_b32_e32 v28, 1.0
	v_mov_b32_e32 v29, 1.0
	v_cndmask_b32_e32 v0, 0, v3, vcc
	v_cvt_pk_bf16_f32 v0, v2, v0
	ds_write_b16 v1, v0 offset:272
	ds_write_b16_d16_hi v1, v0 offset:544
	v_mov_b32_e32 v30, 1.0
	v_mov_b32_e32 v31, 1.0
	v_mov_b32_e32 v20, 1.0
	v_mov_b32_e32 v21, 1.0
	v_mov_b32_e32 v22, 1.0
	v_mov_b32_e32 v23, 1.0
	v_mov_b32_e32 v16, 1.0
	v_mov_b32_e32 v17, 1.0
	v_mov_b32_e32 v18, 1.0
	v_mov_b32_e32 v19, 1.0
	v_mov_b32_e32 v8, 1.0
	v_mov_b32_e32 v9, 1.0
	v_mov_b32_e32 v10, 1.0
	v_mov_b32_e32 v11, 1.0
	v_mov_b32_e32 v4, 1.0
	v_mov_b32_e32 v5, 1.0
	v_mov_b32_e32 v6, 1.0
	v_mov_b32_e32 v7, 1.0
	v_mov_b32_e32 v12, 1.0
	v_mov_b32_e32 v13, 1.0
	v_mov_b32_e32 v14, 1.0
	v_mov_b32_e32 v15, 1.0
	v_mov_b32_e32 v0, 1.0
	v_mov_b32_e32 v1, 1.0
	v_mov_b32_e32 v2, 1.0
	v_mov_b32_e32 v3, 1.0
	s_cbranch_scc1 .LBB0_1110
; __device__ __forceinline__ unsigned cvt_pk_c(float lo, float hi) { const f32x2_cv v = {lo, hi}; const bf16x2_cv b = __builtin_convertvector(v, bf16x2_cv); return __builtin_bit_cast(unsigned, b); }
; __device__ __forceinline__ bf16x8 pk8(const float* v) { u32x4 w; w.x = cvt_pk_bf16(v[0], v[1]); w.y = cvt_pk_bf16(v[2], v[3]); w.z = cvt_pk_bf16(v[4], v[5]); w.w = cvt_pk_bf16(v[6], v[7]); return __builtin_bit_cast(bf16x8, w); }
; template <int DIR> __device__ __forceinline__ void h3_dir(unsigned char* lds, const bf16_t* zrow, int h, const bf16_t* slot, f32x4 (&o)[8]) {
;     ...
;     for (int d = 1; d < 8; ++d) {
;         const int m = DIR ? wid + d : wid - d;
;         if (m < 0 || m > 7) break;
;         f32x4 sc = {0.f, 0.f, 0.f, 0.f};
; #pragma unroll
;         for (int ks = 0; ks < 4; ++ks) {
;             float tmp[8];
; #pragma unroll
;             for (int e = 0; e < 8; ++e) tmp[e] = qin[8 * ks + e] * run[8 * ks + e];
;             const bf16x8 bb = *(const bf16x8*)(KO + (16 * m + r) * HP + 32 * ks + 8 * kq);
;             sc = __builtin_amdgcn_mfma_f32_16x16x32_bf16(pk8(tmp), bb, sc, 0, 0, 0);
;             const f32x4 a = *(const f32x4*)(TOTE + m * 128 + 32 * ks + 8 * kq), b = *(const f32x4*)(TOTE + m * 128 + 32 * ks + 8 * kq + 4);
;             run[8 * ks] *= a[0]; run[8 * ks + 1] *= a[1]; run[8 * ks + 2] *= a[2]; run[8 * ks + 3] *= a[3]; run[8 * ks + 4] *= b[0]; run[8 * ks + 5] *= b[1]; run[8 * ks + 6] *= b[2]; run[8 * ks + 7] *= b[3];
;         }
; #pragma unroll
;         for (int i = 0; i < 4; i += 2) { const unsigned w = cvt_pk_c(sc[i], sc[i + 1]); Pw[(4 * kq + i) * HP + 16 * m + r] = (bf16_t)(w & 0xffffu); Pw[(4 * kq + i + 1) * HP + 16 * m + r] = (bf16_t)(w >> 16); }
;     }
	v_lshl_or_b32 v0, s3, 4, v83
	v_mad_u64_u32 v[12:13], s[36:37], v0, s27, v[40:41]
	ds_read_b128 v[0:3], v12 offset:8192
	v_lshl_add_u32 v71, v84, 4, v40
	v_lshl_add_u32 v67, s3, 9, v71
	v_cvt_pk_bf16_f32 v4, v60, v61
	v_cvt_pk_bf16_f32 v5, v62, v63
	v_cvt_pk_bf16_f32 v6, v64, v65
	v_cvt_pk_bf16_f32 v7, v66, v59
	v_lshlrev_b32_e32 v44, 1, v83
	s_waitcnt lgkmcnt(0)
	v_mfma_f32_16x16x32_bf16 v[0:3], v[4:7], v[0:3], 0
	ds_read_b128 v[28:31], v67 offset:4112
	ds_read_b128 v[24:27], v67 offset:4096
	ds_read_b128 v[4:7], v12 offset:8256
	v_cvt_pk_bf16_f32 v8, v57, v58
	v_cvt_pk_bf16_f32 v9, v54, v55
	v_cvt_pk_bf16_f32 v10, v56, v51
	v_cvt_pk_bf16_f32 v11, v52, v53
	v_add_u32_e32 v45, s6, v44
	s_waitcnt lgkmcnt(0)
	v_mfma_f32_16x16x32_bf16 v[0:3], v[8:11], v[4:7], v[0:3]
	ds_read_b128 v[16:19], v67 offset:4240
	ds_read_b128 v[20:23], v67 offset:4224
	ds_read_b128 v[4:7], v12 offset:8320
	v_cvt_pk_bf16_f32 v8, v49, v50
	v_cvt_pk_bf16_f32 v9, v46, v47
	v_cvt_pk_bf16_f32 v10, v48, v41
	v_cvt_pk_bf16_f32 v11, v42, v34
	s_lshl_b32 s3, s3, 5
	s_waitcnt lgkmcnt(0)
	v_mfma_f32_16x16x32_bf16 v[0:3], v[8:11], v[4:7], v[0:3]
	ds_read_b128 v[4:7], v67 offset:4368
	ds_read_b128 v[8:11], v67 offset:4352
	ds_read_b128 v[12:15], v12 offset:8384
	v_cvt_pk_bf16_f32 v72, v32, v33
	v_cvt_pk_bf16_f32 v73, v36, v37
	v_cvt_pk_bf16_f32 v74, v35, v43
	v_cvt_pk_bf16_f32 v75, v38, v39
	v_add_u32_e32 v70, s3, v45
	s_waitcnt lgkmcnt(0)
	v_mfma_f32_16x16x32_bf16 v[72:75], v[72:75], v[12:15], v[0:3]
	ds_read_b128 v[12:15], v67 offset:4480
	s_nop 1
	ds_read_b128 v[0:3], v67 offset:4496
	v_mul_u32_u24_e32 v67, 0x220, v84
	v_lshlrev_b32_e32 v68, 1, v67
	s_nop 1
	v_cvt_pk_bf16_f32 v72, v72, v73
	v_add_u32_e32 v73, v70, v68
	v_add_u32_e32 v68, s6, v68
	ds_write_b16 v73, v72
	v_add3_u32 v73, v68, s3, v44
	v_mul_u32_u24_e32 v69, 0x88, v69
	ds_write_b16_d16_hi v73, v72 offset:272
	v_lshlrev_b32_e32 v73, 1, v69
	v_cvt_pk_bf16_f32 v72, v74, v75
	v_add_u32_e32 v70, v70, v73
	ds_write_b16 v70, v72
	v_add_u32_e32 v70, s6, v73
	v_add3_u32 v73, v70, s3, v44
	s_add_i32 s3, s35, -2
	s_cmp_gt_u32 s3, 7
	ds_write_b16_d16_hi v73, v72 offset:272
	s_cbranch_scc1 .LBB0_1110
	v_lshl_or_b32 v72, s3, 4, v83
	v_mad_u64_u32 v[98:99], s[36:37], v72, s27, v[40:41]
	ds_read_b128 v[72:75], v98 offset:8192
	v_lshl_add_u32 v99, s3, 9, v71
	v_mul_f32_e32 v76, v60, v24
	v_mul_f32_e32 v77, v61, v25
	v_mul_f32_e32 v78, v62, v26
	v_mul_f32_e32 v79, v63, v27
	v_mul_f32_e32 v84, v64, v28
	v_mul_f32_e32 v85, v65, v29
	v_mul_f32_e32 v86, v66, v30
	v_mul_f32_e32 v87, v59, v31
	v_cvt_pk_bf16_f32 v76, v76, v77
	v_cvt_pk_bf16_f32 v77, v78, v79
	v_cvt_pk_bf16_f32 v78, v84, v85
	v_cvt_pk_bf16_f32 v79, v86, v87
	ds_read_b128 v[84:87], v99 offset:4096
	ds_read_b128 v[88:91], v99 offset:4112
	s_waitcnt lgkmcnt(2)
	v_mfma_f32_16x16x32_bf16 v[72:75], v[76:79], v[72:75], 0
	ds_read_b128 v[76:79], v98 offset:8256
	v_mul_f32_e32 v92, v52, v18
	s_waitcnt lgkmcnt(2)
	v_pk_mul_f32 v[26:27], v[26:27], v[86:87]
	v_pk_mul_f32 v[24:25], v[24:25], v[84:85]
	s_waitcnt lgkmcnt(1)
	v_pk_mul_f32 v[30:31], v[30:31], v[90:91]
	v_mul_f32_e32 v84, v57, v20
	v_mul_f32_e32 v85, v58, v21
	v_mul_f32_e32 v86, v54, v22
	v_mul_f32_e32 v87, v55, v23
	v_mul_f32_e32 v90, v56, v16
	v_mul_f32_e32 v91, v51, v17
	v_mul_f32_e32 v93, v53, v19
	v_cvt_pk_bf16_f32 v84, v84, v85
	v_cvt_pk_bf16_f32 v85, v86, v87
	v_cvt_pk_bf16_f32 v86, v90, v91
	v_cvt_pk_bf16_f32 v87, v92, v93
	ds_read_b128 v[90:93], v99 offset:4224
	s_waitcnt lgkmcnt(1)
	v_mfma_f32_16x16x32_bf16 v[72:75], v[84:87], v[76:79], v[72:75]
	ds_read_b128 v[76:79], v98 offset:8320
	v_pk_mul_f32 v[28:29], v[28:29], v[88:89]
	v_mul_f32_e32 v84, v49, v8
	s_waitcnt lgkmcnt(1)
	v_pk_mul_f32 v[20:21], v[20:21], v[90:91]
	v_mul_f32_e32 v85, v50, v9
	v_mul_f32_e32 v86, v46, v10
	v_mul_f32_e32 v87, v47, v11
	v_mul_f32_e32 v88, v48, v4
	v_mul_f32_e32 v89, v41, v5
	v_mul_f32_e32 v90, v42, v6
	v_mul_f32_e32 v91, v34, v7
	ds_read_b128 v[94:97], v99 offset:4240
	v_cvt_pk_bf16_f32 v84, v84, v85
	v_cvt_pk_bf16_f32 v85, v86, v87
	v_cvt_pk_bf16_f32 v86, v88, v89
	v_cvt_pk_bf16_f32 v87, v90, v91
	ds_read_b128 v[88:91], v99 offset:4352
	s_waitcnt lgkmcnt(2)
	v_mfma_f32_16x16x32_bf16 v[72:75], v[84:87], v[76:79], v[72:75]
	ds_read_b128 v[76:79], v99 offset:4368
	ds_read_b128 v[84:87], v98 offset:8384
	v_pk_mul_f32 v[22:23], v[22:23], v[92:93]
	s_waitcnt lgkmcnt(3)
	v_pk_mul_f32 v[16:17], v[16:17], v[94:95]
	s_waitcnt lgkmcnt(2)
	v_pk_mul_f32 v[10:11], v[10:11], v[90:91]
	v_pk_mul_f32 v[8:9], v[8:9], v[88:89]
	v_mul_f32_e32 v88, v32, v12
	v_mul_f32_e32 v89, v33, v13
	v_mul_f32_e32 v90, v36, v14
	v_mul_f32_e32 v91, v37, v15
	v_mul_f32_e32 v92, v35, v0
	v_mul_f32_e32 v93, v43, v1
	v_mul_f32_e32 v94, v38, v2
	v_mul_f32_e32 v95, v39, v3
	v_cvt_pk_bf16_f32 v88, v88, v89
	v_cvt_pk_bf16_f32 v89, v90, v91
	v_cvt_pk_bf16_f32 v90, v92, v93
	v_cvt_pk_bf16_f32 v91, v94, v95
	s_lshl_b32 s3, s3, 5
	s_waitcnt lgkmcnt(0)
	v_mfma_f32_16x16x32_bf16 v[72:75], v[88:91], v[84:87], v[72:75]
	v_mul_f32_e64 v18, v18, v96
	v_mul_f32_e64 v19, v19, v97
	ds_read_b128 v[92:95], v99 offset:4480
	ds_read_b128 v[96:99], v99 offset:4496
	v_pk_mul_f32 v[4:5], v[4:5], v[76:77]
	v_add_u32_e32 v76, s3, v45
	s_nop 1
	v_cvt_pk_bf16_f32 v72, v72, v73
	v_lshl_add_u32 v73, v67, 1, v76
	ds_write_b16 v73, v72
	v_add3_u32 v73, v68, s3, v44
	ds_write_b16_d16_hi v73, v72 offset:272
	v_cvt_pk_bf16_f32 v72, v74, v75
	v_lshl_add_u32 v73, v69, 1, v76
	ds_write_b16 v73, v72
	v_add3_u32 v73, v70, s3, v44
	s_add_i32 s3, s35, -3
	v_pk_mul_f32 v[6:7], v[6:7], v[78:79]
	s_waitcnt lgkmcnt(4)
	v_pk_mul_f32 v[14:15], v[14:15], v[94:95]
	v_pk_mul_f32 v[12:13], v[12:13], v[92:93]
	s_waitcnt lgkmcnt(3)
	v_pk_mul_f32 v[2:3], v[2:3], v[98:99]
	v_pk_mul_f32 v[0:1], v[0:1], v[96:97]
	s_cmp_gt_u32 s3, 7
	ds_write_b16_d16_hi v73, v72 offset:272
	s_cbranch_scc1 .LBB0_1110
; __device__ __forceinline__ unsigned cvt_pk_c(float lo, float hi) { const f32x2_cv v = {lo, hi}; const bf16x2_cv b = __builtin_convertvector(v, bf16x2_cv); return __builtin_bit_cast(unsigned, b); }
; __device__ __forceinline__ bf16x8 pk8(const float* v) { u32x4 w; w.x = cvt_pk_bf16(v[0], v[1]); w.y = cvt_pk_bf16(v[2], v[3]); w.z = cvt_pk_bf16(v[4], v[5]); w.w = cvt_pk_bf16(v[6], v[7]); return __builtin_bit_cast(bf16x8, w); }
; template <int DIR> __device__ __forceinline__ void h3_dir(unsigned char* lds, const bf16_t* zrow, int h, const bf16_t* slot, f32x4 (&o)[8]) {
;     ...
;     for (int d = 1; d < 8; ++d) {
;         const int m = DIR ? wid + d : wid - d;
;         if (m < 0 || m > 7) break;
;         f32x4 sc = {0.f, 0.f, 0.f, 0.f};
; #pragma unroll
;         for (int ks = 0; ks < 4; ++ks) {
;             float tmp[8];
; #pragma unroll
;             for (int e = 0; e < 8; ++e) tmp[e] = qin[8 * ks + e] * run[8 * ks + e];
;             const bf16x8 bb = *(const bf16x8*)(KO + (16 * m + r) * HP + 32 * ks + 8 * kq);
;             sc = __builtin_amdgcn_mfma_f32_16x16x32_bf16(pk8(tmp), bb, sc, 0, 0, 0);
;             const f32x4 a = *(const f32x4*)(TOTE + m * 128 + 32 * ks + 8 * kq), b = *(const f32x4*)(TOTE + m * 128 + 32 * ks + 8 * kq + 4);
;             run[8 * ks] *= a[0]; run[8 * ks + 1] *= a[1]; run[8 * ks + 2] *= a[2]; run[8 * ks + 3] *= a[3]; run[8 * ks + 4] *= b[0]; run[8 * ks + 5] *= b[1]; run[8 * ks + 6] *= b[2]; run[8 * ks + 7] *= b[3];
;         }
; #pragma unroll
;         for (int i = 0; i < 4; i += 2) { const unsigned w = cvt_pk_c(sc[i], sc[i + 1]); Pw[(4 * kq + i) * HP + 16 * m + r] = (bf16_t)(w & 0xffffu); Pw[(4 * kq + i + 1) * HP + 16 * m + r] = (bf16_t)(w >> 16); }
;     }
	v_lshl_or_b32 v72, s3, 4, v83
	v_mad_u64_u32 v[98:99], s[36:37], v72, s27, v[40:41]
	ds_read_b128 v[72:75], v98 offset:8192
	v_lshl_add_u32 v99, s3, 9, v71
	v_mul_f32_e32 v76, v60, v24
	v_mul_f32_e32 v77, v61, v25
	v_mul_f32_e32 v78, v62, v26
	v_mul_f32_e32 v79, v63, v27
	v_mul_f32_e32 v84, v64, v28
	v_mul_f32_e32 v85, v65, v29
	v_mul_f32_e32 v86, v66, v30
	v_mul_f32_e32 v87, v59, v31
	v_cvt_pk_bf16_f32 v76, v76, v77
	v_cvt_pk_bf16_f32 v77, v78, v79
	v_cvt_pk_bf16_f32 v78, v84, v85
	v_cvt_pk_bf16_f32 v79, v86, v87
	ds_read_b128 v[84:87], v99 offset:4096
	ds_read_b128 v[88:91], v99 offset:4112
	s_waitcnt lgkmcnt(2)
	v_mfma_f32_16x16x32_bf16 v[72:75], v[76:79], v[72:75], 0
	ds_read_b128 v[76:79], v98 offset:8256
	v_mul_f32_e32 v92, v52, v18
	s_waitcnt lgkmcnt(2)
	v_pk_mul_f32 v[26:27], v[26:27], v[86:87]
	v_pk_mul_f32 v[24:25], v[24:25], v[84:85]
	s_waitcnt lgkmcnt(1)
	v_pk_mul_f32 v[30:31], v[30:31], v[90:91]
	v_mul_f32_e32 v84, v57, v20
	v_mul_f32_e32 v85, v58, v21
	v_mul_f32_e32 v86, v54, v22
	v_mul_f32_e32 v87, v55, v23
	v_mul_f32_e32 v90, v56, v16
	v_mul_f32_e32 v91, v51, v17
	v_mul_f32_e32 v93, v53, v19
	v_cvt_pk_bf16_f32 v84, v84, v85
	v_cvt_pk_bf16_f32 v85, v86, v87
	v_cvt_pk_bf16_f32 v86, v90, v91
	v_cvt_pk_bf16_f32 v87, v92, v93
	ds_read_b128 v[90:93], v99 offset:4224
	s_waitcnt lgkmcnt(1)
	v_mfma_f32_16x16x32_bf16 v[72:75], v[84:87], v[76:79], v[72:75]
	ds_read_b128 v[76:79], v98 offset:8320
	v_pk_mul_f32 v[28:29], v[28:29], v[88:89]
	v_mul_f32_e32 v84, v49, v8
	s_waitcnt lgkmcnt(1)
	v_pk_mul_f32 v[20:21], v[20:21], v[90:91]
	v_mul_f32_e32 v85, v50, v9
	v_mul_f32_e32 v86, v46, v10
	v_mul_f32_e32 v87, v47, v11
	v_mul_f32_e32 v88, v48, v4
	v_mul_f32_e32 v89, v41, v5
	v_mul_f32_e32 v90, v42, v6
	v_mul_f32_e32 v91, v34, v7
	ds_read_b128 v[94:97], v99 offset:4240
	v_cvt_pk_bf16_f32 v84, v84, v85
	v_cvt_pk_bf16_f32 v85, v86, v87
	v_cvt_pk_bf16_f32 v86, v88, v89
	v_cvt_pk_bf16_f32 v87, v90, v91
	ds_read_b128 v[88:91], v99 offset:4352
	s_waitcnt lgkmcnt(2)
	v_mfma_f32_16x16x32_bf16 v[72:75], v[84:87], v[76:79], v[72:75]
	ds_read_b128 v[76:79], v99 offset:4368
	ds_read_b128 v[84:87], v98 offset:8384
	v_pk_mul_f32 v[22:23], v[22:23], v[92:93]
	s_waitcnt lgkmcnt(3)
	v_pk_mul_f32 v[16:17], v[16:17], v[94:95]
	s_waitcnt lgkmcnt(2)
	v_pk_mul_f32 v[10:11], v[10:11], v[90:91]
	v_pk_mul_f32 v[8:9], v[8:9], v[88:89]
	v_mul_f32_e32 v88, v32, v12
	v_mul_f32_e32 v89, v33, v13
	v_mul_f32_e32 v90, v36, v14
	v_mul_f32_e32 v91, v37, v15
	v_mul_f32_e32 v92, v35, v0
	v_mul_f32_e32 v93, v43, v1
	v_mul_f32_e32 v94, v38, v2
	v_mul_f32_e32 v95, v39, v3
	v_cvt_pk_bf16_f32 v88, v88, v89
	v_cvt_pk_bf16_f32 v89, v90, v91
	v_cvt_pk_bf16_f32 v90, v92, v93
	v_cvt_pk_bf16_f32 v91, v94, v95
	s_lshl_b32 s3, s3, 5
	s_waitcnt lgkmcnt(0)
	v_mfma_f32_16x16x32_bf16 v[72:75], v[88:91], v[84:87], v[72:75]
	v_mul_f32_e64 v18, v18, v96
	v_mul_f32_e64 v19, v19, v97
	ds_read_b128 v[92:95], v99 offset:4480
	ds_read_b128 v[96:99], v99 offset:4496
	v_pk_mul_f32 v[4:5], v[4:5], v[76:77]
	v_add_u32_e32 v76, s3, v45
	s_nop 1
	v_cvt_pk_bf16_f32 v72, v72, v73
	v_lshl_add_u32 v73, v67, 1, v76
	ds_write_b16 v73, v72
	v_add3_u32 v73, v68, s3, v44
	ds_write_b16_d16_hi v73, v72 offset:272
	v_cvt_pk_bf16_f32 v72, v74, v75
	v_lshl_add_u32 v73, v69, 1, v76
	ds_write_b16 v73, v72
	v_add3_u32 v73, v70, s3, v44
	s_add_i32 s3, s35, -4
	v_pk_mul_f32 v[6:7], v[6:7], v[78:79]
	s_waitcnt lgkmcnt(4)
	v_pk_mul_f32 v[14:15], v[14:15], v[94:95]
	v_pk_mul_f32 v[12:13], v[12:13], v[92:93]
	s_waitcnt lgkmcnt(3)
	v_pk_mul_f32 v[2:3], v[2:3], v[98:99]
	v_pk_mul_f32 v[0:1], v[0:1], v[96:97]
	s_cmp_gt_u32 s3, 7
	ds_write_b16_d16_hi v73, v72 offset:272
	s_cbranch_scc1 .LBB0_1110
	v_lshl_or_b32 v72, s3, 4, v83
	v_mad_u64_u32 v[98:99], s[36:37], v72, s27, v[40:41]
	ds_read_b128 v[72:75], v98 offset:8192
	v_lshl_add_u32 v99, s3, 9, v71
	v_mul_f32_e32 v76, v60, v24
	v_mul_f32_e32 v77, v61, v25
	v_mul_f32_e32 v78, v62, v26
	v_mul_f32_e32 v79, v63, v27
	v_mul_f32_e32 v84, v64, v28
	v_mul_f32_e32 v85, v65, v29
	v_mul_f32_e32 v86, v66, v30
	v_mul_f32_e32 v87, v59, v31
	v_cvt_pk_bf16_f32 v76, v76, v77
	v_cvt_pk_bf16_f32 v77, v78, v79
	v_cvt_pk_bf16_f32 v78, v84, v85
	v_cvt_pk_bf16_f32 v79, v86, v87
	ds_read_b128 v[84:87], v99 offset:4096
	ds_read_b128 v[88:91], v99 offset:4112
	s_waitcnt lgkmcnt(2)
	v_mfma_f32_16x16x32_bf16 v[72:75], v[76:79], v[72:75], 0
	ds_read_b128 v[76:79], v98 offset:8256
	v_mul_f32_e32 v92, v52, v18
	s_waitcnt lgkmcnt(2)
	v_pk_mul_f32 v[26:27], v[26:27], v[86:87]
	v_pk_mul_f32 v[24:25], v[24:25], v[84:85]
	s_waitcnt lgkmcnt(1)
	v_pk_mul_f32 v[30:31], v[30:31], v[90:91]
	v_mul_f32_e32 v84, v57, v20
	v_mul_f32_e32 v85, v58, v21
	v_mul_f32_e32 v86, v54, v22
	v_mul_f32_e32 v87, v55, v23
	v_mul_f32_e32 v90, v56, v16
	v_mul_f32_e32 v91, v51, v17
	v_mul_f32_e32 v93, v53, v19
	v_cvt_pk_bf16_f32 v84, v84, v85
	v_cvt_pk_bf16_f32 v85, v86, v87
	v_cvt_pk_bf16_f32 v86, v90, v91
	v_cvt_pk_bf16_f32 v87, v92, v93
	ds_read_b128 v[90:93], v99 offset:4224
	s_waitcnt lgkmcnt(1)
	v_mfma_f32_16x16x32_bf16 v[72:75], v[84:87], v[76:79], v[72:75]
	ds_read_b128 v[76:79], v98 offset:8320
	v_pk_mul_f32 v[28:29], v[28:29], v[88:89]
	v_mul_f32_e32 v84, v49, v8
	s_waitcnt lgkmcnt(1)
	v_pk_mul_f32 v[20:21], v[20:21], v[90:91]
	v_mul_f32_e32 v85, v50, v9
	v_mul_f32_e32 v86, v46, v10
	v_mul_f32_e32 v87, v47, v11
	v_mul_f32_e32 v88, v48, v4
	v_mul_f32_e32 v89, v41, v5
	v_mul_f32_e32 v90, v42, v6
	v_mul_f32_e32 v91, v34, v7
	ds_read_b128 v[94:97], v99 offset:4240
	v_cvt_pk_bf16_f32 v84, v84, v85
	v_cvt_pk_bf16_f32 v85, v86, v87
	v_cvt_pk_bf16_f32 v86, v88, v89
	v_cvt_pk_bf16_f32 v87, v90, v91
	ds_read_b128 v[88:91], v99 offset:4352
	s_waitcnt lgkmcnt(2)
; __device__ __forceinline__ unsigned cvt_pk_c(float lo, float hi) { const f32x2_cv v = {lo, hi}; const bf16x2_cv b = __builtin_convertvector(v, bf16x2_cv); return __builtin_bit_cast(unsigned, b); }
; __device__ __forceinline__ bf16x8 pk8(const float* v) { u32x4 w; w.x = cvt_pk_bf16(v[0], v[1]); w.y = cvt_pk_bf16(v[2], v[3]); w.z = cvt_pk_bf16(v[4], v[5]); w.w = cvt_pk_bf16(v[6], v[7]); return __builtin_bit_cast(bf16x8, w); }
; template <int DIR> __device__ __forceinline__ void h3_dir(unsigned char* lds, const bf16_t* zrow, int h, const bf16_t* slot, f32x4 (&o)[8]) {
;     ...
;     for (int d = 1; d < 8; ++d) {
;         const int m = DIR ? wid + d : wid - d;
;         if (m < 0 || m > 7) break;
;         f32x4 sc = {0.f, 0.f, 0.f, 0.f};
; #pragma unroll
;         for (int ks = 0; ks < 4; ++ks) {
;             float tmp[8];
; #pragma unroll
;             for (int e = 0; e < 8; ++e) tmp[e] = qin[8 * ks + e] * run[8 * ks + e];
;             const bf16x8 bb = *(const bf16x8*)(KO + (16 * m + r) * HP + 32 * ks + 8 * kq);
;             sc = __builtin_amdgcn_mfma_f32_16x16x32_bf16(pk8(tmp), bb, sc, 0, 0, 0);
;             const f32x4 a = *(const f32x4*)(TOTE + m * 128 + 32 * ks + 8 * kq), b = *(const f32x4*)(TOTE + m * 128 + 32 * ks + 8 * kq + 4);
;             run[8 * ks] *= a[0]; run[8 * ks + 1] *= a[1]; run[8 * ks + 2] *= a[2]; run[8 * ks + 3] *= a[3]; run[8 * ks + 4] *= b[0]; run[8 * ks + 5] *= b[1]; run[8 * ks + 6] *= b[2]; run[8 * ks + 7] *= b[3];
;         }
; #pragma unroll
;         for (int i = 0; i < 4; i += 2) { const unsigned w = cvt_pk_c(sc[i], sc[i + 1]); Pw[(4 * kq + i) * HP + 16 * m + r] = (bf16_t)(w & 0xffffu); Pw[(4 * kq + i + 1) * HP + 16 * m + r] = (bf16_t)(w >> 16); }
;     }
	v_mfma_f32_16x16x32_bf16 v[72:75], v[84:87], v[76:79], v[72:75]
	ds_read_b128 v[76:79], v99 offset:4368
	ds_read_b128 v[84:87], v98 offset:8384
	v_pk_mul_f32 v[22:23], v[22:23], v[92:93]
	s_waitcnt lgkmcnt(3)
	v_pk_mul_f32 v[16:17], v[16:17], v[94:95]
	s_waitcnt lgkmcnt(2)
	v_pk_mul_f32 v[10:11], v[10:11], v[90:91]
	v_pk_mul_f32 v[8:9], v[8:9], v[88:89]
	v_mul_f32_e32 v88, v32, v12
	v_mul_f32_e32 v89, v33, v13
	v_mul_f32_e32 v90, v36, v14
	v_mul_f32_e32 v91, v37, v15
	v_mul_f32_e32 v92, v35, v0
	v_mul_f32_e32 v93, v43, v1
	v_mul_f32_e32 v94, v38, v2
	v_mul_f32_e32 v95, v39, v3
	v_cvt_pk_bf16_f32 v88, v88, v89
	v_cvt_pk_bf16_f32 v89, v90, v91
	v_cvt_pk_bf16_f32 v90, v92, v93
	v_cvt_pk_bf16_f32 v91, v94, v95
	s_lshl_b32 s3, s3, 5
	s_waitcnt lgkmcnt(0)
	v_mfma_f32_16x16x32_bf16 v[72:75], v[88:91], v[84:87], v[72:75]
	v_mul_f32_e64 v18, v18, v96
	v_mul_f32_e64 v19, v19, v97
	ds_read_b128 v[92:95], v99 offset:4480
	ds_read_b128 v[96:99], v99 offset:4496
	v_pk_mul_f32 v[4:5], v[4:5], v[76:77]
	v_add_u32_e32 v76, s3, v45
	s_nop 1
	v_cvt_pk_bf16_f32 v72, v72, v73
	v_lshl_add_u32 v73, v67, 1, v76
	ds_write_b16 v73, v72
	v_add3_u32 v73, v68, s3, v44
	ds_write_b16_d16_hi v73, v72 offset:272
	v_cvt_pk_bf16_f32 v72, v74, v75
	v_lshl_add_u32 v73, v69, 1, v76
	ds_write_b16 v73, v72
	v_add3_u32 v73, v70, s3, v44
	s_add_i32 s3, s35, -5
	v_pk_mul_f32 v[6:7], v[6:7], v[78:79]
	s_waitcnt lgkmcnt(4)
	v_pk_mul_f32 v[14:15], v[14:15], v[94:95]
	v_pk_mul_f32 v[12:13], v[12:13], v[92:93]
	s_waitcnt lgkmcnt(3)
	v_pk_mul_f32 v[2:3], v[2:3], v[98:99]
	v_pk_mul_f32 v[0:1], v[0:1], v[96:97]
	s_cmp_gt_u32 s3, 7
	ds_write_b16_d16_hi v73, v72 offset:272
	s_cbranch_scc1 .LBB0_1110
	v_lshl_or_b32 v72, s3, 4, v83
	v_mad_u64_u32 v[98:99], s[36:37], v72, s27, v[40:41]
	ds_read_b128 v[72:75], v98 offset:8192
	v_lshl_add_u32 v99, s3, 9, v71
	v_mul_f32_e32 v76, v60, v24
	v_mul_f32_e32 v77, v61, v25
	v_mul_f32_e32 v78, v62, v26
	v_mul_f32_e32 v79, v63, v27
	v_mul_f32_e32 v84, v64, v28
	v_mul_f32_e32 v85, v65, v29
	v_mul_f32_e32 v86, v66, v30
	v_mul_f32_e32 v87, v59, v31
	v_cvt_pk_bf16_f32 v76, v76, v77
	v_cvt_pk_bf16_f32 v77, v78, v79
	v_cvt_pk_bf16_f32 v78, v84, v85
	v_cvt_pk_bf16_f32 v79, v86, v87
	ds_read_b128 v[84:87], v99 offset:4096
	ds_read_b128 v[88:91], v99 offset:4112
	s_waitcnt lgkmcnt(2)
	v_mfma_f32_16x16x32_bf16 v[72:75], v[76:79], v[72:75], 0
	ds_read_b128 v[76:79], v98 offset:8256
	v_mul_f32_e32 v92, v52, v18
	s_waitcnt lgkmcnt(2)
	v_pk_mul_f32 v[26:27], v[26:27], v[86:87]
	v_pk_mul_f32 v[24:25], v[24:25], v[84:85]
	s_waitcnt lgkmcnt(1)
	v_pk_mul_f32 v[30:31], v[30:31], v[90:91]
	v_mul_f32_e32 v84, v57, v20
	v_mul_f32_e32 v85, v58, v21
	v_mul_f32_e32 v86, v54, v22
	v_mul_f32_e32 v87, v55, v23
	v_mul_f32_e32 v90, v56, v16
	v_mul_f32_e32 v91, v51, v17
	v_mul_f32_e32 v93, v53, v19
	v_cvt_pk_bf16_f32 v84, v84, v85
	v_cvt_pk_bf16_f32 v85, v86, v87
	v_cvt_pk_bf16_f32 v86, v90, v91
	v_cvt_pk_bf16_f32 v87, v92, v93
	ds_read_b128 v[90:93], v99 offset:4224
	s_waitcnt lgkmcnt(1)
	v_mfma_f32_16x16x32_bf16 v[72:75], v[84:87], v[76:79], v[72:75]
	ds_read_b128 v[76:79], v98 offset:8320
	v_pk_mul_f32 v[28:29], v[28:29], v[88:89]
	v_mul_f32_e32 v84, v49, v8
	s_waitcnt lgkmcnt(1)
	v_pk_mul_f32 v[20:21], v[20:21], v[90:91]
	v_mul_f32_e32 v85, v50, v9
	v_mul_f32_e32 v86, v46, v10
	v_mul_f32_e32 v87, v47, v11
	v_mul_f32_e32 v88, v48, v4
	v_mul_f32_e32 v89, v41, v5
	v_mul_f32_e32 v90, v42, v6
	v_mul_f32_e32 v91, v34, v7
	ds_read_b128 v[94:97], v99 offset:4240
	v_cvt_pk_bf16_f32 v84, v84, v85
	v_cvt_pk_bf16_f32 v85, v86, v87
	v_cvt_pk_bf16_f32 v86, v88, v89
	v_cvt_pk_bf16_f32 v87, v90, v91
	ds_read_b128 v[88:91], v99 offset:4352
	s_waitcnt lgkmcnt(2)
	v_mfma_f32_16x16x32_bf16 v[72:75], v[84:87], v[76:79], v[72:75]
	ds_read_b128 v[76:79], v99 offset:4368
	ds_read_b128 v[84:87], v98 offset:8384
	v_pk_mul_f32 v[22:23], v[22:23], v[92:93]
	s_waitcnt lgkmcnt(3)
	v_pk_mul_f32 v[16:17], v[16:17], v[94:95]
	s_waitcnt lgkmcnt(2)
	v_pk_mul_f32 v[10:11], v[10:11], v[90:91]
	v_pk_mul_f32 v[8:9], v[8:9], v[88:89]
	v_mul_f32_e32 v88, v32, v12
	v_mul_f32_e32 v89, v33, v13
	v_mul_f32_e32 v90, v36, v14
	v_mul_f32_e32 v91, v37, v15
	v_mul_f32_e32 v92, v35, v0
	v_mul_f32_e32 v93, v43, v1
	v_mul_f32_e32 v94, v38, v2
	v_mul_f32_e32 v95, v39, v3
	v_cvt_pk_bf16_f32 v88, v88, v89
	v_cvt_pk_bf16_f32 v89, v90, v91
	v_cvt_pk_bf16_f32 v90, v92, v93
	v_cvt_pk_bf16_f32 v91, v94, v95
	s_lshl_b32 s3, s3, 5
	s_waitcnt lgkmcnt(0)
	v_mfma_f32_16x16x32_bf16 v[72:75], v[88:91], v[84:87], v[72:75]
	v_mul_f32_e64 v18, v18, v96
	v_mul_f32_e64 v19, v19, v97
	ds_read_b128 v[92:95], v99 offset:4480
	ds_read_b128 v[96:99], v99 offset:4496
	v_pk_mul_f32 v[4:5], v[4:5], v[76:77]
	v_add_u32_e32 v76, s3, v45
	s_nop 1
	v_cvt_pk_bf16_f32 v72, v72, v73
	v_lshl_add_u32 v73, v67, 1, v76
	ds_write_b16 v73, v72
	v_add3_u32 v73, v68, s3, v44
	ds_write_b16_d16_hi v73, v72 offset:272
	v_cvt_pk_bf16_f32 v72, v74, v75
	v_lshl_add_u32 v73, v69, 1, v76
	ds_write_b16 v73, v72
	v_add3_u32 v73, v70, s3, v44
	s_add_i32 s3, s35, -6
	v_pk_mul_f32 v[6:7], v[6:7], v[78:79]
	s_waitcnt lgkmcnt(4)
	v_pk_mul_f32 v[14:15], v[14:15], v[94:95]
	v_pk_mul_f32 v[12:13], v[12:13], v[92:93]
	s_waitcnt lgkmcnt(3)
	v_pk_mul_f32 v[2:3], v[2:3], v[98:99]
	v_pk_mul_f32 v[0:1], v[0:1], v[96:97]
	s_cmp_gt_u32 s3, 7
	ds_write_b16_d16_hi v73, v72 offset:272
	s_cbranch_scc1 .LBB0_1110
; __device__ __forceinline__ unsigned cvt_pk_c(float lo, float hi) { const f32x2_cv v = {lo, hi}; const bf16x2_cv b = __builtin_convertvector(v, bf16x2_cv); return __builtin_bit_cast(unsigned, b); }
; __device__ __forceinline__ bf16x8 pk8(const float* v) { u32x4 w; w.x = cvt_pk_bf16(v[0], v[1]); w.y = cvt_pk_bf16(v[2], v[3]); w.z = cvt_pk_bf16(v[4], v[5]); w.w = cvt_pk_bf16(v[6], v[7]); return __builtin_bit_cast(bf16x8, w); }
; template <int DIR> __device__ __forceinline__ void h3_dir(unsigned char* lds, const bf16_t* zrow, int h, const bf16_t* slot, f32x4 (&o)[8]) {
;     ...
;     for (int d = 1; d < 8; ++d) {
;         const int m = DIR ? wid + d : wid - d;
;         if (m < 0 || m > 7) break;
;         f32x4 sc = {0.f, 0.f, 0.f, 0.f};
; #pragma unroll
;         for (int ks = 0; ks < 4; ++ks) {
;             float tmp[8];
; #pragma unroll
;             for (int e = 0; e < 8; ++e) tmp[e] = qin[8 * ks + e] * run[8 * ks + e];
;             const bf16x8 bb = *(const bf16x8*)(KO + (16 * m + r) * HP + 32 * ks + 8 * kq);
;             sc = __builtin_amdgcn_mfma_f32_16x16x32_bf16(pk8(tmp), bb, sc, 0, 0, 0);
;             const f32x4 a = *(const f32x4*)(TOTE + m * 128 + 32 * ks + 8 * kq), b = *(const f32x4*)(TOTE + m * 128 + 32 * ks + 8 * kq + 4);
;             run[8 * ks] *= a[0]; run[8 * ks + 1] *= a[1]; run[8 * ks + 2] *= a[2]; run[8 * ks + 3] *= a[3]; run[8 * ks + 4] *= b[0]; run[8 * ks + 5] *= b[1]; run[8 * ks + 6] *= b[2]; run[8 * ks + 7] *= b[3];
;         }
; #pragma unroll
;         for (int i = 0; i < 4; i += 2) { const unsigned w = cvt_pk_c(sc[i], sc[i + 1]); Pw[(4 * kq + i) * HP + 16 * m + r] = (bf16_t)(w & 0xffffu); Pw[(4 * kq + i + 1) * HP + 16 * m + r] = (bf16_t)(w >> 16); }
;     }
	v_lshl_or_b32 v72, s3, 4, v83
	v_mad_u64_u32 v[98:99], s[36:37], v72, s27, v[40:41]
	ds_read_b128 v[72:75], v98 offset:8192
	v_lshl_add_u32 v99, s3, 9, v71
	v_mul_f32_e32 v76, v60, v24
	v_mul_f32_e32 v77, v61, v25
	v_mul_f32_e32 v78, v62, v26
	v_mul_f32_e32 v79, v63, v27
	v_mul_f32_e32 v84, v64, v28
	v_mul_f32_e32 v85, v65, v29
	v_mul_f32_e32 v86, v66, v30
	v_mul_f32_e32 v87, v59, v31
	v_cvt_pk_bf16_f32 v76, v76, v77
	v_cvt_pk_bf16_f32 v77, v78, v79
	v_cvt_pk_bf16_f32 v78, v84, v85
	v_cvt_pk_bf16_f32 v79, v86, v87
	ds_read_b128 v[84:87], v99 offset:4096
	ds_read_b128 v[88:91], v99 offset:4112
	s_waitcnt lgkmcnt(2)
	v_mfma_f32_16x16x32_bf16 v[72:75], v[76:79], v[72:75], 0
	ds_read_b128 v[76:79], v98 offset:8256
	v_mul_f32_e32 v92, v52, v18
	s_waitcnt lgkmcnt(2)
	v_pk_mul_f32 v[26:27], v[26:27], v[86:87]
	v_pk_mul_f32 v[24:25], v[24:25], v[84:85]
	s_waitcnt lgkmcnt(1)
	v_pk_mul_f32 v[30:31], v[30:31], v[90:91]
	v_mul_f32_e32 v84, v57, v20
	v_mul_f32_e32 v85, v58, v21
	v_mul_f32_e32 v86, v54, v22
	v_mul_f32_e32 v87, v55, v23
	v_mul_f32_e32 v90, v56, v16
	v_mul_f32_e32 v91, v51, v17
	v_mul_f32_e32 v93, v53, v19
	v_cvt_pk_bf16_f32 v84, v84, v85
	v_cvt_pk_bf16_f32 v85, v86, v87
	v_cvt_pk_bf16_f32 v86, v90, v91
	v_cvt_pk_bf16_f32 v87, v92, v93
	ds_read_b128 v[90:93], v99 offset:4224
	s_waitcnt lgkmcnt(1)
	v_mfma_f32_16x16x32_bf16 v[72:75], v[84:87], v[76:79], v[72:75]
	ds_read_b128 v[76:79], v98 offset:8320
	v_pk_mul_f32 v[28:29], v[28:29], v[88:89]
	v_mul_f32_e32 v84, v49, v8
	s_waitcnt lgkmcnt(1)
	v_pk_mul_f32 v[20:21], v[20:21], v[90:91]
	v_mul_f32_e32 v85, v50, v9
	v_mul_f32_e32 v86, v46, v10
	v_mul_f32_e32 v87, v47, v11
	v_mul_f32_e32 v88, v48, v4
	v_mul_f32_e32 v89, v41, v5
	v_mul_f32_e32 v90, v42, v6
	v_mul_f32_e32 v91, v34, v7
	ds_read_b128 v[94:97], v99 offset:4240
	v_cvt_pk_bf16_f32 v84, v84, v85
	v_cvt_pk_bf16_f32 v85, v86, v87
	v_cvt_pk_bf16_f32 v86, v88, v89
	v_cvt_pk_bf16_f32 v87, v90, v91
	ds_read_b128 v[88:91], v99 offset:4352
	s_waitcnt lgkmcnt(2)
	v_mfma_f32_16x16x32_bf16 v[72:75], v[84:87], v[76:79], v[72:75]
	ds_read_b128 v[76:79], v99 offset:4368
	ds_read_b128 v[84:87], v98 offset:8384
	v_pk_mul_f32 v[22:23], v[22:23], v[92:93]
	s_waitcnt lgkmcnt(3)
	v_pk_mul_f32 v[16:17], v[16:17], v[94:95]
	s_waitcnt lgkmcnt(2)
	v_pk_mul_f32 v[10:11], v[10:11], v[90:91]
	v_pk_mul_f32 v[8:9], v[8:9], v[88:89]
	v_mul_f32_e32 v88, v32, v12
	v_mul_f32_e32 v89, v33, v13
	v_mul_f32_e32 v90, v36, v14
	v_mul_f32_e32 v91, v37, v15
	v_mul_f32_e32 v92, v35, v0
	v_mul_f32_e32 v93, v43, v1
	v_mul_f32_e32 v94, v38, v2
	v_mul_f32_e32 v95, v39, v3
	v_cvt_pk_bf16_f32 v88, v88, v89
	v_cvt_pk_bf16_f32 v89, v90, v91
	v_cvt_pk_bf16_f32 v90, v92, v93
	v_cvt_pk_bf16_f32 v91, v94, v95
	v_pk_mul_f32 v[18:19], v[18:19], v[96:97]
	s_waitcnt lgkmcnt(0)
	v_mfma_f32_16x16x32_bf16 v[72:75], v[88:91], v[84:87], v[72:75]
	ds_read_b128 v[92:95], v99 offset:4480
	ds_read_b128 v[96:99], v99 offset:4496
	s_lshl_b32 s3, s3, 5
	v_pk_mul_f32 v[4:5], v[4:5], v[76:77]
	v_add_u32_e32 v76, s3, v45
	s_nop 2
	v_cvt_pk_bf16_f32 v72, v72, v73
	v_lshl_add_u32 v73, v67, 1, v76
	ds_write_b16 v73, v72
	v_add3_u32 v73, v68, s3, v44
	ds_write_b16_d16_hi v73, v72 offset:272
	v_cvt_pk_bf16_f32 v72, v74, v75
	v_lshl_add_u32 v73, v69, 1, v76
	s_add_i32 s35, s35, -7
	v_pk_mul_f32 v[6:7], v[6:7], v[78:79]
	s_waitcnt lgkmcnt(3)
	v_pk_mul_f32 v[14:15], v[14:15], v[94:95]
	v_pk_mul_f32 v[12:13], v[12:13], v[92:93]
	s_waitcnt lgkmcnt(2)
	v_pk_mul_f32 v[2:3], v[2:3], v[98:99]
	v_pk_mul_f32 v[0:1], v[0:1], v[96:97]
	ds_write_b16 v73, v72
	v_add3_u32 v73, v70, s3, v44
	s_cmp_gt_u32 s35, 7
	ds_write_b16_d16_hi v73, v72 offset:272
	s_cbranch_scc1 .LBB0_1110
	v_lshl_or_b32 v72, s35, 4, v83
	v_mad_u64_u32 v[98:99], s[36:37], v72, s27, v[40:41]
	ds_read_b128 v[72:75], v98 offset:8192
	v_lshl_add_u32 v71, s35, 9, v71
	v_mul_f32_e32 v76, v60, v24
	v_mul_f32_e32 v77, v61, v25
	v_mul_f32_e32 v78, v62, v26
	v_mul_f32_e32 v79, v63, v27
	v_mul_f32_e32 v84, v64, v28
	v_mul_f32_e32 v85, v65, v29
	v_mul_f32_e32 v86, v66, v30
	v_mul_f32_e32 v87, v59, v31
	v_cvt_pk_bf16_f32 v76, v76, v77
	v_cvt_pk_bf16_f32 v77, v78, v79
	v_cvt_pk_bf16_f32 v78, v84, v85
	v_cvt_pk_bf16_f32 v79, v86, v87
	ds_read_b128 v[84:87], v71 offset:4096
	ds_read_b128 v[88:91], v71 offset:4112
	s_waitcnt lgkmcnt(2)
	v_mfma_f32_16x16x32_bf16 v[72:75], v[76:79], v[72:75], 0
	ds_read_b128 v[76:79], v98 offset:8256
	v_mul_f32_e32 v92, v52, v18
	s_waitcnt lgkmcnt(2)
	v_pk_mul_f32 v[26:27], v[26:27], v[86:87]
	v_pk_mul_f32 v[24:25], v[24:25], v[84:85]
	s_waitcnt lgkmcnt(1)
	v_pk_mul_f32 v[30:31], v[30:31], v[90:91]
	v_mul_f32_e32 v84, v57, v20
	v_mul_f32_e32 v85, v58, v21
	v_mul_f32_e32 v86, v54, v22
	v_mul_f32_e32 v87, v55, v23
	v_mul_f32_e32 v90, v56, v16
	v_mul_f32_e32 v91, v51, v17
	v_mul_f32_e32 v93, v53, v19
	v_cvt_pk_bf16_f32 v84, v84, v85
	v_cvt_pk_bf16_f32 v85, v86, v87
	v_cvt_pk_bf16_f32 v86, v90, v91
	v_cvt_pk_bf16_f32 v87, v92, v93
	ds_read_b128 v[90:93], v71 offset:4224
	ds_read_b128 v[94:97], v71 offset:4240
	s_waitcnt lgkmcnt(2)
	v_mfma_f32_16x16x32_bf16 v[72:75], v[84:87], v[76:79], v[72:75]
	ds_read_b128 v[76:79], v98 offset:8320
	v_pk_mul_f32 v[28:29], v[28:29], v[88:89]
	s_waitcnt lgkmcnt(2)
	v_pk_mul_f32 v[20:21], v[20:21], v[90:91]
	v_mul_f32_e32 v84, v49, v8
	v_mul_f32_e32 v85, v50, v9
	v_mul_f32_e32 v86, v46, v10
	v_mul_f32_e32 v87, v47, v11
	v_mul_f32_e32 v88, v48, v4
	v_mul_f32_e32 v89, v41, v5
	v_mul_f32_e32 v90, v42, v6
	v_mul_f32_e32 v91, v34, v7
	v_cvt_pk_bf16_f32 v84, v84, v85
	v_cvt_pk_bf16_f32 v85, v86, v87
	v_cvt_pk_bf16_f32 v86, v88, v89
	v_cvt_pk_bf16_f32 v87, v90, v91
	ds_read_b128 v[88:91], v71 offset:4352
	s_waitcnt lgkmcnt(1)
; __device__ __forceinline__ bf16x8 pk8(const float* v) { u32x4 w; w.x = cvt_pk_bf16(v[0], v[1]); w.y = cvt_pk_bf16(v[2], v[3]); w.z = cvt_pk_bf16(v[4], v[5]); w.w = cvt_pk_bf16(v[6], v[7]); return __builtin_bit_cast(bf16x8, w); }
; #define WAVE_LDS_FENCE() do { asm volatile("s_waitcnt lgkmcnt(0)" ::: "memory"); __builtin_amdgcn_wave_barrier(); } while (0)
; template <int DIR> __device__ __forceinline__ void h3_dir(unsigned char* lds, const bf16_t* zrow, int h, const bf16_t* slot, f32x4 (&o)[8]) {
;     ...
; #pragma unroll
;     for (int i = 0; i < 32; ++i) qin[i] *= run[i];
;     WAVE_LDS_FENCE();
; #pragma unroll
;     for (int ks = 0; ks < 4; ++ks) {
;         const bf16x8 aq = pk8(qin + 8 * ks), ap = *(const bf16x8*)(Pw + r * HP + 32 * ks + 8 * kq);
; #pragma unroll
;         for (int nt = 0; nt < 8; ++nt) {
;             o[nt] = __builtin_amdgcn_mfma_f32_16x16x32_bf16(aq, *(const bf16x8*)(ST + (16 * nt + r) * HP + 32 * ks + 8 * kq), o[nt], 0, 0, 0);
;             o[nt] = __builtin_amdgcn_mfma_f32_16x16x32_bf16(ap, *(const bf16x8*)(VT + (16 * nt + r) * HP + 32 * ks + 8 * kq), o[nt], 0, 0, 0);
;         }
;     }
	v_mfma_f32_16x16x32_bf16 v[72:75], v[84:87], v[76:79], v[72:75]
	ds_read_b128 v[76:79], v71 offset:4368
	ds_read_b128 v[84:87], v98 offset:8384
	v_pk_mul_f32 v[22:23], v[22:23], v[92:93]
	v_pk_mul_f32 v[16:17], v[16:17], v[94:95]
	s_waitcnt lgkmcnt(2)
	v_pk_mul_f32 v[10:11], v[10:11], v[90:91]
	v_pk_mul_f32 v[8:9], v[8:9], v[88:89]
	v_mul_f32_e32 v88, v32, v12
	v_mul_f32_e32 v89, v33, v13
	v_mul_f32_e32 v90, v36, v14
	v_mul_f32_e32 v91, v37, v15
	v_mul_f32_e32 v92, v35, v0
	v_mul_f32_e32 v93, v43, v1
	v_mul_f32_e32 v94, v38, v2
	v_mul_f32_e32 v95, v39, v3
	v_cvt_pk_bf16_f32 v88, v88, v89
	v_cvt_pk_bf16_f32 v89, v90, v91
	v_cvt_pk_bf16_f32 v90, v92, v93
	v_cvt_pk_bf16_f32 v91, v94, v95
	v_pk_mul_f32 v[18:19], v[18:19], v[96:97]
	s_waitcnt lgkmcnt(0)
	v_mfma_f32_16x16x32_bf16 v[72:75], v[88:91], v[84:87], v[72:75]
	ds_read_b128 v[92:95], v71 offset:4480
	ds_read_b128 v[96:99], v71 offset:4496
	s_lshl_b32 s3, s35, 5
	v_add_u32_e32 v45, s3, v45
	v_lshl_add_u32 v67, v67, 1, v45
	s_nop 2
	v_cvt_pk_bf16_f32 v71, v72, v73
	ds_write_b16 v67, v71
	v_add3_u32 v67, v68, s3, v44
	v_pk_mul_f32 v[6:7], v[6:7], v[78:79]
	v_pk_mul_f32 v[4:5], v[4:5], v[76:77]
	s_waitcnt lgkmcnt(2)
	v_pk_mul_f32 v[14:15], v[14:15], v[94:95]
	v_pk_mul_f32 v[12:13], v[12:13], v[92:93]
	s_waitcnt lgkmcnt(1)
	v_pk_mul_f32 v[2:3], v[2:3], v[98:99]
	v_pk_mul_f32 v[0:1], v[0:1], v[96:97]
	ds_write_b16_d16_hi v67, v71 offset:272
	v_cvt_pk_bf16_f32 v67, v74, v75
	v_lshl_add_u32 v45, v69, 1, v45
	v_add3_u32 v44, v70, s3, v44
	ds_write_b16 v45, v67
	ds_write_b16_d16_hi v44, v67 offset:272
.LBB0_1110:
	v_mul_u32_u24_e32 v45, 0x88, v83
	v_lshlrev_b32_e32 v45, 1, v45
	v_lshlrev_b32_e32 v44, 1, v82
	v_add_u32_e32 v110, v40, v45
	v_mul_u32_u24_e32 v40, 0x110, v83
	v_mul_f32_e32 v24, v60, v24
	v_mul_f32_e32 v25, v61, v25
	v_mul_f32_e32 v26, v62, v26
	v_mul_f32_e32 v27, v63, v27
	v_mul_f32_e32 v28, v64, v28
	v_mul_f32_e32 v29, v65, v29
	v_mul_f32_e32 v30, v66, v30
	v_mul_f32_e32 v31, v59, v31
	v_add3_u32 v102, s6, v40, v44
	s_waitcnt lgkmcnt(0)
	v_cvt_pk_bf16_f32 v24, v24, v25
	v_cvt_pk_bf16_f32 v25, v26, v27
	v_cvt_pk_bf16_f32 v26, v28, v29
	v_cvt_pk_bf16_f32 v27, v30, v31
	ds_read_b128 v[28:31], v110 offset:43008
	ds_read_b128 v[60:63], v102
	s_add_i32 s35, 0, 0x13000
	v_add3_u32 v111, s35, v44, v45
	ds_read_b128 v[64:67], v111
	s_waitcnt lgkmcnt(2)
	v_mfma_f32_16x16x32_bf16 v[28:31], v[24:27], v[28:31], 0
	v_add_u32_e32 v40, 0xa800, v110
	ds_read_b128 v[68:71], v40 offset:30464
	v_mul_f32_e32 v45, v54, v22
	s_waitcnt lgkmcnt(1)
	v_mfma_f32_16x16x32_bf16 v[28:31], v[60:63], v[64:67], v[28:31]
	ds_read_b128 v[64:67], v110 offset:47360
	ds_read_b128 v[72:75], v110 offset:51712
	ds_read_b128 v[76:79], v111 offset:4352
	ds_read_b128 v[82:85], v111 offset:8704
	v_mul_f32_e32 v54, v55, v23
	s_waitcnt lgkmcnt(3)
	v_mfma_f32_16x16x32_bf16 v[64:67], v[24:27], v[64:67], 0
	v_mul_f32_e32 v55, v56, v16
	v_mul_f32_e32 v51, v51, v17
	v_mul_f32_e32 v56, v52, v18
	s_waitcnt lgkmcnt(2)
	v_mfma_f32_16x16x32_bf16 v[72:75], v[24:27], v[72:75], 0
	v_mul_f32_e32 v44, v58, v21
	v_add_u32_e32 v116, 0xa8c0, v110
	v_mov_b32_e32 v151, v254
	s_waitcnt lgkmcnt(1)
	v_mfma_f32_16x16x32_bf16 v[64:67], v[60:63], v[76:79], v[64:67]
	s_waitcnt lgkmcnt(0)
	v_mfma_f32_16x16x32_bf16 v[72:75], v[60:63], v[82:85], v[72:75]
	ds_read_b128 v[76:79], v110 offset:56064
	ds_read_b128 v[82:85], v110 offset:60416
	ds_read_b128 v[86:89], v111 offset:13056
	ds_read_b128 v[90:93], v111 offset:17408
	s_waitcnt lgkmcnt(3)
	v_mfma_f32_16x16x32_bf16 v[76:79], v[24:27], v[76:79], 0
	s_waitcnt lgkmcnt(2)
	v_mfma_f32_16x16x32_bf16 v[82:85], v[24:27], v[82:85], 0
	s_waitcnt lgkmcnt(1)
	v_mfma_f32_16x16x32_bf16 v[76:79], v[60:63], v[86:89], v[76:79]
	s_waitcnt lgkmcnt(0)
	v_mfma_f32_16x16x32_bf16 v[82:85], v[60:63], v[90:93], v[82:85]
	ds_read_b128 v[86:89], v110 offset:64768
	ds_read_b128 v[90:93], v40 offset:26112
	ds_read_b128 v[94:97], v111 offset:21760
	ds_read_b128 v[98:101], v111 offset:26112
	v_mul_f32_e32 v40, v57, v20
	s_waitcnt lgkmcnt(3)
	v_mfma_f32_16x16x32_bf16 v[86:89], v[24:27], v[86:89], 0
	v_mul_f32_e32 v57, v53, v19
	s_waitcnt lgkmcnt(2)
	v_mfma_f32_16x16x32_bf16 v[90:93], v[24:27], v[90:93], 0
	v_mfma_f32_16x16x32_bf16 v[16:19], v[24:27], v[68:71], 0
	ds_read_b128 v[24:27], v111 offset:30464
	v_cvt_pk_bf16_f32 v52, v40, v44
	v_cvt_pk_bf16_f32 v53, v45, v54
	v_cvt_pk_bf16_f32 v54, v55, v51
	v_cvt_pk_bf16_f32 v55, v56, v57
	ds_read_b128 v[56:59], v110 offset:43072
	s_waitcnt lgkmcnt(1)
	v_mfma_f32_16x16x32_bf16 v[16:19], v[60:63], v[24:27], v[16:19]
	ds_read_b128 v[24:27], v102 offset:64
	v_mul_f32_e32 v40, v49, v8
	v_mfma_f32_16x16x32_bf16 v[86:89], v[60:63], v[94:97], v[86:89]
	v_mul_f32_e32 v94, v50, v9
	v_mfma_f32_16x16x32_bf16 v[20:23], v[60:63], v[98:101], v[90:93]
	s_waitcnt lgkmcnt(1)
	v_mfma_f32_16x16x32_bf16 v[28:31], v[52:55], v[56:59], v[28:31]
	ds_read_b128 v[56:59], v111 offset:64
	ds_read_b128 v[60:63], v110 offset:64832
	s_waitcnt lgkmcnt(1)
	v_mfma_f32_16x16x32_bf16 v[28:31], v[24:27], v[56:59], v[28:31]
	ds_read_b128 v[56:59], v110 offset:47424
	ds_read_b128 v[68:71], v110 offset:51776
	s_waitcnt lgkmcnt(1)
	v_mfma_f32_16x16x32_bf16 v[56:59], v[52:55], v[56:59], v[64:67]
	s_nop 2
	ds_read_b128 v[64:67], v111 offset:4416
	ds_read_b128 v[90:93], v111 offset:8768
	s_waitcnt lgkmcnt(1)
	v_mfma_f32_16x16x32_bf16 v[56:59], v[24:27], v[64:67], v[56:59]
	v_mfma_f32_16x16x32_bf16 v[64:67], v[52:55], v[68:71], v[72:75]
	s_waitcnt lgkmcnt(0)
	v_mfma_f32_16x16x32_bf16 v[64:67], v[24:27], v[90:93], v[64:67]
	ds_read_b128 v[68:71], v110 offset:56128
	ds_read_b128 v[72:75], v111 offset:13120
	ds_read_b128 v[90:93], v110 offset:60480
	s_waitcnt lgkmcnt(2)
; __device__ __forceinline__ bf16x8 pk8(const float* v) { u32x4 w; w.x = cvt_pk_bf16(v[0], v[1]); w.y = cvt_pk_bf16(v[2], v[3]); w.z = cvt_pk_bf16(v[4], v[5]); w.w = cvt_pk_bf16(v[6], v[7]); return __builtin_bit_cast(bf16x8, w); }
; template <int DIR> __device__ __forceinline__ void h3_dir(unsigned char* lds, const bf16_t* zrow, int h, const bf16_t* slot, f32x4 (&o)[8]) {
;     ...
; #pragma unroll
;     for (int ks = 0; ks < 4; ++ks) {
;         const bf16x8 aq = pk8(qin + 8 * ks), ap = *(const bf16x8*)(Pw + r * HP + 32 * ks + 8 * kq);
; #pragma unroll
;         for (int nt = 0; nt < 8; ++nt) {
;             o[nt] = __builtin_amdgcn_mfma_f32_16x16x32_bf16(aq, *(const bf16x8*)(ST + (16 * nt + r) * HP + 32 * ks + 8 * kq), o[nt], 0, 0, 0);
;             o[nt] = __builtin_amdgcn_mfma_f32_16x16x32_bf16(ap, *(const bf16x8*)(VT + (16 * nt + r) * HP + 32 * ks + 8 * kq), o[nt], 0, 0, 0);
;         }
;     }
;     __syncthreads();
	v_mfma_f32_16x16x32_bf16 v[68:71], v[52:55], v[68:71], v[76:79]
	s_nop 2
	ds_read_b128 v[76:79], v111 offset:17472
	s_waitcnt lgkmcnt(2)
	v_mfma_f32_16x16x32_bf16 v[68:71], v[24:27], v[72:75], v[68:71]
	v_mul_f32_e32 v72, v46, v10
	v_mul_f32_e32 v73, v47, v11
	v_mul_f32_e32 v74, v48, v4
	s_waitcnt lgkmcnt(1)
	v_mfma_f32_16x16x32_bf16 v[8:11], v[52:55], v[90:93], v[82:85]
	v_mul_f32_e32 v90, v32, v12
	v_add_u32_e32 v32, 0xa840, v110
	v_mul_f32_e32 v75, v41, v5
	v_mul_f32_e32 v82, v42, v6
	v_mul_f32_e32 v83, v34, v7
	s_waitcnt lgkmcnt(0)
	v_mfma_f32_16x16x32_bf16 v[4:7], v[24:27], v[76:79], v[8:11]
	v_mul_f32_e32 v91, v33, v13
	v_mul_f32_e32 v92, v43, v1
	v_mul_f32_e32 v93, v38, v2
	ds_read_b128 v[8:11], v111 offset:21824
	v_mfma_f32_16x16x32_bf16 v[44:47], v[52:55], v[60:63], v[86:89]
	ds_read_b128 v[48:51], v32 offset:26112
	ds_read_b128 v[60:63], v111 offset:26176
	s_nop 0
	v_mul_f32_e32 v87, v36, v14
	v_mul_f32_e32 v88, v37, v15
	ds_read_b128 v[12:15], v111 offset:30528
	v_mul_f32_e32 v89, v35, v0
	ds_read_b128 v[32:35], v32 offset:30464
	s_waitcnt lgkmcnt(4)
	v_mfma_f32_16x16x32_bf16 v[8:11], v[24:27], v[8:11], v[44:47]
	v_cvt_pk_bf16_f32 v40, v40, v94
	v_cvt_pk_bf16_f32 v41, v72, v73
	v_cvt_pk_bf16_f32 v42, v74, v75
	s_waitcnt lgkmcnt(0)
	v_mfma_f32_16x16x32_bf16 v[16:19], v[52:55], v[32:35], v[16:19]
	v_cvt_pk_bf16_f32 v43, v82, v83
	ds_read_b128 v[32:35], v102 offset:128
	ds_read_b128 v[44:47], v110 offset:43136
	v_mul_f32_e32 v94, v39, v3
	v_mfma_f32_16x16x32_bf16 v[20:23], v[52:55], v[48:51], v[20:23]
	ds_read_b128 v[0:3], v111 offset:128
	v_add_u32_e32 v82, 0xa880, v110
	v_mfma_f32_16x16x32_bf16 v[20:23], v[24:27], v[60:63], v[20:23]
	v_mfma_f32_16x16x32_bf16 v[12:15], v[24:27], v[12:15], v[16:19]
	s_waitcnt lgkmcnt(1)
	v_mfma_f32_16x16x32_bf16 v[16:19], v[40:43], v[44:47], v[28:31]
	ds_read_b128 v[24:27], v110 offset:47488
	s_nop 1
	ds_read_b128 v[28:31], v110 offset:64896
	s_waitcnt lgkmcnt(2)
	v_mfma_f32_16x16x32_bf16 v[0:3], v[32:35], v[0:3], v[16:19]
	s_nop 2
	ds_read_b128 v[16:19], v110 offset:51840
	ds_read_b128 v[36:39], v111 offset:4480
	ds_read_b128 v[44:47], v111 offset:8832
	s_waitcnt lgkmcnt(4)
	v_mfma_f32_16x16x32_bf16 v[24:27], v[40:43], v[24:27], v[56:59]
	ds_read_b128 v[48:51], v110 offset:56192
	ds_read_b128 v[52:55], v110 offset:60544
	s_nop 0
	ds_read_b128 v[56:59], v111 offset:13184
	ds_read_b128 v[60:63], v111 offset:17536
	s_waitcnt lgkmcnt(2)
	v_mfma_f32_16x16x32_bf16 v[4:7], v[40:43], v[52:55], v[4:7]
	v_mfma_f32_16x16x32_bf16 v[16:19], v[40:43], v[16:19], v[64:67]
	v_mfma_f32_16x16x32_bf16 v[36:39], v[32:35], v[36:39], v[24:27]
	s_nop 2
	ds_read_b128 v[24:27], v111 offset:21888
	ds_read_b128 v[72:75], v111 offset:26240
	ds_read_b128 v[76:79], v82 offset:30464
	ds_read_b128 v[64:67], v82 offset:26112
	ds_read_b128 v[82:85], v111 offset:30592
	v_cvt_pk_bf16_f32 v86, v90, v91
	s_waitcnt lgkmcnt(5)
	v_mfma_f32_16x16x32_bf16 v[60:63], v[32:35], v[60:63], v[4:7]
	v_cvt_pk_bf16_f32 v87, v87, v88
	v_cvt_pk_bf16_f32 v88, v89, v92
	v_cvt_pk_bf16_f32 v89, v93, v94
	v_mfma_f32_16x16x32_bf16 v[4:7], v[40:43], v[28:31], v[8:11]
	v_mfma_f32_16x16x32_bf16 v[16:19], v[32:35], v[44:47], v[16:19]
	v_mfma_f32_16x16x32_bf16 v[44:47], v[40:43], v[48:51], v[68:71]
	ds_read_b128 v[48:51], v102 offset:192
	s_nop 1
	ds_read_b128 v[68:71], v110 offset:43200
	ds_read_b128 v[90:93], v110 offset:47552
	ds_read_b128 v[94:97], v110 offset:51904
	s_waitcnt lgkmcnt(8)
	v_mfma_f32_16x16x32_bf16 v[208:211], v[32:35], v[24:27], v[4:7]
	s_waitcnt lgkmcnt(5)
	v_mfma_f32_16x16x32_bf16 v[4:7], v[40:43], v[64:67], v[20:23]
	v_mfma_f32_16x16x32_bf16 v[44:47], v[32:35], v[56:59], v[44:47]
	ds_read_b128 v[56:59], v111 offset:4544
	ds_read_b128 v[98:101], v111 offset:8896
	ds_read_b128 v[102:105], v110 offset:56256
	ds_read_b128 v[106:109], v110 offset:60608
	ds_read_b128 v[52:55], v111 offset:13248
	ds_read_b128 v[152:155], v111 offset:17600
	ds_read_b128 v[156:159], v111 offset:192
	ds_read_b128 v[188:191], v110 offset:64960
	ds_read_b128 v[192:195], v111 offset:21952
	ds_read_b128 v[196:199], v111 offset:26304
	ds_read_b128 v[200:203], v116 offset:30464
	ds_read_b128 v[28:31], v116 offset:26112
	ds_read_b128 v[204:207], v111 offset:30656
	s_waitcnt lgkmcnt(0)
	s_barrier
; template <int DIR> __device__ __forceinline__ void h3_dir(unsigned char* lds, const bf16_t* zrow, int h, const bf16_t* slot, f32x4 (&o)[8]) {
;     ...
;     float bl[32], qin[32]; bf16x8 kin[4];
;     load32(zrow + (size_t)(1 + DIR) * ZSEG + 8 * kq, bl);
;     load32(zrow + 8 * kq, qin);
;     {
;         float kk[32];
; #pragma unroll
;         for (int i = 0; i < 32; ++i) kk[i] = 1.0f - __builtin_amdgcn_exp2f(bl[i]);
;         scan16x8<DIR>(bl); scan16x8<DIR>(bl + 8); scan16x8<DIR>(bl + 16); scan16x8<DIR>(bl + 24);
;     ...
;             o[nt] = __builtin_amdgcn_mfma_f32_16x16x32_bf16(ap, *(const bf16x8*)(VT + (16 * nt + r) * HP + 32 * ks + 8 * kq), o[nt], 0, 0, 0);
	v_mfma_f32_16x16x32_bf16 v[20:23], v[32:35], v[72:75], v[4:7]
	v_bfe_u32 v150, v151, 4, 2
	v_lshlrev_b32_e32 v116, 4, v150
	v_lshl_add_u64 v[80:81], v[80:81], 0, v[116:117]
	v_add_co_u32_e32 v4, vcc, s28, v80
	v_lshl_add_u64 v[24:25], v[80:81], 0, s[14:15]
	s_nop 0
	v_addc_co_u32_e32 v5, vcc, 0, v81, vcc
	global_load_dwordx4 v[4:7], v[4:5], off
	v_mfma_f32_16x16x32_bf16 v[8:11], v[40:43], v[76:79], v[12:15]
	global_load_dwordx4 v[40:43], v[24:25], off offset:128
	global_load_dwordx4 v[64:67], v[24:25], off offset:192
	v_readfirstlane_b32 s3, v151
	global_load_dwordx4 v[12:15], v[24:25], off offset:64
	v_mfma_f32_16x16x32_bf16 v[32:35], v[32:35], v[82:85], v[8:11]
	s_ashr_i32 s36, s3, 6
	v_and_b32_e32 v149, 15, v151
	v_lshlrev_b32_e32 v148, 3, v150
	v_mfma_f32_16x16x32_bf16 v[8:11], v[86:89], v[102:105], v[44:47]
	v_cmp_eq_u32_e32 vcc, 0, v149
	s_lshl_b32 s3, s36, 9
	s_waitcnt vmcnt(3)
	v_lshlrev_b32_e32 v182, 16, v4
	v_and_b32_e32 v181, 0xffff0000, v4
	v_lshlrev_b32_e32 v180, 16, v5
	v_and_b32_e32 v179, 0xffff0000, v5
	v_lshlrev_b32_e32 v177, 16, v6
	v_and_b32_e32 v178, 0xffff0000, v6
	v_lshlrev_b32_e32 v176, 16, v7
	v_and_b32_e32 v174, 0xffff0000, v7
	v_mfma_f32_16x16x32_bf16 v[4:7], v[86:89], v[94:97], v[16:19]
	s_waitcnt vmcnt(0)
	v_lshlrev_b32_e32 v175, 16, v12
	v_and_b32_e32 v173, 0xffff0000, v12
	v_lshlrev_b32_e32 v116, 16, v13
	v_mfma_f32_16x16x32_bf16 v[4:7], v[48:51], v[98:101], v[4:7]
	v_and_b32_e32 v172, 0xffff0000, v13
	v_lshlrev_b32_e32 v168, 16, v14
	v_and_b32_e32 v169, 0xffff0000, v14
	v_lshlrev_b32_e32 v170, 16, v15
	v_and_b32_e32 v171, 0xffff0000, v15
	v_mfma_f32_16x16x32_bf16 v[12:15], v[86:89], v[106:109], v[60:63]
	global_load_dwordx4 v[108:111], v[80:81], off
	global_load_dwordx4 v[104:107], v[80:81], off offset:64
	global_load_dwordx4 v[100:103], v[80:81], off offset:128
	global_load_dwordx4 v[96:99], v[80:81], off offset:192
	v_mov_b32_e32 v60, v177
	v_mov_b32_e32 v62, v176
	v_mfma_f32_16x16x32_bf16 v[0:3], v[86:89], v[68:71], v[0:3]
	v_mov_b32_e32 v61, v178
	v_mov_b32_e32 v63, v174
	v_lshlrev_b32_e32 v164, 16, v40
	v_mfma_f32_16x16x32_bf16 v[24:27], v[48:51], v[156:159], v[0:3]
	v_lshlrev_b32_e32 v156, 16, v64
	v_and_b32_e32 v157, 0xffff0000, v64
	v_lshlrev_b32_e32 v158, 16, v65
	v_mfma_f32_16x16x32_bf16 v[0:3], v[86:89], v[90:93], v[36:39]
	v_and_b32_e32 v159, 0xffff0000, v65
	v_mov_b32_e32 v65, v181
	v_mov_b32_e32 v64, v182
	v_mfma_f32_16x16x32_bf16 v[16:19], v[86:89], v[188:191], v[208:211]
	v_and_b32_e32 v165, 0xffff0000, v40
	v_lshlrev_b32_e32 v166, 16, v41
	v_and_b32_e32 v167, 0xffff0000, v41
	v_mfma_f32_16x16x32_bf16 v[20:23], v[86:89], v[28:31], v[20:23]
	v_lshlrev_b32_e32 v160, 16, v42
	v_and_b32_e32 v161, 0xffff0000, v42
	v_lshlrev_b32_e32 v162, 16, v43
	v_mfma_f32_16x16x32_bf16 v[28:31], v[86:89], v[200:203], v[32:35]
	v_and_b32_e32 v163, 0xffff0000, v43
	v_mov_b32_e32 v40, v160
	v_mov_b32_e32 v42, v162
	v_mfma_f32_16x16x32_bf16 v[12:15], v[48:51], v[152:155], v[12:15]
	v_lshlrev_b32_e32 v152, 16, v66
	v_and_b32_e32 v153, 0xffff0000, v66
	v_lshlrev_b32_e32 v154, 16, v67
	v_and_b32_e32 v155, 0xffff0000, v67
	v_mov_b32_e32 v67, v179
	v_mov_b32_e32 v66, v180
	s_nop 1
	v_add_f32_dpp v64, v64, v64 row_shl:1 row_mask:0xf bank_mask:0xf bound_ctrl:1
	v_add_f32_dpp v65, v65, v65 row_shl:1 row_mask:0xf bank_mask:0xf bound_ctrl:1
	v_add_f32_dpp v66, v66, v66 row_shl:1 row_mask:0xf bank_mask:0xf bound_ctrl:1
	v_add_f32_dpp v67, v67, v67 row_shl:1 row_mask:0xf bank_mask:0xf bound_ctrl:1
	v_add_f32_dpp v60, v60, v60 row_shl:1 row_mask:0xf bank_mask:0xf bound_ctrl:1
	v_add_f32_dpp v61, v61, v61 row_shl:1 row_mask:0xf bank_mask:0xf bound_ctrl:1
	v_add_f32_dpp v62, v62, v62 row_shl:1 row_mask:0xf bank_mask:0xf bound_ctrl:1
	v_add_f32_dpp v63, v63, v63 row_shl:1 row_mask:0xf bank_mask:0xf bound_ctrl:1
	v_mfma_f32_16x16x32_bf16 v[0:3], v[48:51], v[56:59], v[0:3]
	s_nop 1
	v_add_f32_dpp v64, v64, v64 row_shl:2 row_mask:0xf bank_mask:0xf bound_ctrl:1
	v_add_f32_dpp v65, v65, v65 row_shl:2 row_mask:0xf bank_mask:0xf bound_ctrl:1
	v_add_f32_dpp v66, v66, v66 row_shl:2 row_mask:0xf bank_mask:0xf bound_ctrl:1
	v_add_f32_dpp v67, v67, v67 row_shl:2 row_mask:0xf bank_mask:0xf bound_ctrl:1
	v_add_f32_dpp v60, v60, v60 row_shl:2 row_mask:0xf bank_mask:0xf bound_ctrl:1
	v_add_f32_dpp v61, v61, v61 row_shl:2 row_mask:0xf bank_mask:0xf bound_ctrl:1
	v_add_f32_dpp v62, v62, v62 row_shl:2 row_mask:0xf bank_mask:0xf bound_ctrl:1
	v_add_f32_dpp v63, v63, v63 row_shl:2 row_mask:0xf bank_mask:0xf bound_ctrl:1
	v_mov_b32_e32 v45, v165
	s_nop 1
	v_add_f32_dpp v64, v64, v64 row_shl:4 row_mask:0xf bank_mask:0xf bound_ctrl:1
	v_add_f32_dpp v65, v65, v65 row_shl:4 row_mask:0xf bank_mask:0xf bound_ctrl:1
	v_add_f32_dpp v66, v66, v66 row_shl:4 row_mask:0xf bank_mask:0xf bound_ctrl:1
	v_add_f32_dpp v67, v67, v67 row_shl:4 row_mask:0xf bank_mask:0xf bound_ctrl:1
	v_add_f32_dpp v60, v60, v60 row_shl:4 row_mask:0xf bank_mask:0xf bound_ctrl:1
	v_add_f32_dpp v61, v61, v61 row_shl:4 row_mask:0xf bank_mask:0xf bound_ctrl:1
	v_add_f32_dpp v62, v62, v62 row_shl:4 row_mask:0xf bank_mask:0xf bound_ctrl:1
	v_add_f32_dpp v63, v63, v63 row_shl:4 row_mask:0xf bank_mask:0xf bound_ctrl:1
	v_mfma_f32_16x16x32_bf16 v[8:11], v[48:51], v[52:55], v[8:11]
	v_mov_b32_e32 v53, v173
	v_mov_b32_e32 v55, v172
	v_mov_b32_e32 v52, v175
	v_mfma_f32_16x16x32_bf16 v[16:19], v[48:51], v[192:195], v[16:19]
	v_mov_b32_e32 v54, v116
	s_nop 1
	v_add_f32_dpp v64, v64, v64 row_shl:8 row_mask:0xf bank_mask:0xf bound_ctrl:1
	v_add_f32_dpp v65, v65, v65 row_shl:8 row_mask:0xf bank_mask:0xf bound_ctrl:1
	v_add_f32_dpp v66, v66, v66 row_shl:8 row_mask:0xf bank_mask:0xf bound_ctrl:1
; __device__ __forceinline__ float bf_lo(unsigned w) { return __uint_as_float(w << 16); }
; __device__ __forceinline__ float bf_hi(unsigned w) { return __uint_as_float(w & 0xffff0000u); }
; template <int DIR> __device__ __forceinline__ void scan16x8(float* v) {
;     if (DIR == 0) { SCAN_STEP("row_shr:", 1); SCAN_STEP("row_shr:", 2); SCAN_STEP("row_shr:", 4); SCAN_STEP("row_shr:", 8); }
;     else          { SCAN_STEP("row_shl:", 1); SCAN_STEP("row_shl:", 2); SCAN_STEP("row_shl:", 4); SCAN_STEP("row_shl:", 8); }
; }
; __device__ __forceinline__ void load32(const bf16_t* p, float (&v)[32]) {
; #pragma unroll
;     for (int ks = 0; ks < 4; ++ks) { const u32x4 w = *(const u32x4*)(p + 32 * ks);
;         v[8 * ks + 0] = bf_lo(w.x); v[8 * ks + 1] = bf_hi(w.x); v[8 * ks + 2] = bf_lo(w.y); v[8 * ks + 3] = bf_hi(w.y); v[8 * ks + 4] = bf_lo(w.z); v[8 * ks + 5] = bf_hi(w.z); v[8 * ks + 6] = bf_lo(w.w); v[8 * ks + 7] = bf_hi(w.w); }
; template <int DIR> __device__ __forceinline__ void h3_dir(unsigned char* lds, const bf16_t* zrow, int h, const bf16_t* slot, f32x4 (&o)[8]) {
;     ...
;         scan16x8<DIR>(bl); scan16x8<DIR>(bl + 8); scan16x8<DIR>(bl + 16); scan16x8<DIR>(bl + 24);
	v_add_f32_dpp v67, v67, v67 row_shl:8 row_mask:0xf bank_mask:0xf bound_ctrl:1
	v_add_f32_dpp v60, v60, v60 row_shl:8 row_mask:0xf bank_mask:0xf bound_ctrl:1
	v_add_f32_dpp v61, v61, v61 row_shl:8 row_mask:0xf bank_mask:0xf bound_ctrl:1
	v_add_f32_dpp v62, v62, v62 row_shl:8 row_mask:0xf bank_mask:0xf bound_ctrl:1
	v_add_f32_dpp v63, v63, v63 row_shl:8 row_mask:0xf bank_mask:0xf bound_ctrl:1
	v_mov_b32_e32 v47, v167
	v_mfma_f32_16x16x32_bf16 v[20:23], v[48:51], v[196:199], v[20:23]
	v_mov_b32_e32 v41, v161
	v_mov_b32_e32 v44, v164
	v_mov_b32_e32 v43, v163
	v_mfma_f32_16x16x32_bf16 v[28:31], v[48:51], v[204:207], v[28:31]
	v_mov_b32_e32 v48, v168
	v_mov_b32_e32 v50, v170
	v_mov_b32_e32 v49, v169
	v_mov_b32_e32 v51, v171
	s_nop 1
	v_add_f32_dpp v52, v52, v52 row_shl:1 row_mask:0xf bank_mask:0xf bound_ctrl:1
	v_add_f32_dpp v53, v53, v53 row_shl:1 row_mask:0xf bank_mask:0xf bound_ctrl:1
	v_add_f32_dpp v54, v54, v54 row_shl:1 row_mask:0xf bank_mask:0xf bound_ctrl:1
	v_add_f32_dpp v55, v55, v55 row_shl:1 row_mask:0xf bank_mask:0xf bound_ctrl:1
	v_add_f32_dpp v48, v48, v48 row_shl:1 row_mask:0xf bank_mask:0xf bound_ctrl:1
	v_add_f32_dpp v49, v49, v49 row_shl:1 row_mask:0xf bank_mask:0xf bound_ctrl:1
	v_add_f32_dpp v50, v50, v50 row_shl:1 row_mask:0xf bank_mask:0xf bound_ctrl:1
	v_add_f32_dpp v51, v51, v51 row_shl:1 row_mask:0xf bank_mask:0xf bound_ctrl:1
	v_mov_b32_e32 v46, v166
	s_nop 1
	v_add_f32_dpp v52, v52, v52 row_shl:2 row_mask:0xf bank_mask:0xf bound_ctrl:1
	v_add_f32_dpp v53, v53, v53 row_shl:2 row_mask:0xf bank_mask:0xf bound_ctrl:1
	v_add_f32_dpp v54, v54, v54 row_shl:2 row_mask:0xf bank_mask:0xf bound_ctrl:1
	v_add_f32_dpp v55, v55, v55 row_shl:2 row_mask:0xf bank_mask:0xf bound_ctrl:1
	v_add_f32_dpp v48, v48, v48 row_shl:2 row_mask:0xf bank_mask:0xf bound_ctrl:1
	v_add_f32_dpp v49, v49, v49 row_shl:2 row_mask:0xf bank_mask:0xf bound_ctrl:1
	v_add_f32_dpp v50, v50, v50 row_shl:2 row_mask:0xf bank_mask:0xf bound_ctrl:1
	v_add_f32_dpp v51, v51, v51 row_shl:2 row_mask:0xf bank_mask:0xf bound_ctrl:1
	v_mov_b32_e32 v32, v152
	s_nop 1
	v_add_f32_dpp v52, v52, v52 row_shl:4 row_mask:0xf bank_mask:0xf bound_ctrl:1
	v_add_f32_dpp v53, v53, v53 row_shl:4 row_mask:0xf bank_mask:0xf bound_ctrl:1
	v_add_f32_dpp v54, v54, v54 row_shl:4 row_mask:0xf bank_mask:0xf bound_ctrl:1
	v_add_f32_dpp v55, v55, v55 row_shl:4 row_mask:0xf bank_mask:0xf bound_ctrl:1
	v_add_f32_dpp v48, v48, v48 row_shl:4 row_mask:0xf bank_mask:0xf bound_ctrl:1
	v_add_f32_dpp v49, v49, v49 row_shl:4 row_mask:0xf bank_mask:0xf bound_ctrl:1
	v_add_f32_dpp v50, v50, v50 row_shl:4 row_mask:0xf bank_mask:0xf bound_ctrl:1
	v_add_f32_dpp v51, v51, v51 row_shl:4 row_mask:0xf bank_mask:0xf bound_ctrl:1
	v_mov_b32_e32 v34, v154
	s_nop 1
	v_add_f32_dpp v52, v52, v52 row_shl:8 row_mask:0xf bank_mask:0xf bound_ctrl:1
	v_add_f32_dpp v53, v53, v53 row_shl:8 row_mask:0xf bank_mask:0xf bound_ctrl:1
	v_add_f32_dpp v54, v54, v54 row_shl:8 row_mask:0xf bank_mask:0xf bound_ctrl:1
	v_add_f32_dpp v55, v55, v55 row_shl:8 row_mask:0xf bank_mask:0xf bound_ctrl:1
	v_add_f32_dpp v48, v48, v48 row_shl:8 row_mask:0xf bank_mask:0xf bound_ctrl:1
	v_add_f32_dpp v49, v49, v49 row_shl:8 row_mask:0xf bank_mask:0xf bound_ctrl:1
	v_add_f32_dpp v50, v50, v50 row_shl:8 row_mask:0xf bank_mask:0xf bound_ctrl:1
	v_add_f32_dpp v51, v51, v51 row_shl:8 row_mask:0xf bank_mask:0xf bound_ctrl:1
	s_nop 1
	v_add_f32_dpp v44, v44, v44 row_shl:1 row_mask:0xf bank_mask:0xf bound_ctrl:1
	v_add_f32_dpp v45, v45, v45 row_shl:1 row_mask:0xf bank_mask:0xf bound_ctrl:1
	v_add_f32_dpp v46, v46, v46 row_shl:1 row_mask:0xf bank_mask:0xf bound_ctrl:1
	v_add_f32_dpp v47, v47, v47 row_shl:1 row_mask:0xf bank_mask:0xf bound_ctrl:1
	v_add_f32_dpp v40, v40, v40 row_shl:1 row_mask:0xf bank_mask:0xf bound_ctrl:1
	v_add_f32_dpp v41, v41, v41 row_shl:1 row_mask:0xf bank_mask:0xf bound_ctrl:1
	v_add_f32_dpp v42, v42, v42 row_shl:1 row_mask:0xf bank_mask:0xf bound_ctrl:1
	v_add_f32_dpp v43, v43, v43 row_shl:1 row_mask:0xf bank_mask:0xf bound_ctrl:1
	v_mov_b32_e32 v37, v157
	s_nop 1
	v_add_f32_dpp v44, v44, v44 row_shl:2 row_mask:0xf bank_mask:0xf bound_ctrl:1
	v_add_f32_dpp v45, v45, v45 row_shl:2 row_mask:0xf bank_mask:0xf bound_ctrl:1
	v_add_f32_dpp v46, v46, v46 row_shl:2 row_mask:0xf bank_mask:0xf bound_ctrl:1
	v_add_f32_dpp v47, v47, v47 row_shl:2 row_mask:0xf bank_mask:0xf bound_ctrl:1
	v_add_f32_dpp v40, v40, v40 row_shl:2 row_mask:0xf bank_mask:0xf bound_ctrl:1
	v_add_f32_dpp v41, v41, v41 row_shl:2 row_mask:0xf bank_mask:0xf bound_ctrl:1
	v_add_f32_dpp v42, v42, v42 row_shl:2 row_mask:0xf bank_mask:0xf bound_ctrl:1
	v_add_f32_dpp v43, v43, v43 row_shl:2 row_mask:0xf bank_mask:0xf bound_ctrl:1
	v_mov_b32_e32 v39, v159
	s_nop 1
	v_add_f32_dpp v44, v44, v44 row_shl:4 row_mask:0xf bank_mask:0xf bound_ctrl:1
	v_add_f32_dpp v45, v45, v45 row_shl:4 row_mask:0xf bank_mask:0xf bound_ctrl:1
	v_add_f32_dpp v46, v46, v46 row_shl:4 row_mask:0xf bank_mask:0xf bound_ctrl:1
	v_add_f32_dpp v47, v47, v47 row_shl:4 row_mask:0xf bank_mask:0xf bound_ctrl:1
	v_add_f32_dpp v40, v40, v40 row_shl:4 row_mask:0xf bank_mask:0xf bound_ctrl:1
	v_add_f32_dpp v41, v41, v41 row_shl:4 row_mask:0xf bank_mask:0xf bound_ctrl:1
	v_add_f32_dpp v42, v42, v42 row_shl:4 row_mask:0xf bank_mask:0xf bound_ctrl:1
	v_add_f32_dpp v43, v43, v43 row_shl:4 row_mask:0xf bank_mask:0xf bound_ctrl:1
	v_mov_b32_e32 v33, v153
	v_mov_b32_e32 v36, v156
	v_mov_b32_e32 v35, v155
	v_mov_b32_e32 v38, v158
	s_nop 1
	v_add_f32_dpp v44, v44, v44 row_shl:8 row_mask:0xf bank_mask:0xf bound_ctrl:1
	v_add_f32_dpp v45, v45, v45 row_shl:8 row_mask:0xf bank_mask:0xf bound_ctrl:1
; template <int DIR> __device__ __forceinline__ void h3_dir(unsigned char* lds, const bf16_t* zrow, int h, const bf16_t* slot, f32x4 (&o)[8]) {
;     ...
;         scan16x8<DIR>(bl); scan16x8<DIR>(bl + 8); scan16x8<DIR>(bl + 16); scan16x8<DIR>(bl + 24);
;         float eb[32];
; #pragma unroll
;         for (int i = 0; i < 32; ++i) { eb[i] = __builtin_amdgcn_exp2f(bl[i]); qin[i] *= eb[i]; }
;         if (r == (DIR ? 0 : 15)) {
; #pragma unroll
;             for (int ks = 0; ks < 4; ++ks) { *(f32x4*)(TOT + wid * 128 + 32 * ks + 8 * kq) = (f32x4){bl[8 * ks], bl[8 * ks + 1], bl[8 * ks + 2], bl[8 * ks + 3]}; *(f32x4*)(TOT + wid * 128 + 32 * ks + 8 * kq + 4) = (f32x4){bl[8 * ks + 4], bl[8 * ks + 5], bl[8 * ks + 6], bl[8 * ks + 7]}; }
; #pragma unroll
;             for (int ks = 0; ks < 4; ++ks) { *(f32x4*)(TOTE + wid * 128 + 32 * ks + 8 * kq) = (f32x4){eb[8 * ks], eb[8 * ks + 1], eb[8 * ks + 2], eb[8 * ks + 3]}; *(f32x4*)(TOTE + wid * 128 + 32 * ks + 8 * kq + 4) = (f32x4){eb[8 * ks + 4], eb[8 * ks + 5], eb[8 * ks + 6], eb[8 * ks + 7]}; }
;         }
	v_add_f32_dpp v46, v46, v46 row_shl:8 row_mask:0xf bank_mask:0xf bound_ctrl:1
	v_add_f32_dpp v47, v47, v47 row_shl:8 row_mask:0xf bank_mask:0xf bound_ctrl:1
	v_add_f32_dpp v40, v40, v40 row_shl:8 row_mask:0xf bank_mask:0xf bound_ctrl:1
	v_add_f32_dpp v41, v41, v41 row_shl:8 row_mask:0xf bank_mask:0xf bound_ctrl:1
	v_add_f32_dpp v42, v42, v42 row_shl:8 row_mask:0xf bank_mask:0xf bound_ctrl:1
	v_add_f32_dpp v43, v43, v43 row_shl:8 row_mask:0xf bank_mask:0xf bound_ctrl:1
	s_nop 1
	v_add_f32_dpp v36, v36, v36 row_shl:1 row_mask:0xf bank_mask:0xf bound_ctrl:1
	v_add_f32_dpp v37, v37, v37 row_shl:1 row_mask:0xf bank_mask:0xf bound_ctrl:1
	v_add_f32_dpp v38, v38, v38 row_shl:1 row_mask:0xf bank_mask:0xf bound_ctrl:1
	v_add_f32_dpp v39, v39, v39 row_shl:1 row_mask:0xf bank_mask:0xf bound_ctrl:1
	v_add_f32_dpp v32, v32, v32 row_shl:1 row_mask:0xf bank_mask:0xf bound_ctrl:1
	v_add_f32_dpp v33, v33, v33 row_shl:1 row_mask:0xf bank_mask:0xf bound_ctrl:1
	v_add_f32_dpp v34, v34, v34 row_shl:1 row_mask:0xf bank_mask:0xf bound_ctrl:1
	v_add_f32_dpp v35, v35, v35 row_shl:1 row_mask:0xf bank_mask:0xf bound_ctrl:1
	v_exp_f32_e32 v92, v64
	s_nop 1
	v_add_f32_dpp v36, v36, v36 row_shl:2 row_mask:0xf bank_mask:0xf bound_ctrl:1
	v_add_f32_dpp v37, v37, v37 row_shl:2 row_mask:0xf bank_mask:0xf bound_ctrl:1
	v_add_f32_dpp v38, v38, v38 row_shl:2 row_mask:0xf bank_mask:0xf bound_ctrl:1
	v_add_f32_dpp v39, v39, v39 row_shl:2 row_mask:0xf bank_mask:0xf bound_ctrl:1
	v_add_f32_dpp v32, v32, v32 row_shl:2 row_mask:0xf bank_mask:0xf bound_ctrl:1
	v_add_f32_dpp v33, v33, v33 row_shl:2 row_mask:0xf bank_mask:0xf bound_ctrl:1
	v_add_f32_dpp v34, v34, v34 row_shl:2 row_mask:0xf bank_mask:0xf bound_ctrl:1
	v_add_f32_dpp v35, v35, v35 row_shl:2 row_mask:0xf bank_mask:0xf bound_ctrl:1
	v_exp_f32_e32 v93, v65
	s_nop 1
	v_add_f32_dpp v36, v36, v36 row_shl:4 row_mask:0xf bank_mask:0xf bound_ctrl:1
	v_add_f32_dpp v37, v37, v37 row_shl:4 row_mask:0xf bank_mask:0xf bound_ctrl:1
	v_add_f32_dpp v38, v38, v38 row_shl:4 row_mask:0xf bank_mask:0xf bound_ctrl:1
	v_add_f32_dpp v39, v39, v39 row_shl:4 row_mask:0xf bank_mask:0xf bound_ctrl:1
	v_add_f32_dpp v32, v32, v32 row_shl:4 row_mask:0xf bank_mask:0xf bound_ctrl:1
	v_add_f32_dpp v33, v33, v33 row_shl:4 row_mask:0xf bank_mask:0xf bound_ctrl:1
	v_add_f32_dpp v34, v34, v34 row_shl:4 row_mask:0xf bank_mask:0xf bound_ctrl:1
	v_add_f32_dpp v35, v35, v35 row_shl:4 row_mask:0xf bank_mask:0xf bound_ctrl:1
	v_exp_f32_e32 v94, v66
	s_nop 1
	v_add_f32_dpp v36, v36, v36 row_shl:8 row_mask:0xf bank_mask:0xf bound_ctrl:1
	v_add_f32_dpp v37, v37, v37 row_shl:8 row_mask:0xf bank_mask:0xf bound_ctrl:1
	v_add_f32_dpp v38, v38, v38 row_shl:8 row_mask:0xf bank_mask:0xf bound_ctrl:1
	v_add_f32_dpp v39, v39, v39 row_shl:8 row_mask:0xf bank_mask:0xf bound_ctrl:1
	v_add_f32_dpp v32, v32, v32 row_shl:8 row_mask:0xf bank_mask:0xf bound_ctrl:1
	v_add_f32_dpp v33, v33, v33 row_shl:8 row_mask:0xf bank_mask:0xf bound_ctrl:1
	v_add_f32_dpp v34, v34, v34 row_shl:8 row_mask:0xf bank_mask:0xf bound_ctrl:1
	v_add_f32_dpp v35, v35, v35 row_shl:8 row_mask:0xf bank_mask:0xf bound_ctrl:1
	v_exp_f32_e32 v95, v67
	v_exp_f32_e32 v88, v60
	v_exp_f32_e32 v89, v61
	v_exp_f32_e32 v90, v62
	v_exp_f32_e32 v91, v63
	v_exp_f32_e32 v84, v52
	v_exp_f32_e32 v85, v53
	v_exp_f32_e32 v86, v54
	v_exp_f32_e32 v87, v55
	v_exp_f32_e32 v80, v48
	v_exp_f32_e32 v81, v49
	v_exp_f32_e32 v82, v50
	v_exp_f32_e32 v83, v51
	v_exp_f32_e32 v76, v44
	v_exp_f32_e32 v77, v45
	v_exp_f32_e32 v78, v46
	v_exp_f32_e32 v79, v47
	v_exp_f32_e32 v72, v40
	v_exp_f32_e32 v73, v41
	v_exp_f32_e32 v74, v42
	v_exp_f32_e32 v75, v43
	v_exp_f32_e32 v68, v36
	v_exp_f32_e32 v69, v37
	v_exp_f32_e32 v70, v38
	v_exp_f32_e32 v71, v39
	v_exp_f32_e32 v56, v32
	v_exp_f32_e32 v57, v33
	v_exp_f32_e32 v58, v34
	v_exp_f32_e32 v59, v35
	s_and_saveexec_b64 s[6:7], vcc
	s_cbranch_execz .LBB0_1112
	s_add_i32 s37, s3, 0
	v_lshl_add_u32 v183, v148, 2, s37
	ds_write_b128 v183, v[64:67]
	ds_write_b128 v183, v[60:63] offset:16
	ds_write_b128 v183, v[52:55] offset:128
	ds_write_b128 v183, v[48:51] offset:144
	ds_write_b128 v183, v[44:47] offset:256
	ds_write_b128 v183, v[40:43] offset:272
	ds_write_b128 v183, v[36:39] offset:384
	ds_write_b128 v183, v[32:35] offset:400
	ds_write_b128 v183, v[92:95] offset:4096
	ds_write_b128 v183, v[88:91] offset:4112
	ds_write_b128 v183, v[84:87] offset:4224
	ds_write_b128 v183, v[80:83] offset:4240
	ds_write_b128 v183, v[76:79] offset:4352
	ds_write_b128 v183, v[72:75] offset:4368
	ds_write_b128 v183, v[68:71] offset:4480
	ds_write_b128 v183, v[56:59] offset:4496
; template <int DIR> __device__ __forceinline__ void h3_dir(unsigned char* lds, const bf16_t* zrow, int h, const bf16_t* slot, f32x4 (&o)[8]) {
;     ...
;         float kk[32];
; #pragma unroll
;         for (int i = 0; i < 32; ++i) kk[i] = 1.0f - __builtin_amdgcn_exp2f(bl[i]);
;         scan16x8<DIR>(bl); scan16x8<DIR>(bl + 8); scan16x8<DIR>(bl + 16); scan16x8<DIR>(bl + 24);
;         float eb[32];
; #pragma unroll
;         for (int i = 0; i < 32; ++i) { eb[i] = __builtin_amdgcn_exp2f(bl[i]); qin[i] *= eb[i]; }
;         if (r == (DIR ? 0 : 15)) {
; #pragma unroll
;             for (int ks = 0; ks < 4; ++ks) { *(f32x4*)(TOT + wid * 128 + 32 * ks + 8 * kq) = (f32x4){bl[8 * ks], bl[8 * ks + 1], bl[8 * ks + 2], bl[8 * ks + 3]}; *(f32x4*)(TOT + wid * 128 + 32 * ks + 8 * kq + 4) = (f32x4){bl[8 * ks + 4], bl[8 * ks + 5], bl[8 * ks + 6], bl[8 * ks + 7]}; }
; #pragma unroll
;             for (int ks = 0; ks < 4; ++ks) { *(f32x4*)(TOTE + wid * 128 + 32 * ks + 8 * kq) = (f32x4){eb[8 * ks], eb[8 * ks + 1], eb[8 * ks + 2], eb[8 * ks + 3]}; *(f32x4*)(TOTE + wid * 128 + 32 * ks + 8 * kq + 4) = (f32x4){eb[8 * ks + 4], eb[8 * ks + 5], eb[8 * ks + 6], eb[8 * ks + 7]}; }
;         }
; #pragma unroll
;         for (int it = 0; it < 4; ++it) { const int p = tid + 512 * it, v = p >> 4, c16 = p & 15; *(u32x4*)(ST + v * HP + c16 * 8) = *(const u32x4*)(slot + (size_t)v * 128 + c16 * 8); }
; #pragma unroll
;         for (int it = 0; it < 4; ++it) { const int p = lane + 64 * it; *(u32x4*)(Pw + (p >> 4) * HP + (p & 15) * 8) = (u32x4){0u, 0u, 0u, 0u}; }
;         __syncthreads();
.LBB0_1112:
	s_or_b64 exec, exec, s[6:7]
	s_waitcnt vmcnt(0)
	v_lshlrev_b32_e32 v214, 16, v96
	v_and_b32_e32 v215, 0xffff0000, v96
	v_exp_f32_e32 v96, v182
	v_lshlrev_b32_e32 v216, 16, v97
	v_and_b32_e32 v217, 0xffff0000, v97
	v_exp_f32_e32 v97, v181
	v_lshlrev_b32_e32 v210, 16, v102
	v_and_b32_e32 v211, 0xffff0000, v102
	v_sub_f32_e32 v219, 1.0, v96
	v_exp_f32_e32 v96, v180
	v_exp_f32_e32 v102, v178
	v_lshlrev_b32_e32 v206, 16, v100
	v_and_b32_e32 v207, 0xffff0000, v100
	v_lshlrev_b32_e32 v218, 16, v98
	v_and_b32_e32 v100, 0xffff0000, v98
	v_exp_f32_e32 v98, v177
	v_sub_f32_e32 v220, 1.0, v97
	v_exp_f32_e32 v97, v179
	v_sub_f32_e32 v221, 1.0, v96
	v_sub_f32_e32 v224, 1.0, v102
	v_exp_f32_e32 v96, v176
	v_exp_f32_e32 v102, v173
	v_sub_f32_e32 v223, 1.0, v98
	v_exp_f32_e32 v98, v175
	v_lshlrev_b32_e32 v194, 16, v110
	v_and_b32_e32 v195, 0xffff0000, v110
	v_sub_f32_e32 v222, 1.0, v97
	v_exp_f32_e32 v97, v174
	v_ashrrev_i32_e32 v110, 4, v151
	v_lshlrev_b32_e32 v196, 16, v111
	v_and_b32_e32 v197, 0xffff0000, v111
	v_lshlrev_b32_e32 v198, 16, v104
	v_and_b32_e32 v199, 0xffff0000, v104
	v_ashrrev_i32_e32 v111, 31, v110
	v_add_u32_e32 v104, 0x200, v151
	s_add_u32 s4, s22, s4
	v_lshlrev_b32_e32 v212, 16, v103
	v_and_b32_e32 v213, 0xffff0000, v103
	v_sub_f32_e32 v225, 1.0, v96
	v_sub_f32_e32 v228, 1.0, v102
	v_lshlrev_b32_e32 v96, 4, v151
	v_lshlrev_b64 v[102:103], 8, v[110:111]
	v_ashrrev_i32_e32 v180, 4, v104
	v_add_u32_e32 v111, 0x400, v151
	s_addc_u32 s5, s23, s5
	v_sub_f32_e32 v227, 1.0, v98
	v_exp_f32_e32 v98, v116
	v_and_b32_e32 v116, 0xf0, v96
	v_ashrrev_i32_e32 v181, 31, v180
	v_ashrrev_i32_e32 v182, 4, v111
	v_lshlrev_b32_e32 v200, 16, v105
	v_and_b32_e32 v201, 0xffff0000, v105
	v_sub_f32_e32 v226, 1.0, v97
	v_lshl_add_u64 v[96:97], s[4:5], 0, v[116:117]
	v_lshlrev_b64 v[104:105], 8, v[180:181]
	v_ashrrev_i32_e32 v183, 31, v182
	v_add_u32_e32 v111, 0x600, v151
	v_lshlrev_b32_e32 v202, 16, v106
	v_and_b32_e32 v203, 0xffff0000, v106
	v_lshlrev_b32_e32 v204, 16, v107
	v_and_b32_e32 v205, 0xffff0000, v107
	v_exp_f32_e32 v229, v172
	v_lshl_add_u64 v[102:103], v[96:97], 0, v[102:103]
	v_lshl_add_u64 v[106:107], v[96:97], 0, v[104:105]
	v_lshlrev_b64 v[172:173], 8, v[182:183]
	v_ashrrev_i32_e32 v188, 4, v111
	v_lshlrev_b32_e32 v190, 16, v108
	v_and_b32_e32 v191, 0xffff0000, v108
	v_lshlrev_b32_e32 v192, 16, v109
	v_and_b32_e32 v193, 0xffff0000, v109
	global_load_dwordx4 v[102:105], v[102:103], off
	s_nop 0
	global_load_dwordx4 v[106:109], v[106:107], off
	v_lshl_add_u64 v[172:173], v[96:97], 0, v[172:173]
	v_ashrrev_i32_e32 v189, 31, v188
	global_load_dwordx4 v[172:175], v[172:173], off
	v_lshlrev_b64 v[176:177], 8, v[188:189]
	v_lshl_add_u64 v[96:97], v[96:97], 0, v[176:177]
	global_load_dwordx4 v[176:179], v[96:97], off
	v_exp_f32_e32 v97, v169
	v_sub_f32_e32 v111, 1.0, v98
	v_exp_f32_e32 v96, v168
	v_exp_f32_e32 v98, v170
	v_sub_f32_e32 v170, 1.0, v97
	v_exp_f32_e32 v97, v165
	v_exp_f32_e32 v168, v171
	v_sub_f32_e32 v169, 1.0, v96
	v_sub_f32_e32 v171, 1.0, v98
	v_exp_f32_e32 v96, v164
	v_exp_f32_e32 v98, v166
	v_sub_f32_e32 v166, 1.0, v97
	v_exp_f32_e32 v97, v161
	v_exp_f32_e32 v164, v167
	v_sub_f32_e32 v165, 1.0, v96
	v_sub_f32_e32 v167, 1.0, v98
	v_exp_f32_e32 v96, v160
	v_exp_f32_e32 v98, v162
	v_sub_f32_e32 v162, 1.0, v97
	v_exp_f32_e32 v97, v157
	v_exp_f32_e32 v160, v163
	v_sub_f32_e32 v161, 1.0, v96
	v_sub_f32_e32 v163, 1.0, v98
	v_exp_f32_e32 v96, v156
	v_exp_f32_e32 v98, v158
	v_sub_f32_e32 v158, 1.0, v97
	v_exp_f32_e32 v97, v153
	v_exp_f32_e32 v156, v159
	v_sub_f32_e32 v157, 1.0, v96
	v_sub_f32_e32 v159, 1.0, v98
	v_exp_f32_e32 v96, v152
	v_exp_f32_e32 v98, v154
	v_lshlrev_b32_e32 v208, 16, v101
	v_and_b32_e32 v209, 0xffff0000, v101
	s_mul_i32 s6, s36, 0x1100
	v_sub_f32_e32 v154, 1.0, v97
	v_mul_f32_e32 v97, v89, v195
	v_mul_f32_e32 v89, v84, v198
	v_mul_f32_e32 v84, v81, v203
	v_mul_f32_e32 v81, v78, v208
	v_mul_f32_e32 v78, v79, v209
	v_mul_f32_e32 v79, v72, v210
	v_mul_f32_e32 v73, v73, v211
	v_add_u32_e32 v72, 0, v116
	v_exp_f32_e32 v152, v155
	v_sub_f32_e32 v153, 1.0, v96
	v_sub_f32_e32 v155, 1.0, v98
	v_mul_f32_e32 v96, v88, v194
	v_mul_f32_e32 v98, v90, v196
	v_mul_f32_e32 v90, v85, v199
	v_mul_f32_e32 v88, v80, v202
	v_mul_f32_e32 v85, v82, v204
	v_mul_f32_e32 v82, v76, v206
	v_mul_f32_e32 v80, v77, v207
	s_add_i32 s4, s6, 0
	v_mad_u64_u32 v[76:77], s[6:7], v110, s27, v[72:73]
	s_add_i32 s4, s4, 0x1b800
	s_add_i32 s3, s3, 0
	v_lshl_add_u32 v110, v148, 2, s3
	v_sub_f32_e32 v151, 1.0, v229
	v_sub_f32_e32 v168, 1.0, v168
	v_sub_f32_e32 v164, 1.0, v164
	v_sub_f32_e32 v160, 1.0, v160
	v_sub_f32_e32 v156, 1.0, v156
	v_sub_f32_e32 v152, 1.0, v152
	v_mul_f32_e32 v92, v92, v190
	v_mul_f32_e32 v93, v93, v191
	v_mul_f32_e32 v94, v94, v192
	v_mul_f32_e32 v95, v95, v193
	v_mul_f32_e32 v91, v91, v197
	v_mul_f32_e32 v86, v86, v200
	s_waitcnt vmcnt(3)
	ds_write_b128 v76, v[102:105] offset:43008
	v_mad_u64_u32 v[76:77], s[6:7], v180, s27, v[72:73]
	s_waitcnt vmcnt(2)
	ds_write_b128 v76, v[106:109] offset:43008
	v_mad_u64_u32 v[76:77], s[6:7], v182, s27, v[72:73]
	s_waitcnt vmcnt(1)
	ds_write_b128 v76, v[172:175] offset:43008
	v_mad_u64_u32 v[76:77], s[6:7], v188, s27, v[72:73]
	v_mul_u32_u24_e32 v72, 0x110, v150
	v_add3_u32 v72, s4, v116, v72
	s_waitcnt vmcnt(0)
	ds_write_b128 v76, v[176:179] offset:43008
	ds_write_b128 v72, v[184:187]
	ds_write_b128 v72, v[184:187] offset:1088
	ds_write_b128 v72, v[184:187] offset:2176
	ds_write_b128 v72, v[184:187] offset:3264
	s_waitcnt lgkmcnt(0)
	s_barrier
; __device__ __forceinline__ bf16x8 pk8(const float* v) { u32x4 w; w.x = cvt_pk_bf16(v[0], v[1]); w.y = cvt_pk_bf16(v[2], v[3]); w.z = cvt_pk_bf16(v[4], v[5]); w.w = cvt_pk_bf16(v[6], v[7]); return __builtin_bit_cast(bf16x8, w); }
; template <int DIR> __device__ __forceinline__ void h3_dir(unsigned char* lds, const bf16_t* zrow, int h, const bf16_t* slot, f32x4 (&o)[8]) {
;     ...
;         float tmp[8];
; #pragma unroll
;         for (int ks = 0; ks < 4; ++ks) {
;             const f32x4 a = *(const f32x4*)(TOT + wid * 128 + 32 * ks + 8 * kq), b = *(const f32x4*)(TOT + wid * 128 + 32 * ks + 8 * kq + 4);
;             const float tw[8] = {a[0], a[1], a[2], a[3], b[0], b[1], b[2], b[3]};
; #pragma unroll
;             for (int e = 0; e < 8; ++e) tmp[e] = kk[8 * ks + e] * __builtin_amdgcn_exp2f(tw[e] - bl[8 * ks + e]);
;             *(bf16x8*)(KO + (16 * wid + r) * HP + 32 * ks + 8 * kq) = pk8(tmp);
; #pragma unroll
;             for (int e = 0; e < 8; ++e) tmp[e] = kk[8 * ks + e] * __builtin_amdgcn_exp2f(fminf(-bl[8 * ks + e], 115.f));
;             kin[ks] = pk8(tmp);
;         }
	ds_read_b128 v[102:105], v110
	ds_read_b128 v[106:109], v110 offset:16
	v_lshl_or_b32 v76, s36, 4, v149
	v_lshl_add_u32 v72, v148, 1, 0
	v_mad_u64_u32 v[76:77], s[6:7], v76, s27, v[72:73]
	s_waitcnt lgkmcnt(1)
	v_sub_f32_e32 v77, v102, v64
	v_sub_f32_e32 v102, v103, v65
	v_sub_f32_e32 v103, v104, v66
	v_exp_f32_e32 v102, v102
	v_exp_f32_e32 v103, v103
	v_sub_f32_e32 v104, v105, v67
	s_waitcnt lgkmcnt(0)
	v_sub_f32_e32 v105, v106, v60
	v_sub_f32_e32 v106, v107, v61
	v_sub_f32_e32 v107, v108, v62
	v_sub_f32_e32 v108, v109, v63
	v_max_f32_e64 v61, -v61, -v61
	v_max_f32_e64 v62, -v62, -v62
	v_max_f32_e64 v63, -v63, -v63
	v_exp_f32_e32 v77, v77
	v_exp_f32_e32 v104, v104
	v_exp_f32_e32 v105, v105
	v_max_f32_e64 v64, -v64, -v64
	v_max_f32_e64 v65, -v65, -v65
	v_max_f32_e64 v66, -v66, -v66
	v_max_f32_e64 v67, -v67, -v67
	v_max_f32_e64 v60, -v60, -v60
	v_min_f32_e32 v61, 0x42e60000, v61
	v_min_f32_e32 v62, 0x42e60000, v62
	v_min_f32_e32 v63, 0x42e60000, v63
	v_exp_f32_e32 v106, v106
	v_exp_f32_e32 v107, v107
	v_exp_f32_e32 v108, v108
	v_min_f32_e32 v64, 0x42e60000, v64
	v_min_f32_e32 v65, 0x42e60000, v65
	v_min_f32_e32 v66, 0x42e60000, v66
	v_min_f32_e32 v67, 0x42e60000, v67
	v_min_f32_e32 v60, 0x42e60000, v60
	v_exp_f32_e32 v61, v61
	v_exp_f32_e32 v62, v62
	v_exp_f32_e32 v63, v63
	v_exp_f32_e32 v64, v64
	v_exp_f32_e32 v65, v65
	v_exp_f32_e32 v66, v66
	v_exp_f32_e32 v67, v67
	v_exp_f32_e32 v60, v60
	v_mul_f32_e32 v102, v220, v102
	v_mul_f32_e32 v103, v221, v103
	v_mul_f32_e32 v77, v219, v77
	v_mul_f32_e32 v104, v222, v104
	v_mul_f32_e32 v105, v223, v105
	v_cvt_pk_bf16_f32 v102, v77, v102
	v_cvt_pk_bf16_f32 v103, v103, v104
	v_mul_f32_e32 v106, v224, v106
	v_mul_f32_e32 v107, v225, v107
	v_mul_f32_e32 v108, v226, v108
	v_cvt_pk_bf16_f32 v104, v105, v106
	v_cvt_pk_bf16_f32 v105, v107, v108
	ds_write_b128 v76, v[102:105] offset:8192
	v_mul_f32_e32 v102, v224, v61
	v_mul_f32_e32 v103, v225, v62
	v_mul_f32_e32 v63, v226, v63
	v_mul_f32_e32 v64, v219, v64
	v_mul_f32_e32 v65, v220, v65
	v_mul_f32_e32 v66, v221, v66
	v_mul_f32_e32 v67, v222, v67
	v_mul_f32_e32 v77, v223, v60
	v_cvt_pk_bf16_f32 v60, v64, v65
	v_cvt_pk_bf16_f32 v61, v66, v67
	v_cvt_pk_bf16_f32 v62, v77, v102
	v_cvt_pk_bf16_f32 v63, v103, v63
	ds_read_b128 v[102:105], v110 offset:128
	ds_read_b128 v[106:109], v110 offset:144
	v_mul_f32_e32 v66, v75, v213
	v_mul_f32_e32 v65, v68, v214
	v_mul_f32_e32 v64, v69, v215
	s_waitcnt lgkmcnt(1)
	v_sub_f32_e32 v67, v102, v52
	v_sub_f32_e32 v68, v103, v53
	v_sub_f32_e32 v69, v104, v54
	v_sub_f32_e32 v75, v105, v55
	s_waitcnt lgkmcnt(0)
	v_sub_f32_e32 v104, v109, v51
	v_max_f32_e64 v52, -v52, -v52
	v_max_f32_e64 v53, -v53, -v53
	v_max_f32_e64 v54, -v54, -v54
	v_max_f32_e64 v55, -v55, -v55
	v_max_f32_e64 v51, -v51, -v51
	v_sub_f32_e32 v77, v106, v48
	v_sub_f32_e32 v102, v107, v49
	v_sub_f32_e32 v103, v108, v50
	v_min_f32_e32 v52, 0x42e60000, v52
	v_min_f32_e32 v53, 0x42e60000, v53
	v_min_f32_e32 v54, 0x42e60000, v54
	v_min_f32_e32 v55, 0x42e60000, v55
	v_max_f32_e64 v48, -v48, -v48
	v_max_f32_e64 v49, -v49, -v49
	v_max_f32_e64 v50, -v50, -v50
	v_min_f32_e32 v51, 0x42e60000, v51
	v_exp_f32_e32 v67, v67
	v_exp_f32_e32 v68, v68
	v_exp_f32_e32 v69, v69
	v_exp_f32_e32 v102, v102
	v_exp_f32_e32 v52, v52
	v_exp_f32_e32 v53, v53
	v_exp_f32_e32 v54, v54
	v_exp_f32_e32 v55, v55
	v_min_f32_e32 v48, 0x42e60000, v48
	v_min_f32_e32 v49, 0x42e60000, v49
	v_min_f32_e32 v50, 0x42e60000, v50
	v_exp_f32_e32 v51, v51
	v_exp_f32_e32 v75, v75
	v_exp_f32_e32 v77, v77
	v_exp_f32_e32 v103, v103
	v_exp_f32_e32 v104, v104
	v_exp_f32_e32 v48, v48
	v_exp_f32_e32 v49, v49
	v_exp_f32_e32 v50, v50
	v_mul_f32_e32 v67, v227, v67
	v_mul_f32_e32 v68, v228, v68
	v_mul_f32_e32 v69, v111, v69
	v_mul_f32_e32 v105, v170, v102
	v_mul_f32_e32 v52, v227, v52
	v_mul_f32_e32 v53, v228, v53
	v_mul_f32_e32 v54, v111, v54
	v_mul_f32_e32 v55, v151, v55
	v_mul_f32_e32 v51, v168, v51
	v_mul_f32_e32 v75, v151, v75
	v_mul_f32_e32 v77, v169, v77
	v_mul_f32_e32 v106, v171, v103
	v_mul_f32_e32 v107, v168, v104
	v_cvt_pk_bf16_f32 v102, v67, v68
	v_cvt_pk_bf16_f32 v103, v69, v75
	v_cvt_pk_bf16_f32 v104, v77, v105
	v_cvt_pk_bf16_f32 v105, v106, v107
	ds_write_b128 v76, v[102:105] offset:8256
	v_mul_f32_e32 v67, v169, v48
	v_mul_f32_e32 v68, v170, v49
	v_mul_f32_e32 v69, v171, v50
	v_cvt_pk_bf16_f32 v48, v52, v53
	v_cvt_pk_bf16_f32 v49, v54, v55
	v_cvt_pk_bf16_f32 v50, v67, v68
	v_cvt_pk_bf16_f32 v51, v69, v51
	ds_read_b128 v[52:55], v110 offset:256
	ds_read_b128 v[102:105], v110 offset:272
	v_mul_f32_e32 v69, v70, v216
	v_mul_f32_e32 v67, v71, v217
	v_mul_f32_e32 v68, v56, v218
	s_waitcnt lgkmcnt(1)
	v_sub_f32_e32 v52, v52, v44
	v_sub_f32_e32 v53, v53, v45
	v_sub_f32_e32 v54, v54, v46
	v_exp_f32_e32 v52, v52
	v_exp_f32_e32 v53, v53
	v_exp_f32_e32 v54, v54
	v_sub_f32_e32 v55, v55, v47
	s_waitcnt lgkmcnt(0)
; __device__ __forceinline__ unsigned cvt_pk_c(float lo, float hi) { const f32x2_cv v = {lo, hi}; const bf16x2_cv b = __builtin_convertvector(v, bf16x2_cv); return __builtin_bit_cast(unsigned, b); }
; __device__ __forceinline__ bf16x8 pk8(const float* v) { u32x4 w; w.x = cvt_pk_bf16(v[0], v[1]); w.y = cvt_pk_bf16(v[2], v[3]); w.z = cvt_pk_bf16(v[4], v[5]); w.w = cvt_pk_bf16(v[6], v[7]); return __builtin_bit_cast(bf16x8, w); }
; template <int DIR> __device__ __forceinline__ void h3_dir(unsigned char* lds, const bf16_t* zrow, int h, const bf16_t* slot, f32x4 (&o)[8]) {
;     ...
; #pragma unroll
;         for (int ks = 0; ks < 4; ++ks) {
;             const f32x4 a = *(const f32x4*)(TOT + wid * 128 + 32 * ks + 8 * kq), b = *(const f32x4*)(TOT + wid * 128 + 32 * ks + 8 * kq + 4);
;             const float tw[8] = {a[0], a[1], a[2], a[3], b[0], b[1], b[2], b[3]};
; #pragma unroll
;             for (int e = 0; e < 8; ++e) tmp[e] = kk[8 * ks + e] * __builtin_amdgcn_exp2f(tw[e] - bl[8 * ks + e]);
;             *(bf16x8*)(KO + (16 * wid + r) * HP + 32 * ks + 8 * kq) = pk8(tmp);
; #pragma unroll
;             for (int e = 0; e < 8; ++e) tmp[e] = kk[8 * ks + e] * __builtin_amdgcn_exp2f(fminf(-bl[8 * ks + e], 115.f));
;             kin[ks] = pk8(tmp);
;         }
;     }
;     __syncthreads();
;     {
;         f32x4 sc = {0.f, 0.f, 0.f, 0.f};
; #pragma unroll
;         for (int ks = 0; ks < 4; ++ks) sc = __builtin_amdgcn_mfma_f32_16x16x32_bf16(pk8(qin + 8 * ks), kin[ks], sc, 0, 0, 0);
; #pragma unroll
;         for (int i = 0; i < 4; i += 2) { const int t = 4 * kq + i; const bool k0 = DIR ? (r >= t) : (r <= t), k1 = DIR ? (r >= t + 1) : (r <= t + 1); const unsigned w = cvt_pk_c(k0 ? sc[i] : 0.f, k1 ? sc[i + 1] : 0.f);
;             Pw[t * HP + 16 * wid + r] = (bf16_t)(w & 0xffffu); Pw[(t + 1) * HP + 16 * wid + r] = (bf16_t)(w >> 16); }
;     }
;     float run[32];
; #pragma unroll
;     for (int i = 0; i < 32; ++i) run[i] = 1.f;
;     for (int d = 1; d < 8; ++d) {
;         const int m = DIR ? wid + d : wid - d;
;         if (m < 0 || m > 7) break;
	v_sub_f32_e32 v56, v102, v40
	v_sub_f32_e32 v70, v103, v41
	v_sub_f32_e32 v71, v104, v42
	v_sub_f32_e32 v75, v105, v43
	v_max_f32_e64 v44, -v44, -v44
	v_max_f32_e64 v45, -v45, -v45
	v_max_f32_e64 v46, -v46, -v46
	v_max_f32_e64 v47, -v47, -v47
	v_max_f32_e64 v40, -v40, -v40
	v_max_f32_e64 v41, -v41, -v41
	v_max_f32_e64 v42, -v42, -v42
	v_max_f32_e64 v43, -v43, -v43
	v_exp_f32_e32 v55, v55
	v_exp_f32_e32 v56, v56
	v_exp_f32_e32 v70, v70
	v_min_f32_e32 v44, 0x42e60000, v44
	v_min_f32_e32 v45, 0x42e60000, v45
	v_min_f32_e32 v46, 0x42e60000, v46
	v_min_f32_e32 v47, 0x42e60000, v47
	v_min_f32_e32 v40, 0x42e60000, v40
	v_min_f32_e32 v41, 0x42e60000, v41
	v_min_f32_e32 v42, 0x42e60000, v42
	v_min_f32_e32 v43, 0x42e60000, v43
	v_exp_f32_e32 v71, v71
	v_exp_f32_e32 v75, v75
	v_exp_f32_e32 v44, v44
	v_exp_f32_e32 v45, v45
	v_exp_f32_e32 v46, v46
	v_exp_f32_e32 v47, v47
	v_exp_f32_e32 v40, v40
	v_exp_f32_e32 v41, v41
	v_exp_f32_e32 v42, v42
	v_exp_f32_e32 v43, v43
	v_mul_f32_e32 v52, v165, v52
	v_mul_f32_e32 v53, v166, v53
	v_mul_f32_e32 v54, v167, v54
	v_mul_f32_e32 v55, v164, v55
	v_mul_f32_e32 v56, v161, v56
	v_mul_f32_e32 v70, v162, v70
	v_cvt_pk_bf16_f32 v52, v52, v53
	v_cvt_pk_bf16_f32 v53, v54, v55
	v_cvt_pk_bf16_f32 v54, v56, v70
	v_mul_f32_e32 v71, v163, v71
	v_mul_f32_e32 v75, v160, v75
	v_cvt_pk_bf16_f32 v55, v71, v75
	ds_write_b128 v76, v[52:55] offset:8320
	v_mul_f32_e32 v44, v165, v44
	v_mul_f32_e32 v45, v166, v45
	v_mul_f32_e32 v46, v167, v46
	v_mul_f32_e32 v47, v164, v47
	v_mul_f32_e32 v52, v161, v40
	v_mul_f32_e32 v53, v162, v41
	v_mul_f32_e32 v54, v163, v42
	v_mul_f32_e32 v43, v160, v43
	v_cvt_pk_bf16_f32 v40, v44, v45
	v_cvt_pk_bf16_f32 v41, v46, v47
	v_cvt_pk_bf16_f32 v42, v52, v53
	v_cvt_pk_bf16_f32 v43, v54, v43
	ds_read_b128 v[44:47], v110 offset:384
	ds_read_b128 v[52:55], v110 offset:400
	v_mul_f32_e32 v87, v87, v201
	v_mul_f32_e32 v83, v83, v205
	v_mul_f32_e32 v74, v74, v212
	s_waitcnt lgkmcnt(1)
	v_sub_f32_e32 v44, v44, v36
	v_sub_f32_e32 v45, v45, v37
	v_sub_f32_e32 v46, v46, v38
	v_sub_f32_e32 v47, v47, v39
	s_waitcnt lgkmcnt(0)
	v_sub_f32_e32 v55, v55, v35
	v_max_f32_e64 v36, -v36, -v36
	v_max_f32_e64 v37, -v37, -v37
	v_max_f32_e64 v38, -v38, -v38
	v_max_f32_e64 v39, -v39, -v39
	v_max_f32_e64 v35, -v35, -v35
	v_exp_f32_e32 v44, v44
	v_exp_f32_e32 v45, v45
	v_exp_f32_e32 v46, v46
	v_sub_f32_e32 v52, v52, v32
	v_sub_f32_e32 v53, v53, v33
	v_sub_f32_e32 v54, v54, v34
	v_min_f32_e32 v36, 0x42e60000, v36
	v_min_f32_e32 v37, 0x42e60000, v37
	v_min_f32_e32 v38, 0x42e60000, v38
	v_min_f32_e32 v39, 0x42e60000, v39
	v_max_f32_e64 v32, -v32, -v32
	v_max_f32_e64 v33, -v33, -v33
	v_max_f32_e64 v34, -v34, -v34
	v_min_f32_e32 v35, 0x42e60000, v35
	v_exp_f32_e32 v47, v47
	v_exp_f32_e32 v52, v52
	v_exp_f32_e32 v53, v53
	v_exp_f32_e32 v36, v36
	v_exp_f32_e32 v37, v37
	v_exp_f32_e32 v38, v38
	v_exp_f32_e32 v39, v39
	v_min_f32_e32 v32, 0x42e60000, v32
	v_min_f32_e32 v33, 0x42e60000, v33
	v_min_f32_e32 v34, 0x42e60000, v34
	v_exp_f32_e32 v35, v35
	v_exp_f32_e32 v54, v54
	v_exp_f32_e32 v55, v55
	v_exp_f32_e32 v32, v32
	v_exp_f32_e32 v33, v33
	v_exp_f32_e32 v34, v34
	v_mul_f32_e32 v44, v157, v44
	v_mul_f32_e32 v45, v158, v45
	v_mul_f32_e32 v46, v159, v46
	v_mul_f32_e32 v47, v156, v47
	v_mul_f32_e32 v52, v153, v52
	v_mul_f32_e32 v53, v154, v53
	v_cvt_pk_bf16_f32 v44, v44, v45
	v_cvt_pk_bf16_f32 v45, v46, v47
	v_cvt_pk_bf16_f32 v46, v52, v53
	v_mul_f32_e32 v36, v157, v36
	v_mul_f32_e32 v37, v158, v37
	v_mul_f32_e32 v38, v159, v38
	v_mul_f32_e32 v39, v156, v39
	v_mul_f32_e32 v35, v152, v35
	v_mul_f32_e32 v54, v155, v54
	v_mul_f32_e32 v55, v152, v55
	v_cvt_pk_bf16_f32 v47, v54, v55
	ds_write_b128 v76, v[44:47] offset:8384
	v_mul_f32_e32 v44, v153, v32
	v_mul_f32_e32 v45, v154, v33
	v_mul_f32_e32 v46, v155, v34
	v_cvt_pk_bf16_f32 v32, v36, v37
	v_cvt_pk_bf16_f32 v33, v38, v39
	v_cvt_pk_bf16_f32 v34, v44, v45
	v_cvt_pk_bf16_f32 v35, v46, v35
	s_waitcnt lgkmcnt(0)
	s_barrier
	v_cvt_pk_bf16_f32 v36, v92, v93
	v_cvt_pk_bf16_f32 v37, v94, v95
	v_cvt_pk_bf16_f32 v38, v96, v97
	v_cvt_pk_bf16_f32 v39, v98, v91
	v_cvt_pk_bf16_f32 v44, v89, v90
	v_cvt_pk_bf16_f32 v45, v86, v87
	v_cvt_pk_bf16_f32 v46, v88, v84
	v_cvt_pk_bf16_f32 v47, v85, v83
	v_lshlrev_b32_e32 v101, 16, v99
	v_mfma_f32_16x16x32_bf16 v[36:39], v[36:39], v[60:63], 0
	v_and_b32_e32 v99, 0xffff0000, v99
	v_mul_f32_e32 v71, v57, v100
	v_mul_f32_e32 v75, v58, v101
	v_mfma_f32_16x16x32_bf16 v[36:39], v[44:47], v[48:51], v[36:39]
	v_cvt_pk_bf16_f32 v44, v82, v80
	v_cvt_pk_bf16_f32 v45, v81, v78
	v_cvt_pk_bf16_f32 v46, v79, v73
	v_cvt_pk_bf16_f32 v47, v74, v66
	v_mul_f32_e32 v70, v59, v99
	v_mfma_f32_16x16x32_bf16 v[36:39], v[44:47], v[40:43], v[36:39]
	v_cvt_pk_bf16_f32 v40, v65, v64
	v_cvt_pk_bf16_f32 v41, v69, v67
	v_cvt_pk_bf16_f32 v42, v68, v71
	v_cvt_pk_bf16_f32 v43, v75, v70
	s_lshl_b32 s3, s36, 5
	v_mfma_f32_16x16x32_bf16 v[32:35], v[40:43], v[32:35], v[36:39]
	v_mul_u32_u24_e32 v77, 0x220, v150
	s_add_i32 s5, s4, s3
	v_lshlrev_b32_e32 v76, 1, v149
	s_nop 2
	v_lshlrev_b32_e32 v36, 2, v150
	v_cmp_ge_u32_e32 vcc, v149, v36
	v_add_u32_e32 v37, s5, v76
	v_mov_b32_e32 v56, 1.0
	v_cndmask_b32_e32 v32, 0, v32, vcc
	v_cmp_gt_u32_e32 vcc, v149, v36
	v_mov_b32_e32 v57, 1.0
	v_mov_b32_e32 v58, 1.0
	v_cndmask_b32_e32 v33, 0, v33, vcc
	v_cvt_pk_bf16_f32 v32, v32, v33
	v_lshlrev_b32_e32 v33, 1, v77
	v_add_u32_e32 v99, s4, v33
	v_add_u32_e32 v38, v37, v33
	v_add3_u32 v33, v99, s3, v76
	ds_write_b16 v38, v32
	ds_write_b16_d16_hi v33, v32 offset:272
	v_or_b32_e32 v32, 2, v36
	v_cmp_ge_u32_e32 vcc, v149, v32
	v_mul_u32_u24_e32 v100, 0x88, v32
	v_mov_b32_e32 v59, 1.0
	v_cndmask_b32_e32 v33, 0, v34, vcc
	v_cmp_gt_u32_e32 vcc, v149, v32
	v_lshlrev_b32_e32 v32, 1, v100
	v_add_u32_e32 v101, s4, v32
	v_cndmask_b32_e32 v34, 0, v35, vcc
	v_cvt_pk_bf16_f32 v33, v33, v34
	v_add_u32_e32 v34, v37, v32
	v_add3_u32 v32, v101, s3, v76
	s_add_i32 s3, s36, 1
	ds_write_b16 v34, v33
	ds_write_b16_d16_hi v32, v33 offset:272
	s_cmp_gt_u32 s3, 7
	v_mov_b32_e32 v60, 1.0
	v_mov_b32_e32 v61, 1.0
	v_mov_b32_e32 v62, 1.0
	v_mov_b32_e32 v63, 1.0
	v_mov_b32_e32 v52, 1.0
	v_mov_b32_e32 v53, 1.0
	v_mov_b32_e32 v54, 1.0
	v_mov_b32_e32 v55, 1.0
	v_mov_b32_e32 v48, 1.0
	v_mov_b32_e32 v49, 1.0
	v_mov_b32_e32 v50, 1.0
	v_mov_b32_e32 v51, 1.0
	v_mov_b32_e32 v44, 1.0
	v_mov_b32_e32 v45, 1.0
	v_mov_b32_e32 v46, 1.0
	v_mov_b32_e32 v47, 1.0
	v_mov_b32_e32 v40, 1.0
	v_mov_b32_e32 v41, 1.0
	v_mov_b32_e32 v42, 1.0
	v_mov_b32_e32 v43, 1.0
	v_mov_b32_e32 v36, 1.0
	v_mov_b32_e32 v37, 1.0
	v_mov_b32_e32 v38, 1.0
	v_mov_b32_e32 v39, 1.0
	v_mov_b32_e32 v32, 1.0
	v_mov_b32_e32 v33, 1.0
	v_mov_b32_e32 v34, 1.0
	v_mov_b32_e32 v35, 1.0
	s_cbranch_scc1 .LBB0_1099
; __device__ __forceinline__ unsigned cvt_pk_c(float lo, float hi) { const f32x2_cv v = {lo, hi}; const bf16x2_cv b = __builtin_convertvector(v, bf16x2_cv); return __builtin_bit_cast(unsigned, b); }
; __device__ __forceinline__ bf16x8 pk8(const float* v) { u32x4 w; w.x = cvt_pk_bf16(v[0], v[1]); w.y = cvt_pk_bf16(v[2], v[3]); w.z = cvt_pk_bf16(v[4], v[5]); w.w = cvt_pk_bf16(v[6], v[7]); return __builtin_bit_cast(bf16x8, w); }
; template <int DIR> __device__ __forceinline__ void h3_dir(unsigned char* lds, const bf16_t* zrow, int h, const bf16_t* slot, f32x4 (&o)[8]) {
;     ...
;     for (int d = 1; d < 8; ++d) {
;         const int m = DIR ? wid + d : wid - d;
;         if (m < 0 || m > 7) break;
;         f32x4 sc = {0.f, 0.f, 0.f, 0.f};
; #pragma unroll
;         for (int ks = 0; ks < 4; ++ks) {
;             float tmp[8];
; #pragma unroll
;             for (int e = 0; e < 8; ++e) tmp[e] = qin[8 * ks + e] * run[8 * ks + e];
;             const bf16x8 bb = *(const bf16x8*)(KO + (16 * m + r) * HP + 32 * ks + 8 * kq);
;             sc = __builtin_amdgcn_mfma_f32_16x16x32_bf16(pk8(tmp), bb, sc, 0, 0, 0);
;             const f32x4 a = *(const f32x4*)(TOTE + m * 128 + 32 * ks + 8 * kq), b = *(const f32x4*)(TOTE + m * 128 + 32 * ks + 8 * kq + 4);
;             run[8 * ks] *= a[0]; run[8 * ks + 1] *= a[1]; run[8 * ks + 2] *= a[2]; run[8 * ks + 3] *= a[3]; run[8 * ks + 4] *= b[0]; run[8 * ks + 5] *= b[1]; run[8 * ks + 6] *= b[2]; run[8 * ks + 7] *= b[3];
;         }
; #pragma unroll
;         for (int i = 0; i < 4; i += 2) { const unsigned w = cvt_pk_c(sc[i], sc[i + 1]); Pw[(4 * kq + i) * HP + 16 * m + r] = (bf16_t)(w & 0xffffu); Pw[(4 * kq + i + 1) * HP + 16 * m + r] = (bf16_t)(w >> 16); }
;     }
	v_lshl_or_b32 v32, s3, 4, v149
	v_mad_u64_u32 v[104:105], s[6:7], v32, s27, v[72:73]
	ds_read_b128 v[32:35], v104 offset:8192
	v_lshl_add_u32 v103, v150, 4, v72
	v_lshl_add_u32 v108, s3, 9, v103
	v_cvt_pk_bf16_f32 v36, v92, v93
	v_cvt_pk_bf16_f32 v37, v94, v95
	v_cvt_pk_bf16_f32 v38, v96, v97
	v_cvt_pk_bf16_f32 v39, v98, v91
	v_add_u32_e32 v102, s4, v76
	s_waitcnt lgkmcnt(0)
	v_mfma_f32_16x16x32_bf16 v[32:35], v[36:39], v[32:35], 0
	ds_read_b128 v[60:63], v108 offset:4112
	ds_read_b128 v[56:59], v108 offset:4096
	ds_read_b128 v[36:39], v104 offset:8256
	v_cvt_pk_bf16_f32 v40, v89, v90
	v_cvt_pk_bf16_f32 v41, v86, v87
	v_cvt_pk_bf16_f32 v42, v88, v84
	v_cvt_pk_bf16_f32 v43, v85, v83
	s_lshl_b32 s3, s3, 5
	s_waitcnt lgkmcnt(0)
	v_mfma_f32_16x16x32_bf16 v[32:35], v[40:43], v[36:39], v[32:35]
	ds_read_b128 v[48:51], v108 offset:4240
	ds_read_b128 v[52:55], v108 offset:4224
	ds_read_b128 v[36:39], v104 offset:8320
	v_cvt_pk_bf16_f32 v40, v82, v80
	v_cvt_pk_bf16_f32 v41, v81, v78
	v_cvt_pk_bf16_f32 v42, v79, v73
	v_cvt_pk_bf16_f32 v43, v74, v66
	s_waitcnt lgkmcnt(0)
	v_mfma_f32_16x16x32_bf16 v[32:35], v[40:43], v[36:39], v[32:35]
	ds_read_b128 v[40:43], v108 offset:4368
	ds_read_b128 v[44:47], v108 offset:4352
	ds_read_b128 v[36:39], v104 offset:8384
	v_cvt_pk_bf16_f32 v104, v65, v64
	v_cvt_pk_bf16_f32 v105, v69, v67
	v_cvt_pk_bf16_f32 v106, v68, v71
	v_cvt_pk_bf16_f32 v107, v75, v70
	s_waitcnt lgkmcnt(0)
	v_mfma_f32_16x16x32_bf16 v[104:107], v[104:107], v[36:39], v[32:35]
	ds_read_b128 v[36:39], v108 offset:4480
	s_nop 1
	ds_read_b128 v[32:35], v108 offset:4496
	v_add_u32_e32 v108, s3, v102
	s_nop 2
	v_cvt_pk_bf16_f32 v104, v104, v105
	v_lshl_add_u32 v105, v77, 1, v108
	ds_write_b16 v105, v104
	v_add3_u32 v105, v99, s3, v76
	ds_write_b16_d16_hi v105, v104 offset:272
	v_cvt_pk_bf16_f32 v104, v106, v107
	v_lshl_add_u32 v105, v100, 1, v108
	ds_write_b16 v105, v104
	v_add3_u32 v105, v101, s3, v76
	s_add_i32 s3, s36, 2
	s_cmp_gt_u32 s3, 7
	ds_write_b16_d16_hi v105, v104 offset:272
	s_cbranch_scc1 .LBB0_1099
	v_lshl_or_b32 v104, s3, 4, v149
	v_mad_u64_u32 v[164:165], s[6:7], v104, s27, v[72:73]
	ds_read_b128 v[104:107], v164 offset:8192
	v_lshl_add_u32 v116, s3, 9, v103
	v_mul_f32_e32 v108, v92, v56
	v_mul_f32_e32 v109, v93, v57
	v_mul_f32_e32 v110, v94, v58
	v_mul_f32_e32 v111, v95, v59
	v_mul_f32_e32 v150, v96, v60
	v_mul_f32_e32 v151, v97, v61
	v_mul_f32_e32 v152, v98, v62
	v_mul_f32_e32 v153, v91, v63
	v_cvt_pk_bf16_f32 v108, v108, v109
	v_cvt_pk_bf16_f32 v109, v110, v111
	v_cvt_pk_bf16_f32 v110, v150, v151
	v_cvt_pk_bf16_f32 v111, v152, v153
	ds_read_b128 v[150:153], v116 offset:4096
	ds_read_b128 v[154:157], v116 offset:4112
	s_waitcnt lgkmcnt(2)
	v_mfma_f32_16x16x32_bf16 v[104:107], v[108:111], v[104:107], 0
	ds_read_b128 v[108:111], v164 offset:8256
	v_mul_f32_e32 v158, v85, v50
	s_waitcnt lgkmcnt(2)
	v_pk_mul_f32 v[58:59], v[58:59], v[152:153]
	v_pk_mul_f32 v[56:57], v[56:57], v[150:151]
	s_waitcnt lgkmcnt(1)
	v_pk_mul_f32 v[62:63], v[62:63], v[156:157]
	v_mul_f32_e32 v150, v89, v52
	v_mul_f32_e32 v151, v90, v53
	v_mul_f32_e32 v152, v86, v54
	v_mul_f32_e32 v153, v87, v55
	v_mul_f32_e32 v156, v88, v48
	v_mul_f32_e32 v157, v84, v49
	v_mul_f32_e32 v159, v83, v51
	v_cvt_pk_bf16_f32 v150, v150, v151
	v_cvt_pk_bf16_f32 v151, v152, v153
	v_cvt_pk_bf16_f32 v152, v156, v157
	v_cvt_pk_bf16_f32 v153, v158, v159
	ds_read_b128 v[156:159], v116 offset:4224
	ds_read_b128 v[160:163], v116 offset:4240
	s_waitcnt lgkmcnt(2)
	v_mfma_f32_16x16x32_bf16 v[104:107], v[150:153], v[108:111], v[104:107]
	ds_read_b128 v[108:111], v164 offset:8320
	v_pk_mul_f32 v[60:61], v[60:61], v[154:155]
	s_waitcnt lgkmcnt(2)
	v_pk_mul_f32 v[52:53], v[52:53], v[156:157]
	v_mul_f32_e32 v150, v82, v44
	v_mul_f32_e32 v151, v80, v45
	v_mul_f32_e32 v152, v81, v46
	v_mul_f32_e32 v153, v78, v47
	v_mul_f32_e32 v154, v79, v40
	v_mul_f32_e32 v155, v73, v41
	v_mul_f32_e32 v156, v74, v42
	v_mul_f32_e32 v157, v66, v43
	v_cvt_pk_bf16_f32 v150, v150, v151
	v_cvt_pk_bf16_f32 v151, v152, v153
	v_cvt_pk_bf16_f32 v152, v154, v155
	v_cvt_pk_bf16_f32 v153, v156, v157
	ds_read_b128 v[154:157], v116 offset:4352
	s_waitcnt lgkmcnt(1)
	v_mfma_f32_16x16x32_bf16 v[104:107], v[150:153], v[108:111], v[104:107]
	ds_read_b128 v[108:111], v116 offset:4368
	ds_read_b128 v[150:153], v164 offset:8384
	v_pk_mul_f32 v[54:55], v[54:55], v[158:159]
	v_pk_mul_f32 v[48:49], v[48:49], v[160:161]
	s_waitcnt lgkmcnt(2)
	v_pk_mul_f32 v[46:47], v[46:47], v[156:157]
	v_pk_mul_f32 v[44:45], v[44:45], v[154:155]
	v_mul_f32_e32 v154, v65, v36
	v_mul_f32_e32 v155, v64, v37
	v_mul_f32_e32 v156, v69, v38
	v_mul_f32_e32 v157, v67, v39
	v_mul_f32_e32 v158, v68, v32
	v_mul_f32_e32 v159, v71, v33
	v_mul_f32_e32 v160, v75, v34
	v_mul_f32_e32 v161, v70, v35
	v_cvt_pk_bf16_f32 v154, v154, v155
	v_cvt_pk_bf16_f32 v155, v156, v157
	v_cvt_pk_bf16_f32 v156, v158, v159
	v_cvt_pk_bf16_f32 v157, v160, v161
	s_lshl_b32 s3, s3, 5
	s_waitcnt lgkmcnt(0)
	v_mfma_f32_16x16x32_bf16 v[104:107], v[154:157], v[150:153], v[104:107]
	v_mul_f32_e64 v50, v50, v162
	v_mul_f32_e64 v51, v51, v163
	ds_read_b128 v[158:161], v116 offset:4480
	ds_read_b128 v[162:165], v116 offset:4496
	v_pk_mul_f32 v[40:41], v[40:41], v[108:109]
	v_add_u32_e32 v108, s3, v102
	s_nop 1
	v_cvt_pk_bf16_f32 v104, v104, v105
	v_lshl_add_u32 v105, v77, 1, v108
	ds_write_b16 v105, v104
	v_add3_u32 v105, v99, s3, v76
	ds_write_b16_d16_hi v105, v104 offset:272
	v_cvt_pk_bf16_f32 v104, v106, v107
	v_lshl_add_u32 v105, v100, 1, v108
	ds_write_b16 v105, v104
	v_add3_u32 v105, v101, s3, v76
	s_add_i32 s3, s36, 3
	v_pk_mul_f32 v[42:43], v[42:43], v[110:111]
	s_waitcnt lgkmcnt(4)
	v_pk_mul_f32 v[38:39], v[38:39], v[160:161]
	v_pk_mul_f32 v[36:37], v[36:37], v[158:159]
	s_waitcnt lgkmcnt(3)
	v_pk_mul_f32 v[34:35], v[34:35], v[164:165]
	v_pk_mul_f32 v[32:33], v[32:33], v[162:163]
	s_cmp_gt_u32 s3, 7
	ds_write_b16_d16_hi v105, v104 offset:272
	s_cbranch_scc1 .LBB0_1099
; __device__ __forceinline__ unsigned cvt_pk_c(float lo, float hi) { const f32x2_cv v = {lo, hi}; const bf16x2_cv b = __builtin_convertvector(v, bf16x2_cv); return __builtin_bit_cast(unsigned, b); }
; __device__ __forceinline__ bf16x8 pk8(const float* v) { u32x4 w; w.x = cvt_pk_bf16(v[0], v[1]); w.y = cvt_pk_bf16(v[2], v[3]); w.z = cvt_pk_bf16(v[4], v[5]); w.w = cvt_pk_bf16(v[6], v[7]); return __builtin_bit_cast(bf16x8, w); }
; template <int DIR> __device__ __forceinline__ void h3_dir(unsigned char* lds, const bf16_t* zrow, int h, const bf16_t* slot, f32x4 (&o)[8]) {
;     ...
;     for (int d = 1; d < 8; ++d) {
;         const int m = DIR ? wid + d : wid - d;
;         if (m < 0 || m > 7) break;
;         f32x4 sc = {0.f, 0.f, 0.f, 0.f};
; #pragma unroll
;         for (int ks = 0; ks < 4; ++ks) {
;             float tmp[8];
; #pragma unroll
;             for (int e = 0; e < 8; ++e) tmp[e] = qin[8 * ks + e] * run[8 * ks + e];
;             const bf16x8 bb = *(const bf16x8*)(KO + (16 * m + r) * HP + 32 * ks + 8 * kq);
;             sc = __builtin_amdgcn_mfma_f32_16x16x32_bf16(pk8(tmp), bb, sc, 0, 0, 0);
;             const f32x4 a = *(const f32x4*)(TOTE + m * 128 + 32 * ks + 8 * kq), b = *(const f32x4*)(TOTE + m * 128 + 32 * ks + 8 * kq + 4);
;             run[8 * ks] *= a[0]; run[8 * ks + 1] *= a[1]; run[8 * ks + 2] *= a[2]; run[8 * ks + 3] *= a[3]; run[8 * ks + 4] *= b[0]; run[8 * ks + 5] *= b[1]; run[8 * ks + 6] *= b[2]; run[8 * ks + 7] *= b[3];
;         }
; #pragma unroll
;         for (int i = 0; i < 4; i += 2) { const unsigned w = cvt_pk_c(sc[i], sc[i + 1]); Pw[(4 * kq + i) * HP + 16 * m + r] = (bf16_t)(w & 0xffffu); Pw[(4 * kq + i + 1) * HP + 16 * m + r] = (bf16_t)(w >> 16); }
;     }
	v_lshl_or_b32 v104, s3, 4, v149
	v_mad_u64_u32 v[164:165], s[6:7], v104, s27, v[72:73]
	ds_read_b128 v[104:107], v164 offset:8192
	v_lshl_add_u32 v116, s3, 9, v103
	v_mul_f32_e32 v108, v92, v56
	v_mul_f32_e32 v109, v93, v57
	v_mul_f32_e32 v110, v94, v58
	v_mul_f32_e32 v111, v95, v59
	v_mul_f32_e32 v150, v96, v60
	v_mul_f32_e32 v151, v97, v61
	v_mul_f32_e32 v152, v98, v62
	v_mul_f32_e32 v153, v91, v63
	v_cvt_pk_bf16_f32 v108, v108, v109
	v_cvt_pk_bf16_f32 v109, v110, v111
	v_cvt_pk_bf16_f32 v110, v150, v151
	v_cvt_pk_bf16_f32 v111, v152, v153
	ds_read_b128 v[150:153], v116 offset:4096
	ds_read_b128 v[154:157], v116 offset:4112
	s_waitcnt lgkmcnt(2)
	v_mfma_f32_16x16x32_bf16 v[104:107], v[108:111], v[104:107], 0
	ds_read_b128 v[108:111], v164 offset:8256
	v_mul_f32_e32 v158, v85, v50
	s_waitcnt lgkmcnt(2)
	v_pk_mul_f32 v[58:59], v[58:59], v[152:153]
	v_pk_mul_f32 v[56:57], v[56:57], v[150:151]
	s_waitcnt lgkmcnt(1)
	v_pk_mul_f32 v[62:63], v[62:63], v[156:157]
	v_mul_f32_e32 v150, v89, v52
	v_mul_f32_e32 v151, v90, v53
	v_mul_f32_e32 v152, v86, v54
	v_mul_f32_e32 v153, v87, v55
	v_mul_f32_e32 v156, v88, v48
	v_mul_f32_e32 v157, v84, v49
	v_mul_f32_e32 v159, v83, v51
	v_cvt_pk_bf16_f32 v150, v150, v151
	v_cvt_pk_bf16_f32 v151, v152, v153
	v_cvt_pk_bf16_f32 v152, v156, v157
	v_cvt_pk_bf16_f32 v153, v158, v159
	ds_read_b128 v[156:159], v116 offset:4224
	ds_read_b128 v[160:163], v116 offset:4240
	s_waitcnt lgkmcnt(2)
	v_mfma_f32_16x16x32_bf16 v[104:107], v[150:153], v[108:111], v[104:107]
	ds_read_b128 v[108:111], v164 offset:8320
	v_pk_mul_f32 v[60:61], v[60:61], v[154:155]
	s_waitcnt lgkmcnt(2)
	v_pk_mul_f32 v[52:53], v[52:53], v[156:157]
	v_mul_f32_e32 v150, v82, v44
	v_mul_f32_e32 v151, v80, v45
	v_mul_f32_e32 v152, v81, v46
	v_mul_f32_e32 v153, v78, v47
	v_mul_f32_e32 v154, v79, v40
	v_mul_f32_e32 v155, v73, v41
	v_mul_f32_e32 v156, v74, v42
	v_mul_f32_e32 v157, v66, v43
	v_cvt_pk_bf16_f32 v150, v150, v151
	v_cvt_pk_bf16_f32 v151, v152, v153
	v_cvt_pk_bf16_f32 v152, v154, v155
	v_cvt_pk_bf16_f32 v153, v156, v157
	ds_read_b128 v[154:157], v116 offset:4352
	s_waitcnt lgkmcnt(1)
	v_mfma_f32_16x16x32_bf16 v[104:107], v[150:153], v[108:111], v[104:107]
	ds_read_b128 v[108:111], v116 offset:4368
	ds_read_b128 v[150:153], v164 offset:8384
	v_pk_mul_f32 v[54:55], v[54:55], v[158:159]
	v_pk_mul_f32 v[48:49], v[48:49], v[160:161]
	s_waitcnt lgkmcnt(2)
	v_pk_mul_f32 v[46:47], v[46:47], v[156:157]
	v_pk_mul_f32 v[44:45], v[44:45], v[154:155]
	v_mul_f32_e32 v154, v65, v36
	v_mul_f32_e32 v155, v64, v37
	v_mul_f32_e32 v156, v69, v38
	v_mul_f32_e32 v157, v67, v39
	v_mul_f32_e32 v158, v68, v32
	v_mul_f32_e32 v159, v71, v33
	v_mul_f32_e32 v160, v75, v34
	v_mul_f32_e32 v161, v70, v35
	v_cvt_pk_bf16_f32 v154, v154, v155
	v_cvt_pk_bf16_f32 v155, v156, v157
	v_cvt_pk_bf16_f32 v156, v158, v159
	v_cvt_pk_bf16_f32 v157, v160, v161
	s_lshl_b32 s3, s3, 5
	s_waitcnt lgkmcnt(0)
	v_mfma_f32_16x16x32_bf16 v[104:107], v[154:157], v[150:153], v[104:107]
	v_mul_f32_e64 v50, v50, v162
	v_mul_f32_e64 v51, v51, v163
	ds_read_b128 v[158:161], v116 offset:4480
	ds_read_b128 v[162:165], v116 offset:4496
	v_pk_mul_f32 v[40:41], v[40:41], v[108:109]
	v_add_u32_e32 v108, s3, v102
	s_nop 1
	v_cvt_pk_bf16_f32 v104, v104, v105
	v_lshl_add_u32 v105, v77, 1, v108
	ds_write_b16 v105, v104
	v_add3_u32 v105, v99, s3, v76
	ds_write_b16_d16_hi v105, v104 offset:272
	v_cvt_pk_bf16_f32 v104, v106, v107
	v_lshl_add_u32 v105, v100, 1, v108
	ds_write_b16 v105, v104
	v_add3_u32 v105, v101, s3, v76
	s_add_i32 s3, s36, 4
	v_pk_mul_f32 v[42:43], v[42:43], v[110:111]
	s_waitcnt lgkmcnt(4)
	v_pk_mul_f32 v[38:39], v[38:39], v[160:161]
	v_pk_mul_f32 v[36:37], v[36:37], v[158:159]
	s_waitcnt lgkmcnt(3)
	v_pk_mul_f32 v[34:35], v[34:35], v[164:165]
	v_pk_mul_f32 v[32:33], v[32:33], v[162:163]
	s_cmp_gt_u32 s3, 7
	ds_write_b16_d16_hi v105, v104 offset:272
	s_cbranch_scc1 .LBB0_1099
	v_lshl_or_b32 v104, s3, 4, v149
	v_mad_u64_u32 v[164:165], s[6:7], v104, s27, v[72:73]
	ds_read_b128 v[104:107], v164 offset:8192
	v_lshl_add_u32 v116, s3, 9, v103
	v_mul_f32_e32 v108, v92, v56
	v_mul_f32_e32 v109, v93, v57
	v_mul_f32_e32 v110, v94, v58
	v_mul_f32_e32 v111, v95, v59
	v_mul_f32_e32 v150, v96, v60
	v_mul_f32_e32 v151, v97, v61
	v_mul_f32_e32 v152, v98, v62
	v_mul_f32_e32 v153, v91, v63
	v_cvt_pk_bf16_f32 v108, v108, v109
	v_cvt_pk_bf16_f32 v109, v110, v111
	v_cvt_pk_bf16_f32 v110, v150, v151
	v_cvt_pk_bf16_f32 v111, v152, v153
	ds_read_b128 v[150:153], v116 offset:4096
	ds_read_b128 v[154:157], v116 offset:4112
	s_waitcnt lgkmcnt(2)
	v_mfma_f32_16x16x32_bf16 v[104:107], v[108:111], v[104:107], 0
	ds_read_b128 v[108:111], v164 offset:8256
	v_mul_f32_e32 v158, v85, v50
	s_waitcnt lgkmcnt(2)
	v_pk_mul_f32 v[58:59], v[58:59], v[152:153]
	v_pk_mul_f32 v[56:57], v[56:57], v[150:151]
	s_waitcnt lgkmcnt(1)
	v_pk_mul_f32 v[62:63], v[62:63], v[156:157]
	v_mul_f32_e32 v150, v89, v52
	v_mul_f32_e32 v151, v90, v53
	v_mul_f32_e32 v152, v86, v54
	v_mul_f32_e32 v153, v87, v55
	v_mul_f32_e32 v156, v88, v48
	v_mul_f32_e32 v157, v84, v49
	v_mul_f32_e32 v159, v83, v51
	v_cvt_pk_bf16_f32 v150, v150, v151
	v_cvt_pk_bf16_f32 v151, v152, v153
	v_cvt_pk_bf16_f32 v152, v156, v157
	v_cvt_pk_bf16_f32 v153, v158, v159
	ds_read_b128 v[156:159], v116 offset:4224
	ds_read_b128 v[160:163], v116 offset:4240
	s_waitcnt lgkmcnt(2)
	v_mfma_f32_16x16x32_bf16 v[104:107], v[150:153], v[108:111], v[104:107]
	ds_read_b128 v[108:111], v164 offset:8320
	v_pk_mul_f32 v[60:61], v[60:61], v[154:155]
	s_waitcnt lgkmcnt(2)
; __device__ __forceinline__ unsigned cvt_pk_c(float lo, float hi) { const f32x2_cv v = {lo, hi}; const bf16x2_cv b = __builtin_convertvector(v, bf16x2_cv); return __builtin_bit_cast(unsigned, b); }
; __device__ __forceinline__ bf16x8 pk8(const float* v) { u32x4 w; w.x = cvt_pk_bf16(v[0], v[1]); w.y = cvt_pk_bf16(v[2], v[3]); w.z = cvt_pk_bf16(v[4], v[5]); w.w = cvt_pk_bf16(v[6], v[7]); return __builtin_bit_cast(bf16x8, w); }
; template <int DIR> __device__ __forceinline__ void h3_dir(unsigned char* lds, const bf16_t* zrow, int h, const bf16_t* slot, f32x4 (&o)[8]) {
;     ...
;     for (int d = 1; d < 8; ++d) {
;         const int m = DIR ? wid + d : wid - d;
;         if (m < 0 || m > 7) break;
;         f32x4 sc = {0.f, 0.f, 0.f, 0.f};
; #pragma unroll
;         for (int ks = 0; ks < 4; ++ks) {
;             float tmp[8];
; #pragma unroll
;             for (int e = 0; e < 8; ++e) tmp[e] = qin[8 * ks + e] * run[8 * ks + e];
;             const bf16x8 bb = *(const bf16x8*)(KO + (16 * m + r) * HP + 32 * ks + 8 * kq);
;             sc = __builtin_amdgcn_mfma_f32_16x16x32_bf16(pk8(tmp), bb, sc, 0, 0, 0);
;             const f32x4 a = *(const f32x4*)(TOTE + m * 128 + 32 * ks + 8 * kq), b = *(const f32x4*)(TOTE + m * 128 + 32 * ks + 8 * kq + 4);
;             run[8 * ks] *= a[0]; run[8 * ks + 1] *= a[1]; run[8 * ks + 2] *= a[2]; run[8 * ks + 3] *= a[3]; run[8 * ks + 4] *= b[0]; run[8 * ks + 5] *= b[1]; run[8 * ks + 6] *= b[2]; run[8 * ks + 7] *= b[3];
;         }
; #pragma unroll
;         for (int i = 0; i < 4; i += 2) { const unsigned w = cvt_pk_c(sc[i], sc[i + 1]); Pw[(4 * kq + i) * HP + 16 * m + r] = (bf16_t)(w & 0xffffu); Pw[(4 * kq + i + 1) * HP + 16 * m + r] = (bf16_t)(w >> 16); }
;     }
	v_pk_mul_f32 v[52:53], v[52:53], v[156:157]
	v_mul_f32_e32 v150, v82, v44
	v_mul_f32_e32 v151, v80, v45
	v_mul_f32_e32 v152, v81, v46
	v_mul_f32_e32 v153, v78, v47
	v_mul_f32_e32 v154, v79, v40
	v_mul_f32_e32 v155, v73, v41
	v_mul_f32_e32 v156, v74, v42
	v_mul_f32_e32 v157, v66, v43
	v_cvt_pk_bf16_f32 v150, v150, v151
	v_cvt_pk_bf16_f32 v151, v152, v153
	v_cvt_pk_bf16_f32 v152, v154, v155
	v_cvt_pk_bf16_f32 v153, v156, v157
	ds_read_b128 v[154:157], v116 offset:4352
	s_waitcnt lgkmcnt(1)
	v_mfma_f32_16x16x32_bf16 v[104:107], v[150:153], v[108:111], v[104:107]
	ds_read_b128 v[108:111], v116 offset:4368
	ds_read_b128 v[150:153], v164 offset:8384
	v_pk_mul_f32 v[54:55], v[54:55], v[158:159]
	v_pk_mul_f32 v[48:49], v[48:49], v[160:161]
	s_waitcnt lgkmcnt(2)
	v_pk_mul_f32 v[46:47], v[46:47], v[156:157]
	v_pk_mul_f32 v[44:45], v[44:45], v[154:155]
	v_mul_f32_e32 v154, v65, v36
	v_mul_f32_e32 v155, v64, v37
	v_mul_f32_e32 v156, v69, v38
	v_mul_f32_e32 v157, v67, v39
	v_mul_f32_e32 v158, v68, v32
	v_mul_f32_e32 v159, v71, v33
	v_mul_f32_e32 v160, v75, v34
	v_mul_f32_e32 v161, v70, v35
	v_cvt_pk_bf16_f32 v154, v154, v155
	v_cvt_pk_bf16_f32 v155, v156, v157
	v_cvt_pk_bf16_f32 v156, v158, v159
	v_cvt_pk_bf16_f32 v157, v160, v161
	s_lshl_b32 s3, s3, 5
	s_waitcnt lgkmcnt(0)
	v_mfma_f32_16x16x32_bf16 v[104:107], v[154:157], v[150:153], v[104:107]
	v_mul_f32_e64 v50, v50, v162
	v_mul_f32_e64 v51, v51, v163
	ds_read_b128 v[158:161], v116 offset:4480
	ds_read_b128 v[162:165], v116 offset:4496
	v_pk_mul_f32 v[40:41], v[40:41], v[108:109]
	v_add_u32_e32 v108, s3, v102
	s_nop 1
	v_cvt_pk_bf16_f32 v104, v104, v105
	v_lshl_add_u32 v105, v77, 1, v108
	ds_write_b16 v105, v104
	v_add3_u32 v105, v99, s3, v76
	ds_write_b16_d16_hi v105, v104 offset:272
	v_cvt_pk_bf16_f32 v104, v106, v107
	v_lshl_add_u32 v105, v100, 1, v108
	ds_write_b16 v105, v104
	v_add3_u32 v105, v101, s3, v76
	s_add_i32 s3, s36, 5
	v_pk_mul_f32 v[42:43], v[42:43], v[110:111]
	s_waitcnt lgkmcnt(4)
	v_pk_mul_f32 v[38:39], v[38:39], v[160:161]
	v_pk_mul_f32 v[36:37], v[36:37], v[158:159]
	s_waitcnt lgkmcnt(3)
	v_pk_mul_f32 v[34:35], v[34:35], v[164:165]
	v_pk_mul_f32 v[32:33], v[32:33], v[162:163]
	s_cmp_gt_u32 s3, 7
	ds_write_b16_d16_hi v105, v104 offset:272
	s_cbranch_scc1 .LBB0_1099
	v_lshl_or_b32 v104, s3, 4, v149
	v_mad_u64_u32 v[164:165], s[6:7], v104, s27, v[72:73]
	ds_read_b128 v[104:107], v164 offset:8192
	v_lshl_add_u32 v116, s3, 9, v103
	v_mul_f32_e32 v108, v92, v56
	v_mul_f32_e32 v109, v93, v57
	v_mul_f32_e32 v110, v94, v58
	v_mul_f32_e32 v111, v95, v59
	v_mul_f32_e32 v150, v96, v60
	v_mul_f32_e32 v151, v97, v61
	v_mul_f32_e32 v152, v98, v62
	v_mul_f32_e32 v153, v91, v63
	v_cvt_pk_bf16_f32 v108, v108, v109
	v_cvt_pk_bf16_f32 v109, v110, v111
	v_cvt_pk_bf16_f32 v110, v150, v151
	v_cvt_pk_bf16_f32 v111, v152, v153
	ds_read_b128 v[150:153], v116 offset:4096
	ds_read_b128 v[154:157], v116 offset:4112
	s_waitcnt lgkmcnt(2)
	v_mfma_f32_16x16x32_bf16 v[104:107], v[108:111], v[104:107], 0
	ds_read_b128 v[108:111], v164 offset:8256
	v_mul_f32_e32 v158, v85, v50
	s_waitcnt lgkmcnt(2)
	v_pk_mul_f32 v[58:59], v[58:59], v[152:153]
	v_pk_mul_f32 v[56:57], v[56:57], v[150:151]
	s_waitcnt lgkmcnt(1)
	v_pk_mul_f32 v[62:63], v[62:63], v[156:157]
	v_mul_f32_e32 v150, v89, v52
	v_mul_f32_e32 v151, v90, v53
	v_mul_f32_e32 v152, v86, v54
	v_mul_f32_e32 v153, v87, v55
	v_mul_f32_e32 v156, v88, v48
	v_mul_f32_e32 v157, v84, v49
	v_mul_f32_e32 v159, v83, v51
	v_cvt_pk_bf16_f32 v150, v150, v151
	v_cvt_pk_bf16_f32 v151, v152, v153
	v_cvt_pk_bf16_f32 v152, v156, v157
	v_cvt_pk_bf16_f32 v153, v158, v159
	ds_read_b128 v[156:159], v116 offset:4224
	ds_read_b128 v[160:163], v116 offset:4240
	s_waitcnt lgkmcnt(2)
	v_mfma_f32_16x16x32_bf16 v[104:107], v[150:153], v[108:111], v[104:107]
	ds_read_b128 v[108:111], v164 offset:8320
	v_pk_mul_f32 v[60:61], v[60:61], v[154:155]
	s_waitcnt lgkmcnt(2)
	v_pk_mul_f32 v[52:53], v[52:53], v[156:157]
	v_mul_f32_e32 v150, v82, v44
	v_mul_f32_e32 v151, v80, v45
	v_mul_f32_e32 v152, v81, v46
	v_mul_f32_e32 v153, v78, v47
	v_mul_f32_e32 v154, v79, v40
	v_mul_f32_e32 v155, v73, v41
	v_mul_f32_e32 v156, v74, v42
	v_mul_f32_e32 v157, v66, v43
	v_cvt_pk_bf16_f32 v150, v150, v151
	v_cvt_pk_bf16_f32 v151, v152, v153
	v_cvt_pk_bf16_f32 v152, v154, v155
	v_cvt_pk_bf16_f32 v153, v156, v157
	ds_read_b128 v[154:157], v116 offset:4352
	s_waitcnt lgkmcnt(1)
	v_mfma_f32_16x16x32_bf16 v[104:107], v[150:153], v[108:111], v[104:107]
	ds_read_b128 v[108:111], v116 offset:4368
	ds_read_b128 v[150:153], v164 offset:8384
	v_pk_mul_f32 v[54:55], v[54:55], v[158:159]
	v_pk_mul_f32 v[48:49], v[48:49], v[160:161]
	s_waitcnt lgkmcnt(2)
	v_pk_mul_f32 v[46:47], v[46:47], v[156:157]
	v_pk_mul_f32 v[44:45], v[44:45], v[154:155]
	v_mul_f32_e32 v154, v65, v36
	v_mul_f32_e32 v155, v64, v37
	v_mul_f32_e32 v156, v69, v38
	v_mul_f32_e32 v157, v67, v39
	v_mul_f32_e32 v158, v68, v32
	v_mul_f32_e32 v159, v71, v33
	v_mul_f32_e32 v160, v75, v34
	v_mul_f32_e32 v161, v70, v35
	v_cvt_pk_bf16_f32 v154, v154, v155
	v_cvt_pk_bf16_f32 v155, v156, v157
	v_cvt_pk_bf16_f32 v156, v158, v159
	v_cvt_pk_bf16_f32 v157, v160, v161
	s_lshl_b32 s3, s3, 5
	s_waitcnt lgkmcnt(0)
	v_mfma_f32_16x16x32_bf16 v[104:107], v[154:157], v[150:153], v[104:107]
	v_mul_f32_e64 v50, v50, v162
	v_mul_f32_e64 v51, v51, v163
	ds_read_b128 v[158:161], v116 offset:4480
	ds_read_b128 v[162:165], v116 offset:4496
	v_pk_mul_f32 v[40:41], v[40:41], v[108:109]
	v_add_u32_e32 v108, s3, v102
	s_nop 1
	v_cvt_pk_bf16_f32 v104, v104, v105
	v_lshl_add_u32 v105, v77, 1, v108
	ds_write_b16 v105, v104
	v_add3_u32 v105, v99, s3, v76
	ds_write_b16_d16_hi v105, v104 offset:272
	v_cvt_pk_bf16_f32 v104, v106, v107
	v_lshl_add_u32 v105, v100, 1, v108
	ds_write_b16 v105, v104
	v_add3_u32 v105, v101, s3, v76
	s_add_i32 s3, s36, 6
	v_pk_mul_f32 v[42:43], v[42:43], v[110:111]
	s_waitcnt lgkmcnt(4)
	v_pk_mul_f32 v[38:39], v[38:39], v[160:161]
	v_pk_mul_f32 v[36:37], v[36:37], v[158:159]
	s_waitcnt lgkmcnt(3)
	v_pk_mul_f32 v[34:35], v[34:35], v[164:165]
	v_pk_mul_f32 v[32:33], v[32:33], v[162:163]
	s_cmp_gt_u32 s3, 7
	ds_write_b16_d16_hi v105, v104 offset:272
	s_cbranch_scc1 .LBB0_1099
; __device__ __forceinline__ unsigned cvt_pk_c(float lo, float hi) { const f32x2_cv v = {lo, hi}; const bf16x2_cv b = __builtin_convertvector(v, bf16x2_cv); return __builtin_bit_cast(unsigned, b); }
; __device__ __forceinline__ bf16x8 pk8(const float* v) { u32x4 w; w.x = cvt_pk_bf16(v[0], v[1]); w.y = cvt_pk_bf16(v[2], v[3]); w.z = cvt_pk_bf16(v[4], v[5]); w.w = cvt_pk_bf16(v[6], v[7]); return __builtin_bit_cast(bf16x8, w); }
; template <int DIR> __device__ __forceinline__ void h3_dir(unsigned char* lds, const bf16_t* zrow, int h, const bf16_t* slot, f32x4 (&o)[8]) {
;     ...
;     for (int d = 1; d < 8; ++d) {
;         const int m = DIR ? wid + d : wid - d;
;         if (m < 0 || m > 7) break;
;         f32x4 sc = {0.f, 0.f, 0.f, 0.f};
; #pragma unroll
;         for (int ks = 0; ks < 4; ++ks) {
;             float tmp[8];
; #pragma unroll
;             for (int e = 0; e < 8; ++e) tmp[e] = qin[8 * ks + e] * run[8 * ks + e];
;             const bf16x8 bb = *(const bf16x8*)(KO + (16 * m + r) * HP + 32 * ks + 8 * kq);
;             sc = __builtin_amdgcn_mfma_f32_16x16x32_bf16(pk8(tmp), bb, sc, 0, 0, 0);
;             const f32x4 a = *(const f32x4*)(TOTE + m * 128 + 32 * ks + 8 * kq), b = *(const f32x4*)(TOTE + m * 128 + 32 * ks + 8 * kq + 4);
;             run[8 * ks] *= a[0]; run[8 * ks + 1] *= a[1]; run[8 * ks + 2] *= a[2]; run[8 * ks + 3] *= a[3]; run[8 * ks + 4] *= b[0]; run[8 * ks + 5] *= b[1]; run[8 * ks + 6] *= b[2]; run[8 * ks + 7] *= b[3];
;         }
; #pragma unroll
;         for (int i = 0; i < 4; i += 2) { const unsigned w = cvt_pk_c(sc[i], sc[i + 1]); Pw[(4 * kq + i) * HP + 16 * m + r] = (bf16_t)(w & 0xffffu); Pw[(4 * kq + i + 1) * HP + 16 * m + r] = (bf16_t)(w >> 16); }
;     }
	v_lshl_or_b32 v104, s3, 4, v149
	v_mad_u64_u32 v[164:165], s[6:7], v104, s27, v[72:73]
	ds_read_b128 v[104:107], v164 offset:8192
	v_lshl_add_u32 v116, s3, 9, v103
	v_mul_f32_e32 v108, v92, v56
	v_mul_f32_e32 v109, v93, v57
	v_mul_f32_e32 v110, v94, v58
	v_mul_f32_e32 v111, v95, v59
	v_mul_f32_e32 v150, v96, v60
	v_mul_f32_e32 v151, v97, v61
	v_mul_f32_e32 v152, v98, v62
	v_mul_f32_e32 v153, v91, v63
	v_cvt_pk_bf16_f32 v108, v108, v109
	v_cvt_pk_bf16_f32 v109, v110, v111
	v_cvt_pk_bf16_f32 v110, v150, v151
	v_cvt_pk_bf16_f32 v111, v152, v153
	ds_read_b128 v[150:153], v116 offset:4096
	ds_read_b128 v[154:157], v116 offset:4112
	s_waitcnt lgkmcnt(2)
	v_mfma_f32_16x16x32_bf16 v[104:107], v[108:111], v[104:107], 0
	ds_read_b128 v[108:111], v164 offset:8256
	v_mul_f32_e32 v158, v85, v50
	s_waitcnt lgkmcnt(2)
	v_pk_mul_f32 v[58:59], v[58:59], v[152:153]
	v_pk_mul_f32 v[56:57], v[56:57], v[150:151]
	s_waitcnt lgkmcnt(1)
	v_pk_mul_f32 v[62:63], v[62:63], v[156:157]
	v_mul_f32_e32 v150, v89, v52
	v_mul_f32_e32 v151, v90, v53
	v_mul_f32_e32 v152, v86, v54
	v_mul_f32_e32 v153, v87, v55
	v_mul_f32_e32 v156, v88, v48
	v_mul_f32_e32 v157, v84, v49
	v_mul_f32_e32 v159, v83, v51
	v_cvt_pk_bf16_f32 v150, v150, v151
	v_cvt_pk_bf16_f32 v151, v152, v153
	v_cvt_pk_bf16_f32 v152, v156, v157
	v_cvt_pk_bf16_f32 v153, v158, v159
	ds_read_b128 v[156:159], v116 offset:4224
	ds_read_b128 v[160:163], v116 offset:4240
	s_waitcnt lgkmcnt(2)
	v_mfma_f32_16x16x32_bf16 v[104:107], v[150:153], v[108:111], v[104:107]
	ds_read_b128 v[108:111], v164 offset:8320
	v_pk_mul_f32 v[60:61], v[60:61], v[154:155]
	s_waitcnt lgkmcnt(2)
	v_pk_mul_f32 v[52:53], v[52:53], v[156:157]
	v_mul_f32_e32 v150, v82, v44
	v_mul_f32_e32 v151, v80, v45
	v_mul_f32_e32 v152, v81, v46
	v_mul_f32_e32 v153, v78, v47
	v_mul_f32_e32 v154, v79, v40
	v_mul_f32_e32 v155, v73, v41
	v_mul_f32_e32 v156, v74, v42
	v_mul_f32_e32 v157, v66, v43
	v_cvt_pk_bf16_f32 v150, v150, v151
	v_cvt_pk_bf16_f32 v151, v152, v153
	v_cvt_pk_bf16_f32 v152, v154, v155
	v_cvt_pk_bf16_f32 v153, v156, v157
	ds_read_b128 v[154:157], v116 offset:4352
	s_waitcnt lgkmcnt(1)
	v_mfma_f32_16x16x32_bf16 v[104:107], v[150:153], v[108:111], v[104:107]
	ds_read_b128 v[108:111], v116 offset:4368
	ds_read_b128 v[150:153], v164 offset:8384
	v_pk_mul_f32 v[54:55], v[54:55], v[158:159]
	v_pk_mul_f32 v[48:49], v[48:49], v[160:161]
	s_waitcnt lgkmcnt(2)
	v_pk_mul_f32 v[46:47], v[46:47], v[156:157]
	v_pk_mul_f32 v[44:45], v[44:45], v[154:155]
	v_mul_f32_e32 v154, v65, v36
	v_mul_f32_e32 v155, v64, v37
	v_mul_f32_e32 v156, v69, v38
	v_mul_f32_e32 v157, v67, v39
	v_mul_f32_e32 v158, v68, v32
	v_mul_f32_e32 v159, v71, v33
	v_mul_f32_e32 v160, v75, v34
	v_mul_f32_e32 v161, v70, v35
	v_cvt_pk_bf16_f32 v154, v154, v155
	v_cvt_pk_bf16_f32 v155, v156, v157
	v_cvt_pk_bf16_f32 v156, v158, v159
	v_cvt_pk_bf16_f32 v157, v160, v161
	v_pk_mul_f32 v[50:51], v[50:51], v[162:163]
	s_waitcnt lgkmcnt(0)
	v_mfma_f32_16x16x32_bf16 v[104:107], v[154:157], v[150:153], v[104:107]
	ds_read_b128 v[158:161], v116 offset:4480
	ds_read_b128 v[162:165], v116 offset:4496
	s_lshl_b32 s3, s3, 5
	v_pk_mul_f32 v[40:41], v[40:41], v[108:109]
	v_add_u32_e32 v108, s3, v102
	s_nop 2
	v_cvt_pk_bf16_f32 v104, v104, v105
	v_lshl_add_u32 v105, v77, 1, v108
	ds_write_b16 v105, v104
	v_add3_u32 v105, v99, s3, v76
	ds_write_b16_d16_hi v105, v104 offset:272
	v_cvt_pk_bf16_f32 v104, v106, v107
	v_lshl_add_u32 v105, v100, 1, v108
	s_add_i32 s36, s36, 7
	v_pk_mul_f32 v[42:43], v[42:43], v[110:111]
	s_waitcnt lgkmcnt(3)
	v_pk_mul_f32 v[38:39], v[38:39], v[160:161]
	v_pk_mul_f32 v[36:37], v[36:37], v[158:159]
	s_waitcnt lgkmcnt(2)
	v_pk_mul_f32 v[34:35], v[34:35], v[164:165]
	v_pk_mul_f32 v[32:33], v[32:33], v[162:163]
	ds_write_b16 v105, v104
	v_add3_u32 v105, v101, s3, v76
	s_cmp_gt_u32 s36, 7
	ds_write_b16_d16_hi v105, v104 offset:272
	s_cbranch_scc1 .LBB0_1099
; __device__ __forceinline__ unsigned cvt_pk_c(float lo, float hi) { const f32x2_cv v = {lo, hi}; const bf16x2_cv b = __builtin_convertvector(v, bf16x2_cv); return __builtin_bit_cast(unsigned, b); }
; __device__ __forceinline__ bf16x8 pk8(const float* v) { u32x4 w; w.x = cvt_pk_bf16(v[0], v[1]); w.y = cvt_pk_bf16(v[2], v[3]); w.z = cvt_pk_bf16(v[4], v[5]); w.w = cvt_pk_bf16(v[6], v[7]); return __builtin_bit_cast(bf16x8, w); }
; template <int DIR> __device__ __forceinline__ void h3_dir(unsigned char* lds, const bf16_t* zrow, int h, const bf16_t* slot, f32x4 (&o)[8]) {
;     ...
;     for (int d = 1; d < 8; ++d) {
;         const int m = DIR ? wid + d : wid - d;
;         if (m < 0 || m > 7) break;
;         f32x4 sc = {0.f, 0.f, 0.f, 0.f};
; #pragma unroll
;         for (int ks = 0; ks < 4; ++ks) {
;             float tmp[8];
; #pragma unroll
;             for (int e = 0; e < 8; ++e) tmp[e] = qin[8 * ks + e] * run[8 * ks + e];
;             const bf16x8 bb = *(const bf16x8*)(KO + (16 * m + r) * HP + 32 * ks + 8 * kq);
;             sc = __builtin_amdgcn_mfma_f32_16x16x32_bf16(pk8(tmp), bb, sc, 0, 0, 0);
;             const f32x4 a = *(const f32x4*)(TOTE + m * 128 + 32 * ks + 8 * kq), b = *(const f32x4*)(TOTE + m * 128 + 32 * ks + 8 * kq + 4);
;             run[8 * ks] *= a[0]; run[8 * ks + 1] *= a[1]; run[8 * ks + 2] *= a[2]; run[8 * ks + 3] *= a[3]; run[8 * ks + 4] *= b[0]; run[8 * ks + 5] *= b[1]; run[8 * ks + 6] *= b[2]; run[8 * ks + 7] *= b[3];
;         }
; #pragma unroll
;         for (int i = 0; i < 4; i += 2) { const unsigned w = cvt_pk_c(sc[i], sc[i + 1]); Pw[(4 * kq + i) * HP + 16 * m + r] = (bf16_t)(w & 0xffffu); Pw[(4 * kq + i + 1) * HP + 16 * m + r] = (bf16_t)(w >> 16); }
;     }
	v_lshl_or_b32 v104, s36, 4, v149
	v_mad_u64_u32 v[164:165], s[6:7], v104, s27, v[72:73]
	ds_read_b128 v[104:107], v164 offset:8192
	v_lshl_add_u32 v103, s36, 9, v103
	v_mul_f32_e32 v108, v92, v56
	v_mul_f32_e32 v109, v93, v57
	v_mul_f32_e32 v110, v94, v58
	v_mul_f32_e32 v111, v95, v59
	v_mul_f32_e32 v150, v97, v61
	v_mul_f32_e32 v151, v98, v62
	v_mul_f32_e32 v152, v91, v63
	v_mul_f32_e32 v116, v96, v60
	v_cvt_pk_bf16_f32 v108, v108, v109
	v_cvt_pk_bf16_f32 v109, v110, v111
	v_cvt_pk_bf16_f32 v110, v116, v150
	v_cvt_pk_bf16_f32 v111, v151, v152
	ds_read_b128 v[150:153], v103 offset:4096
	ds_read_b128 v[154:157], v103 offset:4112
	s_waitcnt lgkmcnt(2)
	v_mfma_f32_16x16x32_bf16 v[104:107], v[108:111], v[104:107], 0
	ds_read_b128 v[108:111], v164 offset:8256
	v_mul_f32_e32 v158, v83, v51
	s_waitcnt lgkmcnt(2)
	v_pk_mul_f32 v[58:59], v[58:59], v[152:153]
	v_pk_mul_f32 v[56:57], v[56:57], v[150:151]
	s_waitcnt lgkmcnt(1)
	v_pk_mul_f32 v[62:63], v[62:63], v[156:157]
	v_mul_f32_e32 v150, v90, v53
	v_mul_f32_e32 v151, v86, v54
	v_mul_f32_e32 v152, v87, v55
	v_mul_f32_e32 v153, v88, v48
	v_mul_f32_e32 v156, v84, v49
	v_mul_f32_e32 v157, v85, v50
	v_mul_f32_e32 v116, v89, v52
	v_cvt_pk_bf16_f32 v150, v116, v150
	v_cvt_pk_bf16_f32 v151, v151, v152
	v_cvt_pk_bf16_f32 v152, v153, v156
	v_cvt_pk_bf16_f32 v153, v157, v158
	ds_read_b128 v[156:159], v103 offset:4224
	ds_read_b128 v[160:163], v103 offset:4240
	s_waitcnt lgkmcnt(2)
	v_mfma_f32_16x16x32_bf16 v[104:107], v[150:153], v[108:111], v[104:107]
	ds_read_b128 v[108:111], v164 offset:8320
	v_pk_mul_f32 v[60:61], v[60:61], v[154:155]
	s_waitcnt lgkmcnt(2)
	v_pk_mul_f32 v[52:53], v[52:53], v[156:157]
	v_mul_f32_e32 v150, v80, v45
	v_mul_f32_e32 v151, v81, v46
	v_mul_f32_e32 v152, v78, v47
	v_mul_f32_e32 v153, v79, v40
	v_mul_f32_e32 v154, v73, v41
	v_mul_f32_e32 v155, v74, v42
	v_mul_f32_e32 v156, v66, v43
	v_mul_f32_e32 v116, v82, v44
	v_cvt_pk_bf16_f32 v150, v116, v150
	v_cvt_pk_bf16_f32 v151, v151, v152
	v_cvt_pk_bf16_f32 v152, v153, v154
	v_cvt_pk_bf16_f32 v153, v155, v156
	ds_read_b128 v[154:157], v103 offset:4352
	s_waitcnt lgkmcnt(1)
	v_mfma_f32_16x16x32_bf16 v[104:107], v[150:153], v[108:111], v[104:107]
	ds_read_b128 v[108:111], v103 offset:4368
	ds_read_b128 v[150:153], v164 offset:8384
	v_pk_mul_f32 v[54:55], v[54:55], v[158:159]
	v_pk_mul_f32 v[48:49], v[48:49], v[160:161]
	s_waitcnt lgkmcnt(2)
	v_pk_mul_f32 v[46:47], v[46:47], v[156:157]
	v_pk_mul_f32 v[44:45], v[44:45], v[154:155]
	v_mul_f32_e32 v154, v64, v37
	v_mul_f32_e32 v155, v69, v38
	v_mul_f32_e32 v156, v67, v39
	v_mul_f32_e32 v157, v68, v32
	v_mul_f32_e32 v116, v65, v36
	v_mul_f32_e32 v158, v71, v33
	v_mul_f32_e32 v159, v75, v34
	v_mul_f32_e32 v160, v70, v35
	v_cvt_pk_bf16_f32 v154, v116, v154
	v_cvt_pk_bf16_f32 v155, v155, v156
	v_cvt_pk_bf16_f32 v156, v157, v158
	v_cvt_pk_bf16_f32 v157, v159, v160
	v_pk_mul_f32 v[50:51], v[50:51], v[162:163]
	s_waitcnt lgkmcnt(0)
	v_mfma_f32_16x16x32_bf16 v[104:107], v[154:157], v[150:153], v[104:107]
	ds_read_b128 v[158:161], v103 offset:4480
	ds_read_b128 v[162:165], v103 offset:4496
	s_lshl_b32 s3, s36, 5
	v_add_u32_e32 v102, s3, v102
	v_lshl_add_u32 v77, v77, 1, v102
	s_nop 2
	v_cvt_pk_bf16_f32 v103, v104, v105
	ds_write_b16 v77, v103
	v_add3_u32 v77, v99, s3, v76
	v_pk_mul_f32 v[42:43], v[42:43], v[110:111]
	v_pk_mul_f32 v[40:41], v[40:41], v[108:109]
	s_waitcnt lgkmcnt(2)
	v_pk_mul_f32 v[38:39], v[38:39], v[160:161]
	v_pk_mul_f32 v[36:37], v[36:37], v[158:159]
	s_waitcnt lgkmcnt(1)
	v_pk_mul_f32 v[34:35], v[34:35], v[164:165]
	v_pk_mul_f32 v[32:33], v[32:33], v[162:163]
	ds_write_b16_d16_hi v77, v103 offset:272
	v_cvt_pk_bf16_f32 v77, v106, v107
	v_lshl_add_u32 v99, v100, 1, v102
	v_add3_u32 v76, v101, s3, v76
	ds_write_b16 v99, v77
	ds_write_b16_d16_hi v76, v77 offset:272
	s_branch .LBB0_1099

; __device__ __forceinline__ u32x4 pack8(const f32x4 a, const f32x4 b) { u32x4 w; w.x = cvt_pk_bf16(a[0], a[1]); w.y = cvt_pk_bf16(a[2], a[3]); w.z = cvt_pk_bf16(b[0], b[1]); w.w = cvt_pk_bf16(b[2], b[3]); return w; }
; __device__ __forceinline__ void cvt_f32_bf16(const float* src, bf16_t* dst, size_t n, size_t gt, size_t GT) {
;     for (size_t i = gt * 8; i < n; i += GT * 8) { const f32x4 a = *(const f32x4*)(src + i), b = *(const f32x4*)(src + i + 4); *(u32x4*)(dst + i) = pack8(a, b); }
; }
.LBB0_1569:
	s_ashr_i32 s11, s10, 31
	v_ashrrev_i32_e32 v1, 31, v0
	s_lshl_b64 s[4:5], s[10:11], 12
	v_lshl_add_u64 v[2:3], v[0:1], 3, s[4:5]
	s_mov_b64 s[4:5], 0x800000
	v_cmp_gt_u64_e32 vcc, s[4:5], v[2:3]
	s_and_saveexec_b64 s[4:5], vcc
	s_cbranch_execz .LBB0_1572
	s_ashr_i32 s9, s8, 31
	s_load_dwordx2 s[16:17], s[12:13], 0x8
	s_lshl_b64 s[6:7], s[8:9], 12
	s_lshl_b64 s[12:13], s[10:11], 13
	s_waitcnt lgkmcnt(0)
	s_add_u32 s12, s14, s12
	s_addc_u32 s13, s15, s13
	v_lshl_add_u64 v[4:5], v[0:1], 4, s[12:13]
	s_mov_b64 s[12:13], 0x1e800000
	v_lshl_add_u64 v[4:5], v[4:5], 0, s[12:13]
	s_lshl_b64 s[12:13], s[8:9], 13
	s_lshl_b64 s[10:11], s[10:11], 14
	s_add_u32 s10, s16, s10
	v_lshlrev_b64 v[0:1], 5, v[0:1]
	s_addc_u32 s11, s17, s11
	v_lshl_add_u64 v[0:1], s[10:11], 0, v[0:1]
	s_mov_b64 s[10:11], 0x4000010
	v_lshl_add_u64 v[0:1], v[0:1], 0, s[10:11]
	s_lshl_b64 s[8:9], s[8:9], 14
	s_mov_b64 s[10:11], 0
	s_mov_b64 s[14:15], 0x7fffff
	s_lshl_b64 s[50:51], s[8:9], 1
	s_add_u32 s52, s50, s8
	s_addc_u32 s53, s51, s9
	s_lshl_b64 s[54:55], s[12:13], 1
	s_add_u32 s56, s54, s12
	s_addc_u32 s57, s55, s13
	s_lshl_b64 s[58:59], s[6:7], 1
	s_add_u32 s60, s58, s6
	s_addc_u32 s61, s59, s7
	s_lshl_b64 s[62:63], s[6:7], 2
	s_lshl_b64 s[64:65], s[8:9], 2
	s_lshl_b64 s[66:67], s[12:13], 2
.Lcvt4_top_p2:
	v_lshl_add_u64 v[200:201], v[2:3], 0, s[60:61]
	v_cmp_ge_u64_e32 vcc, s[14:15], v[200:201]
	s_cmp_eq_u64 vcc, exec
	s_cbranch_scc0 .Lcvt4_rem_p2
	v_lshl_add_u64 v[202:203], v[0:1], 0, s[8:9]
	v_lshl_add_u64 v[204:205], v[0:1], 0, s[50:51]
	v_lshl_add_u64 v[206:207], v[0:1], 0, s[52:53]
	global_load_dwordx4 v[208:211], v[0:1], off offset:-16
	global_load_dwordx4 v[212:215], v[0:1], off
	global_load_dwordx4 v[216:219], v[202:203], off offset:-16
	global_load_dwordx4 v[220:223], v[202:203], off
	global_load_dwordx4 v[224:227], v[204:205], off offset:-16
	global_load_dwordx4 v[228:231], v[204:205], off
	global_load_dwordx4 v[232:235], v[206:207], off offset:-16
	global_load_dwordx4 v[236:239], v[206:207], off
	v_lshl_add_u64 v[240:241], v[4:5], 0, s[12:13]
	v_lshl_add_u64 v[242:243], v[4:5], 0, s[54:55]
	v_lshl_add_u64 v[244:245], v[4:5], 0, s[56:57]
	s_waitcnt vmcnt(6)
	v_cvt_pk_bf16_f32 v208, v208, v209
	v_cvt_pk_bf16_f32 v209, v210, v211
	v_cvt_pk_bf16_f32 v210, v212, v213
	v_cvt_pk_bf16_f32 v211, v214, v215
	global_store_dwordx4 v[4:5], v[208:211], off
	s_waitcnt vmcnt(5)
	v_cvt_pk_bf16_f32 v216, v216, v217
	v_cvt_pk_bf16_f32 v217, v218, v219
	v_cvt_pk_bf16_f32 v218, v220, v221
	v_cvt_pk_bf16_f32 v219, v222, v223
	global_store_dwordx4 v[240:241], v[216:219], off
	s_waitcnt vmcnt(4)
	v_cvt_pk_bf16_f32 v224, v224, v225
	v_cvt_pk_bf16_f32 v225, v226, v227
	v_cvt_pk_bf16_f32 v226, v228, v229
	v_cvt_pk_bf16_f32 v227, v230, v231
	global_store_dwordx4 v[242:243], v[224:227], off
	s_waitcnt vmcnt(3)
	v_cvt_pk_bf16_f32 v232, v232, v233
	v_cvt_pk_bf16_f32 v233, v234, v235
	v_cvt_pk_bf16_f32 v234, v236, v237
	v_cvt_pk_bf16_f32 v235, v238, v239
	global_store_dwordx4 v[244:245], v[232:235], off
	v_lshl_add_u64 v[0:1], v[0:1], 0, s[64:65]
	v_lshl_add_u64 v[4:5], v[4:5], 0, s[66:67]
	v_lshl_add_u64 v[2:3], v[2:3], 0, s[62:63]
	v_cmp_ge_u64_e32 vcc, s[14:15], v[2:3]
	s_cbranch_vccnz .Lcvt4_top_p2
	s_branch .LBB0_1572
.Lcvt4_rem_p2:
	v_cmp_ge_u64_e32 vcc, s[14:15], v[2:3]
	s_and_b64 exec, exec, vcc
	s_cbranch_execz .LBB0_1572

; __device__ __forceinline__ u32x4 pack8(const f32x4 a, const f32x4 b) { u32x4 w; w.x = cvt_pk_bf16(a[0], a[1]); w.y = cvt_pk_bf16(a[2], a[3]); w.z = cvt_pk_bf16(b[0], b[1]); w.w = cvt_pk_bf16(b[2], b[3]); return w; }
; __device__ __forceinline__ void cvt_f32_bf16(const float* src, bf16_t* dst, size_t n, size_t gt, size_t GT) {
;     for (size_t i = gt * 8; i < n; i += GT * 8) { const f32x4 a = *(const f32x4*)(src + i), b = *(const f32x4*)(src + i + 4); *(u32x4*)(dst + i) = pack8(a, b); }
; }
.LBB0_2219:
	s_ashr_i32 s9, s8, 31
	s_lshl_b64 s[4:5], s[8:9], 9
	v_ashrrev_i32_e32 v1, 31, v0
	v_lshl_add_u64 v[2:3], s[4:5], 0, v[0:1]
	v_lshlrev_b64 v[4:5], 3, v[2:3]
	s_mov_b64 s[4:5], 0x800000
	s_ashr_i32 s7, s6, 31
	v_cmp_gt_u64_e32 vcc, s[4:5], v[4:5]
	s_and_saveexec_b64 s[4:5], vcc
	s_cbranch_execz .LBB0_2222
	s_load_dwordx2 s[18:19], s[10:11], 0x8
	s_lshl_b64 s[14:15], s[6:7], 12
	s_lshl_b64 s[16:17], s[8:9], 13
	s_waitcnt lgkmcnt(0)
	s_add_u32 s16, s12, s16
	s_addc_u32 s17, s13, s17
	v_lshl_add_u64 v[6:7], v[0:1], 4, s[16:17]
	s_mov_b64 s[16:17], 0x1e800000
	v_lshl_add_u64 v[6:7], v[6:7], 0, s[16:17]
	s_lshl_b64 s[16:17], s[6:7], 13
	s_lshl_b64 s[20:21], s[8:9], 14
	s_add_u32 s18, s18, s20
	v_lshlrev_b64 v[8:9], 5, v[0:1]
	s_addc_u32 s19, s19, s21
	v_lshl_add_u64 v[8:9], s[18:19], 0, v[8:9]
	s_mov_b64 s[18:19], 0x6000010
	v_lshl_add_u64 v[8:9], v[8:9], 0, s[18:19]
	s_lshl_b64 s[18:19], s[6:7], 14
	s_mov_b64 s[20:21], 0
	s_mov_b64 s[22:23], 0x7fffff
	s_lshl_b64 s[50:51], s[18:19], 1
	s_add_u32 s52, s50, s18
	s_addc_u32 s53, s51, s19
	s_lshl_b64 s[54:55], s[16:17], 1
	s_add_u32 s56, s54, s16
	s_addc_u32 s57, s55, s17
	s_lshl_b64 s[58:59], s[14:15], 1
	s_add_u32 s60, s58, s14
	s_addc_u32 s61, s59, s15
	s_lshl_b64 s[62:63], s[14:15], 2
	s_lshl_b64 s[64:65], s[18:19], 2
	s_lshl_b64 s[66:67], s[16:17], 2

; __device__ __forceinline__ bf16x8 pk8(const float* v) { u32x4 w; w.x = cvt_pk_bf16(v[0], v[1]); w.y = cvt_pk_bf16(v[2], v[3]); w.z = cvt_pk_bf16(v[4], v[5]); w.w = cvt_pk_bf16(v[6], v[7]); return __builtin_bit_cast(bf16x8, w); }
; #define WAVE_LDS_FENCE() do { asm volatile("s_waitcnt lgkmcnt(0)" ::: "memory"); __builtin_amdgcn_wave_barrier(); } while (0)
; template <int DIR> __device__ __forceinline__ void h3_dir(unsigned char* lds, const bf16_t* zrow, int h, const bf16_t* slot, f32x4 (&o)[8]) {
;     ...
; #pragma unroll
;     for (int i = 0; i < 32; ++i) qin[i] *= run[i];
;     WAVE_LDS_FENCE();
; #pragma unroll
;     for (int ks = 0; ks < 4; ++ks) {
;         const bf16x8 aq = pk8(qin + 8 * ks), ap = *(const bf16x8*)(Pw + r * HP + 32 * ks + 8 * kq);
; #pragma unroll
;         for (int nt = 0; nt < 8; ++nt) {
;             o[nt] = __builtin_amdgcn_mfma_f32_16x16x32_bf16(aq, *(const bf16x8*)(ST + (16 * nt + r) * HP + 32 * ks + 8 * kq), o[nt], 0, 0, 0);
;             o[nt] = __builtin_amdgcn_mfma_f32_16x16x32_bf16(ap, *(const bf16x8*)(VT + (16 * nt + r) * HP + 32 * ks + 8 * kq), o[nt], 0, 0, 0);
;         }
;     }
.LBB0_2608:
	v_mul_u32_u24_e32 v77, 0x88, v149
	v_lshlrev_b32_e32 v77, 1, v77
	v_mul_f32_e32 v56, v92, v56
	v_mul_f32_e32 v57, v93, v57
	v_mul_f32_e32 v58, v94, v58
	v_mul_f32_e32 v59, v95, v59
	v_mul_f32_e32 v60, v96, v60
	v_mul_f32_e32 v61, v97, v61
	v_mul_f32_e32 v62, v98, v62
	v_mul_f32_e32 v63, v91, v63
	v_lshlrev_b32_e32 v76, 1, v148
	v_add_u32_e32 v72, v72, v77
	v_mul_u32_u24_e32 v91, 0x110, v149
	s_waitcnt lgkmcnt(0)
	v_cvt_pk_bf16_f32 v56, v56, v57
	v_cvt_pk_bf16_f32 v57, v58, v59
	v_cvt_pk_bf16_f32 v58, v60, v61
	v_cvt_pk_bf16_f32 v59, v62, v63
	ds_read_b128 v[60:63], v72 offset:43008
	v_add3_u32 v108, s4, v91, v76
	ds_read_b128 v[92:95], v108
	v_add3_u32 v76, s35, v76, v77
	v_add_u32_e32 v77, 0xa800, v72
	ds_read_b128 v[96:99], v77 offset:30464
	s_waitcnt lgkmcnt(2)
	v_mfma_f32_16x16x32_bf16 v[24:27], v[56:59], v[60:63], v[24:27]
	ds_read_b128 v[60:63], v76
	v_mul_f32_e32 v52, v89, v52
	v_mul_f32_e32 v53, v90, v53
	s_waitcnt lgkmcnt(0)
	v_mfma_f32_16x16x32_bf16 v[24:27], v[92:95], v[60:63], v[24:27]
	ds_read_b128 v[60:63], v72 offset:47360
	ds_read_b128 v[100:103], v72 offset:51712
	v_mul_f32_e32 v54, v86, v54
	v_mul_f32_e32 v55, v87, v55
	s_waitcnt lgkmcnt(1)
	v_mfma_f32_16x16x32_bf16 v[0:3], v[56:59], v[60:63], v[0:3]
	ds_read_b128 v[60:63], v76 offset:4352
	ds_read_b128 v[104:107], v76 offset:8704
	v_mul_f32_e32 v78, v78, v47
	v_mul_f32_e32 v43, v66, v43
	s_waitcnt lgkmcnt(1)
	v_mfma_f32_16x16x32_bf16 v[0:3], v[92:95], v[60:63], v[0:3]
	v_mul_f32_e32 v79, v79, v40
	v_mul_f32_e32 v65, v65, v36
	v_add_u32_e32 v36, 0xa880, v72
	v_mfma_f32_16x16x32_bf16 v[4:7], v[56:59], v[100:103], v[4:7]
	ds_read_b128 v[60:63], v72 offset:56064
	ds_read_b128 v[100:103], v72 offset:60416
	v_mul_f32_e32 v64, v64, v37
	v_mul_f32_e32 v66, v69, v38
	s_waitcnt lgkmcnt(2)
	v_mfma_f32_16x16x32_bf16 v[4:7], v[92:95], v[104:107], v[4:7]
	v_mul_f32_e32 v67, v67, v39
	v_mul_f32_e32 v68, v68, v32
	s_add_i32 s17, s17, s16
	s_waitcnt lgkmcnt(1)
	v_mfma_f32_16x16x32_bf16 v[8:11], v[56:59], v[60:63], v[8:11]
	ds_read_b128 v[60:63], v76 offset:13056
	ds_read_b128 v[104:107], v76 offset:17408
	s_cmpk_lt_i32 s17, 0x800
	s_waitcnt lgkmcnt(1)
	v_mfma_f32_16x16x32_bf16 v[8:11], v[92:95], v[60:63], v[8:11]
	v_mfma_f32_16x16x32_bf16 v[12:15], v[56:59], v[100:103], v[12:15]
	ds_read_b128 v[60:63], v72 offset:64768
	ds_read_b128 v[100:103], v77 offset:26112
	v_mul_f32_e32 v77, v82, v44
	s_waitcnt lgkmcnt(2)
	v_mfma_f32_16x16x32_bf16 v[12:15], v[92:95], v[104:107], v[12:15]
	s_waitcnt lgkmcnt(1)
	v_mfma_f32_16x16x32_bf16 v[16:19], v[56:59], v[60:63], v[16:19]
	ds_read_b128 v[60:63], v76 offset:21760
	ds_read_b128 v[104:107], v76 offset:26112
	s_waitcnt lgkmcnt(1)
	v_mfma_f32_16x16x32_bf16 v[16:19], v[92:95], v[60:63], v[16:19]
	v_mul_f32_e32 v60, v88, v48
	v_mul_f32_e32 v61, v84, v49
	v_mul_f32_e32 v62, v85, v50
	v_mul_f32_e32 v63, v83, v51
	ds_read_b128 v[48:51], v76 offset:30464
	v_mfma_f32_16x16x32_bf16 v[28:31], v[56:59], v[96:99], v[28:31]
	v_cvt_pk_bf16_f32 v52, v52, v53
	v_cvt_pk_bf16_f32 v53, v54, v55
	v_cvt_pk_bf16_f32 v54, v60, v61
	v_mfma_f32_16x16x32_bf16 v[20:23], v[56:59], v[100:103], v[20:23]
	v_cvt_pk_bf16_f32 v55, v62, v63
	ds_read_b128 v[56:59], v72 offset:43072
	s_waitcnt lgkmcnt(1)
	v_mfma_f32_16x16x32_bf16 v[28:31], v[92:95], v[48:51], v[28:31]
	ds_read_b128 v[48:51], v108 offset:64
	s_waitcnt lgkmcnt(1)
	v_mfma_f32_16x16x32_bf16 v[24:27], v[52:55], v[56:59], v[24:27]
	ds_read_b128 v[56:59], v76 offset:64
	ds_read_b128 v[60:63], v72 offset:64832
	s_waitcnt lgkmcnt(1)
	v_mfma_f32_16x16x32_bf16 v[24:27], v[48:51], v[56:59], v[24:27]
	ds_read_b128 v[56:59], v72 offset:47424
	ds_read_b128 v[84:87], v72 offset:51776
	s_waitcnt lgkmcnt(1)
	v_mfma_f32_16x16x32_bf16 v[0:3], v[52:55], v[56:59], v[0:3]
	ds_read_b128 v[56:59], v76 offset:4416
	ds_read_b128 v[88:91], v76 offset:8768
	s_waitcnt lgkmcnt(1)
	v_mfma_f32_16x16x32_bf16 v[0:3], v[48:51], v[56:59], v[0:3]
	v_mfma_f32_16x16x32_bf16 v[4:7], v[52:55], v[84:87], v[4:7]
	ds_read_b128 v[56:59], v72 offset:56128
	ds_read_b128 v[84:87], v72 offset:60480
	s_waitcnt lgkmcnt(2)
	v_mfma_f32_16x16x32_bf16 v[4:7], v[48:51], v[88:91], v[4:7]
	s_waitcnt lgkmcnt(1)
	v_mfma_f32_16x16x32_bf16 v[8:11], v[52:55], v[56:59], v[8:11]
	ds_read_b128 v[56:59], v76 offset:13120
	ds_read_b128 v[88:91], v76 offset:17472
	s_waitcnt lgkmcnt(1)
	v_mfma_f32_16x16x32_bf16 v[8:11], v[48:51], v[56:59], v[8:11]
	ds_read_b128 v[56:59], v76 offset:21824
	v_mfma_f32_16x16x32_bf16 v[16:19], v[52:55], v[60:63], v[16:19]
	v_mfma_f32_16x16x32_bf16 v[12:15], v[52:55], v[84:87], v[12:15]
	v_add_u32_e32 v86, 0xa840, v72
	v_mul_f32_e32 v84, v80, v45
	v_mul_f32_e32 v85, v81, v46
	ds_read_b128 v[60:63], v86 offset:26112
	ds_read_b128 v[80:83], v76 offset:26176
	s_waitcnt lgkmcnt(2)
	v_mfma_f32_16x16x32_bf16 v[16:19], v[48:51], v[56:59], v[16:19]
	ds_read_b128 v[44:47], v76 offset:30528
	ds_read_b128 v[56:59], v86 offset:30464
	v_cvt_pk_bf16_f32 v40, v77, v84
	v_mfma_f32_16x16x32_bf16 v[20:23], v[92:95], v[104:107], v[20:23]
	s_waitcnt lgkmcnt(0)
	v_mfma_f32_16x16x32_bf16 v[28:31], v[52:55], v[56:59], v[28:31]
	v_mfma_f32_16x16x32_bf16 v[20:23], v[52:55], v[60:63], v[20:23]
	v_mul_f32_e32 v60, v73, v41
	v_mul_f32_e32 v61, v74, v42
	v_cvt_pk_bf16_f32 v41, v85, v78
	v_cvt_pk_bf16_f32 v42, v79, v60
	v_cvt_pk_bf16_f32 v43, v61, v43
	ds_read_b128 v[52:55], v72 offset:43136
	v_mfma_f32_16x16x32_bf16 v[28:31], v[48:51], v[44:47], v[28:31]
	ds_read_b128 v[44:47], v108 offset:128
	v_mfma_f32_16x16x32_bf16 v[12:15], v[48:51], v[88:91], v[12:15]
	v_mfma_f32_16x16x32_bf16 v[20:23], v[48:51], v[80:83], v[20:23]
	s_waitcnt lgkmcnt(1)
; template <int DIR> __device__ __forceinline__ void h3_dir(unsigned char* lds, const bf16_t* zrow, int h, const bf16_t* slot, f32x4 (&o)[8]) {
;     ...
;     for (int ks = 0; ks < 4; ++ks) {
;         const bf16x8 aq = pk8(qin + 8 * ks), ap = *(const bf16x8*)(Pw + r * HP + 32 * ks + 8 * kq);
; #pragma unroll
;         for (int nt = 0; nt < 8; ++nt) {
;             o[nt] = __builtin_amdgcn_mfma_f32_16x16x32_bf16(aq, *(const bf16x8*)(ST + (16 * nt + r) * HP + 32 * ks + 8 * kq), o[nt], 0, 0, 0);
;             o[nt] = __builtin_amdgcn_mfma_f32_16x16x32_bf16(ap, *(const bf16x8*)(VT + (16 * nt + r) * HP + 32 * ks + 8 * kq), o[nt], 0, 0, 0);
;         }
;     }
;     __syncthreads();
; }
; template <bool STORE> __device__ __forceinline__ void h3_phase(unsigned char* lds, unsigned char* ws, const bf16_t* SF, const float* norm_g, int G, int blk) {
;     int tid_l = threadIdx.x; asm volatile("" : "+v"(tid_l)); const int tid = tid_l, lane = tid & 63, wid = __builtin_amdgcn_readfirstlane(tid >> 6), r = lane & 15, kq = lane >> 4;
;     bf16_t* Z = (bf16_t*)(ws + WS_Z); bf16_t* VT = (bf16_t*)(lds + L_VT); float* STGF = (float*)(lds + L_KO) + wid * 16 * 132;
;     for (int unit = blk; unit < 2048; unit += G) {
;         const int b = unit >> 10, c = (unit >> 3) & 127, h = unit & 7, chain = b * 8 + h;
;         const size_t tok0 = (size_t)b * SEQ + c * 128 + 16 * wid;
;         const bf16_t* zrow = Z + ((size_t)h * M + tok0 + r) * 128;
;         {
; #pragma unroll
;           for (int ks = 0; ks < 4; ++ks) { const u32x4 w = *(const u32x4*)(zrow + 3 * ZSEG + 8 * kq + 32 * ks);
; #pragma unroll
;               for (int e = 0; e < 4; ++e) { VT[(32 * ks + 8 * kq + 2 * e) * HP + 16 * wid + r] = (bf16_t)(w[e] & 0xffffu); VT[(32 * ks + 8 * kq + 2 * e + 1) * HP + 16 * wid + r] = (bf16_t)(w[e] >> 16); } } }
;         f32x4 o[8];
; #pragma unroll
;         for (int nt = 0; nt < 8; ++nt) o[nt] = (f32x4){0.f, 0.f, 0.f, 0.f};
;         h3_dir<0>(lds, zrow, h, SF + ((size_t)chain * 128 + c) * 16384, o);
;         h3_dir<1>(lds, zrow, h, (const bf16_t*)(ws + WS_SB) + ((size_t)chain * 128 + c) * 16384, o);
;         float ssq[4];
; #pragma unroll
;         for (int i = 0; i < 4; ++i) { float s = 0.f;
; #pragma unroll
;             for (int nt = 0; nt < 8; ++nt) s += o[nt][i] * o[nt][i];
;             s += __shfl_xor(s, 1); s += __shfl_xor(s, 2); s += __shfl_xor(s, 4); s += __shfl_xor(s, 8);
	v_mfma_f32_16x16x32_bf16 v[24:27], v[40:43], v[52:55], v[24:27]
	ds_read_b128 v[48:51], v76 offset:128
	ds_read_b128 v[52:55], v72 offset:64896
	s_waitcnt lgkmcnt(1)
	v_mfma_f32_16x16x32_bf16 v[24:27], v[44:47], v[48:51], v[24:27]
	ds_read_b128 v[48:51], v72 offset:47488
	ds_read_b128 v[56:59], v72 offset:51840
	s_waitcnt lgkmcnt(1)
	v_mfma_f32_16x16x32_bf16 v[0:3], v[40:43], v[48:51], v[0:3]
	ds_read_b128 v[48:51], v76 offset:4480
	ds_read_b128 v[60:63], v76 offset:8832
	s_waitcnt lgkmcnt(1)
	v_mfma_f32_16x16x32_bf16 v[0:3], v[44:47], v[48:51], v[0:3]
	v_mfma_f32_16x16x32_bf16 v[4:7], v[40:43], v[56:59], v[4:7]
	ds_read_b128 v[48:51], v72 offset:56192
	ds_read_b128 v[56:59], v72 offset:60544
	s_waitcnt lgkmcnt(2)
	v_mfma_f32_16x16x32_bf16 v[4:7], v[44:47], v[60:63], v[4:7]
	s_waitcnt lgkmcnt(1)
	v_mfma_f32_16x16x32_bf16 v[8:11], v[40:43], v[48:51], v[8:11]
	ds_read_b128 v[48:51], v76 offset:13184
	ds_read_b128 v[60:63], v76 offset:17536
	s_waitcnt lgkmcnt(1)
	v_mfma_f32_16x16x32_bf16 v[48:51], v[44:47], v[48:51], v[8:11]
	v_mfma_f32_16x16x32_bf16 v[8:11], v[40:43], v[56:59], v[12:15]
	s_waitcnt lgkmcnt(0)
	v_mfma_f32_16x16x32_bf16 v[56:59], v[44:47], v[60:63], v[8:11]
	v_mfma_f32_16x16x32_bf16 v[12:15], v[40:43], v[52:55], v[16:19]
	s_nop 4
	ds_read_b128 v[8:11], v76 offset:21888
	ds_read_b128 v[16:19], v36 offset:26112
	ds_read_b128 v[52:55], v76 offset:26240
	s_waitcnt lgkmcnt(2)
	v_mfma_f32_16x16x32_bf16 v[60:63], v[44:47], v[8:11], v[12:15]
	ds_read_b128 v[8:11], v76 offset:30592
	s_waitcnt lgkmcnt(2)
	v_mfma_f32_16x16x32_bf16 v[12:15], v[40:43], v[16:19], v[20:23]
	ds_read_b128 v[16:19], v36 offset:30464
	v_cvt_pk_bf16_f32 v32, v65, v64
	s_waitcnt lgkmcnt(2)
	v_mfma_f32_16x16x32_bf16 v[36:39], v[44:47], v[52:55], v[12:15]
	v_mul_f32_e32 v20, v71, v33
	v_mul_f32_e32 v21, v75, v34
	v_mul_f32_e32 v22, v70, v35
	v_cvt_pk_bf16_f32 v33, v66, v67
	s_waitcnt lgkmcnt(0)
	v_mfma_f32_16x16x32_bf16 v[12:15], v[40:43], v[16:19], v[28:31]
	v_cvt_pk_bf16_f32 v34, v68, v20
	v_cvt_pk_bf16_f32 v35, v21, v22
	ds_read_b128 v[16:19], v72 offset:43200
	ds_read_b128 v[40:43], v108 offset:192
	v_mfma_f32_16x16x32_bf16 v[28:31], v[44:47], v[8:11], v[12:15]
	v_add_u32_e32 v52, 0xa8c0, v72
	s_waitcnt lgkmcnt(1)
	v_mfma_f32_16x16x32_bf16 v[8:11], v[32:35], v[16:19], v[24:27]
	s_nop 1
	ds_read_b128 v[12:15], v76 offset:192
	ds_read_b128 v[16:19], v72 offset:64960
	s_waitcnt lgkmcnt(1)
	v_mfma_f32_16x16x32_bf16 v[20:23], v[40:43], v[12:15], v[8:11]
	s_nop 2
	ds_read_b128 v[8:11], v72 offset:47552
	ds_read_b128 v[24:27], v72 offset:51904
	s_waitcnt lgkmcnt(1)
	v_mfma_f32_16x16x32_bf16 v[0:3], v[32:35], v[8:11], v[0:3]
	ds_read_b128 v[8:11], v76 offset:4544
	ds_read_b128 v[44:47], v76 offset:8896
	s_waitcnt lgkmcnt(1)
	v_mfma_f32_16x16x32_bf16 v[12:15], v[40:43], v[8:11], v[0:3]
	v_mfma_f32_16x16x32_bf16 v[0:3], v[32:35], v[24:27], v[4:7]
	s_waitcnt lgkmcnt(0)
	v_mfma_f32_16x16x32_bf16 v[8:11], v[40:43], v[44:47], v[0:3]
	s_nop 5
	ds_read_b128 v[0:3], v72 offset:56256
	ds_read_b128 v[24:27], v72 offset:60608
	ds_read_b128 v[4:7], v76 offset:13248
	ds_read_b128 v[44:47], v76 offset:17600
	s_waitcnt lgkmcnt(3)
	v_mfma_f32_16x16x32_bf16 v[0:3], v[32:35], v[0:3], v[48:51]
	s_waitcnt lgkmcnt(1)
	v_mfma_f32_16x16x32_bf16 v[4:7], v[40:43], v[4:7], v[0:3]
	v_mfma_f32_16x16x32_bf16 v[0:3], v[32:35], v[24:27], v[56:59]
	s_waitcnt lgkmcnt(0)
	v_mfma_f32_16x16x32_bf16 v[0:3], v[40:43], v[44:47], v[0:3]
	ds_read_b128 v[24:27], v76 offset:21952
	ds_read_b128 v[44:47], v76 offset:26304
	ds_read_b128 v[48:51], v52 offset:30464
	ds_read_b128 v[52:55], v52 offset:26112
	ds_read_b128 v[56:59], v76 offset:30656
	s_waitcnt lgkmcnt(0)
	v_mfma_f32_16x16x32_bf16 v[16:19], v[32:35], v[16:19], v[60:63]
	s_barrier
	v_mfma_f32_16x16x32_bf16 v[16:19], v[40:43], v[24:27], v[16:19]
	v_and_b32_e32 v24, 64, v147
	v_add_u32_e32 v61, 64, v24
	v_xor_b32_e32 v60, 1, v147
	v_mfma_f32_16x16x32_bf16 v[24:27], v[32:35], v[52:55], v[36:39]
	v_cmp_lt_i32_e32 vcc, v60, v61
	v_mfma_f32_16x16x32_bf16 v[28:31], v[32:35], v[48:51], v[28:31]
	s_nop 0
	v_mul_f32_e32 v37, v12, v12
	v_fmac_f32_e32 v37, v20, v20
	v_fmac_f32_e32 v37, v8, v8
	v_mfma_f32_16x16x32_bf16 v[24:27], v[40:43], v[44:47], v[24:27]
	v_fmac_f32_e32 v37, v4, v4
	v_fmac_f32_e32 v37, v0, v0
	v_fmac_f32_e32 v37, v16, v16
	v_mfma_f32_16x16x32_bf16 v[28:31], v[40:43], v[56:59], v[28:31]
	v_cndmask_b32_e32 v36, v147, v60, vcc
	s_nop 2
	v_fmac_f32_e32 v37, v24, v24
	v_lshlrev_b32_e32 v36, 2, v36
	v_xor_b32_e32 v33, 2, v147
	v_cmp_lt_i32_e32 vcc, v33, v61
	v_fmac_f32_e32 v37, v28, v28
	ds_bpermute_b32 v32, v36, v37
	v_cndmask_b32_e32 v33, v147, v33, vcc
	v_lshlrev_b32_e32 v33, 2, v33
	v_xor_b32_e32 v35, 4, v147
	v_cmp_lt_i32_e32 vcc, v35, v61
	s_waitcnt lgkmcnt(0)
	v_add_f32_e32 v32, v37, v32
	ds_bpermute_b32 v34, v33, v32
	v_cndmask_b32_e32 v35, v147, v35, vcc
	v_lshlrev_b32_e32 v35, 2, v35
	v_xor_b32_e32 v37, 8, v147
	v_cmp_lt_i32_e32 vcc, v37, v61
	s_waitcnt lgkmcnt(0)
	v_add_f32_e32 v32, v32, v34
	ds_bpermute_b32 v34, v35, v32
	v_cndmask_b32_e32 v37, v147, v37, vcc
	v_lshlrev_b32_e32 v37, 2, v37
	v_mul_f32_e32 v40, v13, v13
	v_fmac_f32_e32 v40, v21, v21
	s_waitcnt lgkmcnt(0)
	v_add_f32_e32 v32, v32, v34
	ds_bpermute_b32 v34, v37, v32
	v_fmac_f32_e32 v40, v9, v9
	v_fmac_f32_e32 v40, v5, v5
	v_fmac_f32_e32 v40, v1, v1
	v_fmac_f32_e32 v40, v17, v17
	s_waitcnt lgkmcnt(0)
; template <bool STORE> __device__ __forceinline__ void h3_phase(unsigned char* lds, unsigned char* ws, const bf16_t* SF, const float* norm_g, int G, int blk) {
;     ...
;         float ssq[4];
; #pragma unroll
;         for (int i = 0; i < 4; ++i) { float s = 0.f;
; #pragma unroll
;             for (int nt = 0; nt < 8; ++nt) s += o[nt][i] * o[nt][i];
;             s += __shfl_xor(s, 1); s += __shfl_xor(s, 2); s += __shfl_xor(s, 4); s += __shfl_xor(s, 8);
;             ssq[i] = 1.0f / sqrtf(s * (1.0f / 128.0f) + LN_EPS); }
	v_add_f32_e32 v32, v32, v34
	v_fmamk_f32 v32, v32, 0x3c000000, v142
	v_mul_f32_e32 v34, 0x4f800000, v32
	v_cmp_gt_f32_e32 vcc, s29, v32
	v_fmac_f32_e32 v40, v25, v25
	v_fmac_f32_e32 v40, v29, v29
	v_cndmask_b32_e32 v32, v32, v34, vcc
	v_sqrt_f32_e32 v34, v32
	ds_bpermute_b32 v41, v36, v40
	v_mul_f32_e32 v44, v14, v14
	v_fmac_f32_e32 v44, v22, v22
	v_add_u32_e32 v38, -1, v34
	v_fma_f32 v39, -v38, v34, v32
	v_cmp_ge_f32_e64 s[4:5], 0, v39
	v_add_u32_e32 v39, 1, v34
	v_fmac_f32_e32 v44, v10, v10
	v_cndmask_b32_e64 v38, v34, v38, s[4:5]
	v_fma_f32 v34, -v39, v34, v32
	v_cmp_lt_f32_e64 s[4:5], 0, v34
	v_fmac_f32_e32 v44, v6, v6
	v_fmac_f32_e32 v44, v2, v2
	v_cndmask_b32_e64 v34, v38, v39, s[4:5]
	v_mul_f32_e32 v38, 0x37800000, v34
	v_cndmask_b32_e32 v34, v34, v38, vcc
	s_waitcnt lgkmcnt(0)
	v_add_f32_e32 v38, v40, v41
	ds_bpermute_b32 v39, v33, v38
	v_cmp_class_f32_e32 vcc, v32, v143
	v_fmac_f32_e32 v44, v18, v18
	v_fmac_f32_e32 v44, v26, v26
	v_cndmask_b32_e32 v32, v34, v32, vcc
	s_waitcnt lgkmcnt(0)
	v_add_f32_e32 v38, v38, v39
	ds_bpermute_b32 v39, v35, v38
	v_div_scale_f32 v34, s[4:5], v32, v32, 1.0
	v_rcp_f32_e32 v40, v34
	v_fmac_f32_e32 v44, v30, v30
	s_waitcnt lgkmcnt(0)
	v_add_f32_e32 v38, v38, v39
	ds_bpermute_b32 v39, v37, v38
	v_fma_f32 v41, -v34, v40, 1.0
	v_fmac_f32_e32 v40, v41, v40
	v_div_scale_f32 v41, vcc, 1.0, v32, 1.0
	s_waitcnt lgkmcnt(0)
	v_add_f32_e32 v38, v38, v39
	v_fmamk_f32 v38, v38, 0x3c000000, v142
	v_mul_f32_e32 v39, 0x4f800000, v38
	v_cmp_gt_f32_e64 s[4:5], s29, v38
	v_mul_f32_e32 v42, v41, v40
	v_fma_f32 v43, -v34, v42, v41
	v_cndmask_b32_e64 v38, v38, v39, s[4:5]
	v_sqrt_f32_e32 v39, v38
	v_fmac_f32_e32 v42, v43, v40
	v_fma_f32 v34, -v34, v42, v41
	ds_bpermute_b32 v45, v36, v44
	v_add_u32_e32 v41, -1, v39
	v_fma_f32 v43, -v41, v39, v38
	v_cmp_ge_f32_e64 s[6:7], 0, v43
	v_add_u32_e32 v43, 1, v39
	v_div_fmas_f32 v34, v34, v40, v42
	v_cndmask_b32_e64 v41, v39, v41, s[6:7]
	v_fma_f32 v39, -v43, v39, v38
	v_cmp_lt_f32_e64 s[6:7], 0, v39
	v_div_fixup_f32 v32, v34, v32, 1.0
	v_mul_f32_e32 v8, v8, v32
	v_cndmask_b32_e64 v39, v41, v43, s[6:7]
	v_mul_f32_e32 v41, 0x37800000, v39
	v_cndmask_b32_e64 v39, v39, v41, s[4:5]
	s_waitcnt lgkmcnt(0)
	v_add_f32_e32 v41, v44, v45
	ds_bpermute_b32 v43, v33, v41
	v_mul_f32_e32 v45, v15, v15
	v_fmac_f32_e32 v45, v23, v23
	v_fmac_f32_e32 v45, v11, v11
	v_fmac_f32_e32 v45, v7, v7
	s_waitcnt lgkmcnt(0)
	v_add_f32_e32 v41, v41, v43
	ds_bpermute_b32 v43, v35, v41
	v_fmac_f32_e32 v45, v3, v3
	v_fmac_f32_e32 v45, v19, v19
	v_fmac_f32_e32 v45, v27, v27
	v_fmac_f32_e32 v45, v31, v31
	s_waitcnt lgkmcnt(0)
	v_add_f32_e32 v40, v41, v43
	ds_bpermute_b32 v41, v37, v40
	ds_bpermute_b32 v36, v36, v45
	v_cmp_class_f32_e64 s[4:5], v38, v143
	v_mul_f32_e32 v4, v4, v32
	v_mul_f32_e32 v20, v20, v32
	v_cndmask_b32_e64 v38, v39, v38, s[4:5]
	v_div_scale_f32 v39, s[4:5], v38, v38, 1.0
	v_rcp_f32_e32 v44, v39
	s_waitcnt lgkmcnt(1)
	v_add_f32_e32 v40, v40, v41
	s_waitcnt lgkmcnt(0)
	v_add_f32_e32 v36, v45, v36
	v_fmamk_f32 v40, v40, 0x3c000000, v142
	ds_bpermute_b32 v33, v33, v36
	v_mul_f32_e32 v41, 0x4f800000, v40
	v_cmp_gt_f32_e64 s[4:5], s29, v40
	v_fma_f32 v34, -v39, v44, 1.0
	v_fmac_f32_e32 v44, v34, v44
	v_cndmask_b32_e64 v40, v40, v41, s[4:5]
	v_div_scale_f32 v34, vcc, 1.0, v38, 1.0
	v_sqrt_f32_e32 v41, v40
	v_mul_f32_e32 v42, v34, v44
	v_fma_f32 v43, -v39, v42, v34
	s_waitcnt lgkmcnt(0)
	v_add_f32_e32 v33, v36, v33
	v_fmac_f32_e32 v42, v43, v44
	ds_bpermute_b32 v35, v35, v33
	v_fma_f32 v34, -v39, v42, v34
	v_add_u32_e32 v39, -1, v41
	v_fma_f32 v43, -v39, v41, v40
	v_cmp_ge_f32_e64 s[6:7], 0, v43
	v_add_u32_e32 v43, 1, v41
	s_waitcnt lgkmcnt(0)
	v_add_f32_e32 v33, v33, v35
	v_cndmask_b32_e64 v39, v41, v39, s[6:7]
	v_fma_f32 v41, -v43, v41, v40
	v_cmp_lt_f32_e64 s[6:7], 0, v41
	ds_bpermute_b32 v35, v37, v33
	v_div_fmas_f32 v34, v34, v44, v42
	v_cndmask_b32_e64 v39, v39, v43, s[6:7]
	v_mul_f32_e32 v41, 0x37800000, v39
	v_cndmask_b32_e64 v39, v39, v41, s[4:5]
	v_cmp_class_f32_e64 s[4:5], v40, v143
	s_waitcnt lgkmcnt(0)
	v_add_f32_e32 v33, v33, v35
	v_fmamk_f32 v33, v33, 0x3c000000, v142
	v_cndmask_b32_e64 v39, v39, v40, s[4:5]
	v_div_scale_f32 v40, s[4:5], v39, v39, 1.0
	v_rcp_f32_e32 v41, v40
	v_mul_f32_e32 v35, 0x4f800000, v33
	v_cmp_gt_f32_e64 s[4:5], s29, v33
	v_div_fixup_f32 v34, v34, v38, 1.0
	v_fma_f32 v36, -v40, v41, 1.0
	v_cndmask_b32_e64 v33, v33, v35, s[4:5]
	v_sqrt_f32_e32 v35, v33
	v_fmac_f32_e32 v41, v36, v41
	v_div_scale_f32 v36, vcc, 1.0, v39, 1.0
	v_mul_f32_e32 v37, v36, v41
	v_fma_f32 v38, -v40, v37, v36
	v_fmac_f32_e32 v37, v38, v41
	v_add_u32_e32 v38, -1, v35
	v_fma_f32 v36, -v40, v37, v36
	v_fma_f32 v40, -v38, v35, v33
	v_cmp_ge_f32_e64 s[6:7], 0, v40
	v_add_u32_e32 v40, 1, v35
	v_div_fmas_f32 v36, v36, v41, v37
	v_cndmask_b32_e64 v38, v35, v38, s[6:7]
	v_fma_f32 v35, -v40, v35, v33
	v_cmp_lt_f32_e64 s[6:7], 0, v35
	v_div_fixup_f32 v36, v36, v39, 1.0
	v_mul_f32_e32 v12, v12, v32
	v_cndmask_b32_e64 v35, v38, v40, s[6:7]
	v_mul_f32_e32 v38, 0x37800000, v35
	v_cndmask_b32_e64 v35, v35, v38, s[4:5]
	v_cmp_class_f32_e64 s[4:5], v33, v143
	v_mul_f32_e32 v9, v9, v34
	v_mul_f32_e32 v10, v10, v36
	v_cndmask_b32_e64 v33, v35, v33, s[4:5]
	v_div_scale_f32 v35, s[4:5], v33, v33, 1.0
	v_rcp_f32_e32 v38, v35
	v_mul_f32_e32 v0, v0, v32
	v_mul_f32_e32 v1, v1, v34
	v_mul_f32_e32 v2, v2, v36
	v_fma_f32 v37, -v35, v38, 1.0
	v_fmac_f32_e32 v38, v37, v38
	v_div_scale_f32 v37, vcc, 1.0, v33, 1.0
	v_mul_f32_e32 v39, v37, v38
	v_fma_f32 v40, -v35, v39, v37
	v_fmac_f32_e32 v39, v40, v38
	v_fma_f32 v35, -v35, v39, v37
	v_div_fmas_f32 v35, v35, v38, v39
	v_div_fixup_f32 v33, v35, v33, 1.0
	v_add_u32_e32 v35, 0x2000, v144
; __device__ __forceinline__ float bf_lo(unsigned w) { return __uint_as_float(w << 16); }
; __device__ __forceinline__ float bf_hi(unsigned w) { return __uint_as_float(w & 0xffff0000u); }
; __device__ __forceinline__ u32x4 pack8(const f32x4 a, const f32x4 b) { u32x4 w; w.x = cvt_pk_bf16(a[0], a[1]); w.y = cvt_pk_bf16(a[2], a[3]); w.z = cvt_pk_bf16(b[0], b[1]); w.w = cvt_pk_bf16(b[2], b[3]); return w; }
; #define WAVE_LDS_FENCE() do { asm volatile("s_waitcnt lgkmcnt(0)" ::: "memory"); __builtin_amdgcn_wave_barrier(); } while (0)
; template <bool STORE> __device__ __forceinline__ void h3_phase(unsigned char* lds, unsigned char* ws, const bf16_t* SF, const float* norm_g, int G, int blk) {
;     ...
; #pragma unroll
;         for (int nt = 0; nt < 8; ++nt)
; #pragma unroll
;             for (int i = 0; i < 4; ++i) STGF[(4 * kq + i) * 132 + 16 * nt + r] = o[nt][i] * ssq[i];
;         WAVE_LDS_FENCE();
; #pragma unroll
;         for (int it = 0; it < 4; ++it) {
;             const int p = lane + 64 * it, row = p >> 4, c8 = p & 15;
;             const f32x4 a = *(const f32x4*)(STGF + row * 132 + c8 * 8), bq = *(const f32x4*)(STGF + row * 132 + c8 * 8 + 4);
;             const f32x4 g0 = *(const f32x4*)(norm_g + c8 * 8), g1 = *(const f32x4*)(norm_g + c8 * 8 + 4);
;             bf16_t* zr = Z + ((size_t)h * M + tok0 + row) * 128 + c8 * 8;
;             const u32x4 gw = *(const u32x4*)(zr + 4 * ZSEG);
;             const f32x4 t0 = {bf_lo(gw.x), bf_hi(gw.x), bf_lo(gw.y), bf_hi(gw.y)}, t1 = {bf_lo(gw.z), bf_hi(gw.z), bf_lo(gw.w), bf_hi(gw.w)};
;             if (STORE || a[0] == 123.456f) *(u32x4*)zr = pack8(a * g0 * t0, bq * g1 * t1);
;         }
;         asm volatile("s_waitcnt lgkmcnt(0)\n\ts_barrier" ::: "memory");
	ds_write2_b32 v35, v8, v4 offset0:32 offset1:48
	v_mul_f32_e32 v4, v5, v34
	ds_write2_b32 v35, v20, v12 offset1:16
	v_mul_f32_e32 v12, v13, v34
	v_add_u32_e32 v13, 0x2400, v144
	ds_write2_b32 v35, v9, v4 offset0:164 offset1:180
	v_mul_f32_e32 v4, v6, v36
	v_mul_f32_e32 v11, v11, v33
	ds_write2_b32 v13, v10, v4 offset0:40 offset1:56
	v_mul_f32_e32 v4, v7, v33
	ds_write2_b32 v13, v11, v4 offset0:172 offset1:188
	v_mul_f32_e32 v4, v16, v32
	ds_write2_b32 v35, v0, v4 offset0:64 offset1:80
	v_mul_f32_e32 v0, v17, v34
	ds_write2_b32 v35, v1, v0 offset0:196 offset1:212
	v_mul_f32_e32 v0, v18, v36
	v_mul_f32_e32 v3, v3, v33
	ds_write2_b32 v13, v2, v0 offset0:72 offset1:88
	v_mul_f32_e32 v0, v19, v33
	ds_write2_b32 v13, v3, v0 offset0:204 offset1:220
	v_mul_f32_e32 v0, v24, v32
	v_mul_f32_e32 v4, v28, v32
	v_mul_f32_e32 v1, v25, v34
	ds_write2_b32 v35, v0, v4 offset0:96 offset1:112
	v_mul_f32_e32 v0, v29, v34
	v_mul_f32_e32 v2, v26, v36
	ds_write2_b32 v35, v1, v0 offset0:228 offset1:244
	v_mul_f32_e32 v0, v30, v36
	v_mul_f32_e32 v3, v27, v33
	ds_write2_b32 v13, v2, v0 offset0:104 offset1:120
	v_mul_f32_e32 v0, v31, v33
	v_mul_f32_e32 v21, v21, v34
	ds_write2_b32 v13, v3, v0 offset0:236 offset1:252
	v_mov_b32_e32 v1, s34
	v_or_b32_e32 v0, s31, v114
	v_mul_f32_e32 v22, v22, v36
	ds_write2_b32 v35, v21, v12 offset0:132 offset1:148
	v_mul_f32_e32 v12, v14, v36
	v_lshlrev_b64 v[0:1], 8, v[0:1]
	v_mul_f32_e32 v23, v23, v33
	ds_write2_b32 v13, v22, v12 offset0:8 offset1:24
	v_mul_f32_e32 v12, v15, v33
	v_lshl_add_u64 v[20:21], v[120:121], 0, v[0:1]
	ds_write2_b32 v13, v23, v12 offset0:140 offset1:156
	v_add_co_u32_e32 v12, vcc, s30, v20
	s_waitcnt lgkmcnt(0)
	s_nop 1
	v_addc_co_u32_e32 v13, vcc, 0, v21, vcc
	global_load_dwordx4 v[0:3], v[12:13], off
	global_load_dwordx4 v[4:7], v[118:119], off offset:512
	global_load_dwordx4 v[8:11], v[118:119], off offset:528
	ds_read_b128 v[12:15], v145 offset:8192
	ds_read_b128 v[16:19], v145 offset:8208
	s_waitcnt vmcnt(2)
	v_lshlrev_b32_e32 v22, 16, v0
	v_and_b32_e32 v23, 0xffff0000, v0
	v_lshlrev_b32_e32 v0, 16, v1
	v_and_b32_e32 v1, 0xffff0000, v1
	s_waitcnt vmcnt(1) lgkmcnt(1)
	v_pk_mul_f32 v[6:7], v[14:15], v[6:7]
	v_pk_mul_f32 v[4:5], v[12:13], v[4:5]
	v_lshlrev_b32_e32 v24, 16, v2
	v_and_b32_e32 v25, 0xffff0000, v2
	v_lshlrev_b32_e32 v2, 16, v3
	v_and_b32_e32 v3, 0xffff0000, v3
	v_pk_mul_f32 v[6:7], v[6:7], v[0:1]
	v_pk_mul_f32 v[0:1], v[4:5], v[22:23]
	s_waitcnt vmcnt(0) lgkmcnt(0)
	v_pk_mul_f32 v[4:5], v[18:19], v[10:11]
	v_pk_mul_f32 v[8:9], v[16:17], v[8:9]
	v_pk_mul_f32 v[4:5], v[4:5], v[2:3]
	v_pk_mul_f32 v[2:3], v[8:9], v[24:25]
	v_cvt_pk_bf16_f32 v0, v0, v1
	v_cvt_pk_bf16_f32 v1, v6, v7
	s_nop 0
	v_cvt_pk_bf16_f32 v2, v2, v3
	v_cvt_pk_bf16_f32 v3, v4, v5
	global_store_dwordx4 v[20:21], v[0:3], off
	s_nop 1
	v_mov_b32_e32 v1, s34
	v_or_b32_e32 v0, s31, v122
	v_lshlrev_b64 v[0:1], 8, v[0:1]
	v_lshl_add_u64 v[20:21], v[120:121], 0, v[0:1]
	v_add_co_u32_e32 v12, vcc, s30, v20
	s_nop 1
	v_addc_co_u32_e32 v13, vcc, 0, v21, vcc
	global_load_dwordx4 v[0:3], v[12:13], off
	global_load_dwordx4 v[4:7], v[118:119], off offset:512
	global_load_dwordx4 v[8:11], v[118:119], off offset:528
	ds_read_b128 v[12:15], v146 offset:8192
	ds_read_b128 v[16:19], v146 offset:8208
	s_waitcnt vmcnt(2)
	v_lshlrev_b32_e32 v22, 16, v0
	v_and_b32_e32 v23, 0xffff0000, v0
	v_lshlrev_b32_e32 v0, 16, v1
	v_and_b32_e32 v1, 0xffff0000, v1
	s_waitcnt vmcnt(1) lgkmcnt(1)
	v_pk_mul_f32 v[6:7], v[14:15], v[6:7]
	v_pk_mul_f32 v[4:5], v[12:13], v[4:5]
	v_lshlrev_b32_e32 v24, 16, v2
	v_and_b32_e32 v25, 0xffff0000, v2
	v_lshlrev_b32_e32 v2, 16, v3
	v_and_b32_e32 v3, 0xffff0000, v3
	v_pk_mul_f32 v[6:7], v[6:7], v[0:1]
	v_pk_mul_f32 v[0:1], v[4:5], v[22:23]
	s_waitcnt vmcnt(0) lgkmcnt(0)
	v_pk_mul_f32 v[4:5], v[18:19], v[10:11]
	v_pk_mul_f32 v[8:9], v[16:17], v[8:9]
	v_pk_mul_f32 v[4:5], v[4:5], v[2:3]
	v_pk_mul_f32 v[2:3], v[8:9], v[24:25]
	v_cvt_pk_bf16_f32 v0, v0, v1
	v_cvt_pk_bf16_f32 v1, v6, v7
	s_nop 0
	v_cvt_pk_bf16_f32 v2, v2, v3
	v_cvt_pk_bf16_f32 v3, v4, v5
	global_store_dwordx4 v[20:21], v[0:3], off
	s_nop 1
	v_mov_b32_e32 v1, s34
	v_or_b32_e32 v0, s31, v124
	v_lshlrev_b64 v[0:1], 8, v[0:1]
	v_lshl_add_u64 v[20:21], v[120:121], 0, v[0:1]
	v_add_co_u32_e32 v12, vcc, s30, v20
	s_nop 1
	v_addc_co_u32_e32 v13, vcc, 0, v21, vcc
	global_load_dwordx4 v[0:3], v[12:13], off
	global_load_dwordx4 v[4:7], v[118:119], off offset:512
	global_load_dwordx4 v[8:11], v[118:119], off offset:528
	ds_read_b128 v[12:15], v146 offset:10304
	ds_read_b128 v[16:19], v146 offset:10320
	s_waitcnt vmcnt(2)
	v_lshlrev_b32_e32 v22, 16, v0
	v_and_b32_e32 v23, 0xffff0000, v0
	v_lshlrev_b32_e32 v0, 16, v1
	v_and_b32_e32 v1, 0xffff0000, v1
	s_waitcnt vmcnt(1) lgkmcnt(1)
	v_pk_mul_f32 v[6:7], v[14:15], v[6:7]
	v_pk_mul_f32 v[4:5], v[12:13], v[4:5]
	v_lshlrev_b32_e32 v24, 16, v2
	v_and_b32_e32 v25, 0xffff0000, v2
	v_lshlrev_b32_e32 v2, 16, v3
	v_and_b32_e32 v3, 0xffff0000, v3
	v_pk_mul_f32 v[6:7], v[6:7], v[0:1]
	v_pk_mul_f32 v[0:1], v[4:5], v[22:23]
	s_waitcnt vmcnt(0) lgkmcnt(0)
	v_pk_mul_f32 v[4:5], v[18:19], v[10:11]
	v_pk_mul_f32 v[8:9], v[16:17], v[8:9]
	v_pk_mul_f32 v[4:5], v[4:5], v[2:3]
	v_pk_mul_f32 v[2:3], v[8:9], v[24:25]
	v_cvt_pk_bf16_f32 v0, v0, v1
	v_cvt_pk_bf16_f32 v1, v6, v7
	s_nop 0
	v_cvt_pk_bf16_f32 v2, v2, v3
	v_cvt_pk_bf16_f32 v3, v4, v5
	global_store_dwordx4 v[20:21], v[0:3], off
	s_nop 1
	v_mov_b32_e32 v1, s34
	v_or_b32_e32 v0, s31, v126
	v_lshlrev_b64 v[0:1], 8, v[0:1]
	v_lshl_add_u64 v[20:21], v[120:121], 0, v[0:1]
	v_add_co_u32_e32 v12, vcc, s30, v20
	s_nop 1
	v_addc_co_u32_e32 v13, vcc, 0, v21, vcc
	global_load_dwordx4 v[0:3], v[12:13], off
	global_load_dwordx4 v[4:7], v[118:119], off offset:512
	global_load_dwordx4 v[8:11], v[118:119], off offset:528
	ds_read_b128 v[12:15], v146 offset:12416
	ds_read_b128 v[16:19], v146 offset:12432
	s_waitcnt vmcnt(2)
	v_lshlrev_b32_e32 v22, 16, v0
	v_and_b32_e32 v23, 0xffff0000, v0
	v_lshlrev_b32_e32 v0, 16, v1
	v_and_b32_e32 v1, 0xffff0000, v1
	s_waitcnt vmcnt(1) lgkmcnt(1)
	v_pk_mul_f32 v[6:7], v[14:15], v[6:7]
	v_pk_mul_f32 v[4:5], v[12:13], v[4:5]
	v_lshlrev_b32_e32 v24, 16, v2
	v_and_b32_e32 v25, 0xffff0000, v2
	v_lshlrev_b32_e32 v2, 16, v3
	v_and_b32_e32 v3, 0xffff0000, v3
	v_pk_mul_f32 v[6:7], v[6:7], v[0:1]
	v_pk_mul_f32 v[0:1], v[4:5], v[22:23]
	s_waitcnt vmcnt(0) lgkmcnt(0)
	v_pk_mul_f32 v[4:5], v[18:19], v[10:11]
	v_pk_mul_f32 v[8:9], v[16:17], v[8:9]
	v_pk_mul_f32 v[4:5], v[4:5], v[2:3]
	v_pk_mul_f32 v[2:3], v[8:9], v[24:25]
	v_cvt_pk_bf16_f32 v0, v0, v1
	v_cvt_pk_bf16_f32 v1, v6, v7
	s_nop 0
	v_cvt_pk_bf16_f32 v2, v2, v3
	v_cvt_pk_bf16_f32 v3, v4, v5
	global_store_dwordx4 v[20:21], v[0:3], off
	s_waitcnt lgkmcnt(0)
	s_barrier
	s_cbranch_scc0 .LBB0_2629
; template <int DIR> __device__ __forceinline__ void h3_dir(unsigned char* lds, const bf16_t* zrow, int h, const bf16_t* slot, f32x4 (&o)[8]) {
;     ...
;     float bl[32], qin[32]; bf16x8 kin[4];
;     load32(zrow + (size_t)(1 + DIR) * ZSEG + 8 * kq, bl);
;     load32(zrow + 8 * kq, qin);
; template <bool STORE> __device__ __forceinline__ void h3_phase(unsigned char* lds, unsigned char* ws, const bf16_t* SF, const float* norm_g, int G, int blk) {
;     ...
;     for (int unit = blk; unit < 2048; unit += G) {
;         const int b = unit >> 10, c = (unit >> 3) & 127, h = unit & 7, chain = b * 8 + h;
;         const size_t tok0 = (size_t)b * SEQ + c * 128 + 16 * wid;
;         const bf16_t* zrow = Z + ((size_t)h * M + tok0 + r) * 128;
;         {
; #pragma unroll
;           for (int ks = 0; ks < 4; ++ks) { const u32x4 w = *(const u32x4*)(zrow + 3 * ZSEG + 8 * kq + 32 * ks);
; #pragma unroll
;               for (int e = 0; e < 4; ++e) { VT[(32 * ks + 8 * kq + 2 * e) * HP + 16 * wid + r] = (bf16_t)(w[e] & 0xffffu); VT[(32 * ks + 8 * kq + 2 * e + 1) * HP + 16 * wid + r] = (bf16_t)(w[e] >> 16); } } }
.LBB0_2609:
	s_ashr_i32 s4, s17, 10
	s_bfe_u32 s3, s17, 0x70003
	s_and_b32 s36, s17, 7
	s_ashr_i32 s5, s4, 31
	s_lshl_b64 s[6:7], s[4:5], 14
	s_lshl_b32 s5, s3, 7
	s_lshl_b32 s31, s36, 15
	s_add_u32 s6, s6, s20
	s_addc_u32 s7, s7, s21
	s_add_u32 s6, s6, s31
	s_addc_u32 s7, s7, 0
	s_add_u32 s31, s6, s5
	s_addc_u32 s34, s7, 0
	v_mov_b32_e32 v1, s34
	v_or_b32_e32 v0, s31, v112
	v_lshlrev_b64 v[0:1], 8, v[0:1]
	v_lshl_add_u64 v[80:81], s[10:11], 0, v[0:1]
	v_lshl_add_u64 v[4:5], v[80:81], 0, v[128:129]
	v_add_co_u32_e32 v0, vcc, s25, v4
	v_lshl_add_u64 v[16:17], v[4:5], 0, s[12:13]
	s_nop 0
	v_addc_co_u32_e32 v1, vcc, 0, v5, vcc
	global_load_dwordx4 v[0:3], v[0:1], off
	s_nop 0
	global_load_dwordx4 v[4:7], v[16:17], off offset:64
	global_load_dwordx4 v[8:11], v[16:17], off offset:128
	global_load_dwordx4 v[12:15], v[16:17], off offset:192
	v_mov_b32_e32 v85, v254
	s_waitcnt vmcnt(3)
	ds_write_b16 v113, v0
	ds_write_b16_d16_hi v115, v0 offset:272
	ds_write_b16 v113, v1 offset:544
	ds_write_b16_d16_hi v123, v1 offset:272
	ds_write_b16 v113, v2 offset:1088
	ds_write_b16_d16_hi v125, v2 offset:272
	ds_write_b16 v113, v3 offset:1632
	ds_write_b16_d16_hi v127, v3 offset:272
	s_waitcnt vmcnt(2)
	ds_write_b16 v113, v4 offset:8704
	ds_write_b16_d16_hi v130, v4 offset:272
	ds_write_b16 v113, v5 offset:9248
	ds_write_b16_d16_hi v131, v5 offset:272
	ds_write_b16 v113, v6 offset:9792
	ds_write_b16_d16_hi v132, v6 offset:272
	ds_write_b16 v113, v7 offset:10336
	ds_write_b16_d16_hi v133, v7 offset:272
	s_waitcnt vmcnt(1)
	ds_write_b16 v113, v8 offset:17408
	ds_write_b16_d16_hi v134, v8 offset:272
	ds_write_b16 v113, v9 offset:17952
	ds_write_b16_d16_hi v135, v9 offset:272
	ds_write_b16 v113, v10 offset:18496
	ds_write_b16_d16_hi v136, v10 offset:272
	ds_write_b16 v113, v11 offset:19040
	ds_write_b16_d16_hi v137, v11 offset:272
	s_waitcnt vmcnt(0)
	ds_write_b16 v113, v12 offset:26112
	ds_write_b16_d16_hi v138, v12 offset:272
	ds_write_b16 v113, v13 offset:26656
	ds_write_b16_d16_hi v139, v13 offset:272
	ds_write_b16 v113, v14 offset:27200
	ds_write_b16_d16_hi v140, v14 offset:272
	ds_write_b16 v113, v15 offset:27744
	ds_write_b16_d16_hi v141, v15 offset:272
	s_nop 0
	v_bfe_u32 v84, v85, 4, 2
	v_lshlrev_b32_e32 v116, 4, v84
	v_lshl_add_u64 v[16:17], v[80:81], 0, v[116:117]
	v_add_co_u32_e32 v0, vcc, s26, v16
	v_lshl_add_u64 v[18:19], v[16:17], 0, s[8:9]
	s_nop 0
	v_addc_co_u32_e32 v1, vcc, 0, v17, vcc
	global_load_dwordx4 v[0:3], v[0:1], off
	s_nop 0
	global_load_dwordx4 v[4:7], v[18:19], off offset:64
	global_load_dwordx4 v[8:11], v[18:19], off offset:128
	global_load_dwordx4 v[12:15], v[18:19], off offset:192
	global_load_dwordx4 v[64:67], v[16:17], off
	global_load_dwordx4 v[52:55], v[16:17], off offset:64
	global_load_dwordx4 v[48:51], v[16:17], off offset:128
	global_load_dwordx4 v[44:47], v[16:17], off offset:192
	v_readfirstlane_b32 s5, v85
	s_ashr_i32 s35, s5, 6
	v_and_b32_e32 v83, 15, v85
	v_lshlrev_b32_e32 v82, 3, v84
	v_cmp_eq_u32_e32 vcc, 15, v83
	s_lshl_b32 s37, s35, 9
	s_waitcnt vmcnt(6)
	v_lshlrev_b32_e32 v111, 16, v4
	v_lshlrev_b32_e32 v107, 16, v0
	v_and_b32_e32 v106, 0xffff0000, v0
	v_lshlrev_b32_e32 v152, 16, v1
	v_and_b32_e32 v151, 0xffff0000, v1
	v_lshlrev_b32_e32 v150, 16, v2
	v_and_b32_e32 v149, 0xffff0000, v2
	v_lshlrev_b32_e32 v148, 16, v3
	v_and_b32_e32 v116, 0xffff0000, v3
	v_mov_b32_e32 v25, v149
	v_mov_b32_e32 v32, v107
	v_mov_b32_e32 v27, v116
	v_mov_b32_e32 v34, v152
	v_mov_b32_e32 v24, v150
	v_mov_b32_e32 v26, v148
	v_mov_b32_e32 v33, v106
	v_mov_b32_e32 v35, v151
	s_nop 1
	v_add_f32_dpp v32, v32, v32 row_shr:1 row_mask:0xf bank_mask:0xf bound_ctrl:1
	v_add_f32_dpp v33, v33, v33 row_shr:1 row_mask:0xf bank_mask:0xf bound_ctrl:1
	v_add_f32_dpp v34, v34, v34 row_shr:1 row_mask:0xf bank_mask:0xf bound_ctrl:1
	v_add_f32_dpp v35, v35, v35 row_shr:1 row_mask:0xf bank_mask:0xf bound_ctrl:1
	v_add_f32_dpp v24, v24, v24 row_shr:1 row_mask:0xf bank_mask:0xf bound_ctrl:1
	v_add_f32_dpp v25, v25, v25 row_shr:1 row_mask:0xf bank_mask:0xf bound_ctrl:1
	v_add_f32_dpp v26, v26, v26 row_shr:1 row_mask:0xf bank_mask:0xf bound_ctrl:1
	v_add_f32_dpp v27, v27, v27 row_shr:1 row_mask:0xf bank_mask:0xf bound_ctrl:1
	v_and_b32_e32 v110, 0xffff0000, v4
	v_lshlrev_b32_e32 v109, 16, v5
	v_and_b32_e32 v108, 0xffff0000, v5
	v_lshlrev_b32_e32 v102, 16, v6
	v_and_b32_e32 v103, 0xffff0000, v6
	v_lshlrev_b32_e32 v104, 16, v7
	v_and_b32_e32 v105, 0xffff0000, v7
	s_nop 1
	v_add_f32_dpp v32, v32, v32 row_shr:2 row_mask:0xf bank_mask:0xf bound_ctrl:1
	v_add_f32_dpp v33, v33, v33 row_shr:2 row_mask:0xf bank_mask:0xf bound_ctrl:1
	v_add_f32_dpp v34, v34, v34 row_shr:2 row_mask:0xf bank_mask:0xf bound_ctrl:1
	v_add_f32_dpp v35, v35, v35 row_shr:2 row_mask:0xf bank_mask:0xf bound_ctrl:1
	v_add_f32_dpp v24, v24, v24 row_shr:2 row_mask:0xf bank_mask:0xf bound_ctrl:1
	v_add_f32_dpp v25, v25, v25 row_shr:2 row_mask:0xf bank_mask:0xf bound_ctrl:1
	v_add_f32_dpp v26, v26, v26 row_shr:2 row_mask:0xf bank_mask:0xf bound_ctrl:1
	v_add_f32_dpp v27, v27, v27 row_shr:2 row_mask:0xf bank_mask:0xf bound_ctrl:1
	v_mov_b32_e32 v17, v103
	v_mov_b32_e32 v20, v111
	v_mov_b32_e32 v19, v105
	v_mov_b32_e32 v22, v109
	v_mov_b32_e32 v16, v102
	v_mov_b32_e32 v18, v104
	v_mov_b32_e32 v21, v110
	v_mov_b32_e32 v23, v108
	s_nop 1
	v_add_f32_dpp v32, v32, v32 row_shr:4 row_mask:0xf bank_mask:0xf bound_ctrl:1
	v_add_f32_dpp v33, v33, v33 row_shr:4 row_mask:0xf bank_mask:0xf bound_ctrl:1
	v_add_f32_dpp v34, v34, v34 row_shr:4 row_mask:0xf bank_mask:0xf bound_ctrl:1
	v_add_f32_dpp v35, v35, v35 row_shr:4 row_mask:0xf bank_mask:0xf bound_ctrl:1
	v_add_f32_dpp v24, v24, v24 row_shr:4 row_mask:0xf bank_mask:0xf bound_ctrl:1
	v_add_f32_dpp v25, v25, v25 row_shr:4 row_mask:0xf bank_mask:0xf bound_ctrl:1
	v_add_f32_dpp v26, v26, v26 row_shr:4 row_mask:0xf bank_mask:0xf bound_ctrl:1
	v_add_f32_dpp v27, v27, v27 row_shr:4 row_mask:0xf bank_mask:0xf bound_ctrl:1
	s_waitcnt vmcnt(5)
; __device__ __forceinline__ float bf_lo(unsigned w) { return __uint_as_float(w << 16); }
; __device__ __forceinline__ float bf_hi(unsigned w) { return __uint_as_float(w & 0xffff0000u); }
; template <int DIR> __device__ __forceinline__ void scan16x8(float* v) {
;     if (DIR == 0) { SCAN_STEP("row_shr:", 1); SCAN_STEP("row_shr:", 2); SCAN_STEP("row_shr:", 4); SCAN_STEP("row_shr:", 8); }
;     else          { SCAN_STEP("row_shl:", 1); SCAN_STEP("row_shl:", 2); SCAN_STEP("row_shl:", 4); SCAN_STEP("row_shl:", 8); }
; }
; __device__ __forceinline__ void load32(const bf16_t* p, float (&v)[32]) {
; #pragma unroll
;     for (int ks = 0; ks < 4; ++ks) { const u32x4 w = *(const u32x4*)(p + 32 * ks);
;         v[8 * ks + 0] = bf_lo(w.x); v[8 * ks + 1] = bf_hi(w.x); v[8 * ks + 2] = bf_lo(w.y); v[8 * ks + 3] = bf_hi(w.y); v[8 * ks + 4] = bf_lo(w.z); v[8 * ks + 5] = bf_hi(w.z); v[8 * ks + 6] = bf_lo(w.w); v[8 * ks + 7] = bf_hi(w.w); }
	v_lshlrev_b32_e32 v98, 16, v8
	s_nop 1
	v_add_f32_dpp v32, v32, v32 row_shr:8 row_mask:0xf bank_mask:0xf bound_ctrl:1
	v_add_f32_dpp v33, v33, v33 row_shr:8 row_mask:0xf bank_mask:0xf bound_ctrl:1
	v_add_f32_dpp v34, v34, v34 row_shr:8 row_mask:0xf bank_mask:0xf bound_ctrl:1
	v_add_f32_dpp v35, v35, v35 row_shr:8 row_mask:0xf bank_mask:0xf bound_ctrl:1
	v_add_f32_dpp v24, v24, v24 row_shr:8 row_mask:0xf bank_mask:0xf bound_ctrl:1
	v_add_f32_dpp v25, v25, v25 row_shr:8 row_mask:0xf bank_mask:0xf bound_ctrl:1
	v_add_f32_dpp v26, v26, v26 row_shr:8 row_mask:0xf bank_mask:0xf bound_ctrl:1
	v_add_f32_dpp v27, v27, v27 row_shr:8 row_mask:0xf bank_mask:0xf bound_ctrl:1
	s_nop 1
	v_add_f32_dpp v20, v20, v20 row_shr:1 row_mask:0xf bank_mask:0xf bound_ctrl:1
	v_add_f32_dpp v21, v21, v21 row_shr:1 row_mask:0xf bank_mask:0xf bound_ctrl:1
	v_add_f32_dpp v22, v22, v22 row_shr:1 row_mask:0xf bank_mask:0xf bound_ctrl:1
	v_add_f32_dpp v23, v23, v23 row_shr:1 row_mask:0xf bank_mask:0xf bound_ctrl:1
	v_add_f32_dpp v16, v16, v16 row_shr:1 row_mask:0xf bank_mask:0xf bound_ctrl:1
	v_add_f32_dpp v17, v17, v17 row_shr:1 row_mask:0xf bank_mask:0xf bound_ctrl:1
	v_add_f32_dpp v18, v18, v18 row_shr:1 row_mask:0xf bank_mask:0xf bound_ctrl:1
	v_add_f32_dpp v19, v19, v19 row_shr:1 row_mask:0xf bank_mask:0xf bound_ctrl:1
	v_and_b32_e32 v99, 0xffff0000, v8
	v_lshlrev_b32_e32 v100, 16, v9
	v_and_b32_e32 v101, 0xffff0000, v9
	v_lshlrev_b32_e32 v94, 16, v10
	v_and_b32_e32 v95, 0xffff0000, v10
	v_lshlrev_b32_e32 v96, 16, v11
	v_and_b32_e32 v97, 0xffff0000, v11
	s_nop 1
	v_add_f32_dpp v20, v20, v20 row_shr:2 row_mask:0xf bank_mask:0xf bound_ctrl:1
	v_add_f32_dpp v21, v21, v21 row_shr:2 row_mask:0xf bank_mask:0xf bound_ctrl:1
	v_add_f32_dpp v22, v22, v22 row_shr:2 row_mask:0xf bank_mask:0xf bound_ctrl:1
	v_add_f32_dpp v23, v23, v23 row_shr:2 row_mask:0xf bank_mask:0xf bound_ctrl:1
	v_add_f32_dpp v16, v16, v16 row_shr:2 row_mask:0xf bank_mask:0xf bound_ctrl:1
	v_add_f32_dpp v17, v17, v17 row_shr:2 row_mask:0xf bank_mask:0xf bound_ctrl:1
	v_add_f32_dpp v18, v18, v18 row_shr:2 row_mask:0xf bank_mask:0xf bound_ctrl:1
	v_add_f32_dpp v19, v19, v19 row_shr:2 row_mask:0xf bank_mask:0xf bound_ctrl:1
	s_waitcnt vmcnt(4)
	v_lshlrev_b32_e32 v90, 16, v12
	v_and_b32_e32 v91, 0xffff0000, v12
	v_lshlrev_b32_e32 v92, 16, v13
	v_and_b32_e32 v93, 0xffff0000, v13
	v_lshlrev_b32_e32 v86, 16, v14
	v_and_b32_e32 v87, 0xffff0000, v14
	v_lshlrev_b32_e32 v88, 16, v15
	v_and_b32_e32 v89, 0xffff0000, v15
	v_mov_b32_e32 v9, v95
	v_mov_b32_e32 v12, v98
	v_mov_b32_e32 v11, v97
	v_mov_b32_e32 v14, v100
	v_mov_b32_e32 v8, v94
	v_mov_b32_e32 v10, v96
	v_mov_b32_e32 v13, v99
	v_mov_b32_e32 v15, v101
	s_nop 1
	v_add_f32_dpp v20, v20, v20 row_shr:4 row_mask:0xf bank_mask:0xf bound_ctrl:1
	v_add_f32_dpp v21, v21, v21 row_shr:4 row_mask:0xf bank_mask:0xf bound_ctrl:1
	v_add_f32_dpp v22, v22, v22 row_shr:4 row_mask:0xf bank_mask:0xf bound_ctrl:1
	v_add_f32_dpp v23, v23, v23 row_shr:4 row_mask:0xf bank_mask:0xf bound_ctrl:1
	v_add_f32_dpp v16, v16, v16 row_shr:4 row_mask:0xf bank_mask:0xf bound_ctrl:1
	v_add_f32_dpp v17, v17, v17 row_shr:4 row_mask:0xf bank_mask:0xf bound_ctrl:1
	v_add_f32_dpp v18, v18, v18 row_shr:4 row_mask:0xf bank_mask:0xf bound_ctrl:1
	v_add_f32_dpp v19, v19, v19 row_shr:4 row_mask:0xf bank_mask:0xf bound_ctrl:1
	v_mov_b32_e32 v1, v87
	s_nop 1
	v_add_f32_dpp v20, v20, v20 row_shr:8 row_mask:0xf bank_mask:0xf bound_ctrl:1
	v_add_f32_dpp v21, v21, v21 row_shr:8 row_mask:0xf bank_mask:0xf bound_ctrl:1
	v_add_f32_dpp v22, v22, v22 row_shr:8 row_mask:0xf bank_mask:0xf bound_ctrl:1
	v_add_f32_dpp v23, v23, v23 row_shr:8 row_mask:0xf bank_mask:0xf bound_ctrl:1
	v_add_f32_dpp v16, v16, v16 row_shr:8 row_mask:0xf bank_mask:0xf bound_ctrl:1
	v_add_f32_dpp v17, v17, v17 row_shr:8 row_mask:0xf bank_mask:0xf bound_ctrl:1
	v_add_f32_dpp v18, v18, v18 row_shr:8 row_mask:0xf bank_mask:0xf bound_ctrl:1
	v_add_f32_dpp v19, v19, v19 row_shr:8 row_mask:0xf bank_mask:0xf bound_ctrl:1
	s_nop 1
	v_add_f32_dpp v12, v12, v12 row_shr:1 row_mask:0xf bank_mask:0xf bound_ctrl:1
	v_add_f32_dpp v13, v13, v13 row_shr:1 row_mask:0xf bank_mask:0xf bound_ctrl:1
	v_add_f32_dpp v14, v14, v14 row_shr:1 row_mask:0xf bank_mask:0xf bound_ctrl:1
	v_add_f32_dpp v15, v15, v15 row_shr:1 row_mask:0xf bank_mask:0xf bound_ctrl:1
	v_add_f32_dpp v8, v8, v8 row_shr:1 row_mask:0xf bank_mask:0xf bound_ctrl:1
	v_add_f32_dpp v9, v9, v9 row_shr:1 row_mask:0xf bank_mask:0xf bound_ctrl:1
	v_add_f32_dpp v10, v10, v10 row_shr:1 row_mask:0xf bank_mask:0xf bound_ctrl:1
	v_add_f32_dpp v11, v11, v11 row_shr:1 row_mask:0xf bank_mask:0xf bound_ctrl:1
	v_mov_b32_e32 v4, v90
	s_nop 1
	v_add_f32_dpp v12, v12, v12 row_shr:2 row_mask:0xf bank_mask:0xf bound_ctrl:1
	v_add_f32_dpp v13, v13, v13 row_shr:2 row_mask:0xf bank_mask:0xf bound_ctrl:1
	v_add_f32_dpp v14, v14, v14 row_shr:2 row_mask:0xf bank_mask:0xf bound_ctrl:1
	v_add_f32_dpp v15, v15, v15 row_shr:2 row_mask:0xf bank_mask:0xf bound_ctrl:1
	v_add_f32_dpp v8, v8, v8 row_shr:2 row_mask:0xf bank_mask:0xf bound_ctrl:1
	v_add_f32_dpp v9, v9, v9 row_shr:2 row_mask:0xf bank_mask:0xf bound_ctrl:1
	v_add_f32_dpp v10, v10, v10 row_shr:2 row_mask:0xf bank_mask:0xf bound_ctrl:1
	v_add_f32_dpp v11, v11, v11 row_shr:2 row_mask:0xf bank_mask:0xf bound_ctrl:1
	v_mov_b32_e32 v3, v89
	v_mov_b32_e32 v6, v92
	v_mov_b32_e32 v0, v86
; template <int DIR> __device__ __forceinline__ void h3_dir(unsigned char* lds, const bf16_t* zrow, int h, const bf16_t* slot, f32x4 (&o)[8]) {
;     ...
; #pragma unroll
;         for (int i = 0; i < 32; ++i) kk[i] = 1.0f - __builtin_amdgcn_exp2f(bl[i]);
;         scan16x8<DIR>(bl); scan16x8<DIR>(bl + 8); scan16x8<DIR>(bl + 16); scan16x8<DIR>(bl + 24);
;         float eb[32];
; #pragma unroll
;         for (int i = 0; i < 32; ++i) { eb[i] = __builtin_amdgcn_exp2f(bl[i]); qin[i] *= eb[i]; }
;         if (r == (DIR ? 0 : 15)) {
; #pragma unroll
;             for (int ks = 0; ks < 4; ++ks) { *(f32x4*)(TOT + wid * 128 + 32 * ks + 8 * kq) = (f32x4){bl[8 * ks], bl[8 * ks + 1], bl[8 * ks + 2], bl[8 * ks + 3]}; *(f32x4*)(TOT + wid * 128 + 32 * ks + 8 * kq + 4) = (f32x4){bl[8 * ks + 4], bl[8 * ks + 5], bl[8 * ks + 6], bl[8 * ks + 7]}; }
; #pragma unroll
;             for (int ks = 0; ks < 4; ++ks) { *(f32x4*)(TOTE + wid * 128 + 32 * ks + 8 * kq) = (f32x4){eb[8 * ks], eb[8 * ks + 1], eb[8 * ks + 2], eb[8 * ks + 3]}; *(f32x4*)(TOTE + wid * 128 + 32 * ks + 8 * kq + 4) = (f32x4){eb[8 * ks + 4], eb[8 * ks + 5], eb[8 * ks + 6], eb[8 * ks + 7]}; }
	v_mov_b32_e32 v2, v88
	v_mov_b32_e32 v5, v91
	v_mov_b32_e32 v7, v93
	s_nop 1
	v_add_f32_dpp v12, v12, v12 row_shr:4 row_mask:0xf bank_mask:0xf bound_ctrl:1
	v_add_f32_dpp v13, v13, v13 row_shr:4 row_mask:0xf bank_mask:0xf bound_ctrl:1
	v_add_f32_dpp v14, v14, v14 row_shr:4 row_mask:0xf bank_mask:0xf bound_ctrl:1
	v_add_f32_dpp v15, v15, v15 row_shr:4 row_mask:0xf bank_mask:0xf bound_ctrl:1
	v_add_f32_dpp v8, v8, v8 row_shr:4 row_mask:0xf bank_mask:0xf bound_ctrl:1
	v_add_f32_dpp v9, v9, v9 row_shr:4 row_mask:0xf bank_mask:0xf bound_ctrl:1
	v_add_f32_dpp v10, v10, v10 row_shr:4 row_mask:0xf bank_mask:0xf bound_ctrl:1
	v_add_f32_dpp v11, v11, v11 row_shr:4 row_mask:0xf bank_mask:0xf bound_ctrl:1
	v_exp_f32_e32 v60, v32
	s_nop 1
	v_add_f32_dpp v12, v12, v12 row_shr:8 row_mask:0xf bank_mask:0xf bound_ctrl:1
	v_add_f32_dpp v13, v13, v13 row_shr:8 row_mask:0xf bank_mask:0xf bound_ctrl:1
	v_add_f32_dpp v14, v14, v14 row_shr:8 row_mask:0xf bank_mask:0xf bound_ctrl:1
	v_add_f32_dpp v15, v15, v15 row_shr:8 row_mask:0xf bank_mask:0xf bound_ctrl:1
	v_add_f32_dpp v8, v8, v8 row_shr:8 row_mask:0xf bank_mask:0xf bound_ctrl:1
	v_add_f32_dpp v9, v9, v9 row_shr:8 row_mask:0xf bank_mask:0xf bound_ctrl:1
	v_add_f32_dpp v10, v10, v10 row_shr:8 row_mask:0xf bank_mask:0xf bound_ctrl:1
	v_add_f32_dpp v11, v11, v11 row_shr:8 row_mask:0xf bank_mask:0xf bound_ctrl:1
	s_nop 1
	v_add_f32_dpp v4, v4, v4 row_shr:1 row_mask:0xf bank_mask:0xf bound_ctrl:1
	v_add_f32_dpp v5, v5, v5 row_shr:1 row_mask:0xf bank_mask:0xf bound_ctrl:1
	v_add_f32_dpp v6, v6, v6 row_shr:1 row_mask:0xf bank_mask:0xf bound_ctrl:1
	v_add_f32_dpp v7, v7, v7 row_shr:1 row_mask:0xf bank_mask:0xf bound_ctrl:1
	v_add_f32_dpp v0, v0, v0 row_shr:1 row_mask:0xf bank_mask:0xf bound_ctrl:1
	v_add_f32_dpp v1, v1, v1 row_shr:1 row_mask:0xf bank_mask:0xf bound_ctrl:1
	v_add_f32_dpp v2, v2, v2 row_shr:1 row_mask:0xf bank_mask:0xf bound_ctrl:1
	v_add_f32_dpp v3, v3, v3 row_shr:1 row_mask:0xf bank_mask:0xf bound_ctrl:1
	v_exp_f32_e32 v61, v33
	s_nop 1
	v_add_f32_dpp v4, v4, v4 row_shr:2 row_mask:0xf bank_mask:0xf bound_ctrl:1
	v_add_f32_dpp v5, v5, v5 row_shr:2 row_mask:0xf bank_mask:0xf bound_ctrl:1
	v_add_f32_dpp v6, v6, v6 row_shr:2 row_mask:0xf bank_mask:0xf bound_ctrl:1
	v_add_f32_dpp v7, v7, v7 row_shr:2 row_mask:0xf bank_mask:0xf bound_ctrl:1
	v_add_f32_dpp v0, v0, v0 row_shr:2 row_mask:0xf bank_mask:0xf bound_ctrl:1
	v_add_f32_dpp v1, v1, v1 row_shr:2 row_mask:0xf bank_mask:0xf bound_ctrl:1
	v_add_f32_dpp v2, v2, v2 row_shr:2 row_mask:0xf bank_mask:0xf bound_ctrl:1
	v_add_f32_dpp v3, v3, v3 row_shr:2 row_mask:0xf bank_mask:0xf bound_ctrl:1
	v_exp_f32_e32 v62, v34
	s_nop 1
	v_add_f32_dpp v4, v4, v4 row_shr:4 row_mask:0xf bank_mask:0xf bound_ctrl:1
	v_add_f32_dpp v5, v5, v5 row_shr:4 row_mask:0xf bank_mask:0xf bound_ctrl:1
	v_add_f32_dpp v6, v6, v6 row_shr:4 row_mask:0xf bank_mask:0xf bound_ctrl:1
	v_add_f32_dpp v7, v7, v7 row_shr:4 row_mask:0xf bank_mask:0xf bound_ctrl:1
	v_add_f32_dpp v0, v0, v0 row_shr:4 row_mask:0xf bank_mask:0xf bound_ctrl:1
	v_add_f32_dpp v1, v1, v1 row_shr:4 row_mask:0xf bank_mask:0xf bound_ctrl:1
	v_add_f32_dpp v2, v2, v2 row_shr:4 row_mask:0xf bank_mask:0xf bound_ctrl:1
	v_add_f32_dpp v3, v3, v3 row_shr:4 row_mask:0xf bank_mask:0xf bound_ctrl:1
	v_exp_f32_e32 v63, v35
	v_exp_f32_e32 v56, v24
	v_exp_f32_e32 v57, v25
	v_exp_f32_e32 v58, v26
	v_exp_f32_e32 v59, v27
	v_exp_f32_e32 v72, v20
	v_exp_f32_e32 v73, v21
	v_exp_f32_e32 v74, v22
	v_exp_f32_e32 v75, v23
	v_exp_f32_e32 v68, v16
	v_exp_f32_e32 v69, v17
	v_exp_f32_e32 v70, v18
	v_exp_f32_e32 v71, v19
	v_exp_f32_e32 v76, v12
	v_exp_f32_e32 v77, v13
	v_exp_f32_e32 v78, v14
	v_exp_f32_e32 v79, v15
	v_exp_f32_e32 v40, v8
	v_exp_f32_e32 v41, v9
	v_exp_f32_e32 v42, v10
	v_exp_f32_e32 v43, v11
	s_nop 1
	v_add_f32_dpp v4, v4, v4 row_shr:8 row_mask:0xf bank_mask:0xf bound_ctrl:1
	v_add_f32_dpp v5, v5, v5 row_shr:8 row_mask:0xf bank_mask:0xf bound_ctrl:1
	v_add_f32_dpp v6, v6, v6 row_shr:8 row_mask:0xf bank_mask:0xf bound_ctrl:1
	v_add_f32_dpp v7, v7, v7 row_shr:8 row_mask:0xf bank_mask:0xf bound_ctrl:1
	v_add_f32_dpp v0, v0, v0 row_shr:8 row_mask:0xf bank_mask:0xf bound_ctrl:1
	v_add_f32_dpp v1, v1, v1 row_shr:8 row_mask:0xf bank_mask:0xf bound_ctrl:1
	v_add_f32_dpp v2, v2, v2 row_shr:8 row_mask:0xf bank_mask:0xf bound_ctrl:1
	v_add_f32_dpp v3, v3, v3 row_shr:8 row_mask:0xf bank_mask:0xf bound_ctrl:1
	s_nop 0
	v_exp_f32_e32 v36, v4
	v_exp_f32_e32 v37, v5
	v_exp_f32_e32 v38, v6
	v_exp_f32_e32 v39, v7
	v_exp_f32_e32 v28, v0
	v_exp_f32_e32 v29, v1
	v_exp_f32_e32 v30, v2
	v_exp_f32_e32 v31, v3
	s_and_saveexec_b64 s[6:7], vcc
	s_cbranch_execz .LBB0_2611
	s_add_i32 s5, s37, 0
	v_lshl_add_u32 v153, v82, 2, s5
	ds_write_b128 v153, v[32:35]
	ds_write_b128 v153, v[24:27] offset:16
	ds_write_b128 v153, v[20:23] offset:128
	ds_write_b128 v153, v[16:19] offset:144
	ds_write_b128 v153, v[12:15] offset:256
	ds_write_b128 v153, v[8:11] offset:272
	ds_write_b128 v153, v[4:7] offset:384
	ds_write_b128 v153, v[0:3] offset:400
	ds_write_b128 v153, v[60:63] offset:4096
	ds_write_b128 v153, v[56:59] offset:4112
	ds_write_b128 v153, v[72:75] offset:4224
	ds_write_b128 v153, v[68:71] offset:4240
	ds_write_b128 v153, v[76:79] offset:4352
	ds_write_b128 v153, v[40:43] offset:4368
	ds_write_b128 v153, v[36:39] offset:4480
	ds_write_b128 v153, v[28:31] offset:4496

; __device__ __forceinline__ bf16x8 pk8(const float* v) { u32x4 w; w.x = cvt_pk_bf16(v[0], v[1]); w.y = cvt_pk_bf16(v[2], v[3]); w.z = cvt_pk_bf16(v[4], v[5]); w.w = cvt_pk_bf16(v[6], v[7]); return __builtin_bit_cast(bf16x8, w); }
; #define WAVE_LDS_FENCE() do { asm volatile("s_waitcnt lgkmcnt(0)" ::: "memory"); __builtin_amdgcn_wave_barrier(); } while (0)
; template <int DIR> __device__ __forceinline__ void h3_dir(unsigned char* lds, const bf16_t* zrow, int h, const bf16_t* slot, f32x4 (&o)[8]) {
;     ...
; #pragma unroll
;     for (int i = 0; i < 32; ++i) qin[i] *= run[i];
;     WAVE_LDS_FENCE();
; #pragma unroll
;     for (int ks = 0; ks < 4; ++ks) {
;         const bf16x8 aq = pk8(qin + 8 * ks), ap = *(const bf16x8*)(Pw + r * HP + 32 * ks + 8 * kq);
; #pragma unroll
;         for (int nt = 0; nt < 8; ++nt) {
;             o[nt] = __builtin_amdgcn_mfma_f32_16x16x32_bf16(aq, *(const bf16x8*)(ST + (16 * nt + r) * HP + 32 * ks + 8 * kq), o[nt], 0, 0, 0);
;             o[nt] = __builtin_amdgcn_mfma_f32_16x16x32_bf16(ap, *(const bf16x8*)(VT + (16 * nt + r) * HP + 32 * ks + 8 * kq), o[nt], 0, 0, 0);
;         }
;     }
.LBB0_2619:
	v_mul_u32_u24_e32 v45, 0x88, v83
	v_lshlrev_b32_e32 v45, 1, v45
	v_lshlrev_b32_e32 v44, 1, v82
	v_add_u32_e32 v110, v40, v45
	v_mul_u32_u24_e32 v40, 0x110, v83
	v_mul_f32_e32 v24, v60, v24
	v_mul_f32_e32 v25, v61, v25
	v_mul_f32_e32 v26, v62, v26
	v_mul_f32_e32 v27, v63, v27
	v_mul_f32_e32 v28, v64, v28
	v_mul_f32_e32 v29, v65, v29
	v_mul_f32_e32 v30, v66, v30
	v_mul_f32_e32 v31, v59, v31
	v_add3_u32 v102, s6, v40, v44
	s_waitcnt lgkmcnt(0)
	v_cvt_pk_bf16_f32 v24, v24, v25
	v_cvt_pk_bf16_f32 v25, v26, v27
	v_cvt_pk_bf16_f32 v26, v28, v29
	v_cvt_pk_bf16_f32 v27, v30, v31
	ds_read_b128 v[28:31], v110 offset:43008
	ds_read_b128 v[60:63], v102
	s_add_i32 s35, 0, 0x13000
	v_add3_u32 v111, s35, v44, v45
	ds_read_b128 v[64:67], v111
	s_waitcnt lgkmcnt(2)
	v_mfma_f32_16x16x32_bf16 v[28:31], v[24:27], v[28:31], 0
	v_add_u32_e32 v40, 0xa800, v110
	ds_read_b128 v[68:71], v40 offset:30464
	v_mul_f32_e32 v45, v54, v22
	s_waitcnt lgkmcnt(1)
	v_mfma_f32_16x16x32_bf16 v[28:31], v[60:63], v[64:67], v[28:31]
	ds_read_b128 v[64:67], v110 offset:47360
	ds_read_b128 v[72:75], v110 offset:51712
	ds_read_b128 v[76:79], v111 offset:4352
	ds_read_b128 v[82:85], v111 offset:8704
	v_mul_f32_e32 v54, v55, v23
	s_waitcnt lgkmcnt(3)
	v_mfma_f32_16x16x32_bf16 v[64:67], v[24:27], v[64:67], 0
	v_mul_f32_e32 v55, v56, v16
	v_mul_f32_e32 v51, v51, v17
	v_mul_f32_e32 v56, v52, v18
	s_waitcnt lgkmcnt(2)
	v_mfma_f32_16x16x32_bf16 v[72:75], v[24:27], v[72:75], 0
	v_mul_f32_e32 v44, v58, v21
	v_add_u32_e32 v116, 0xa8c0, v110
	v_mov_b32_e32 v151, v254
	s_waitcnt lgkmcnt(1)
	v_mfma_f32_16x16x32_bf16 v[64:67], v[60:63], v[76:79], v[64:67]
	s_waitcnt lgkmcnt(0)
	v_mfma_f32_16x16x32_bf16 v[72:75], v[60:63], v[82:85], v[72:75]
	ds_read_b128 v[76:79], v110 offset:56064
	ds_read_b128 v[82:85], v110 offset:60416
	ds_read_b128 v[86:89], v111 offset:13056
	ds_read_b128 v[90:93], v111 offset:17408
	s_waitcnt lgkmcnt(3)
	v_mfma_f32_16x16x32_bf16 v[76:79], v[24:27], v[76:79], 0
	s_waitcnt lgkmcnt(2)
	v_mfma_f32_16x16x32_bf16 v[82:85], v[24:27], v[82:85], 0
	s_waitcnt lgkmcnt(1)
	v_mfma_f32_16x16x32_bf16 v[76:79], v[60:63], v[86:89], v[76:79]
	s_waitcnt lgkmcnt(0)
	v_mfma_f32_16x16x32_bf16 v[82:85], v[60:63], v[90:93], v[82:85]
	ds_read_b128 v[86:89], v110 offset:64768
	ds_read_b128 v[90:93], v40 offset:26112
	ds_read_b128 v[94:97], v111 offset:21760
	ds_read_b128 v[98:101], v111 offset:26112
	v_mul_f32_e32 v40, v57, v20
	s_waitcnt lgkmcnt(3)
	v_mfma_f32_16x16x32_bf16 v[86:89], v[24:27], v[86:89], 0
	v_mul_f32_e32 v57, v53, v19
	s_waitcnt lgkmcnt(2)
	v_mfma_f32_16x16x32_bf16 v[90:93], v[24:27], v[90:93], 0
	v_mfma_f32_16x16x32_bf16 v[16:19], v[24:27], v[68:71], 0
	ds_read_b128 v[24:27], v111 offset:30464
	v_cvt_pk_bf16_f32 v52, v40, v44
	v_cvt_pk_bf16_f32 v53, v45, v54
	v_cvt_pk_bf16_f32 v54, v55, v51
	v_cvt_pk_bf16_f32 v55, v56, v57
	ds_read_b128 v[56:59], v110 offset:43072
	s_waitcnt lgkmcnt(1)
	v_mfma_f32_16x16x32_bf16 v[16:19], v[60:63], v[24:27], v[16:19]
	ds_read_b128 v[24:27], v102 offset:64
	v_mul_f32_e32 v40, v49, v8
	v_mfma_f32_16x16x32_bf16 v[86:89], v[60:63], v[94:97], v[86:89]
	v_mul_f32_e32 v94, v50, v9
	v_mfma_f32_16x16x32_bf16 v[20:23], v[60:63], v[98:101], v[90:93]
	s_waitcnt lgkmcnt(1)
	v_mfma_f32_16x16x32_bf16 v[28:31], v[52:55], v[56:59], v[28:31]
	ds_read_b128 v[56:59], v111 offset:64
	ds_read_b128 v[60:63], v110 offset:64832
	s_waitcnt lgkmcnt(1)
	v_mfma_f32_16x16x32_bf16 v[28:31], v[24:27], v[56:59], v[28:31]
	ds_read_b128 v[56:59], v110 offset:47424
	ds_read_b128 v[68:71], v110 offset:51776
	s_waitcnt lgkmcnt(1)
	v_mfma_f32_16x16x32_bf16 v[56:59], v[52:55], v[56:59], v[64:67]
	s_nop 2
	ds_read_b128 v[64:67], v111 offset:4416
	ds_read_b128 v[90:93], v111 offset:8768
	s_waitcnt lgkmcnt(1)
	v_mfma_f32_16x16x32_bf16 v[56:59], v[24:27], v[64:67], v[56:59]
	v_mfma_f32_16x16x32_bf16 v[64:67], v[52:55], v[68:71], v[72:75]
	s_waitcnt lgkmcnt(0)
	v_mfma_f32_16x16x32_bf16 v[64:67], v[24:27], v[90:93], v[64:67]
	ds_read_b128 v[68:71], v110 offset:56128
	ds_read_b128 v[72:75], v111 offset:13120
	ds_read_b128 v[90:93], v110 offset:60480
	s_waitcnt lgkmcnt(2)
	v_mfma_f32_16x16x32_bf16 v[68:71], v[52:55], v[68:71], v[76:79]
	s_nop 2
	ds_read_b128 v[76:79], v111 offset:17472
	s_waitcnt lgkmcnt(2)
	v_mfma_f32_16x16x32_bf16 v[68:71], v[24:27], v[72:75], v[68:71]
	v_mul_f32_e32 v72, v46, v10
	v_mul_f32_e32 v73, v47, v11
	v_mul_f32_e32 v74, v48, v4
	s_waitcnt lgkmcnt(1)
	v_mfma_f32_16x16x32_bf16 v[8:11], v[52:55], v[90:93], v[82:85]
	v_mul_f32_e32 v90, v32, v12
	v_add_u32_e32 v32, 0xa840, v110
	v_mul_f32_e32 v75, v41, v5
	v_mul_f32_e32 v82, v42, v6
	v_mul_f32_e32 v83, v34, v7
	s_waitcnt lgkmcnt(0)
	v_mfma_f32_16x16x32_bf16 v[4:7], v[24:27], v[76:79], v[8:11]
	v_mul_f32_e32 v91, v33, v13
	v_mul_f32_e32 v92, v43, v1
	v_mul_f32_e32 v93, v38, v2
	ds_read_b128 v[8:11], v111 offset:21824
	v_mfma_f32_16x16x32_bf16 v[44:47], v[52:55], v[60:63], v[86:89]
	ds_read_b128 v[48:51], v32 offset:26112
	ds_read_b128 v[60:63], v111 offset:26176
	s_nop 0
	v_mul_f32_e32 v87, v36, v14
	v_mul_f32_e32 v88, v37, v15
	ds_read_b128 v[12:15], v111 offset:30528
	v_mul_f32_e32 v89, v35, v0
	ds_read_b128 v[32:35], v32 offset:30464
	s_waitcnt lgkmcnt(4)
	v_mfma_f32_16x16x32_bf16 v[8:11], v[24:27], v[8:11], v[44:47]
	v_cvt_pk_bf16_f32 v40, v40, v94
	v_cvt_pk_bf16_f32 v41, v72, v73
	v_cvt_pk_bf16_f32 v42, v74, v75
	s_waitcnt lgkmcnt(0)
	v_mfma_f32_16x16x32_bf16 v[16:19], v[52:55], v[32:35], v[16:19]
	v_cvt_pk_bf16_f32 v43, v82, v83
	ds_read_b128 v[32:35], v102 offset:128
	ds_read_b128 v[44:47], v110 offset:43136
	v_mul_f32_e32 v94, v39, v3
	v_mfma_f32_16x16x32_bf16 v[20:23], v[52:55], v[48:51], v[20:23]
	ds_read_b128 v[0:3], v111 offset:128
	v_add_u32_e32 v82, 0xa880, v110
	v_mfma_f32_16x16x32_bf16 v[20:23], v[24:27], v[60:63], v[20:23]
	v_mfma_f32_16x16x32_bf16 v[12:15], v[24:27], v[12:15], v[16:19]
	s_waitcnt lgkmcnt(1)
; __device__ __forceinline__ bf16x8 pk8(const float* v) { u32x4 w; w.x = cvt_pk_bf16(v[0], v[1]); w.y = cvt_pk_bf16(v[2], v[3]); w.z = cvt_pk_bf16(v[4], v[5]); w.w = cvt_pk_bf16(v[6], v[7]); return __builtin_bit_cast(bf16x8, w); }
; template <int DIR> __device__ __forceinline__ void h3_dir(unsigned char* lds, const bf16_t* zrow, int h, const bf16_t* slot, f32x4 (&o)[8]) {
;     ...
;     float bl[32], qin[32]; bf16x8 kin[4];
;     load32(zrow + (size_t)(1 + DIR) * ZSEG + 8 * kq, bl);
;     load32(zrow + 8 * kq, qin);
;     {
;     ...
;     for (int ks = 0; ks < 4; ++ks) {
;         const bf16x8 aq = pk8(qin + 8 * ks), ap = *(const bf16x8*)(Pw + r * HP + 32 * ks + 8 * kq);
; #pragma unroll
;         for (int nt = 0; nt < 8; ++nt) {
;             o[nt] = __builtin_amdgcn_mfma_f32_16x16x32_bf16(aq, *(const bf16x8*)(ST + (16 * nt + r) * HP + 32 * ks + 8 * kq), o[nt], 0, 0, 0);
;             o[nt] = __builtin_amdgcn_mfma_f32_16x16x32_bf16(ap, *(const bf16x8*)(VT + (16 * nt + r) * HP + 32 * ks + 8 * kq), o[nt], 0, 0, 0);
;         }
;     }
;     __syncthreads();
	v_mfma_f32_16x16x32_bf16 v[16:19], v[40:43], v[44:47], v[28:31]
	ds_read_b128 v[24:27], v110 offset:47488
	s_nop 1
	ds_read_b128 v[28:31], v110 offset:64896
	s_waitcnt lgkmcnt(2)
	v_mfma_f32_16x16x32_bf16 v[0:3], v[32:35], v[0:3], v[16:19]
	s_nop 2
	ds_read_b128 v[16:19], v110 offset:51840
	ds_read_b128 v[36:39], v111 offset:4480
	ds_read_b128 v[44:47], v111 offset:8832
	s_waitcnt lgkmcnt(4)
	v_mfma_f32_16x16x32_bf16 v[24:27], v[40:43], v[24:27], v[56:59]
	ds_read_b128 v[48:51], v110 offset:56192
	ds_read_b128 v[52:55], v110 offset:60544
	s_nop 0
	ds_read_b128 v[56:59], v111 offset:13184
	ds_read_b128 v[60:63], v111 offset:17536
	s_waitcnt lgkmcnt(2)
	v_mfma_f32_16x16x32_bf16 v[4:7], v[40:43], v[52:55], v[4:7]
	v_mfma_f32_16x16x32_bf16 v[16:19], v[40:43], v[16:19], v[64:67]
	v_mfma_f32_16x16x32_bf16 v[36:39], v[32:35], v[36:39], v[24:27]
	s_nop 2
	ds_read_b128 v[24:27], v111 offset:21888
	ds_read_b128 v[72:75], v111 offset:26240
	ds_read_b128 v[76:79], v82 offset:30464
	ds_read_b128 v[64:67], v82 offset:26112
	ds_read_b128 v[82:85], v111 offset:30592
	v_cvt_pk_bf16_f32 v86, v90, v91
	s_waitcnt lgkmcnt(5)
	v_mfma_f32_16x16x32_bf16 v[60:63], v[32:35], v[60:63], v[4:7]
	v_cvt_pk_bf16_f32 v87, v87, v88
	v_cvt_pk_bf16_f32 v88, v89, v92
	v_cvt_pk_bf16_f32 v89, v93, v94
	v_mfma_f32_16x16x32_bf16 v[4:7], v[40:43], v[28:31], v[8:11]
	v_mfma_f32_16x16x32_bf16 v[16:19], v[32:35], v[44:47], v[16:19]
	v_mfma_f32_16x16x32_bf16 v[44:47], v[40:43], v[48:51], v[68:71]
	ds_read_b128 v[48:51], v102 offset:192
	s_nop 1
	ds_read_b128 v[68:71], v110 offset:43200
	ds_read_b128 v[90:93], v110 offset:47552
	ds_read_b128 v[94:97], v110 offset:51904
	s_waitcnt lgkmcnt(8)
	v_mfma_f32_16x16x32_bf16 v[208:211], v[32:35], v[24:27], v[4:7]
	s_waitcnt lgkmcnt(5)
	v_mfma_f32_16x16x32_bf16 v[4:7], v[40:43], v[64:67], v[20:23]
	v_mfma_f32_16x16x32_bf16 v[44:47], v[32:35], v[56:59], v[44:47]
	ds_read_b128 v[56:59], v111 offset:4544
	ds_read_b128 v[98:101], v111 offset:8896
	ds_read_b128 v[102:105], v110 offset:56256
	ds_read_b128 v[106:109], v110 offset:60608
	ds_read_b128 v[52:55], v111 offset:13248
	ds_read_b128 v[152:155], v111 offset:17600
	ds_read_b128 v[156:159], v111 offset:192
	ds_read_b128 v[188:191], v110 offset:64960
	ds_read_b128 v[192:195], v111 offset:21952
	ds_read_b128 v[196:199], v111 offset:26304
	ds_read_b128 v[200:203], v116 offset:30464
	ds_read_b128 v[28:31], v116 offset:26112
	ds_read_b128 v[204:207], v111 offset:30656
	s_waitcnt lgkmcnt(0)
	s_barrier
	v_mfma_f32_16x16x32_bf16 v[20:23], v[32:35], v[72:75], v[4:7]
	v_bfe_u32 v150, v151, 4, 2
	v_lshlrev_b32_e32 v116, 4, v150
	v_lshl_add_u64 v[80:81], v[80:81], 0, v[116:117]
	v_add_co_u32_e32 v4, vcc, s28, v80
	v_lshl_add_u64 v[24:25], v[80:81], 0, s[14:15]
	s_nop 0
	v_addc_co_u32_e32 v5, vcc, 0, v81, vcc
	global_load_dwordx4 v[4:7], v[4:5], off
	v_mfma_f32_16x16x32_bf16 v[8:11], v[40:43], v[76:79], v[12:15]
	global_load_dwordx4 v[40:43], v[24:25], off offset:128
	global_load_dwordx4 v[64:67], v[24:25], off offset:192
	v_readfirstlane_b32 s3, v151
	global_load_dwordx4 v[12:15], v[24:25], off offset:64
	v_mfma_f32_16x16x32_bf16 v[32:35], v[32:35], v[82:85], v[8:11]
	s_ashr_i32 s36, s3, 6
	v_and_b32_e32 v149, 15, v151
	v_lshlrev_b32_e32 v148, 3, v150
	v_mfma_f32_16x16x32_bf16 v[8:11], v[86:89], v[102:105], v[44:47]
	v_cmp_eq_u32_e32 vcc, 0, v149
	s_lshl_b32 s3, s36, 9
	s_waitcnt vmcnt(3)
	v_lshlrev_b32_e32 v182, 16, v4
	v_and_b32_e32 v181, 0xffff0000, v4
	v_lshlrev_b32_e32 v180, 16, v5
	v_and_b32_e32 v179, 0xffff0000, v5
	v_lshlrev_b32_e32 v177, 16, v6
	v_and_b32_e32 v178, 0xffff0000, v6
	v_lshlrev_b32_e32 v176, 16, v7
	v_and_b32_e32 v174, 0xffff0000, v7
	v_mfma_f32_16x16x32_bf16 v[4:7], v[86:89], v[94:97], v[16:19]
	s_waitcnt vmcnt(0)
	v_lshlrev_b32_e32 v175, 16, v12
	v_and_b32_e32 v173, 0xffff0000, v12
	v_lshlrev_b32_e32 v116, 16, v13
	v_mfma_f32_16x16x32_bf16 v[4:7], v[48:51], v[98:101], v[4:7]
	v_and_b32_e32 v172, 0xffff0000, v13
	v_lshlrev_b32_e32 v168, 16, v14
	v_and_b32_e32 v169, 0xffff0000, v14
	v_lshlrev_b32_e32 v170, 16, v15
	v_and_b32_e32 v171, 0xffff0000, v15
	v_mfma_f32_16x16x32_bf16 v[12:15], v[86:89], v[106:109], v[60:63]
	global_load_dwordx4 v[108:111], v[80:81], off
	global_load_dwordx4 v[104:107], v[80:81], off offset:64
	global_load_dwordx4 v[100:103], v[80:81], off offset:128
	global_load_dwordx4 v[96:99], v[80:81], off offset:192
	v_mov_b32_e32 v61, v178
	v_mov_b32_e32 v63, v174
	v_mfma_f32_16x16x32_bf16 v[0:3], v[86:89], v[68:71], v[0:3]
	v_mov_b32_e32 v60, v177
	v_mov_b32_e32 v62, v176
	v_lshlrev_b32_e32 v164, 16, v40
	v_mfma_f32_16x16x32_bf16 v[24:27], v[48:51], v[156:159], v[0:3]
	v_lshlrev_b32_e32 v156, 16, v64
	v_and_b32_e32 v157, 0xffff0000, v64
	v_lshlrev_b32_e32 v158, 16, v65
	v_mfma_f32_16x16x32_bf16 v[0:3], v[86:89], v[90:93], v[36:39]
	v_and_b32_e32 v159, 0xffff0000, v65
	v_mov_b32_e32 v64, v182
	v_mov_b32_e32 v65, v181
	v_mfma_f32_16x16x32_bf16 v[16:19], v[86:89], v[188:191], v[208:211]
	v_and_b32_e32 v165, 0xffff0000, v40
	v_lshlrev_b32_e32 v166, 16, v41
	v_and_b32_e32 v167, 0xffff0000, v41
	v_mfma_f32_16x16x32_bf16 v[20:23], v[86:89], v[28:31], v[20:23]
	v_lshlrev_b32_e32 v160, 16, v42
	v_and_b32_e32 v161, 0xffff0000, v42
	v_lshlrev_b32_e32 v162, 16, v43
	v_mfma_f32_16x16x32_bf16 v[28:31], v[86:89], v[200:203], v[32:35]
	v_and_b32_e32 v163, 0xffff0000, v43
	v_mov_b32_e32 v47, v167
	v_mov_b32_e32 v41, v161
	v_mfma_f32_16x16x32_bf16 v[12:15], v[48:51], v[152:155], v[12:15]
	v_lshlrev_b32_e32 v152, 16, v66
	v_and_b32_e32 v153, 0xffff0000, v66
	v_lshlrev_b32_e32 v154, 16, v67
	v_and_b32_e32 v155, 0xffff0000, v67
	v_mov_b32_e32 v67, v179
	v_mov_b32_e32 v66, v180
	s_nop 1
; __device__ __forceinline__ float bf_lo(unsigned w) { return __uint_as_float(w << 16); }
; __device__ __forceinline__ float bf_hi(unsigned w) { return __uint_as_float(w & 0xffff0000u); }
; template <int DIR> __device__ __forceinline__ void scan16x8(float* v) {
;     if (DIR == 0) { SCAN_STEP("row_shr:", 1); SCAN_STEP("row_shr:", 2); SCAN_STEP("row_shr:", 4); SCAN_STEP("row_shr:", 8); }
;     else          { SCAN_STEP("row_shl:", 1); SCAN_STEP("row_shl:", 2); SCAN_STEP("row_shl:", 4); SCAN_STEP("row_shl:", 8); }
; }
; __device__ __forceinline__ void load32(const bf16_t* p, float (&v)[32]) {
; #pragma unroll
;     for (int ks = 0; ks < 4; ++ks) { const u32x4 w = *(const u32x4*)(p + 32 * ks);
;         v[8 * ks + 0] = bf_lo(w.x); v[8 * ks + 1] = bf_hi(w.x); v[8 * ks + 2] = bf_lo(w.y); v[8 * ks + 3] = bf_hi(w.y); v[8 * ks + 4] = bf_lo(w.z); v[8 * ks + 5] = bf_hi(w.z); v[8 * ks + 6] = bf_lo(w.w); v[8 * ks + 7] = bf_hi(w.w); }
	v_add_f32_dpp v64, v64, v64 row_shl:1 row_mask:0xf bank_mask:0xf bound_ctrl:1
	v_add_f32_dpp v65, v65, v65 row_shl:1 row_mask:0xf bank_mask:0xf bound_ctrl:1
	v_add_f32_dpp v66, v66, v66 row_shl:1 row_mask:0xf bank_mask:0xf bound_ctrl:1
	v_add_f32_dpp v67, v67, v67 row_shl:1 row_mask:0xf bank_mask:0xf bound_ctrl:1
	v_add_f32_dpp v60, v60, v60 row_shl:1 row_mask:0xf bank_mask:0xf bound_ctrl:1
	v_add_f32_dpp v61, v61, v61 row_shl:1 row_mask:0xf bank_mask:0xf bound_ctrl:1
	v_add_f32_dpp v62, v62, v62 row_shl:1 row_mask:0xf bank_mask:0xf bound_ctrl:1
	v_add_f32_dpp v63, v63, v63 row_shl:1 row_mask:0xf bank_mask:0xf bound_ctrl:1
	v_mfma_f32_16x16x32_bf16 v[0:3], v[48:51], v[56:59], v[0:3]
	s_nop 1
	v_add_f32_dpp v64, v64, v64 row_shl:2 row_mask:0xf bank_mask:0xf bound_ctrl:1
	v_add_f32_dpp v65, v65, v65 row_shl:2 row_mask:0xf bank_mask:0xf bound_ctrl:1
	v_add_f32_dpp v66, v66, v66 row_shl:2 row_mask:0xf bank_mask:0xf bound_ctrl:1
	v_add_f32_dpp v67, v67, v67 row_shl:2 row_mask:0xf bank_mask:0xf bound_ctrl:1
	v_add_f32_dpp v60, v60, v60 row_shl:2 row_mask:0xf bank_mask:0xf bound_ctrl:1
	v_add_f32_dpp v61, v61, v61 row_shl:2 row_mask:0xf bank_mask:0xf bound_ctrl:1
	v_add_f32_dpp v62, v62, v62 row_shl:2 row_mask:0xf bank_mask:0xf bound_ctrl:1
	v_add_f32_dpp v63, v63, v63 row_shl:2 row_mask:0xf bank_mask:0xf bound_ctrl:1
	v_mov_b32_e32 v44, v164
	s_nop 1
	v_add_f32_dpp v64, v64, v64 row_shl:4 row_mask:0xf bank_mask:0xf bound_ctrl:1
	v_add_f32_dpp v65, v65, v65 row_shl:4 row_mask:0xf bank_mask:0xf bound_ctrl:1
	v_add_f32_dpp v66, v66, v66 row_shl:4 row_mask:0xf bank_mask:0xf bound_ctrl:1
	v_add_f32_dpp v67, v67, v67 row_shl:4 row_mask:0xf bank_mask:0xf bound_ctrl:1
	v_add_f32_dpp v60, v60, v60 row_shl:4 row_mask:0xf bank_mask:0xf bound_ctrl:1
	v_add_f32_dpp v61, v61, v61 row_shl:4 row_mask:0xf bank_mask:0xf bound_ctrl:1
	v_add_f32_dpp v62, v62, v62 row_shl:4 row_mask:0xf bank_mask:0xf bound_ctrl:1
	v_add_f32_dpp v63, v63, v63 row_shl:4 row_mask:0xf bank_mask:0xf bound_ctrl:1
	v_mfma_f32_16x16x32_bf16 v[8:11], v[48:51], v[52:55], v[8:11]
	v_mov_b32_e32 v55, v172
	v_mov_b32_e32 v52, v175
	v_mov_b32_e32 v54, v116
	v_mfma_f32_16x16x32_bf16 v[16:19], v[48:51], v[192:195], v[16:19]
	v_mov_b32_e32 v53, v173
	s_nop 1
	v_add_f32_dpp v64, v64, v64 row_shl:8 row_mask:0xf bank_mask:0xf bound_ctrl:1
	v_add_f32_dpp v65, v65, v65 row_shl:8 row_mask:0xf bank_mask:0xf bound_ctrl:1
	v_add_f32_dpp v66, v66, v66 row_shl:8 row_mask:0xf bank_mask:0xf bound_ctrl:1
	v_add_f32_dpp v67, v67, v67 row_shl:8 row_mask:0xf bank_mask:0xf bound_ctrl:1
	v_add_f32_dpp v60, v60, v60 row_shl:8 row_mask:0xf bank_mask:0xf bound_ctrl:1
	v_add_f32_dpp v61, v61, v61 row_shl:8 row_mask:0xf bank_mask:0xf bound_ctrl:1
	v_add_f32_dpp v62, v62, v62 row_shl:8 row_mask:0xf bank_mask:0xf bound_ctrl:1
	v_add_f32_dpp v63, v63, v63 row_shl:8 row_mask:0xf bank_mask:0xf bound_ctrl:1
	v_mov_b32_e32 v43, v163
	v_mfma_f32_16x16x32_bf16 v[20:23], v[48:51], v[196:199], v[20:23]
	v_mov_b32_e32 v46, v166
	v_mov_b32_e32 v40, v160
	v_mov_b32_e32 v42, v162
	v_mfma_f32_16x16x32_bf16 v[28:31], v[48:51], v[204:207], v[28:31]
	v_mov_b32_e32 v49, v169
	v_mov_b32_e32 v51, v171
	v_mov_b32_e32 v48, v168
	v_mov_b32_e32 v50, v170
	s_nop 1
	v_add_f32_dpp v52, v52, v52 row_shl:1 row_mask:0xf bank_mask:0xf bound_ctrl:1
	v_add_f32_dpp v53, v53, v53 row_shl:1 row_mask:0xf bank_mask:0xf bound_ctrl:1
	v_add_f32_dpp v54, v54, v54 row_shl:1 row_mask:0xf bank_mask:0xf bound_ctrl:1
	v_add_f32_dpp v55, v55, v55 row_shl:1 row_mask:0xf bank_mask:0xf bound_ctrl:1
	v_add_f32_dpp v48, v48, v48 row_shl:1 row_mask:0xf bank_mask:0xf bound_ctrl:1
	v_add_f32_dpp v49, v49, v49 row_shl:1 row_mask:0xf bank_mask:0xf bound_ctrl:1
	v_add_f32_dpp v50, v50, v50 row_shl:1 row_mask:0xf bank_mask:0xf bound_ctrl:1
	v_add_f32_dpp v51, v51, v51 row_shl:1 row_mask:0xf bank_mask:0xf bound_ctrl:1
	v_mov_b32_e32 v45, v165
	s_nop 1
	v_add_f32_dpp v52, v52, v52 row_shl:2 row_mask:0xf bank_mask:0xf bound_ctrl:1
	v_add_f32_dpp v53, v53, v53 row_shl:2 row_mask:0xf bank_mask:0xf bound_ctrl:1
	v_add_f32_dpp v54, v54, v54 row_shl:2 row_mask:0xf bank_mask:0xf bound_ctrl:1
	v_add_f32_dpp v55, v55, v55 row_shl:2 row_mask:0xf bank_mask:0xf bound_ctrl:1
	v_add_f32_dpp v48, v48, v48 row_shl:2 row_mask:0xf bank_mask:0xf bound_ctrl:1
	v_add_f32_dpp v49, v49, v49 row_shl:2 row_mask:0xf bank_mask:0xf bound_ctrl:1
	v_add_f32_dpp v50, v50, v50 row_shl:2 row_mask:0xf bank_mask:0xf bound_ctrl:1
	v_add_f32_dpp v51, v51, v51 row_shl:2 row_mask:0xf bank_mask:0xf bound_ctrl:1
	v_mov_b32_e32 v39, v159
	s_nop 1
	v_add_f32_dpp v52, v52, v52 row_shl:4 row_mask:0xf bank_mask:0xf bound_ctrl:1
	v_add_f32_dpp v53, v53, v53 row_shl:4 row_mask:0xf bank_mask:0xf bound_ctrl:1
	v_add_f32_dpp v54, v54, v54 row_shl:4 row_mask:0xf bank_mask:0xf bound_ctrl:1
	v_add_f32_dpp v55, v55, v55 row_shl:4 row_mask:0xf bank_mask:0xf bound_ctrl:1
	v_add_f32_dpp v48, v48, v48 row_shl:4 row_mask:0xf bank_mask:0xf bound_ctrl:1
	v_add_f32_dpp v49, v49, v49 row_shl:4 row_mask:0xf bank_mask:0xf bound_ctrl:1
	v_add_f32_dpp v50, v50, v50 row_shl:4 row_mask:0xf bank_mask:0xf bound_ctrl:1
	v_add_f32_dpp v51, v51, v51 row_shl:4 row_mask:0xf bank_mask:0xf bound_ctrl:1
	v_mov_b32_e32 v33, v153
	s_nop 1
	v_add_f32_dpp v52, v52, v52 row_shl:8 row_mask:0xf bank_mask:0xf bound_ctrl:1
	v_add_f32_dpp v53, v53, v53 row_shl:8 row_mask:0xf bank_mask:0xf bound_ctrl:1
	v_add_f32_dpp v54, v54, v54 row_shl:8 row_mask:0xf bank_mask:0xf bound_ctrl:1
	v_add_f32_dpp v55, v55, v55 row_shl:8 row_mask:0xf bank_mask:0xf bound_ctrl:1
	v_add_f32_dpp v48, v48, v48 row_shl:8 row_mask:0xf bank_mask:0xf bound_ctrl:1
; template <int DIR> __device__ __forceinline__ void h3_dir(unsigned char* lds, const bf16_t* zrow, int h, const bf16_t* slot, f32x4 (&o)[8]) {
;     ...
; #pragma unroll
;         for (int i = 0; i < 32; ++i) kk[i] = 1.0f - __builtin_amdgcn_exp2f(bl[i]);
;         scan16x8<DIR>(bl); scan16x8<DIR>(bl + 8); scan16x8<DIR>(bl + 16); scan16x8<DIR>(bl + 24);
;         float eb[32];
; #pragma unroll
;         for (int i = 0; i < 32; ++i) { eb[i] = __builtin_amdgcn_exp2f(bl[i]); qin[i] *= eb[i]; }
;         if (r == (DIR ? 0 : 15)) {
	v_add_f32_dpp v49, v49, v49 row_shl:8 row_mask:0xf bank_mask:0xf bound_ctrl:1
	v_add_f32_dpp v50, v50, v50 row_shl:8 row_mask:0xf bank_mask:0xf bound_ctrl:1
	v_add_f32_dpp v51, v51, v51 row_shl:8 row_mask:0xf bank_mask:0xf bound_ctrl:1
	s_nop 1
	v_add_f32_dpp v44, v44, v44 row_shl:1 row_mask:0xf bank_mask:0xf bound_ctrl:1
	v_add_f32_dpp v45, v45, v45 row_shl:1 row_mask:0xf bank_mask:0xf bound_ctrl:1
	v_add_f32_dpp v46, v46, v46 row_shl:1 row_mask:0xf bank_mask:0xf bound_ctrl:1
	v_add_f32_dpp v47, v47, v47 row_shl:1 row_mask:0xf bank_mask:0xf bound_ctrl:1
	v_add_f32_dpp v40, v40, v40 row_shl:1 row_mask:0xf bank_mask:0xf bound_ctrl:1
	v_add_f32_dpp v41, v41, v41 row_shl:1 row_mask:0xf bank_mask:0xf bound_ctrl:1
	v_add_f32_dpp v42, v42, v42 row_shl:1 row_mask:0xf bank_mask:0xf bound_ctrl:1
	v_add_f32_dpp v43, v43, v43 row_shl:1 row_mask:0xf bank_mask:0xf bound_ctrl:1
	v_mov_b32_e32 v36, v156
	s_nop 1
	v_add_f32_dpp v44, v44, v44 row_shl:2 row_mask:0xf bank_mask:0xf bound_ctrl:1
	v_add_f32_dpp v45, v45, v45 row_shl:2 row_mask:0xf bank_mask:0xf bound_ctrl:1
	v_add_f32_dpp v46, v46, v46 row_shl:2 row_mask:0xf bank_mask:0xf bound_ctrl:1
	v_add_f32_dpp v47, v47, v47 row_shl:2 row_mask:0xf bank_mask:0xf bound_ctrl:1
	v_add_f32_dpp v40, v40, v40 row_shl:2 row_mask:0xf bank_mask:0xf bound_ctrl:1
	v_add_f32_dpp v41, v41, v41 row_shl:2 row_mask:0xf bank_mask:0xf bound_ctrl:1
	v_add_f32_dpp v42, v42, v42 row_shl:2 row_mask:0xf bank_mask:0xf bound_ctrl:1
	v_add_f32_dpp v43, v43, v43 row_shl:2 row_mask:0xf bank_mask:0xf bound_ctrl:1
	v_mov_b32_e32 v35, v155
	s_nop 1
	v_add_f32_dpp v44, v44, v44 row_shl:4 row_mask:0xf bank_mask:0xf bound_ctrl:1
	v_add_f32_dpp v45, v45, v45 row_shl:4 row_mask:0xf bank_mask:0xf bound_ctrl:1
	v_add_f32_dpp v46, v46, v46 row_shl:4 row_mask:0xf bank_mask:0xf bound_ctrl:1
	v_add_f32_dpp v47, v47, v47 row_shl:4 row_mask:0xf bank_mask:0xf bound_ctrl:1
	v_add_f32_dpp v40, v40, v40 row_shl:4 row_mask:0xf bank_mask:0xf bound_ctrl:1
	v_add_f32_dpp v41, v41, v41 row_shl:4 row_mask:0xf bank_mask:0xf bound_ctrl:1
	v_add_f32_dpp v42, v42, v42 row_shl:4 row_mask:0xf bank_mask:0xf bound_ctrl:1
	v_add_f32_dpp v43, v43, v43 row_shl:4 row_mask:0xf bank_mask:0xf bound_ctrl:1
	v_mov_b32_e32 v38, v158
	v_mov_b32_e32 v32, v152
	v_mov_b32_e32 v34, v154
	v_mov_b32_e32 v37, v157
	s_nop 1
	v_add_f32_dpp v44, v44, v44 row_shl:8 row_mask:0xf bank_mask:0xf bound_ctrl:1
	v_add_f32_dpp v45, v45, v45 row_shl:8 row_mask:0xf bank_mask:0xf bound_ctrl:1
	v_add_f32_dpp v46, v46, v46 row_shl:8 row_mask:0xf bank_mask:0xf bound_ctrl:1
	v_add_f32_dpp v47, v47, v47 row_shl:8 row_mask:0xf bank_mask:0xf bound_ctrl:1
	v_add_f32_dpp v40, v40, v40 row_shl:8 row_mask:0xf bank_mask:0xf bound_ctrl:1
	v_add_f32_dpp v41, v41, v41 row_shl:8 row_mask:0xf bank_mask:0xf bound_ctrl:1
	v_add_f32_dpp v42, v42, v42 row_shl:8 row_mask:0xf bank_mask:0xf bound_ctrl:1
	v_add_f32_dpp v43, v43, v43 row_shl:8 row_mask:0xf bank_mask:0xf bound_ctrl:1
	s_nop 1
	v_add_f32_dpp v36, v36, v36 row_shl:1 row_mask:0xf bank_mask:0xf bound_ctrl:1
	v_add_f32_dpp v37, v37, v37 row_shl:1 row_mask:0xf bank_mask:0xf bound_ctrl:1
	v_add_f32_dpp v38, v38, v38 row_shl:1 row_mask:0xf bank_mask:0xf bound_ctrl:1
	v_add_f32_dpp v39, v39, v39 row_shl:1 row_mask:0xf bank_mask:0xf bound_ctrl:1
	v_add_f32_dpp v32, v32, v32 row_shl:1 row_mask:0xf bank_mask:0xf bound_ctrl:1
	v_add_f32_dpp v33, v33, v33 row_shl:1 row_mask:0xf bank_mask:0xf bound_ctrl:1
	v_add_f32_dpp v34, v34, v34 row_shl:1 row_mask:0xf bank_mask:0xf bound_ctrl:1
	v_add_f32_dpp v35, v35, v35 row_shl:1 row_mask:0xf bank_mask:0xf bound_ctrl:1
	v_exp_f32_e32 v92, v64
	s_nop 1
	v_add_f32_dpp v36, v36, v36 row_shl:2 row_mask:0xf bank_mask:0xf bound_ctrl:1
	v_add_f32_dpp v37, v37, v37 row_shl:2 row_mask:0xf bank_mask:0xf bound_ctrl:1
	v_add_f32_dpp v38, v38, v38 row_shl:2 row_mask:0xf bank_mask:0xf bound_ctrl:1
	v_add_f32_dpp v39, v39, v39 row_shl:2 row_mask:0xf bank_mask:0xf bound_ctrl:1
	v_add_f32_dpp v32, v32, v32 row_shl:2 row_mask:0xf bank_mask:0xf bound_ctrl:1
	v_add_f32_dpp v33, v33, v33 row_shl:2 row_mask:0xf bank_mask:0xf bound_ctrl:1
	v_add_f32_dpp v34, v34, v34 row_shl:2 row_mask:0xf bank_mask:0xf bound_ctrl:1
	v_add_f32_dpp v35, v35, v35 row_shl:2 row_mask:0xf bank_mask:0xf bound_ctrl:1
	v_exp_f32_e32 v93, v65
	s_nop 1
	v_add_f32_dpp v36, v36, v36 row_shl:4 row_mask:0xf bank_mask:0xf bound_ctrl:1
	v_add_f32_dpp v37, v37, v37 row_shl:4 row_mask:0xf bank_mask:0xf bound_ctrl:1
	v_add_f32_dpp v38, v38, v38 row_shl:4 row_mask:0xf bank_mask:0xf bound_ctrl:1
	v_add_f32_dpp v39, v39, v39 row_shl:4 row_mask:0xf bank_mask:0xf bound_ctrl:1
	v_add_f32_dpp v32, v32, v32 row_shl:4 row_mask:0xf bank_mask:0xf bound_ctrl:1
	v_add_f32_dpp v33, v33, v33 row_shl:4 row_mask:0xf bank_mask:0xf bound_ctrl:1
	v_add_f32_dpp v34, v34, v34 row_shl:4 row_mask:0xf bank_mask:0xf bound_ctrl:1
	v_add_f32_dpp v35, v35, v35 row_shl:4 row_mask:0xf bank_mask:0xf bound_ctrl:1
	v_exp_f32_e32 v94, v66
	s_nop 1
	v_add_f32_dpp v36, v36, v36 row_shl:8 row_mask:0xf bank_mask:0xf bound_ctrl:1
	v_add_f32_dpp v37, v37, v37 row_shl:8 row_mask:0xf bank_mask:0xf bound_ctrl:1
	v_add_f32_dpp v38, v38, v38 row_shl:8 row_mask:0xf bank_mask:0xf bound_ctrl:1
	v_add_f32_dpp v39, v39, v39 row_shl:8 row_mask:0xf bank_mask:0xf bound_ctrl:1
	v_add_f32_dpp v32, v32, v32 row_shl:8 row_mask:0xf bank_mask:0xf bound_ctrl:1
	v_add_f32_dpp v33, v33, v33 row_shl:8 row_mask:0xf bank_mask:0xf bound_ctrl:1
	v_add_f32_dpp v34, v34, v34 row_shl:8 row_mask:0xf bank_mask:0xf bound_ctrl:1
	v_add_f32_dpp v35, v35, v35 row_shl:8 row_mask:0xf bank_mask:0xf bound_ctrl:1
	v_exp_f32_e32 v95, v67
	v_exp_f32_e32 v88, v60
	v_exp_f32_e32 v89, v61
	v_exp_f32_e32 v90, v62
	v_exp_f32_e32 v91, v63
	v_exp_f32_e32 v84, v52
	v_exp_f32_e32 v85, v53
	v_exp_f32_e32 v86, v54
	v_exp_f32_e32 v87, v55
	v_exp_f32_e32 v80, v48
	v_exp_f32_e32 v81, v49
	v_exp_f32_e32 v82, v50
	v_exp_f32_e32 v83, v51
	v_exp_f32_e32 v76, v44
	v_exp_f32_e32 v77, v45
	v_exp_f32_e32 v78, v46
	v_exp_f32_e32 v79, v47
	v_exp_f32_e32 v72, v40
	v_exp_f32_e32 v73, v41
	v_exp_f32_e32 v74, v42
	v_exp_f32_e32 v75, v43
	v_exp_f32_e32 v68, v36
	v_exp_f32_e32 v69, v37
	v_exp_f32_e32 v70, v38
	v_exp_f32_e32 v71, v39
	v_exp_f32_e32 v56, v32
	v_exp_f32_e32 v57, v33
	v_exp_f32_e32 v58, v34
	v_exp_f32_e32 v59, v35
	s_and_saveexec_b64 s[6:7], vcc
	s_cbranch_execz .LBB0_2621
; template <int DIR> __device__ __forceinline__ void h3_dir(unsigned char* lds, const bf16_t* zrow, int h, const bf16_t* slot, f32x4 (&o)[8]) {
;     ...
;         if (r == (DIR ? 0 : 15)) {
; #pragma unroll
;             for (int ks = 0; ks < 4; ++ks) { *(f32x4*)(TOT + wid * 128 + 32 * ks + 8 * kq) = (f32x4){bl[8 * ks], bl[8 * ks + 1], bl[8 * ks + 2], bl[8 * ks + 3]}; *(f32x4*)(TOT + wid * 128 + 32 * ks + 8 * kq + 4) = (f32x4){bl[8 * ks + 4], bl[8 * ks + 5], bl[8 * ks + 6], bl[8 * ks + 7]}; }
; #pragma unroll
;             for (int ks = 0; ks < 4; ++ks) { *(f32x4*)(TOTE + wid * 128 + 32 * ks + 8 * kq) = (f32x4){eb[8 * ks], eb[8 * ks + 1], eb[8 * ks + 2], eb[8 * ks + 3]}; *(f32x4*)(TOTE + wid * 128 + 32 * ks + 8 * kq + 4) = (f32x4){eb[8 * ks + 4], eb[8 * ks + 5], eb[8 * ks + 6], eb[8 * ks + 7]}; }
;         }
	s_add_i32 s37, s3, 0
	v_lshl_add_u32 v183, v148, 2, s37
	ds_write_b128 v183, v[64:67]
	ds_write_b128 v183, v[60:63] offset:16
	ds_write_b128 v183, v[52:55] offset:128
	ds_write_b128 v183, v[48:51] offset:144
	ds_write_b128 v183, v[44:47] offset:256
	ds_write_b128 v183, v[40:43] offset:272
	ds_write_b128 v183, v[36:39] offset:384
	ds_write_b128 v183, v[32:35] offset:400
	ds_write_b128 v183, v[92:95] offset:4096
	ds_write_b128 v183, v[88:91] offset:4112
	ds_write_b128 v183, v[84:87] offset:4224
	ds_write_b128 v183, v[80:83] offset:4240
	ds_write_b128 v183, v[76:79] offset:4352
	ds_write_b128 v183, v[72:75] offset:4368
	ds_write_b128 v183, v[68:71] offset:4480
	ds_write_b128 v183, v[56:59] offset:4496
